# all nine GEMM K-loops restructured: 64 MFMAs per barrier pair, all fragments loaded in the load segment using spare VGPRs, half-specific tile staging
# speedup vs baseline: 1.0001x; 1.0001x over previous
; #define PG8_STAGE(bufoff, gbase, voff) do { _Pragma("unroll") for (int _i = 0; _i < 2; ++_i) \
;         __builtin_amdgcn_global_load_lds((const unsigned*)((const char*)(gbase) + (voff)[_i]), (PG8_LAS unsigned*)(lds + (bufoff) + ldsw + _i * 8192), 16, 0, 0); } while (0)
; #define PG8_LDA(dst, b, h) do { _Pragma("unroll") for (int m = 0; m < 4; ++m) _Pragma("unroll") for (int k = 0; k < 2; ++k) dst[m][k] = *(const PG8_LAS bf16x8*)(lds + PG8_SA(b, h) + aoff + m * 2048 + k * 1024); } while (0)
; #define PG8_LDB(dst, b, h) do { _Pragma("unroll") for (int n = 0; n < 2; ++n) _Pragma("unroll") for (int k = 0; k < 2; ++k) dst[n][k] = *(const PG8_LAS bf16x8*)(lds + PG8_SB(b, h) + boff + n * 2048 + k * 1024); } while (0)
; #define PG8_WAIT_V(n) asm volatile("s_waitcnt vmcnt(" #n ")" ::: "memory")
; template <class Epi, class Sched, bool ALIGN_EPI = false, bool SP2 = false>
; __device__ __forceinline__ void gemm_phase(PG8_LAS unsigned char* lds, const Gemm g, const Sched& S, const Epi& E) {
;     ...
;     f32x4 acc[2][2][4][2];
; #pragma unroll
;     for (int a = 0; a < 2; ++a)
; #pragma unroll
;         for (int b = 0; b < 2; ++b)
; #pragma unroll
;             for (int m = 0; m < 4; ++m)
; #pragma unroll
;                 for (int n = 0; n < 2; ++n) acc[a][b][m][n] = (f32x4){0.f, 0.f, 0.f, 0.f};
;     ...
;         const bool has_next = S.next(ui + 1, nxt);
;         const char* nA = has_next ? (const char*)g.A + (size_t)nxt.pm * tstep : cA; const char* nB = has_next ? (const char*)g.Bt + (size_t)nxt.pn * tstep : cB;
;         for (int t = 0; t < nt; t += 2) {
;             const bool last = (t == nt - 2);
;             const char* a1 = cA + (size_t)(t + 1) * kstep;
;             const char* a2 = last ? nA : cA + (size_t)(t + 2) * kstep; const char* b2 = last ? nB : cB + (size_t)(t + 2) * kstep;
;             const char* a3 = a2 + kstep; const char* b3 = b2 + kstep;
;             if (last && has_next) S.a_ready(nxt);
;             if constexpr (SP2) {
;             PG8_LDB(B0, 0, 0); PG8_LDB(B1, 0, 1); PG8_SCHED; PG8_LDA(At, 0, 0); PG8_STAGE(PG8_SA(1, 1), a1 + hstep, voffA);
;             PG8_WAIT_V(8); PG8_WAIT_L(0); PG8_BAR; PG8_MMA(0, 0, At, B0); PG8_MMA(0, 1, At, B1); PG8_BAR; PG8_SCHED;
;             PG8_LDA(At, 0, 1); PG8_STAGE(PG8_SB(0, 0), b2, voffB); PG8_STAGE(PG8_SB(0, 1), b2 + hstep, voffB); PG8_STAGE(PG8_SA(0, 0), a2, voffA);
.LBB0_126:
	s_ashr_i32 s73, s72, 31
	s_lshl_b64 s[12:13], s[72:73], 20
	s_add_u32 s82, s40, s12
	s_addc_u32 s83, s41, s13
	s_and_b64 s[12:13], s[4:5], exec
	s_cselect_b32 s12, s83, s91
	s_cselect_b32 s13, s82, s90
	s_ashr_i32 s71, s70, 31
	s_lshl_b64 s[66:67], s[70:71], 20
	s_add_u32 s86, s78, s66
	s_addc_u32 s87, s79, s67
	s_and_b64 s[66:67], s[4:5], exec
	s_cselect_b32 s71, s87, s93
	s_cselect_b32 s73, s86, s92
	s_add_u32 s90, s90, 0x80080
	s_addc_u32 s91, s91, 0
	s_add_u32 vcc_lo, s92, 0x100
	v_mov_b64_e32 v[0:1], 0
	v_mov_b64_e32 v[2:3], 0
	v_mov_b64_e32 v[4:5], 0
	v_mov_b64_e32 v[6:7], 0
	v_mov_b64_e32 v[8:9], 0
	v_mov_b64_e32 v[10:11], 0
	v_mov_b64_e32 v[12:13], 0
	v_mov_b64_e32 v[14:15], 0
	v_mov_b64_e32 v[16:17], 0
	v_mov_b64_e32 v[18:19], 0
	v_mov_b64_e32 v[20:21], 0
	v_mov_b64_e32 v[22:23], 0
	v_mov_b64_e32 v[24:25], 0
	v_mov_b64_e32 v[26:27], 0
	v_mov_b64_e32 v[28:29], 0
	v_mov_b64_e32 v[30:31], 0
	v_mov_b64_e32 v[32:33], 0
	v_mov_b64_e32 v[34:35], 0
	v_mov_b64_e32 v[36:37], 0
	v_mov_b64_e32 v[38:39], 0
	v_mov_b64_e32 v[40:41], 0
	v_mov_b64_e32 v[42:43], 0
	v_mov_b64_e32 v[44:45], 0
	v_mov_b64_e32 v[46:47], 0
	v_mov_b64_e32 v[48:49], 0
	v_mov_b64_e32 v[50:51], 0
	v_mov_b64_e32 v[52:53], 0
	v_mov_b64_e32 v[54:55], 0
	v_mov_b64_e32 v[56:57], 0
	v_mov_b64_e32 v[58:59], 0
	v_mov_b64_e32 v[60:61], 0
	v_mov_b64_e32 v[62:63], 0
	v_mov_b64_e32 v[64:65], 0
	v_mov_b64_e32 v[66:67], 0
	v_mov_b64_e32 v[68:69], 0
	v_mov_b64_e32 v[70:71], 0
	v_mov_b64_e32 v[72:73], 0
	v_mov_b64_e32 v[74:75], 0
	v_mov_b64_e32 v[76:77], 0
	v_mov_b64_e32 v[78:79], 0
	v_mov_b64_e32 v[80:81], 0
	v_mov_b64_e32 v[82:83], 0
	v_mov_b64_e32 v[84:85], 0
	v_mov_b64_e32 v[86:87], 0
	v_mov_b64_e32 v[88:89], 0
	v_mov_b64_e32 v[90:91], 0
	v_mov_b64_e32 v[92:93], 0
	v_mov_b64_e32 v[94:95], 0
	v_mov_b64_e32 v[96:97], 0
	v_mov_b64_e32 v[98:99], 0
	v_mov_b64_e32 v[100:101], 0
	v_mov_b64_e32 v[102:103], 0
	v_mov_b64_e32 v[104:105], 0
	v_mov_b64_e32 v[106:107], 0
	v_mov_b64_e32 v[108:109], 0
	v_mov_b64_e32 v[110:111], 0
	v_mov_b64_e32 v[112:113], 0
	v_mov_b64_e32 v[114:115], 0
	v_mov_b64_e32 v[116:117], 0
	v_mov_b64_e32 v[118:119], 0
	v_mov_b64_e32 v[120:121], 0
	v_mov_b64_e32 v[122:123], 0
	v_mov_b64_e32 v[124:125], 0
	v_mov_b64_e32 v[126:127], 0
	s_addc_u32 vcc_hi, s93, 0
	s_mov_b32 s66, -2
	v_mov_b32_e32 v129, v155
	v_mov_b32_e32 v131, v159
	v_mov_b32_e32 v133, v163
	v_mov_b32_e32 v135, v167
	v_mov_b32_e32 v139, v173
	v_mov_b32_e32 v141, v175
	v_mov_b32_e32 v166, v216
	v_add_u32_e32 v172, 0x18000, v131
	v_add_u32_e32 v174, 0x1c000, v131
	s_cmp_lg_u32 s10, 0
	s_cbranch_scc0 .Lspf0_pre
	s_add_i32 m0, s3, 0xc000
	s_nop 0
	global_load_lds_dwordx4 v138, s[90:91]
	s_add_u32 s98, s90, 0x20000
	s_addc_u32 s99, s91, 0
	s_add_i32 m0, s3, 0xd000
	s_nop 0
	global_load_lds_dwordx4 v138, s[98:99]
	s_add_u32 s98, s90, 0xfff80000
	s_addc_u32 s99, s91, -1
	s_add_i32 m0, s3, 0x8000
	s_nop 0
	global_load_lds_dwordx4 v138, s[98:99]
	s_add_u32 s98, s90, 0xfffa0000
	s_addc_u32 s99, s91, -1
	s_add_i32 m0, s3, 0x9000
	s_nop 0
	global_load_lds_dwordx4 v138, s[98:99]
.Lspf0_pre:
.LBB0_127:
	s_add_u32 s67, s90, 0xfff80080
	s_addc_u32 s74, s91, -1
	s_cmp_eq_u32 s66, 28
	s_cselect_b32 s95, s12, s74
	s_cselect_b32 s94, s13, s67
	s_cselect_b32 s93, s71, vcc_hi
	s_cselect_b32 s92, s73, vcc_lo
	s_cmp_lg_u32 s10, 0
	s_cbranch_scc0 .Lspf0_a_h1
	s_add_u32 s98, vcc_lo, 0xffffff80
	s_addc_u32 s99, vcc_hi, -1
	s_add_i32 m0, s3, 0x18000
	ds_read_b128 v[146:149], v135
	ds_read_b128 v[150:153], v135 offset:1024
	ds_read_b128 v[168:171], v135 offset:2048
	global_load_lds_dwordx4 v132, s[98:99]
	s_add_i32 m0, s3, 0x1a000
	ds_read_b128 v[178:181], v135 offset:3072
	ds_read_b128 v[182:185], v139
	ds_read_b128 v[186:189], v139 offset:1024
	global_load_lds_dwordx4 v128, s[98:99]
	s_add_u32 s98, vcc_lo, 0x1ff80
	s_addc_u32 s99, vcc_hi, 0
	s_add_i32 m0, s3, 0x19000
	ds_read_b128 v[190:193], v139 offset:2048
	ds_read_b128 v[194:197], v139 offset:3072
	ds_read_b128 v[198:201], v141
	global_load_lds_dwordx4 v132, s[98:99]
	s_add_i32 m0, s3, 0x1b000
	ds_read_b128 v[202:205], v141 offset:1024
	ds_read_b128 v[206:209], v141 offset:2048
	ds_read_b128 v[210:213], v141 offset:3072
	global_load_lds_dwordx4 v128, s[98:99]
	s_add_u32 s98, vcc_lo, 0x7ff80
	s_addc_u32 s99, vcc_hi, 0
	s_add_i32 m0, s3, 0x1c000
	ds_read_b128 v[218:221], v141 offset:4096
	ds_read_b128 v[224:227], v141 offset:5120
	ds_read_b128 v[228:231], v141 offset:6144
	global_load_lds_dwordx4 v132, s[98:99]
	s_add_i32 m0, s3, 0x1e000
	ds_read_b128 v[232:235], v141 offset:7168
	ds_read_b128 v[154:157], v141 offset:16384
	ds_read_b128 v[158:161], v141 offset:17408
	global_load_lds_dwordx4 v128, s[98:99]
	s_add_u32 s98, vcc_lo, 0x9ff80
	s_addc_u32 s99, vcc_hi, 0
	s_add_i32 m0, s3, 0x1d000
	ds_read_b128 v[162:165], v141 offset:18432
	ds_read_b128 v[214:217], v141 offset:19456
	ds_read_b128 v[236:239], v141 offset:20480
	global_load_lds_dwordx4 v132, s[98:99]
	s_add_i32 m0, s3, 0x1f000
	ds_read_b128 v[240:243], v141 offset:21504
	ds_read_b128 v[244:247], v141 offset:22528
	ds_read_b128 v[248:251], v141 offset:23552
	global_load_lds_dwordx4 v128, s[98:99]
	s_branch .Lspf0_a_rd
; #define PG8_STAGE(bufoff, gbase, voff) do { _Pragma("unroll") for (int _i = 0; _i < 2; ++_i) \
;         __builtin_amdgcn_global_load_lds((const unsigned*)((const char*)(gbase) + (voff)[_i]), (PG8_LAS unsigned*)(lds + (bufoff) + ldsw + _i * 8192), 16, 0, 0); } while (0)
; #define PG8_LDA(dst, b, h) do { _Pragma("unroll") for (int m = 0; m < 4; ++m) _Pragma("unroll") for (int k = 0; k < 2; ++k) dst[m][k] = *(const PG8_LAS bf16x8*)(lds + PG8_SA(b, h) + aoff + m * 2048 + k * 1024); } while (0)
; #define PG8_LDB(dst, b, h) do { _Pragma("unroll") for (int n = 0; n < 2; ++n) _Pragma("unroll") for (int k = 0; k < 2; ++k) dst[n][k] = *(const PG8_LAS bf16x8*)(lds + PG8_SB(b, h) + boff + n * 2048 + k * 1024); } while (0)
; #define PG8_MMA(ai, bj, At, Bt) do { __builtin_amdgcn_s_setprio(1); _Pragma("unroll") for (int m = 0; m < 4; ++m) _Pragma("unroll") for (int n = 0; n < 2; ++n) _Pragma("unroll") for (int k = 0; k < 2; ++k) \
;         acc[ai][bj][m][n] = __builtin_amdgcn_mfma_f32_16x16x32_bf16(Bt[n][k], At[m][k], acc[ai][bj][m][n], 0, 0, 0); __builtin_amdgcn_s_setprio(0); } while (0)
; #define PG8_WAIT_V(n) asm volatile("s_waitcnt vmcnt(" #n ")" ::: "memory")
; #define PG8_WAIT_L(n) asm volatile("s_waitcnt lgkmcnt(" #n ")" ::: "memory")
; #define PG8_BAR __builtin_amdgcn_s_barrier()
; #define PG8_SCHED __builtin_amdgcn_sched_barrier(0)
; template <class Epi, class Sched, bool ALIGN_EPI = false, bool SP2 = false>
; __device__ __forceinline__ void gemm_phase(PG8_LAS unsigned char* lds, const Gemm g, const Sched& S, const Epi& E) {
;     ...
;             PG8_LDB(B0, 0, 0); PG8_LDB(B1, 0, 1); PG8_SCHED; PG8_LDA(At, 0, 0); PG8_STAGE(PG8_SA(1, 1), a1 + hstep, voffA);
;             PG8_WAIT_V(8); PG8_WAIT_L(0); PG8_BAR; PG8_MMA(0, 0, At, B0); PG8_MMA(0, 1, At, B1); PG8_BAR; PG8_SCHED;
;             PG8_LDA(At, 0, 1); PG8_STAGE(PG8_SB(0, 0), b2, voffB); PG8_STAGE(PG8_SB(0, 1), b2 + hstep, voffB); PG8_STAGE(PG8_SA(0, 0), a2, voffA);
;             PG8_WAIT_V(8); PG8_WAIT_L(0); PG8_BAR; PG8_MMA(1, 0, At, B0); PG8_MMA(1, 1, At, B1); PG8_BAR; PG8_SCHED;
.Lspf0_a_h1:
	s_add_u32 s98, s90, 0xfff80000
	s_addc_u32 s99, s91, -1
	s_add_i32 m0, s3, 0xa000
	ds_read_b128 v[146:149], v135
	ds_read_b128 v[150:153], v135 offset:1024
	ds_read_b128 v[168:171], v135 offset:2048
	global_load_lds_dwordx4 v140, s[98:99]
	s_add_u32 s98, s90, 0xfff60000
	s_addc_u32 s99, s91, -1
	s_add_i32 m0, s3, 0x9000
	ds_read_b128 v[178:181], v135 offset:3072
	ds_read_b128 v[182:185], v139
	ds_read_b128 v[186:189], v139 offset:1024
	global_load_lds_dwordx4 v140, s[98:99]
	s_add_i32 m0, s3, 0xe000
	ds_read_b128 v[190:193], v139 offset:2048
	ds_read_b128 v[194:197], v139 offset:3072
	ds_read_b128 v[198:201], v141
	global_load_lds_dwordx4 v140, s[90:91]
	s_add_u32 s98, s90, 0xfffe0000
	s_addc_u32 s99, s91, -1
	s_add_i32 m0, s3, 0xd000
	ds_read_b128 v[202:205], v141 offset:1024
	ds_read_b128 v[206:209], v141 offset:2048
	ds_read_b128 v[210:213], v141 offset:3072
	global_load_lds_dwordx4 v140, s[98:99]
	s_add_i32 m0, s3, 0x0
	ds_read_b128 v[218:221], v141 offset:4096
	ds_read_b128 v[224:227], v141 offset:5120
	ds_read_b128 v[228:231], v141 offset:6144
	global_load_lds_dwordx4 v134, s[94:95]
	s_add_u32 s98, s94, 0xfffe0000
	s_addc_u32 s99, s95, -1
	s_add_i32 m0, s3, 0xfffff000
	ds_read_b128 v[232:235], v141 offset:7168
	ds_read_b128 v[154:157], v141 offset:16384
	ds_read_b128 v[158:161], v141 offset:17408
	global_load_lds_dwordx4 v134, s[98:99]
	s_add_u32 s98, s94, 0x80000
	s_addc_u32 s99, s95, 0
	s_add_i32 m0, s3, 0x4000
	ds_read_b128 v[162:165], v141 offset:18432
	ds_read_b128 v[214:217], v141 offset:19456
	ds_read_b128 v[236:239], v141 offset:20480
	global_load_lds_dwordx4 v134, s[98:99]
	s_add_u32 s98, s94, 0x60000
	s_addc_u32 s99, s95, 0
	s_add_i32 m0, s3, 0x3000
	ds_read_b128 v[240:243], v141 offset:21504
	ds_read_b128 v[244:247], v141 offset:22528
	ds_read_b128 v[248:251], v141 offset:23552
	global_load_lds_dwordx4 v134, s[98:99]
.Lspf0_a_rd:
	s_waitcnt lgkmcnt(0)
	s_setprio 1
	s_barrier
	v_mfma_f32_16x16x32_bf16 v[124:127], v[146:149], v[198:201], v[124:127]
	v_mfma_f32_16x16x32_bf16 v[120:123], v[168:171], v[198:201], v[120:123]
	v_mfma_f32_16x16x32_bf16 v[108:111], v[146:149], v[206:209], v[108:111]
	v_mfma_f32_16x16x32_bf16 v[104:107], v[168:171], v[206:209], v[104:107]
	v_mfma_f32_16x16x32_bf16 v[92:95], v[146:149], v[218:221], v[92:95]
	v_mfma_f32_16x16x32_bf16 v[88:91], v[168:171], v[218:221], v[88:91]
	v_mfma_f32_16x16x32_bf16 v[76:79], v[146:149], v[228:231], v[76:79]
	v_mfma_f32_16x16x32_bf16 v[72:75], v[168:171], v[228:231], v[72:75]
	v_mfma_f32_16x16x32_bf16 v[124:127], v[150:153], v[202:205], v[124:127]
	v_mfma_f32_16x16x32_bf16 v[120:123], v[178:181], v[202:205], v[120:123]
	v_mfma_f32_16x16x32_bf16 v[108:111], v[150:153], v[210:213], v[108:111]
	v_mfma_f32_16x16x32_bf16 v[104:107], v[178:181], v[210:213], v[104:107]
	v_mfma_f32_16x16x32_bf16 v[92:95], v[150:153], v[224:227], v[92:95]
	v_mfma_f32_16x16x32_bf16 v[88:91], v[178:181], v[224:227], v[88:91]
	v_mfma_f32_16x16x32_bf16 v[76:79], v[150:153], v[232:235], v[76:79]
	v_mfma_f32_16x16x32_bf16 v[72:75], v[178:181], v[232:235], v[72:75]
	v_mfma_f32_16x16x32_bf16 v[116:119], v[182:185], v[198:201], v[116:119]
	v_mfma_f32_16x16x32_bf16 v[112:115], v[190:193], v[198:201], v[112:115]
	v_mfma_f32_16x16x32_bf16 v[100:103], v[182:185], v[206:209], v[100:103]
	v_mfma_f32_16x16x32_bf16 v[96:99], v[190:193], v[206:209], v[96:99]
	v_mfma_f32_16x16x32_bf16 v[84:87], v[182:185], v[218:221], v[84:87]
	v_mfma_f32_16x16x32_bf16 v[80:83], v[190:193], v[218:221], v[80:83]
	v_mfma_f32_16x16x32_bf16 v[68:71], v[182:185], v[228:231], v[68:71]
	v_mfma_f32_16x16x32_bf16 v[64:67], v[190:193], v[228:231], v[64:67]
	v_mfma_f32_16x16x32_bf16 v[116:119], v[186:189], v[202:205], v[116:119]
	v_mfma_f32_16x16x32_bf16 v[112:115], v[194:197], v[202:205], v[112:115]
	v_mfma_f32_16x16x32_bf16 v[100:103], v[186:189], v[210:213], v[100:103]
	v_mfma_f32_16x16x32_bf16 v[96:99], v[194:197], v[210:213], v[96:99]
	v_mfma_f32_16x16x32_bf16 v[84:87], v[186:189], v[224:227], v[84:87]
	v_mfma_f32_16x16x32_bf16 v[80:83], v[194:197], v[224:227], v[80:83]
	v_mfma_f32_16x16x32_bf16 v[68:71], v[186:189], v[232:235], v[68:71]
	v_mfma_f32_16x16x32_bf16 v[64:67], v[194:197], v[232:235], v[64:67]
	v_mfma_f32_16x16x32_bf16 v[60:63], v[146:149], v[154:157], v[60:63]
	v_mfma_f32_16x16x32_bf16 v[56:59], v[168:171], v[154:157], v[56:59]
	v_mfma_f32_16x16x32_bf16 v[44:47], v[146:149], v[162:165], v[44:47]
	v_mfma_f32_16x16x32_bf16 v[40:43], v[168:171], v[162:165], v[40:43]
	v_mfma_f32_16x16x32_bf16 v[28:31], v[146:149], v[236:239], v[28:31]
	v_mfma_f32_16x16x32_bf16 v[24:27], v[168:171], v[236:239], v[24:27]
	v_mfma_f32_16x16x32_bf16 v[12:15], v[146:149], v[244:247], v[12:15]
	v_mfma_f32_16x16x32_bf16 v[8:11], v[168:171], v[244:247], v[8:11]
	v_mfma_f32_16x16x32_bf16 v[60:63], v[150:153], v[158:161], v[60:63]
	v_mfma_f32_16x16x32_bf16 v[56:59], v[178:181], v[158:161], v[56:59]
	v_mfma_f32_16x16x32_bf16 v[44:47], v[150:153], v[214:217], v[44:47]
	v_mfma_f32_16x16x32_bf16 v[40:43], v[178:181], v[214:217], v[40:43]
	v_mfma_f32_16x16x32_bf16 v[28:31], v[150:153], v[240:243], v[28:31]
	v_mfma_f32_16x16x32_bf16 v[24:27], v[178:181], v[240:243], v[24:27]
	v_mfma_f32_16x16x32_bf16 v[12:15], v[150:153], v[248:251], v[12:15]
	v_mfma_f32_16x16x32_bf16 v[8:11], v[178:181], v[248:251], v[8:11]
	v_mfma_f32_16x16x32_bf16 v[52:55], v[182:185], v[154:157], v[52:55]
	v_mfma_f32_16x16x32_bf16 v[48:51], v[190:193], v[154:157], v[48:51]
	v_mfma_f32_16x16x32_bf16 v[36:39], v[182:185], v[162:165], v[36:39]
	v_mfma_f32_16x16x32_bf16 v[32:35], v[190:193], v[162:165], v[32:35]
	v_mfma_f32_16x16x32_bf16 v[20:23], v[182:185], v[236:239], v[20:23]
	v_mfma_f32_16x16x32_bf16 v[16:19], v[190:193], v[236:239], v[16:19]
	v_mfma_f32_16x16x32_bf16 v[4:7], v[182:185], v[244:247], v[4:7]
	v_mfma_f32_16x16x32_bf16 v[0:3], v[190:193], v[244:247], v[0:3]
	v_mfma_f32_16x16x32_bf16 v[52:55], v[186:189], v[158:161], v[52:55]
	v_mfma_f32_16x16x32_bf16 v[48:51], v[194:197], v[158:161], v[48:51]
	v_mfma_f32_16x16x32_bf16 v[36:39], v[186:189], v[214:217], v[36:39]
	v_mfma_f32_16x16x32_bf16 v[32:35], v[194:197], v[214:217], v[32:35]
	v_mfma_f32_16x16x32_bf16 v[20:23], v[186:189], v[240:243], v[20:23]
	v_mfma_f32_16x16x32_bf16 v[16:19], v[194:197], v[240:243], v[16:19]
	v_mfma_f32_16x16x32_bf16 v[4:7], v[186:189], v[248:251], v[4:7]
	v_mfma_f32_16x16x32_bf16 v[0:3], v[194:197], v[248:251], v[0:3]
	s_waitcnt vmcnt(0)
	s_barrier
; #define PG8_STAGE(bufoff, gbase, voff) do { _Pragma("unroll") for (int _i = 0; _i < 2; ++_i) \
;         __builtin_amdgcn_global_load_lds((const unsigned*)((const char*)(gbase) + (voff)[_i]), (PG8_LAS unsigned*)(lds + (bufoff) + ldsw + _i * 8192), 16, 0, 0); } while (0)
; #define PG8_LDA(dst, b, h) do { _Pragma("unroll") for (int m = 0; m < 4; ++m) _Pragma("unroll") for (int k = 0; k < 2; ++k) dst[m][k] = *(const PG8_LAS bf16x8*)(lds + PG8_SA(b, h) + aoff + m * 2048 + k * 1024); } while (0)
; #define PG8_LDB(dst, b, h) do { _Pragma("unroll") for (int n = 0; n < 2; ++n) _Pragma("unroll") for (int k = 0; k < 2; ++k) dst[n][k] = *(const PG8_LAS bf16x8*)(lds + PG8_SB(b, h) + boff + n * 2048 + k * 1024); } while (0)
; #define PG8_MMA(ai, bj, At, Bt) do { __builtin_amdgcn_s_setprio(1); _Pragma("unroll") for (int m = 0; m < 4; ++m) _Pragma("unroll") for (int n = 0; n < 2; ++n) _Pragma("unroll") for (int k = 0; k < 2; ++k) \
;         acc[ai][bj][m][n] = __builtin_amdgcn_mfma_f32_16x16x32_bf16(Bt[n][k], At[m][k], acc[ai][bj][m][n], 0, 0, 0); __builtin_amdgcn_s_setprio(0); } while (0)
; #define PG8_WAIT_V(n) asm volatile("s_waitcnt vmcnt(" #n ")" ::: "memory")
; #define PG8_WAIT_L(n) asm volatile("s_waitcnt lgkmcnt(" #n ")" ::: "memory")
; #define PG8_BAR __builtin_amdgcn_s_barrier()
; #define PG8_SCHED __builtin_amdgcn_sched_barrier(0)
; template <class Epi, class Sched, bool ALIGN_EPI = false, bool SP2 = false>
; __device__ __forceinline__ void gemm_phase(PG8_LAS unsigned char* lds, const Gemm g, const Sched& S, const Epi& E) {
;     ...
;             PG8_LDA(At, 0, 1); PG8_STAGE(PG8_SB(0, 0), b2, voffB); PG8_STAGE(PG8_SB(0, 1), b2 + hstep, voffB); PG8_STAGE(PG8_SA(0, 0), a2, voffA);
;             PG8_WAIT_V(8); PG8_WAIT_L(0); PG8_BAR; PG8_MMA(1, 0, At, B0); PG8_MMA(1, 1, At, B1); PG8_BAR; PG8_SCHED;
;             PG8_LDB(B0, 1, 0); PG8_LDB(B1, 1, 1); PG8_SCHED; PG8_LDA(At, 1, 0); PG8_STAGE(PG8_SA(0, 1), a2 + hstep, voffA);
;             PG8_WAIT_V(8); PG8_WAIT_L(0); PG8_BAR; PG8_MMA(0, 0, At, B0); PG8_MMA(0, 1, At, B1); PG8_BAR; PG8_SCHED;
;             PG8_LDA(At, 1, 1); PG8_STAGE(PG8_SB(1, 0), b3, voffB); PG8_STAGE(PG8_SB(1, 1), b3 + hstep, voffB); PG8_STAGE(PG8_SA(1, 0), a3, voffA);
	s_setprio 0
	s_cmp_lg_u32 s10, 0
	s_cbranch_scc0 .Lspf0_b_h1
	s_add_i32 m0, s3, 0x10000
	ds_read_b128 v[146:149], v172
	ds_read_b128 v[150:153], v172 offset:1024
	ds_read_b128 v[168:171], v172 offset:2048
	global_load_lds_dwordx4 v132, s[92:93]
	s_add_i32 m0, s3, 0x12000
	ds_read_b128 v[178:181], v172 offset:3072
	ds_read_b128 v[182:185], v174
	ds_read_b128 v[186:189], v174 offset:1024
	global_load_lds_dwordx4 v128, s[92:93]
	s_add_u32 s98, s92, 0x20000
	s_addc_u32 s99, s93, 0
	s_add_i32 m0, s3, 0x11000
	ds_read_b128 v[190:193], v174 offset:2048
	ds_read_b128 v[194:197], v174 offset:3072
	ds_read_b128 v[198:201], v141 offset:32768
	global_load_lds_dwordx4 v132, s[98:99]
	s_add_i32 m0, s3, 0x13000
	ds_read_b128 v[202:205], v141 offset:33792
	ds_read_b128 v[206:209], v141 offset:34816
	ds_read_b128 v[210:213], v141 offset:35840
	global_load_lds_dwordx4 v128, s[98:99]
	s_add_u32 s98, s92, 0x80000
	s_addc_u32 s99, s93, 0
	s_add_i32 m0, s3, 0x14000
	ds_read_b128 v[218:221], v141 offset:36864
	ds_read_b128 v[224:227], v141 offset:37888
	ds_read_b128 v[228:231], v141 offset:38912
	global_load_lds_dwordx4 v132, s[98:99]
	s_add_i32 m0, s3, 0x16000
	ds_read_b128 v[232:235], v141 offset:39936
	ds_read_b128 v[154:157], v141 offset:49152
	ds_read_b128 v[158:161], v141 offset:50176
	global_load_lds_dwordx4 v128, s[98:99]
	s_add_u32 s98, s92, 0xa0000
	s_addc_u32 s99, s93, 0
	s_add_i32 m0, s3, 0x15000
	ds_read_b128 v[162:165], v141 offset:51200
	ds_read_b128 v[214:217], v141 offset:52224
	ds_read_b128 v[236:239], v141 offset:53248
	global_load_lds_dwordx4 v132, s[98:99]
	s_add_i32 m0, s3, 0x17000
	ds_read_b128 v[240:243], v141 offset:54272
	ds_read_b128 v[244:247], v141 offset:55296
	ds_read_b128 v[248:251], v141 offset:56320
	global_load_lds_dwordx4 v128, s[98:99]
	s_branch .Lspf0_b_rd
.Lspf0_b_h1:
	s_add_i32 m0, s3, 0x2000
	ds_read_b128 v[146:149], v172
	ds_read_b128 v[150:153], v172 offset:1024
	ds_read_b128 v[168:171], v172 offset:2048
	global_load_lds_dwordx4 v130, s[94:95]
	s_add_u32 s98, s94, 0xfffe0000
	s_addc_u32 s99, s95, -1
	s_add_i32 m0, s3, 0x1000
	ds_read_b128 v[178:181], v172 offset:3072
	ds_read_b128 v[182:185], v174
	ds_read_b128 v[186:189], v174 offset:1024
	global_load_lds_dwordx4 v130, s[98:99]
	s_add_u32 s98, s94, 0x80000
	s_addc_u32 s99, s95, 0
	s_add_i32 m0, s3, 0x6000
	ds_read_b128 v[190:193], v174 offset:2048
	ds_read_b128 v[194:197], v174 offset:3072
	ds_read_b128 v[198:201], v141 offset:32768
	global_load_lds_dwordx4 v130, s[98:99]
	s_add_u32 s98, s94, 0x60000
	s_addc_u32 s99, s95, 0
	s_add_i32 m0, s3, 0x5000
	ds_read_b128 v[202:205], v141 offset:33792
	ds_read_b128 v[206:209], v141 offset:34816
	ds_read_b128 v[210:213], v141 offset:35840
	global_load_lds_dwordx4 v130, s[98:99]
	s_add_u32 s98, s94, 0x80
	s_addc_u32 s99, s95, 0
	s_add_i32 m0, s3, 0x8000
	ds_read_b128 v[218:221], v141 offset:36864
	ds_read_b128 v[224:227], v141 offset:37888
	ds_read_b128 v[228:231], v141 offset:38912
	global_load_lds_dwordx4 v134, s[98:99]
	s_add_u32 s98, s94, 0xfffe0080
	s_addc_u32 s99, s95, -1
	s_add_i32 m0, s3, 0x7000
	ds_read_b128 v[232:235], v141 offset:39936
	ds_read_b128 v[154:157], v141 offset:49152
	ds_read_b128 v[158:161], v141 offset:50176
	global_load_lds_dwordx4 v134, s[98:99]
	s_add_u32 s98, s94, 0x80080
	s_addc_u32 s99, s95, 0
	s_add_i32 m0, s3, 0xc000
	ds_read_b128 v[162:165], v141 offset:51200
	ds_read_b128 v[214:217], v141 offset:52224
	ds_read_b128 v[236:239], v141 offset:53248
	global_load_lds_dwordx4 v134, s[98:99]
	s_add_u32 s98, s94, 0x60080
	s_addc_u32 s99, s95, 0
	s_add_i32 m0, s3, 0xb000
	ds_read_b128 v[240:243], v141 offset:54272
	ds_read_b128 v[244:247], v141 offset:55296
	ds_read_b128 v[248:251], v141 offset:56320
	global_load_lds_dwordx4 v134, s[98:99]
; #define PG8_STAGE(bufoff, gbase, voff) do { _Pragma("unroll") for (int _i = 0; _i < 2; ++_i) \
;         __builtin_amdgcn_global_load_lds((const unsigned*)((const char*)(gbase) + (voff)[_i]), (PG8_LAS unsigned*)(lds + (bufoff) + ldsw + _i * 8192), 16, 0, 0); } while (0)
; #define PG8_LDA(dst, b, h) do { _Pragma("unroll") for (int m = 0; m < 4; ++m) _Pragma("unroll") for (int k = 0; k < 2; ++k) dst[m][k] = *(const PG8_LAS bf16x8*)(lds + PG8_SA(b, h) + aoff + m * 2048 + k * 1024); } while (0)
; #define PG8_MMA(ai, bj, At, Bt) do { __builtin_amdgcn_s_setprio(1); _Pragma("unroll") for (int m = 0; m < 4; ++m) _Pragma("unroll") for (int n = 0; n < 2; ++n) _Pragma("unroll") for (int k = 0; k < 2; ++k) \
;         acc[ai][bj][m][n] = __builtin_amdgcn_mfma_f32_16x16x32_bf16(Bt[n][k], At[m][k], acc[ai][bj][m][n], 0, 0, 0); __builtin_amdgcn_s_setprio(0); } while (0)
; #define PG8_WAIT_V(n) asm volatile("s_waitcnt vmcnt(" #n ")" ::: "memory")
; #define PG8_WAIT_L(n) asm volatile("s_waitcnt lgkmcnt(" #n ")" ::: "memory")
; #define PG8_BAR __builtin_amdgcn_s_barrier()
; #define PG8_SCHED __builtin_amdgcn_sched_barrier(0)
; template <class Epi, class Sched, bool ALIGN_EPI = false, bool SP2 = false>
; __device__ __forceinline__ void gemm_phase(PG8_LAS unsigned char* lds, const Gemm g, const Sched& S, const Epi& E) {
;     ...
;             PG8_WAIT_V(8); PG8_WAIT_L(0); PG8_BAR; PG8_MMA(0, 0, At, B0); PG8_MMA(0, 1, At, B1); PG8_BAR; PG8_SCHED;
;             PG8_LDA(At, 1, 1); PG8_STAGE(PG8_SB(1, 0), b3, voffB); PG8_STAGE(PG8_SB(1, 1), b3 + hstep, voffB); PG8_STAGE(PG8_SA(1, 0), a3, voffA);
;             PG8_WAIT_V(8); PG8_WAIT_L(0); PG8_BAR; PG8_MMA(1, 0, At, B0); PG8_MMA(1, 1, At, B1); PG8_BAR; PG8_SCHED;
.Lspf0_b_rd:
	s_waitcnt lgkmcnt(0)
	s_setprio 1
	s_barrier
	v_mfma_f32_16x16x32_bf16 v[124:127], v[146:149], v[198:201], v[124:127]
	v_mfma_f32_16x16x32_bf16 v[120:123], v[168:171], v[198:201], v[120:123]
	v_mfma_f32_16x16x32_bf16 v[108:111], v[146:149], v[206:209], v[108:111]
	v_mfma_f32_16x16x32_bf16 v[104:107], v[168:171], v[206:209], v[104:107]
	v_mfma_f32_16x16x32_bf16 v[92:95], v[146:149], v[218:221], v[92:95]
	v_mfma_f32_16x16x32_bf16 v[88:91], v[168:171], v[218:221], v[88:91]
	v_mfma_f32_16x16x32_bf16 v[76:79], v[146:149], v[228:231], v[76:79]
	v_mfma_f32_16x16x32_bf16 v[72:75], v[168:171], v[228:231], v[72:75]
	v_mfma_f32_16x16x32_bf16 v[124:127], v[150:153], v[202:205], v[124:127]
	v_mfma_f32_16x16x32_bf16 v[120:123], v[178:181], v[202:205], v[120:123]
	v_mfma_f32_16x16x32_bf16 v[108:111], v[150:153], v[210:213], v[108:111]
	v_mfma_f32_16x16x32_bf16 v[104:107], v[178:181], v[210:213], v[104:107]
	v_mfma_f32_16x16x32_bf16 v[92:95], v[150:153], v[224:227], v[92:95]
	v_mfma_f32_16x16x32_bf16 v[88:91], v[178:181], v[224:227], v[88:91]
	v_mfma_f32_16x16x32_bf16 v[76:79], v[150:153], v[232:235], v[76:79]
	v_mfma_f32_16x16x32_bf16 v[72:75], v[178:181], v[232:235], v[72:75]
	v_mfma_f32_16x16x32_bf16 v[116:119], v[182:185], v[198:201], v[116:119]
	v_mfma_f32_16x16x32_bf16 v[112:115], v[190:193], v[198:201], v[112:115]
	v_mfma_f32_16x16x32_bf16 v[100:103], v[182:185], v[206:209], v[100:103]
	v_mfma_f32_16x16x32_bf16 v[96:99], v[190:193], v[206:209], v[96:99]
	v_mfma_f32_16x16x32_bf16 v[84:87], v[182:185], v[218:221], v[84:87]
	v_mfma_f32_16x16x32_bf16 v[80:83], v[190:193], v[218:221], v[80:83]
	v_mfma_f32_16x16x32_bf16 v[68:71], v[182:185], v[228:231], v[68:71]
	v_mfma_f32_16x16x32_bf16 v[64:67], v[190:193], v[228:231], v[64:67]
	v_mfma_f32_16x16x32_bf16 v[116:119], v[186:189], v[202:205], v[116:119]
	v_mfma_f32_16x16x32_bf16 v[112:115], v[194:197], v[202:205], v[112:115]
	v_mfma_f32_16x16x32_bf16 v[100:103], v[186:189], v[210:213], v[100:103]
	v_mfma_f32_16x16x32_bf16 v[96:99], v[194:197], v[210:213], v[96:99]
	v_mfma_f32_16x16x32_bf16 v[84:87], v[186:189], v[224:227], v[84:87]
	v_mfma_f32_16x16x32_bf16 v[80:83], v[194:197], v[224:227], v[80:83]
	v_mfma_f32_16x16x32_bf16 v[68:71], v[186:189], v[232:235], v[68:71]
	v_mfma_f32_16x16x32_bf16 v[64:67], v[194:197], v[232:235], v[64:67]
	v_mfma_f32_16x16x32_bf16 v[60:63], v[146:149], v[154:157], v[60:63]
	v_mfma_f32_16x16x32_bf16 v[56:59], v[168:171], v[154:157], v[56:59]
	v_mfma_f32_16x16x32_bf16 v[44:47], v[146:149], v[162:165], v[44:47]
	v_mfma_f32_16x16x32_bf16 v[40:43], v[168:171], v[162:165], v[40:43]
	v_mfma_f32_16x16x32_bf16 v[28:31], v[146:149], v[236:239], v[28:31]
	v_mfma_f32_16x16x32_bf16 v[24:27], v[168:171], v[236:239], v[24:27]
	v_mfma_f32_16x16x32_bf16 v[12:15], v[146:149], v[244:247], v[12:15]
	v_mfma_f32_16x16x32_bf16 v[8:11], v[168:171], v[244:247], v[8:11]
	v_mfma_f32_16x16x32_bf16 v[60:63], v[150:153], v[158:161], v[60:63]
	v_mfma_f32_16x16x32_bf16 v[56:59], v[178:181], v[158:161], v[56:59]
	v_mfma_f32_16x16x32_bf16 v[44:47], v[150:153], v[214:217], v[44:47]
	v_mfma_f32_16x16x32_bf16 v[40:43], v[178:181], v[214:217], v[40:43]
	v_mfma_f32_16x16x32_bf16 v[28:31], v[150:153], v[240:243], v[28:31]
	v_mfma_f32_16x16x32_bf16 v[24:27], v[178:181], v[240:243], v[24:27]
	v_mfma_f32_16x16x32_bf16 v[12:15], v[150:153], v[248:251], v[12:15]
	v_mfma_f32_16x16x32_bf16 v[8:11], v[178:181], v[248:251], v[8:11]
	v_mfma_f32_16x16x32_bf16 v[52:55], v[182:185], v[154:157], v[52:55]
	v_mfma_f32_16x16x32_bf16 v[48:51], v[190:193], v[154:157], v[48:51]
	v_mfma_f32_16x16x32_bf16 v[36:39], v[182:185], v[162:165], v[36:39]
	v_mfma_f32_16x16x32_bf16 v[32:35], v[190:193], v[162:165], v[32:35]
	v_mfma_f32_16x16x32_bf16 v[20:23], v[182:185], v[236:239], v[20:23]
	v_mfma_f32_16x16x32_bf16 v[16:19], v[190:193], v[236:239], v[16:19]
	v_mfma_f32_16x16x32_bf16 v[4:7], v[182:185], v[244:247], v[4:7]
	v_mfma_f32_16x16x32_bf16 v[0:3], v[190:193], v[244:247], v[0:3]
	v_mfma_f32_16x16x32_bf16 v[52:55], v[186:189], v[158:161], v[52:55]
	v_mfma_f32_16x16x32_bf16 v[48:51], v[194:197], v[158:161], v[48:51]
	v_mfma_f32_16x16x32_bf16 v[36:39], v[186:189], v[214:217], v[36:39]
	v_mfma_f32_16x16x32_bf16 v[32:35], v[194:197], v[214:217], v[32:35]
	v_mfma_f32_16x16x32_bf16 v[20:23], v[186:189], v[240:243], v[20:23]
	v_mfma_f32_16x16x32_bf16 v[16:19], v[194:197], v[240:243], v[16:19]
	v_mfma_f32_16x16x32_bf16 v[4:7], v[186:189], v[248:251], v[4:7]
	v_mfma_f32_16x16x32_bf16 v[0:3], v[194:197], v[248:251], v[0:3]
	s_waitcnt vmcnt(0)
	s_barrier
	s_setprio 0
	s_add_i32 s66, s66, 2
	s_add_u32 s90, s90, 0x100
	s_addc_u32 s91, s91, 0
	s_add_u32 vcc_lo, vcc_lo, 0x100
	s_addc_u32 vcc_hi, vcc_hi, 0
	s_cmp_gt_u32 s66, 29
	s_cbranch_scc0 .LBB0_127
	v_mov_b32_e32 v216, v166
	v_mov_b32_e32 v175, v141
	v_mov_b32_e32 v173, v139
	v_mov_b32_e32 v167, v135
	v_mov_b32_e32 v163, v133
	v_mov_b32_e32 v159, v131
	v_mov_b32_e32 v155, v129
	s_and_b64 vcc, exec, s[10:11]
	s_cbranch_vccz .LBB0_130
	s_barrier

; #define PG8_STAGE(bufoff, gbase, voff) do { _Pragma("unroll") for (int _i = 0; _i < 2; ++_i) \
;         __builtin_amdgcn_global_load_lds((const unsigned*)((const char*)(gbase) + (voff)[_i]), (PG8_LAS unsigned*)(lds + (bufoff) + ldsw + _i * 8192), 16, 0, 0); } while (0)
; #define PG8_WAIT_V(n) asm volatile("s_waitcnt vmcnt(" #n ")" ::: "memory")
; #define PG8_BAR __builtin_amdgcn_s_barrier()
; template <class Epi, class Sched, bool ALIGN_EPI = false, bool SP2 = false>
; __device__ __forceinline__ void gemm_phase(PG8_LAS unsigned char* lds, const Gemm g, const Sched& S, const Epi& E) {
;     ...
;     const int tid = tid_o, wid = __builtin_amdgcn_readfirstlane(tid >> 6), lane = tid & 63, wr = wid >> 2, wc = wid & 3, fr = lane & 15, fq = lane >> 4;
;     const int K = g.K, nt = K / BK;
;     unsigned voffA[2], voffB[2];
; #pragma unroll
;     for (int i = 0; i < 2; ++i) { int R, C; stage_rc(tid * 16 + i * 8192, R, C); const int Rb = Epi::PERM ? ((R & ~31) + perm32(R & 31)) : R;
;         voffA[i] = (unsigned)(R * K + C) * 2u; voffB[i] = (unsigned)(Rb * K + C) * 2u; }
;     const size_t kstep = (size_t)(BK * 2);
;     const size_t hstep = (size_t)HALF * K * 2;
;     const size_t tstep = 2 * hstep;
;     const unsigned ldsw = (unsigned)wid * 1024u;
;     const int aoff = lds_byte(wr * 64 + fr, fq * 8), boff = lds_byte(wc * 32 + fr, fq * 8);
;     ...
;     if constexpr (SP2) {
;         PG8_STAGE(PG8_SB(0, 0), cB, voffB); PG8_STAGE(PG8_SB(0, 1), cB + hstep, voffB); PG8_STAGE(PG8_SA(0, 0), cA, voffA); PG8_STAGE(PG8_SA(0, 1), cA + hstep, voffA);
;         if (wr == 1) PG8_BAR;
;         PG8_WAIT_V(2); PG8_BAR;
;         PG8_STAGE(PG8_SB(1, 0), cB + kstep, voffB); PG8_STAGE(PG8_SA(1, 0), cA + kstep, voffA); PG8_STAGE(PG8_SB(1, 1), cB + hstep + kstep, voffB);
;         PG8_WAIT_V(6); PG8_BAR;
.LBB0_234:
	v_bfe_u32 v17, v15, 4, 2
	v_and_b32_e32 v18, 15, v15
	v_lshlrev_b32_e32 v19, 4, v17
	v_lshlrev_b32_e32 v15, 2, v15
	s_mov_b64 s[46:47], 0x80
	s_and_b32 s69, s7, 3
	v_lshl_or_b32 v217, s10, 6, v18
	v_lshl_or_b32 v18, v18, 6, v19
	s_lshl_b32 s7, s10, 13
	v_and_b32_e32 v15, 32, v15
	s_add_i32 m0, s15, 0x18000
	v_lshl_add_u64 v[6:7], v[6:7], 0, s[46:47]
	v_bitop3_b32 v19, v18, s7, v15 bitop3:0xde
	s_lshl_b32 s7, s69, 12
	s_waitcnt vmcnt(0)
	s_barrier
	global_load_lds_dwordx4 v[6:7], off
	v_lshl_add_u64 v[4:5], v[4:5], 0, s[46:47]
	s_add_i32 m0, s15, 0x1a000
	s_add_i32 s70, s15, 0x8000
	s_add_i32 s71, s15, 0xa000
	global_load_lds_dwordx4 v[4:5], off
	v_lshl_add_u64 v[0:1], v[0:1], 0, s[46:47]
	s_mov_b32 m0, s70
	s_add_u32 s66, s82, 0x160080
	global_load_lds_dwordx4 v[0:1], off
	v_lshl_add_u64 v[0:1], v[2:3], 0, s[46:47]
	s_mov_b32 m0, s71
	s_addc_u32 s67, s83, 0
	global_load_lds_dwordx4 v[0:1], off
	s_add_i32 m0, s15, 0x1c000
	v_lshl_add_u64 v[0:1], s[66:67], 0, v[188:189]
	global_load_lds_dwordx4 v[0:1], off
	v_lshl_add_u64 v[0:1], s[66:67], 0, v[190:191]
	s_add_i32 m0, s15, 0x1e000
	s_mov_b64 s[10:11], 0x160080
	global_load_lds_dwordx4 v[0:1], off
	v_lshlrev_b32_e32 v0, 2, v17
	v_lshl_or_b32 v219, s69, 5, v0
	v_lshrrev_b32_e32 v1, 1, v8
	v_mul_lo_u32 v0, v9, s8
	v_mad_u64_u32 v[0:1], s[66:67], v1, s9, v[0:1]
	v_or_b32_e32 v0, v0, v10
	v_add_lshl_u32 v0, v0, v11, 1
	v_mov_b32_e32 v1, v189
	v_lshl_add_u64 v[192:193], v[0:1], 0, s[10:11]
	v_lshrrev_b32_e32 v1, 1, v12
	v_mul_lo_u32 v0, v13, s8
	v_mad_u64_u32 v[0:1], s[8:9], v1, s9, v[0:1]
	s_waitcnt vmcnt(6)
	s_cmpk_lt_u32 s6, 0x100
	v_or_b32_e32 v0, v0, v14
	v_bitop3_b32 v218, v18, s7, v15 bitop3:0xde
	s_cselect_b64 s[86:87], -1, 0
	v_add_lshl_u32 v0, v0, v16, 1
	v_mov_b32_e32 v1, v189
	s_add_i32 s73, 0, 0x10000
	s_add_i32 s80, 0, 0x14000
	v_cmp_eq_u32_e64 s[6:7], 0, v17
	v_lshl_add_u64 v[194:195], v[0:1], 0, s[10:11]
	v_mov_b64_e32 v[196:197], 0x100
	v_mov_b64_e32 v[198:199], 0xff
	v_add_u32_e32 v220, s73, v218
	v_add_u32_e32 v221, s80, v218
	v_add_u32_e32 v223, 0, v19
	v_mbcnt_hi_u32_b32 v224, -1, v216
	s_mov_b32 s81, 0
	s_barrier
	s_branch .LBB0_237

; #define PG8_STAGE(bufoff, gbase, voff) do { _Pragma("unroll") for (int _i = 0; _i < 2; ++_i) \
;         __builtin_amdgcn_global_load_lds((const unsigned*)((const char*)(gbase) + (voff)[_i]), (PG8_LAS unsigned*)(lds + (bufoff) + ldsw + _i * 8192), 16, 0, 0); } while (0)
; #define PG8_LDA(dst, b, h) do { _Pragma("unroll") for (int m = 0; m < 4; ++m) _Pragma("unroll") for (int k = 0; k < 2; ++k) dst[m][k] = *(const PG8_LAS bf16x8*)(lds + PG8_SA(b, h) + aoff + m * 2048 + k * 1024); } while (0)
; #define PG8_LDB(dst, b, h) do { _Pragma("unroll") for (int n = 0; n < 2; ++n) _Pragma("unroll") for (int k = 0; k < 2; ++k) dst[n][k] = *(const PG8_LAS bf16x8*)(lds + PG8_SB(b, h) + boff + n * 2048 + k * 1024); } while (0)
; #define PG8_WAIT_V(n) asm volatile("s_waitcnt vmcnt(" #n ")" ::: "memory")
; template <class Epi, class Sched, bool ALIGN_EPI = false, bool SP2 = false>
; __device__ __forceinline__ void gemm_phase(PG8_LAS unsigned char* lds, const Gemm g, const Sched& S, const Epi& E) {
;     ...
;     f32x4 acc[2][2][4][2];
; #pragma unroll
;     for (int a = 0; a < 2; ++a)
; #pragma unroll
;         for (int b = 0; b < 2; ++b)
; #pragma unroll
;             for (int m = 0; m < 4; ++m)
; #pragma unroll
;                 for (int n = 0; n < 2; ++n) acc[a][b][m][n] = (f32x4){0.f, 0.f, 0.f, 0.f};
;     ...
;         const bool has_next = S.next(ui + 1, nxt);
;         const char* nA = has_next ? (const char*)g.A + (size_t)nxt.pm * tstep : cA; const char* nB = has_next ? (const char*)g.Bt + (size_t)nxt.pn * tstep : cB;
;         for (int t = 0; t < nt; t += 2) {
;             const bool last = (t == nt - 2);
;             const char* a1 = cA + (size_t)(t + 1) * kstep;
;             const char* a2 = last ? nA : cA + (size_t)(t + 2) * kstep; const char* b2 = last ? nB : cB + (size_t)(t + 2) * kstep;
;             const char* a3 = a2 + kstep; const char* b3 = b2 + kstep;
;             if (last && has_next) S.a_ready(nxt);
;             if constexpr (SP2) {
;             PG8_LDB(B0, 0, 0); PG8_LDB(B1, 0, 1); PG8_SCHED; PG8_LDA(At, 0, 0); PG8_STAGE(PG8_SA(1, 1), a1 + hstep, voffA);
;             PG8_WAIT_V(8); PG8_WAIT_L(0); PG8_BAR; PG8_MMA(0, 0, At, B0); PG8_MMA(0, 1, At, B1); PG8_BAR; PG8_SCHED;
;             PG8_LDA(At, 0, 1); PG8_STAGE(PG8_SB(0, 0), b2, voffB); PG8_STAGE(PG8_SB(0, 1), b2 + hstep, voffB); PG8_STAGE(PG8_SA(0, 0), a2, voffA);
.LBB0_247:
	s_add_u32 s22, s82, 0x100
	v_mov_b64_e32 v[0:1], 0
	v_mov_b64_e32 v[2:3], 0
	v_mov_b64_e32 v[4:5], 0
	v_mov_b64_e32 v[6:7], 0
	v_mov_b64_e32 v[8:9], 0
	v_mov_b64_e32 v[10:11], 0
	v_mov_b64_e32 v[12:13], 0
	v_mov_b64_e32 v[14:15], 0
	v_mov_b64_e32 v[16:17], 0
	v_mov_b64_e32 v[18:19], 0
	v_mov_b64_e32 v[20:21], 0
	v_mov_b64_e32 v[22:23], 0
	v_mov_b64_e32 v[24:25], 0
	v_mov_b64_e32 v[26:27], 0
	v_mov_b64_e32 v[28:29], 0
	v_mov_b64_e32 v[30:31], 0
	v_mov_b64_e32 v[32:33], 0
	v_mov_b64_e32 v[34:35], 0
	v_mov_b64_e32 v[36:37], 0
	v_mov_b64_e32 v[38:39], 0
	v_mov_b64_e32 v[40:41], 0
	v_mov_b64_e32 v[42:43], 0
	v_mov_b64_e32 v[44:45], 0
	v_mov_b64_e32 v[46:47], 0
	v_mov_b64_e32 v[48:49], 0
	v_mov_b64_e32 v[50:51], 0
	v_mov_b64_e32 v[52:53], 0
	v_mov_b64_e32 v[54:55], 0
	v_mov_b64_e32 v[56:57], 0
	v_mov_b64_e32 v[58:59], 0
	v_mov_b64_e32 v[60:61], 0
	v_mov_b64_e32 v[62:63], 0
	v_mov_b64_e32 v[64:65], 0
	v_mov_b64_e32 v[66:67], 0
	v_mov_b64_e32 v[68:69], 0
	v_mov_b64_e32 v[70:71], 0
	v_mov_b64_e32 v[72:73], 0
	v_mov_b64_e32 v[74:75], 0
	v_mov_b64_e32 v[76:77], 0
	v_mov_b64_e32 v[78:79], 0
	v_mov_b64_e32 v[80:81], 0
	v_mov_b64_e32 v[82:83], 0
	v_mov_b64_e32 v[84:85], 0
	v_mov_b64_e32 v[86:87], 0
	v_mov_b64_e32 v[88:89], 0
	v_mov_b64_e32 v[90:91], 0
	v_mov_b64_e32 v[92:93], 0
	v_mov_b64_e32 v[94:95], 0
	v_mov_b64_e32 v[96:97], 0
	v_mov_b64_e32 v[98:99], 0
	v_mov_b64_e32 v[100:101], 0
	v_mov_b64_e32 v[102:103], 0
	v_mov_b64_e32 v[104:105], 0
	v_mov_b64_e32 v[106:107], 0
	v_mov_b64_e32 v[108:109], 0
	v_mov_b64_e32 v[110:111], 0
	v_mov_b64_e32 v[112:113], 0
	v_mov_b64_e32 v[114:115], 0
	v_mov_b64_e32 v[116:117], 0
	v_mov_b64_e32 v[118:119], 0
	v_mov_b64_e32 v[120:121], 0
	v_mov_b64_e32 v[122:123], 0
	v_mov_b64_e32 v[124:125], 0
	v_mov_b64_e32 v[126:127], 0
	s_addc_u32 vcc_lo, s83, 0
	s_mov_b32 s66, -2
	s_waitcnt lgkmcnt(0)
	v_mov_b32_e32 v189, v218
	v_mov_b32_e32 v191, v220
	v_mov_b32_e32 v193, v221
	v_mov_b32_e32 v195, v223
	v_add_u32_e32 v225, 0x18000, v189
	v_add_u32_e32 v246, 0x1c000, v189
	s_cmp_lg_u32 s86, 0
	s_cbranch_scc0 .Lspf1_pre
	s_add_i32 m0, s14, 0xc000
	s_nop 0
	global_load_lds_dwordx4 v192, s[92:93]
	s_add_u32 s98, s92, 0x58000
	s_addc_u32 s99, s93, 0
	s_add_i32 m0, s14, 0xd000
	s_nop 0
	global_load_lds_dwordx4 v192, s[98:99]
	s_add_u32 s98, s92, 0xffea0000
	s_addc_u32 s99, s93, -1
	s_add_i32 m0, s14, 0x8000
	s_nop 0
	global_load_lds_dwordx4 v192, s[98:99]
	s_add_u32 s98, s92, 0xffef8000
	s_addc_u32 s99, s93, -1
	s_add_i32 m0, s14, 0x9000
	s_nop 0
	global_load_lds_dwordx4 v192, s[98:99]
.Lspf1_pre:
.LBB0_248:
	s_add_u32 s10, s92, 0x100
	s_addc_u32 s11, s93, 0
	s_cmpk_eq_i32 s66, 0x54
	s_cselect_b32 s95, s89, s11
	s_cselect_b32 s94, s88, s10
	s_cselect_b32 s83, s91, vcc_lo
	s_cselect_b32 s82, s90, s22
	s_cmp_lg_u32 s86, 0
	s_cbranch_scc0 .Lspf1_a_h1
	s_add_u32 s98, s22, 0xffffff80
	s_addc_u32 s99, vcc_lo, -1
	s_add_i32 m0, s14, 0x18000
	ds_read_b128 v[128:131], v191
	ds_read_b128 v[132:135], v191 offset:1024
	ds_read_b128 v[136:139], v191 offset:2048
	global_load_lds_dwordx4 v188, s[98:99]
	s_add_i32 m0, s14, 0x1a000
	ds_read_b128 v[140:143], v191 offset:3072
	ds_read_b128 v[144:147], v193
	ds_read_b128 v[148:151], v193 offset:1024
	global_load_lds_dwordx4 v190, s[98:99]
	s_add_u32 s98, s22, 0x57f80
	s_addc_u32 s99, vcc_lo, 0
	s_add_i32 m0, s14, 0x19000
	ds_read_b128 v[152:155], v193 offset:2048
	ds_read_b128 v[156:159], v193 offset:3072
	ds_read_b128 v[160:163], v195
	global_load_lds_dwordx4 v188, s[98:99]
	s_add_i32 m0, s14, 0x1b000
	ds_read_b128 v[164:167], v195 offset:1024
	ds_read_b128 v[168:171], v195 offset:2048
	ds_read_b128 v[172:175], v195 offset:3072
	global_load_lds_dwordx4 v190, s[98:99]
	s_add_u32 s98, s22, 0x15ff80
	s_addc_u32 s99, vcc_lo, 0
	s_add_i32 m0, s14, 0x1c000
	ds_read_b128 v[176:179], v195 offset:4096
	ds_read_b128 v[180:183], v195 offset:5120
	ds_read_b128 v[184:187], v195 offset:6144
	global_load_lds_dwordx4 v188, s[98:99]
	s_add_i32 m0, s14, 0x1e000
	ds_read_b128 v[200:203], v195 offset:7168
	ds_read_b128 v[204:207], v195 offset:16384
	ds_read_b128 v[208:211], v195 offset:17408
	global_load_lds_dwordx4 v190, s[98:99]
	s_add_u32 s98, s22, 0x1b7f80
	s_addc_u32 s99, vcc_lo, 0
	s_add_i32 m0, s14, 0x1d000
	ds_read_b128 v[212:215], v195 offset:18432
	ds_read_b128 v[226:229], v195 offset:19456
	ds_read_b128 v[230:233], v195 offset:20480
	global_load_lds_dwordx4 v188, s[98:99]
	s_add_i32 m0, s14, 0x1f000
	ds_read_b128 v[234:237], v195 offset:21504
	ds_read_b128 v[238:241], v195 offset:22528
	ds_read_b128 v[242:245], v195 offset:23552
	global_load_lds_dwordx4 v190, s[98:99]
	s_branch .Lspf1_a_rd
.Lspf1_a_h1:
	s_add_u32 s98, s92, 0xffea0000
	s_addc_u32 s99, s93, -1
	s_add_i32 m0, s14, 0xa000
	ds_read_b128 v[128:131], v191
	ds_read_b128 v[132:135], v191 offset:1024
	ds_read_b128 v[136:139], v191 offset:2048
	global_load_lds_dwordx4 v194, s[98:99]
	s_add_u32 s98, s92, 0xffe48000
	s_addc_u32 s99, s93, -1
	s_add_i32 m0, s14, 0x9000
	ds_read_b128 v[140:143], v191 offset:3072
	ds_read_b128 v[144:147], v193
	ds_read_b128 v[148:151], v193 offset:1024
	global_load_lds_dwordx4 v194, s[98:99]
	s_add_i32 m0, s14, 0xe000
	ds_read_b128 v[152:155], v193 offset:2048
	ds_read_b128 v[156:159], v193 offset:3072
	ds_read_b128 v[160:163], v195
	global_load_lds_dwordx4 v194, s[92:93]
	s_add_u32 s98, s92, 0xfffa8000
	s_addc_u32 s99, s93, -1
	s_add_i32 m0, s14, 0xd000
	ds_read_b128 v[164:167], v195 offset:1024
	ds_read_b128 v[168:171], v195 offset:2048
	ds_read_b128 v[172:175], v195 offset:3072
	global_load_lds_dwordx4 v194, s[98:99]
	s_add_i32 m0, s14, 0x0
	ds_read_b128 v[176:179], v195 offset:4096
	ds_read_b128 v[180:183], v195 offset:5120
	ds_read_b128 v[184:187], v195 offset:6144
	global_load_lds_dwordx4 v188, s[94:95]
	s_add_u32 s98, s94, 0xfffa8000
	s_addc_u32 s99, s95, -1
	s_add_i32 m0, s14, 0xfffff000
	ds_read_b128 v[200:203], v195 offset:7168
	ds_read_b128 v[204:207], v195 offset:16384
	ds_read_b128 v[208:211], v195 offset:17408
	global_load_lds_dwordx4 v188, s[98:99]
	s_add_u32 s98, s94, 0x160000
	s_addc_u32 s99, s95, 0
	s_add_i32 m0, s14, 0x4000
	ds_read_b128 v[212:215], v195 offset:18432
	ds_read_b128 v[226:229], v195 offset:19456
	ds_read_b128 v[230:233], v195 offset:20480
	global_load_lds_dwordx4 v188, s[98:99]
	s_add_u32 s98, s94, 0x108000
	s_addc_u32 s99, s95, 0
	s_add_i32 m0, s14, 0x3000
	ds_read_b128 v[234:237], v195 offset:21504
	ds_read_b128 v[238:241], v195 offset:22528
	ds_read_b128 v[242:245], v195 offset:23552
	global_load_lds_dwordx4 v188, s[98:99]
; #define PG8_STAGE(bufoff, gbase, voff) do { _Pragma("unroll") for (int _i = 0; _i < 2; ++_i) \
;         __builtin_amdgcn_global_load_lds((const unsigned*)((const char*)(gbase) + (voff)[_i]), (PG8_LAS unsigned*)(lds + (bufoff) + ldsw + _i * 8192), 16, 0, 0); } while (0)
; #define PG8_LDA(dst, b, h) do { _Pragma("unroll") for (int m = 0; m < 4; ++m) _Pragma("unroll") for (int k = 0; k < 2; ++k) dst[m][k] = *(const PG8_LAS bf16x8*)(lds + PG8_SA(b, h) + aoff + m * 2048 + k * 1024); } while (0)
; #define PG8_LDB(dst, b, h) do { _Pragma("unroll") for (int n = 0; n < 2; ++n) _Pragma("unroll") for (int k = 0; k < 2; ++k) dst[n][k] = *(const PG8_LAS bf16x8*)(lds + PG8_SB(b, h) + boff + n * 2048 + k * 1024); } while (0)
; #define PG8_MMA(ai, bj, At, Bt) do { __builtin_amdgcn_s_setprio(1); _Pragma("unroll") for (int m = 0; m < 4; ++m) _Pragma("unroll") for (int n = 0; n < 2; ++n) _Pragma("unroll") for (int k = 0; k < 2; ++k) \
;         acc[ai][bj][m][n] = __builtin_amdgcn_mfma_f32_16x16x32_bf16(Bt[n][k], At[m][k], acc[ai][bj][m][n], 0, 0, 0); __builtin_amdgcn_s_setprio(0); } while (0)
; #define PG8_WAIT_V(n) asm volatile("s_waitcnt vmcnt(" #n ")" ::: "memory")
; #define PG8_WAIT_L(n) asm volatile("s_waitcnt lgkmcnt(" #n ")" ::: "memory")
; template <class Epi, class Sched, bool ALIGN_EPI = false, bool SP2 = false>
; __device__ __forceinline__ void gemm_phase(PG8_LAS unsigned char* lds, const Gemm g, const Sched& S, const Epi& E) {
;     ...
;             PG8_LDB(B0, 0, 0); PG8_LDB(B1, 0, 1); PG8_SCHED; PG8_LDA(At, 0, 0); PG8_STAGE(PG8_SA(1, 1), a1 + hstep, voffA);
;             PG8_WAIT_V(8); PG8_WAIT_L(0); PG8_BAR; PG8_MMA(0, 0, At, B0); PG8_MMA(0, 1, At, B1); PG8_BAR; PG8_SCHED;
;             PG8_LDA(At, 0, 1); PG8_STAGE(PG8_SB(0, 0), b2, voffB); PG8_STAGE(PG8_SB(0, 1), b2 + hstep, voffB); PG8_STAGE(PG8_SA(0, 0), a2, voffA);
;             PG8_WAIT_V(8); PG8_WAIT_L(0); PG8_BAR; PG8_MMA(1, 0, At, B0); PG8_MMA(1, 1, At, B1); PG8_BAR; PG8_SCHED;
;             PG8_LDB(B0, 1, 0); PG8_LDB(B1, 1, 1); PG8_SCHED; PG8_LDA(At, 1, 0); PG8_STAGE(PG8_SA(0, 1), a2 + hstep, voffA);
;             PG8_WAIT_V(8); PG8_WAIT_L(0); PG8_BAR; PG8_MMA(0, 0, At, B0); PG8_MMA(0, 1, At, B1); PG8_BAR; PG8_SCHED;
;             PG8_LDA(At, 1, 1); PG8_STAGE(PG8_SB(1, 0), b3, voffB); PG8_STAGE(PG8_SB(1, 1), b3 + hstep, voffB); PG8_STAGE(PG8_SA(1, 0), a3, voffA);
.Lspf1_a_rd:
	s_waitcnt lgkmcnt(0)
	s_setprio 1
	s_barrier
	v_mfma_f32_16x16x32_bf16 v[124:127], v[128:131], v[160:163], v[124:127]
	v_mfma_f32_16x16x32_bf16 v[120:123], v[136:139], v[160:163], v[120:123]
	v_mfma_f32_16x16x32_bf16 v[108:111], v[128:131], v[168:171], v[108:111]
	v_mfma_f32_16x16x32_bf16 v[104:107], v[136:139], v[168:171], v[104:107]
	v_mfma_f32_16x16x32_bf16 v[92:95], v[128:131], v[176:179], v[92:95]
	v_mfma_f32_16x16x32_bf16 v[88:91], v[136:139], v[176:179], v[88:91]
	v_mfma_f32_16x16x32_bf16 v[76:79], v[128:131], v[184:187], v[76:79]
	v_mfma_f32_16x16x32_bf16 v[72:75], v[136:139], v[184:187], v[72:75]
	v_mfma_f32_16x16x32_bf16 v[124:127], v[132:135], v[164:167], v[124:127]
	v_mfma_f32_16x16x32_bf16 v[120:123], v[140:143], v[164:167], v[120:123]
	v_mfma_f32_16x16x32_bf16 v[108:111], v[132:135], v[172:175], v[108:111]
	v_mfma_f32_16x16x32_bf16 v[104:107], v[140:143], v[172:175], v[104:107]
	v_mfma_f32_16x16x32_bf16 v[92:95], v[132:135], v[180:183], v[92:95]
	v_mfma_f32_16x16x32_bf16 v[88:91], v[140:143], v[180:183], v[88:91]
	v_mfma_f32_16x16x32_bf16 v[76:79], v[132:135], v[200:203], v[76:79]
	v_mfma_f32_16x16x32_bf16 v[72:75], v[140:143], v[200:203], v[72:75]
	v_mfma_f32_16x16x32_bf16 v[116:119], v[144:147], v[160:163], v[116:119]
	v_mfma_f32_16x16x32_bf16 v[112:115], v[152:155], v[160:163], v[112:115]
	v_mfma_f32_16x16x32_bf16 v[100:103], v[144:147], v[168:171], v[100:103]
	v_mfma_f32_16x16x32_bf16 v[96:99], v[152:155], v[168:171], v[96:99]
	v_mfma_f32_16x16x32_bf16 v[84:87], v[144:147], v[176:179], v[84:87]
	v_mfma_f32_16x16x32_bf16 v[80:83], v[152:155], v[176:179], v[80:83]
	v_mfma_f32_16x16x32_bf16 v[68:71], v[144:147], v[184:187], v[68:71]
	v_mfma_f32_16x16x32_bf16 v[64:67], v[152:155], v[184:187], v[64:67]
	v_mfma_f32_16x16x32_bf16 v[116:119], v[148:151], v[164:167], v[116:119]
	v_mfma_f32_16x16x32_bf16 v[112:115], v[156:159], v[164:167], v[112:115]
	v_mfma_f32_16x16x32_bf16 v[100:103], v[148:151], v[172:175], v[100:103]
	v_mfma_f32_16x16x32_bf16 v[96:99], v[156:159], v[172:175], v[96:99]
	v_mfma_f32_16x16x32_bf16 v[84:87], v[148:151], v[180:183], v[84:87]
	v_mfma_f32_16x16x32_bf16 v[80:83], v[156:159], v[180:183], v[80:83]
	v_mfma_f32_16x16x32_bf16 v[68:71], v[148:151], v[200:203], v[68:71]
	v_mfma_f32_16x16x32_bf16 v[64:67], v[156:159], v[200:203], v[64:67]
	v_mfma_f32_16x16x32_bf16 v[60:63], v[128:131], v[204:207], v[60:63]
	v_mfma_f32_16x16x32_bf16 v[56:59], v[136:139], v[204:207], v[56:59]
	v_mfma_f32_16x16x32_bf16 v[44:47], v[128:131], v[212:215], v[44:47]
	v_mfma_f32_16x16x32_bf16 v[40:43], v[136:139], v[212:215], v[40:43]
	v_mfma_f32_16x16x32_bf16 v[28:31], v[128:131], v[230:233], v[28:31]
	v_mfma_f32_16x16x32_bf16 v[24:27], v[136:139], v[230:233], v[24:27]
	v_mfma_f32_16x16x32_bf16 v[12:15], v[128:131], v[238:241], v[12:15]
	v_mfma_f32_16x16x32_bf16 v[8:11], v[136:139], v[238:241], v[8:11]
	v_mfma_f32_16x16x32_bf16 v[60:63], v[132:135], v[208:211], v[60:63]
	v_mfma_f32_16x16x32_bf16 v[56:59], v[140:143], v[208:211], v[56:59]
	v_mfma_f32_16x16x32_bf16 v[44:47], v[132:135], v[226:229], v[44:47]
	v_mfma_f32_16x16x32_bf16 v[40:43], v[140:143], v[226:229], v[40:43]
	v_mfma_f32_16x16x32_bf16 v[28:31], v[132:135], v[234:237], v[28:31]
	v_mfma_f32_16x16x32_bf16 v[24:27], v[140:143], v[234:237], v[24:27]
	v_mfma_f32_16x16x32_bf16 v[12:15], v[132:135], v[242:245], v[12:15]
	v_mfma_f32_16x16x32_bf16 v[8:11], v[140:143], v[242:245], v[8:11]
	v_mfma_f32_16x16x32_bf16 v[52:55], v[144:147], v[204:207], v[52:55]
	v_mfma_f32_16x16x32_bf16 v[48:51], v[152:155], v[204:207], v[48:51]
	v_mfma_f32_16x16x32_bf16 v[36:39], v[144:147], v[212:215], v[36:39]
	v_mfma_f32_16x16x32_bf16 v[32:35], v[152:155], v[212:215], v[32:35]
	v_mfma_f32_16x16x32_bf16 v[20:23], v[144:147], v[230:233], v[20:23]
	v_mfma_f32_16x16x32_bf16 v[16:19], v[152:155], v[230:233], v[16:19]
	v_mfma_f32_16x16x32_bf16 v[4:7], v[144:147], v[238:241], v[4:7]
	v_mfma_f32_16x16x32_bf16 v[0:3], v[152:155], v[238:241], v[0:3]
	v_mfma_f32_16x16x32_bf16 v[52:55], v[148:151], v[208:211], v[52:55]
	v_mfma_f32_16x16x32_bf16 v[48:51], v[156:159], v[208:211], v[48:51]
	v_mfma_f32_16x16x32_bf16 v[36:39], v[148:151], v[226:229], v[36:39]
	v_mfma_f32_16x16x32_bf16 v[32:35], v[156:159], v[226:229], v[32:35]
	v_mfma_f32_16x16x32_bf16 v[20:23], v[148:151], v[234:237], v[20:23]
	v_mfma_f32_16x16x32_bf16 v[16:19], v[156:159], v[234:237], v[16:19]
	v_mfma_f32_16x16x32_bf16 v[4:7], v[148:151], v[242:245], v[4:7]
	v_mfma_f32_16x16x32_bf16 v[0:3], v[156:159], v[242:245], v[0:3]
	s_waitcnt vmcnt(0)
	s_barrier
	s_setprio 0
	s_cmp_lg_u32 s86, 0
	s_cbranch_scc0 .Lspf1_b_h1
	s_add_i32 m0, s14, 0x10000
	ds_read_b128 v[128:131], v225
	ds_read_b128 v[132:135], v225 offset:1024
	ds_read_b128 v[136:139], v225 offset:2048
	global_load_lds_dwordx4 v188, s[82:83]
	s_add_i32 m0, s14, 0x12000
	ds_read_b128 v[140:143], v225 offset:3072
	ds_read_b128 v[144:147], v246
	ds_read_b128 v[148:151], v246 offset:1024
	global_load_lds_dwordx4 v190, s[82:83]
	s_add_u32 s98, s82, 0x58000
	s_addc_u32 s99, s83, 0
	s_add_i32 m0, s14, 0x11000
	ds_read_b128 v[152:155], v246 offset:2048
	ds_read_b128 v[156:159], v246 offset:3072
	ds_read_b128 v[160:163], v195 offset:32768
	global_load_lds_dwordx4 v188, s[98:99]
	s_add_i32 m0, s14, 0x13000
	ds_read_b128 v[164:167], v195 offset:33792
	ds_read_b128 v[168:171], v195 offset:34816
	ds_read_b128 v[172:175], v195 offset:35840
	global_load_lds_dwordx4 v190, s[98:99]
	s_add_u32 s98, s82, 0x160000
	s_addc_u32 s99, s83, 0
	s_add_i32 m0, s14, 0x14000
	ds_read_b128 v[176:179], v195 offset:36864
	ds_read_b128 v[180:183], v195 offset:37888
	ds_read_b128 v[184:187], v195 offset:38912
	global_load_lds_dwordx4 v188, s[98:99]
	s_add_i32 m0, s14, 0x16000
	ds_read_b128 v[200:203], v195 offset:39936
	ds_read_b128 v[204:207], v195 offset:49152
	ds_read_b128 v[208:211], v195 offset:50176
	global_load_lds_dwordx4 v190, s[98:99]
	s_add_u32 s98, s82, 0x1b8000
	s_addc_u32 s99, s83, 0
	s_add_i32 m0, s14, 0x15000
	ds_read_b128 v[212:215], v195 offset:51200
	ds_read_b128 v[226:229], v195 offset:52224
	ds_read_b128 v[230:233], v195 offset:53248
	global_load_lds_dwordx4 v188, s[98:99]
	s_add_i32 m0, s14, 0x17000
	ds_read_b128 v[234:237], v195 offset:54272
	ds_read_b128 v[238:241], v195 offset:55296
	ds_read_b128 v[242:245], v195 offset:56320
	global_load_lds_dwordx4 v190, s[98:99]
	s_branch .Lspf1_b_rd
; #define PG8_STAGE(bufoff, gbase, voff) do { _Pragma("unroll") for (int _i = 0; _i < 2; ++_i) \
;         __builtin_amdgcn_global_load_lds((const unsigned*)((const char*)(gbase) + (voff)[_i]), (PG8_LAS unsigned*)(lds + (bufoff) + ldsw + _i * 8192), 16, 0, 0); } while (0)
; #define PG8_LDA(dst, b, h) do { _Pragma("unroll") for (int m = 0; m < 4; ++m) _Pragma("unroll") for (int k = 0; k < 2; ++k) dst[m][k] = *(const PG8_LAS bf16x8*)(lds + PG8_SA(b, h) + aoff + m * 2048 + k * 1024); } while (0)
; #define PG8_LDB(dst, b, h) do { _Pragma("unroll") for (int n = 0; n < 2; ++n) _Pragma("unroll") for (int k = 0; k < 2; ++k) dst[n][k] = *(const PG8_LAS bf16x8*)(lds + PG8_SB(b, h) + boff + n * 2048 + k * 1024); } while (0)
; #define PG8_MMA(ai, bj, At, Bt) do { __builtin_amdgcn_s_setprio(1); _Pragma("unroll") for (int m = 0; m < 4; ++m) _Pragma("unroll") for (int n = 0; n < 2; ++n) _Pragma("unroll") for (int k = 0; k < 2; ++k) \
;         acc[ai][bj][m][n] = __builtin_amdgcn_mfma_f32_16x16x32_bf16(Bt[n][k], At[m][k], acc[ai][bj][m][n], 0, 0, 0); __builtin_amdgcn_s_setprio(0); } while (0)
; #define PG8_WAIT_V(n) asm volatile("s_waitcnt vmcnt(" #n ")" ::: "memory")
; #define PG8_WAIT_L(n) asm volatile("s_waitcnt lgkmcnt(" #n ")" ::: "memory")
; #define PG8_BAR __builtin_amdgcn_s_barrier()
; #define PG8_SCHED __builtin_amdgcn_sched_barrier(0)
; template <class Epi, class Sched, bool ALIGN_EPI = false, bool SP2 = false>
; __device__ __forceinline__ void gemm_phase(PG8_LAS unsigned char* lds, const Gemm g, const Sched& S, const Epi& E) {
;     ...
;             PG8_LDB(B0, 1, 0); PG8_LDB(B1, 1, 1); PG8_SCHED; PG8_LDA(At, 1, 0); PG8_STAGE(PG8_SA(0, 1), a2 + hstep, voffA);
;             PG8_WAIT_V(8); PG8_WAIT_L(0); PG8_BAR; PG8_MMA(0, 0, At, B0); PG8_MMA(0, 1, At, B1); PG8_BAR; PG8_SCHED;
;             PG8_LDA(At, 1, 1); PG8_STAGE(PG8_SB(1, 0), b3, voffB); PG8_STAGE(PG8_SB(1, 1), b3 + hstep, voffB); PG8_STAGE(PG8_SA(1, 0), a3, voffA);
;             PG8_WAIT_V(8); PG8_WAIT_L(0); PG8_BAR; PG8_MMA(1, 0, At, B0); PG8_MMA(1, 1, At, B1); PG8_BAR; PG8_SCHED;
.Lspf1_b_h1:
	s_add_i32 m0, s14, 0x2000
	ds_read_b128 v[128:131], v225
	ds_read_b128 v[132:135], v225 offset:1024
	ds_read_b128 v[136:139], v225 offset:2048
	global_load_lds_dwordx4 v190, s[94:95]
	s_add_u32 s98, s94, 0xfffa8000
	s_addc_u32 s99, s95, -1
	s_add_i32 m0, s14, 0x1000
	ds_read_b128 v[140:143], v225 offset:3072
	ds_read_b128 v[144:147], v246
	ds_read_b128 v[148:151], v246 offset:1024
	global_load_lds_dwordx4 v190, s[98:99]
	s_add_u32 s98, s94, 0x160000
	s_addc_u32 s99, s95, 0
	s_add_i32 m0, s14, 0x6000
	ds_read_b128 v[152:155], v246 offset:2048
	ds_read_b128 v[156:159], v246 offset:3072
	ds_read_b128 v[160:163], v195 offset:32768
	global_load_lds_dwordx4 v190, s[98:99]
	s_add_u32 s98, s94, 0x108000
	s_addc_u32 s99, s95, 0
	s_add_i32 m0, s14, 0x5000
	ds_read_b128 v[164:167], v195 offset:33792
	ds_read_b128 v[168:171], v195 offset:34816
	ds_read_b128 v[172:175], v195 offset:35840
	global_load_lds_dwordx4 v190, s[98:99]
	s_add_u32 s98, s94, 0x80
	s_addc_u32 s99, s95, 0
	s_add_i32 m0, s14, 0x8000
	ds_read_b128 v[176:179], v195 offset:36864
	ds_read_b128 v[180:183], v195 offset:37888
	ds_read_b128 v[184:187], v195 offset:38912
	global_load_lds_dwordx4 v188, s[98:99]
	s_add_u32 s98, s94, 0xfffa8080
	s_addc_u32 s99, s95, -1
	s_add_i32 m0, s14, 0x7000
	ds_read_b128 v[200:203], v195 offset:39936
	ds_read_b128 v[204:207], v195 offset:49152
	ds_read_b128 v[208:211], v195 offset:50176
	global_load_lds_dwordx4 v188, s[98:99]
	s_add_u32 s98, s94, 0x160080
	s_addc_u32 s99, s95, 0
	s_add_i32 m0, s14, 0xc000
	ds_read_b128 v[212:215], v195 offset:51200
	ds_read_b128 v[226:229], v195 offset:52224
	ds_read_b128 v[230:233], v195 offset:53248
	global_load_lds_dwordx4 v188, s[98:99]
	s_add_u32 s98, s94, 0x108080
	s_addc_u32 s99, s95, 0
	s_add_i32 m0, s14, 0xb000
	ds_read_b128 v[234:237], v195 offset:54272
	ds_read_b128 v[238:241], v195 offset:55296
	ds_read_b128 v[242:245], v195 offset:56320
	global_load_lds_dwordx4 v188, s[98:99]
.Lspf1_b_rd:
	s_waitcnt lgkmcnt(0)
	s_setprio 1
	s_barrier
	v_mfma_f32_16x16x32_bf16 v[124:127], v[128:131], v[160:163], v[124:127]
	v_mfma_f32_16x16x32_bf16 v[120:123], v[136:139], v[160:163], v[120:123]
	v_mfma_f32_16x16x32_bf16 v[108:111], v[128:131], v[168:171], v[108:111]
	v_mfma_f32_16x16x32_bf16 v[104:107], v[136:139], v[168:171], v[104:107]
	v_mfma_f32_16x16x32_bf16 v[92:95], v[128:131], v[176:179], v[92:95]
	v_mfma_f32_16x16x32_bf16 v[88:91], v[136:139], v[176:179], v[88:91]
	v_mfma_f32_16x16x32_bf16 v[76:79], v[128:131], v[184:187], v[76:79]
	v_mfma_f32_16x16x32_bf16 v[72:75], v[136:139], v[184:187], v[72:75]
	v_mfma_f32_16x16x32_bf16 v[124:127], v[132:135], v[164:167], v[124:127]
	v_mfma_f32_16x16x32_bf16 v[120:123], v[140:143], v[164:167], v[120:123]
	v_mfma_f32_16x16x32_bf16 v[108:111], v[132:135], v[172:175], v[108:111]
	v_mfma_f32_16x16x32_bf16 v[104:107], v[140:143], v[172:175], v[104:107]
	v_mfma_f32_16x16x32_bf16 v[92:95], v[132:135], v[180:183], v[92:95]
	v_mfma_f32_16x16x32_bf16 v[88:91], v[140:143], v[180:183], v[88:91]
	v_mfma_f32_16x16x32_bf16 v[76:79], v[132:135], v[200:203], v[76:79]
	v_mfma_f32_16x16x32_bf16 v[72:75], v[140:143], v[200:203], v[72:75]
	v_mfma_f32_16x16x32_bf16 v[116:119], v[144:147], v[160:163], v[116:119]
	v_mfma_f32_16x16x32_bf16 v[112:115], v[152:155], v[160:163], v[112:115]
	v_mfma_f32_16x16x32_bf16 v[100:103], v[144:147], v[168:171], v[100:103]
	v_mfma_f32_16x16x32_bf16 v[96:99], v[152:155], v[168:171], v[96:99]
	v_mfma_f32_16x16x32_bf16 v[84:87], v[144:147], v[176:179], v[84:87]
	v_mfma_f32_16x16x32_bf16 v[80:83], v[152:155], v[176:179], v[80:83]
	v_mfma_f32_16x16x32_bf16 v[68:71], v[144:147], v[184:187], v[68:71]
	v_mfma_f32_16x16x32_bf16 v[64:67], v[152:155], v[184:187], v[64:67]
	v_mfma_f32_16x16x32_bf16 v[116:119], v[148:151], v[164:167], v[116:119]
	v_mfma_f32_16x16x32_bf16 v[112:115], v[156:159], v[164:167], v[112:115]
	v_mfma_f32_16x16x32_bf16 v[100:103], v[148:151], v[172:175], v[100:103]
	v_mfma_f32_16x16x32_bf16 v[96:99], v[156:159], v[172:175], v[96:99]
	v_mfma_f32_16x16x32_bf16 v[84:87], v[148:151], v[180:183], v[84:87]
	v_mfma_f32_16x16x32_bf16 v[80:83], v[156:159], v[180:183], v[80:83]
	v_mfma_f32_16x16x32_bf16 v[68:71], v[148:151], v[200:203], v[68:71]
	v_mfma_f32_16x16x32_bf16 v[64:67], v[156:159], v[200:203], v[64:67]
	v_mfma_f32_16x16x32_bf16 v[60:63], v[128:131], v[204:207], v[60:63]
	v_mfma_f32_16x16x32_bf16 v[56:59], v[136:139], v[204:207], v[56:59]
	v_mfma_f32_16x16x32_bf16 v[44:47], v[128:131], v[212:215], v[44:47]
	v_mfma_f32_16x16x32_bf16 v[40:43], v[136:139], v[212:215], v[40:43]
	v_mfma_f32_16x16x32_bf16 v[28:31], v[128:131], v[230:233], v[28:31]
	v_mfma_f32_16x16x32_bf16 v[24:27], v[136:139], v[230:233], v[24:27]
	v_mfma_f32_16x16x32_bf16 v[12:15], v[128:131], v[238:241], v[12:15]
	v_mfma_f32_16x16x32_bf16 v[8:11], v[136:139], v[238:241], v[8:11]
	v_mfma_f32_16x16x32_bf16 v[60:63], v[132:135], v[208:211], v[60:63]
	v_mfma_f32_16x16x32_bf16 v[56:59], v[140:143], v[208:211], v[56:59]
	v_mfma_f32_16x16x32_bf16 v[44:47], v[132:135], v[226:229], v[44:47]
	v_mfma_f32_16x16x32_bf16 v[40:43], v[140:143], v[226:229], v[40:43]
	v_mfma_f32_16x16x32_bf16 v[28:31], v[132:135], v[234:237], v[28:31]
	v_mfma_f32_16x16x32_bf16 v[24:27], v[140:143], v[234:237], v[24:27]
	v_mfma_f32_16x16x32_bf16 v[12:15], v[132:135], v[242:245], v[12:15]
	v_mfma_f32_16x16x32_bf16 v[8:11], v[140:143], v[242:245], v[8:11]
	v_mfma_f32_16x16x32_bf16 v[52:55], v[144:147], v[204:207], v[52:55]
	v_mfma_f32_16x16x32_bf16 v[48:51], v[152:155], v[204:207], v[48:51]
	v_mfma_f32_16x16x32_bf16 v[36:39], v[144:147], v[212:215], v[36:39]
	v_mfma_f32_16x16x32_bf16 v[32:35], v[152:155], v[212:215], v[32:35]
	v_mfma_f32_16x16x32_bf16 v[20:23], v[144:147], v[230:233], v[20:23]
	v_mfma_f32_16x16x32_bf16 v[16:19], v[152:155], v[230:233], v[16:19]
	v_mfma_f32_16x16x32_bf16 v[4:7], v[144:147], v[238:241], v[4:7]
	v_mfma_f32_16x16x32_bf16 v[0:3], v[152:155], v[238:241], v[0:3]
	v_mfma_f32_16x16x32_bf16 v[52:55], v[148:151], v[208:211], v[52:55]
	v_mfma_f32_16x16x32_bf16 v[48:51], v[156:159], v[208:211], v[48:51]
	v_mfma_f32_16x16x32_bf16 v[36:39], v[148:151], v[226:229], v[36:39]
	v_mfma_f32_16x16x32_bf16 v[32:35], v[156:159], v[226:229], v[32:35]
	v_mfma_f32_16x16x32_bf16 v[20:23], v[148:151], v[234:237], v[20:23]
	v_mfma_f32_16x16x32_bf16 v[16:19], v[156:159], v[234:237], v[16:19]
	v_mfma_f32_16x16x32_bf16 v[4:7], v[148:151], v[242:245], v[4:7]
	v_mfma_f32_16x16x32_bf16 v[0:3], v[156:159], v[242:245], v[0:3]
	s_waitcnt vmcnt(0)
	s_barrier
	s_setprio 0
	s_add_i32 s66, s66, 2
	s_add_u32 s22, s22, 0x100
	s_addc_u32 vcc_lo, vcc_lo, 0
	s_cmpk_gt_u32 s66, 0x55
	s_mov_b64 s[92:93], s[10:11]
	s_cbranch_scc0 .LBB0_248
	v_mov_b32_e32 v223, v195
	v_mov_b32_e32 v221, v193
	v_mov_b32_e32 v220, v191
	v_mov_b32_e32 v218, v189
	s_and_b64 vcc, exec, s[86:87]
	s_cbranch_vccz .LBB0_251
	s_barrier

; #define PG8_STAGE(bufoff, gbase, voff) do { _Pragma("unroll") for (int _i = 0; _i < 2; ++_i) \
;         __builtin_amdgcn_global_load_lds((const unsigned*)((const char*)(gbase) + (voff)[_i]), (PG8_LAS unsigned*)(lds + (bufoff) + ldsw + _i * 8192), 16, 0, 0); } while (0)
; #define PG8_WAIT_V(n) asm volatile("s_waitcnt vmcnt(" #n ")" ::: "memory")
; #define PG8_BAR __builtin_amdgcn_s_barrier()
; template <class Epi, class Sched, bool ALIGN_EPI = false, bool SP2 = false>
; __device__ __forceinline__ void gemm_phase(PG8_LAS unsigned char* lds, const Gemm g, const Sched& S, const Epi& E) {
;     ...
;     const int tid = tid_o, wid = __builtin_amdgcn_readfirstlane(tid >> 6), lane = tid & 63, wr = wid >> 2, wc = wid & 3, fr = lane & 15, fq = lane >> 4;
;     const int K = g.K, nt = K / BK;
;     unsigned voffA[2], voffB[2];
; #pragma unroll
;     for (int i = 0; i < 2; ++i) { int R, C; stage_rc(tid * 16 + i * 8192, R, C); const int Rb = Epi::PERM ? ((R & ~31) + perm32(R & 31)) : R;
;         voffA[i] = (unsigned)(R * K + C) * 2u; voffB[i] = (unsigned)(Rb * K + C) * 2u; }
;     const size_t kstep = (size_t)(BK * 2);
;     const size_t hstep = (size_t)HALF * K * 2;
;     const size_t tstep = 2 * hstep;
;     const unsigned ldsw = (unsigned)wid * 1024u;
;     const int aoff = lds_byte(wr * 64 + fr, fq * 8), boff = lds_byte(wc * 32 + fr, fq * 8);
;     ...
;     if constexpr (SP2) {
;         PG8_STAGE(PG8_SB(0, 0), cB, voffB); PG8_STAGE(PG8_SB(0, 1), cB + hstep, voffB); PG8_STAGE(PG8_SA(0, 0), cA, voffA); PG8_STAGE(PG8_SA(0, 1), cA + hstep, voffA);
;         if (wr == 1) PG8_BAR;
;         PG8_WAIT_V(2); PG8_BAR;
;         PG8_STAGE(PG8_SB(1, 0), cB + kstep, voffB); PG8_STAGE(PG8_SA(1, 0), cA + kstep, voffA); PG8_STAGE(PG8_SB(1, 1), cB + hstep + kstep, voffB);
;         PG8_WAIT_V(6); PG8_BAR;
.LBB0_393:
	v_lshrrev_b32_e32 v16, 1, v14
	v_and_b32_e32 v16, 24, v16
	s_lshl_b32 s6, s6, 5
	s_mov_b64 s[44:45], 0x80
	v_and_b32_e32 v15, 15, v14
	v_lshlrev_b32_e32 v17, 1, v16
	v_lshlrev_b32_e32 v14, 2, v14
	s_and_b32 s12, s6, 0x60
	s_add_i32 m0, s14, 0x18000
	v_lshl_add_u64 v[6:7], v[6:7], 0, s[44:45]
	v_lshl_or_b32 v17, v15, 6, v17
	s_lshl_b32 s7, s8, 13
	v_and_b32_e32 v14, 32, v14
	s_lshl_b32 s6, s12, 7
	s_waitcnt vmcnt(0)
	s_barrier
	global_load_lds_dwordx4 v[6:7], off
	v_lshl_add_u64 v[4:5], v[4:5], 0, s[44:45]
	s_add_i32 m0, s14, 0x1a000
	s_add_i32 s68, s14, 0x8000
	s_add_i32 s69, s14, 0xa000
	v_bitop3_b32 v177, v17, s6, v14 bitop3:0xde
	global_load_lds_dwordx4 v[4:5], off
	v_lshl_add_u64 v[0:1], v[0:1], 0, s[44:45]
	s_mov_b32 m0, s68
	s_add_u32 s6, s96, 0x80080
	v_bitop3_b32 v18, v17, s7, v14 bitop3:0xde
	global_load_lds_dwordx4 v[0:1], off
	v_lshl_add_u64 v[0:1], v[2:3], 0, s[44:45]
	s_mov_b32 m0, s69
	s_addc_u32 s7, s97, 0
	global_load_lds_dwordx4 v[0:1], off
	s_add_i32 m0, s14, 0x1c000
	v_lshl_add_u64 v[0:1], s[6:7], 0, v[138:139]
	global_load_lds_dwordx4 v[0:1], off
	v_lshl_add_u64 v[0:1], s[6:7], 0, v[142:143]
	s_add_i32 m0, s14, 0x1e000
	s_cmpk_lt_u32 s9, 0x100
	global_load_lds_dwordx4 v[0:1], off
	v_lshlrev_b32_e32 v0, 2, v16
	v_mov_b32_e32 v1, v139
	v_lshl_add_u64 v[144:145], s[42:43], 0, v[0:1]
	v_lshlrev_b32_e32 v0, 15, v8
	v_and_b32_e32 v0, 0xffff0000, v0
	v_lshl_add_u32 v0, v9, 12, v0
	v_and_b32_e32 v1, 1, v8
	v_lshl_or_b32 v0, v1, 6, v0
	s_cselect_b64 s[86:87], -1, 0
	s_ashr_i32 s9, s8, 31
	v_lshl_add_u32 v146, v10, 1, v0
	v_lshlrev_b32_e32 v0, 15, v11
	v_lshl_or_b32 v176, s8, 6, v15
	s_lshl_b64 s[8:9], s[8:9], 12
	v_and_b32_e32 v0, 0xffff0000, v0
	s_waitcnt vmcnt(6)
	s_add_u32 s70, s72, s8
	v_lshl_add_u32 v0, v12, 12, v0
	v_and_b32_e32 v1, 1, v11
	s_addc_u32 s71, s22, s9
	v_lshl_or_b32 v0, v1, 6, v0
	s_add_i32 s80, 0, 0x10000
	s_add_i32 s81, 0, 0x14000
	v_cmp_eq_u32_e64 s[6:7], 0, v15
	v_or_b32_e32 v178, s12, v16
	v_mov_b32_e32 v147, v139
	v_lshl_add_u32 v148, v13, 1, v0
	v_mov_b32_e32 v149, v139
	v_mov_b64_e32 v[150:151], 0x400
	v_mov_b64_e32 v[152:153], 0x3ff
	v_add_u32_e32 v179, s80, v177
	v_add_u32_e32 v180, s81, v177
	v_add_u32_e32 v181, 0, v18
	v_mbcnt_hi_u32_b32 v182, -1, v216
	v_mov_b32_e32 v183, 0x358637bd
	v_mov_b32_e32 v184, 0x3e0293ee
	v_mov_b32_e32 v185, 0x3e38aa3b
	s_barrier
	s_branch .LBB0_396

; #define PG8_STAGE(bufoff, gbase, voff) do { _Pragma("unroll") for (int _i = 0; _i < 2; ++_i) \
;         __builtin_amdgcn_global_load_lds((const unsigned*)((const char*)(gbase) + (voff)[_i]), (PG8_LAS unsigned*)(lds + (bufoff) + ldsw + _i * 8192), 16, 0, 0); } while (0)
; #define PG8_LDA(dst, b, h) do { _Pragma("unroll") for (int m = 0; m < 4; ++m) _Pragma("unroll") for (int k = 0; k < 2; ++k) dst[m][k] = *(const PG8_LAS bf16x8*)(lds + PG8_SA(b, h) + aoff + m * 2048 + k * 1024); } while (0)
; #define PG8_LDB(dst, b, h) do { _Pragma("unroll") for (int n = 0; n < 2; ++n) _Pragma("unroll") for (int k = 0; k < 2; ++k) dst[n][k] = *(const PG8_LAS bf16x8*)(lds + PG8_SB(b, h) + boff + n * 2048 + k * 1024); } while (0)
; #define PG8_WAIT_V(n) asm volatile("s_waitcnt vmcnt(" #n ")" ::: "memory")
; template <class Epi, class Sched, bool ALIGN_EPI = false, bool SP2 = false>
; __device__ __forceinline__ void gemm_phase(PG8_LAS unsigned char* lds, const Gemm g, const Sched& S, const Epi& E) {
;     ...
;     f32x4 acc[2][2][4][2];
; #pragma unroll
;     for (int a = 0; a < 2; ++a)
; #pragma unroll
;         for (int b = 0; b < 2; ++b)
; #pragma unroll
;             for (int m = 0; m < 4; ++m)
; #pragma unroll
;                 for (int n = 0; n < 2; ++n) acc[a][b][m][n] = (f32x4){0.f, 0.f, 0.f, 0.f};
;     ...
;         const bool has_next = S.next(ui + 1, nxt);
;         const char* nA = has_next ? (const char*)g.A + (size_t)nxt.pm * tstep : cA; const char* nB = has_next ? (const char*)g.Bt + (size_t)nxt.pn * tstep : cB;
;         for (int t = 0; t < nt; t += 2) {
;             const bool last = (t == nt - 2);
;             const char* a1 = cA + (size_t)(t + 1) * kstep;
;             const char* a2 = last ? nA : cA + (size_t)(t + 2) * kstep; const char* b2 = last ? nB : cB + (size_t)(t + 2) * kstep;
;             const char* a3 = a2 + kstep; const char* b3 = b2 + kstep;
;             if (last && has_next) S.a_ready(nxt);
;             if constexpr (SP2) {
;             PG8_LDB(B0, 0, 0); PG8_LDB(B1, 0, 1); PG8_SCHED; PG8_LDA(At, 0, 0); PG8_STAGE(PG8_SA(1, 1), a1 + hstep, voffA);
;             PG8_WAIT_V(8); PG8_WAIT_L(0); PG8_BAR; PG8_MMA(0, 0, At, B0); PG8_MMA(0, 1, At, B1); PG8_BAR; PG8_SCHED;
;             PG8_LDA(At, 0, 1); PG8_STAGE(PG8_SB(0, 0), b2, voffB); PG8_STAGE(PG8_SB(0, 1), b2 + hstep, voffB); PG8_STAGE(PG8_SA(0, 0), a2, voffA);
.LBB0_402:
	s_ashr_i32 s91, s90, 31
	s_lshl_b64 s[12:13], s[90:91], 20
	s_add_u32 s92, s40, s12
	s_addc_u32 s93, s41, s13
	s_and_b64 s[12:13], s[8:9], exec
	s_cselect_b32 s12, s93, s11
	s_cselect_b32 s13, s92, s10
	s_ashr_i32 s89, s88, 31
	s_lshl_b64 s[66:67], s[88:89], 20
	s_add_u32 s82, s84, s66
	s_addc_u32 s83, s85, s67
	s_and_b64 s[66:67], s[8:9], exec
	s_cselect_b32 s47, s83, s97
	s_cselect_b32 s89, s82, s96
	s_add_u32 s10, s10, 0x80080
	s_addc_u32 s11, s11, 0
	s_add_u32 s91, s96, 0x100
	v_mov_b64_e32 v[0:1], 0
	v_mov_b64_e32 v[2:3], 0
	v_mov_b64_e32 v[4:5], 0
	v_mov_b64_e32 v[6:7], 0
	v_mov_b64_e32 v[8:9], 0
	v_mov_b64_e32 v[10:11], 0
	v_mov_b64_e32 v[12:13], 0
	v_mov_b64_e32 v[14:15], 0
	v_mov_b64_e32 v[16:17], 0
	v_mov_b64_e32 v[18:19], 0
	v_mov_b64_e32 v[20:21], 0
	v_mov_b64_e32 v[22:23], 0
	v_mov_b64_e32 v[24:25], 0
	v_mov_b64_e32 v[26:27], 0
	v_mov_b64_e32 v[28:29], 0
	v_mov_b64_e32 v[30:31], 0
	v_mov_b64_e32 v[32:33], 0
	v_mov_b64_e32 v[34:35], 0
	v_mov_b64_e32 v[36:37], 0
	v_mov_b64_e32 v[38:39], 0
	v_mov_b64_e32 v[40:41], 0
	v_mov_b64_e32 v[42:43], 0
	v_mov_b64_e32 v[44:45], 0
	v_mov_b64_e32 v[46:47], 0
	v_mov_b64_e32 v[48:49], 0
	v_mov_b64_e32 v[50:51], 0
	v_mov_b64_e32 v[52:53], 0
	v_mov_b64_e32 v[54:55], 0
	v_mov_b64_e32 v[56:57], 0
	v_mov_b64_e32 v[58:59], 0
	v_mov_b64_e32 v[60:61], 0
	v_mov_b64_e32 v[62:63], 0
	v_mov_b64_e32 v[64:65], 0
	v_mov_b64_e32 v[66:67], 0
	v_mov_b64_e32 v[68:69], 0
	v_mov_b64_e32 v[70:71], 0
	v_mov_b64_e32 v[72:73], 0
	v_mov_b64_e32 v[74:75], 0
	v_mov_b64_e32 v[76:77], 0
	v_mov_b64_e32 v[78:79], 0
	v_mov_b64_e32 v[80:81], 0
	v_mov_b64_e32 v[82:83], 0
	v_mov_b64_e32 v[84:85], 0
	v_mov_b64_e32 v[86:87], 0
	v_mov_b64_e32 v[88:89], 0
	v_mov_b64_e32 v[90:91], 0
	v_mov_b64_e32 v[92:93], 0
	v_mov_b64_e32 v[94:95], 0
	v_mov_b64_e32 v[96:97], 0
	v_mov_b64_e32 v[98:99], 0
	v_mov_b64_e32 v[100:101], 0
	v_mov_b64_e32 v[102:103], 0
	v_mov_b64_e32 v[104:105], 0
	v_mov_b64_e32 v[106:107], 0
	v_mov_b64_e32 v[108:109], 0
	v_mov_b64_e32 v[110:111], 0
	v_mov_b64_e32 v[112:113], 0
	v_mov_b64_e32 v[114:115], 0
	v_mov_b64_e32 v[116:117], 0
	v_mov_b64_e32 v[118:119], 0
	v_mov_b64_e32 v[120:121], 0
	v_mov_b64_e32 v[122:123], 0
	v_mov_b64_e32 v[124:125], 0
	v_mov_b64_e32 v[126:127], 0
	s_addc_u32 s95, s97, 0
	s_mov_b32 s66, -2
	s_waitcnt lgkmcnt(0)
	v_mov_b32_e32 v137, v176
	v_mov_b32_e32 v139, v177
	v_mov_b32_e32 v141, v178
	v_mov_b32_e32 v143, v179
	v_mov_b32_e32 v147, v180
	v_mov_b32_e32 v149, v181
	v_add_u32_e32 v214, 0x18000, v139
	v_add_u32_e32 v215, 0x1c000, v139
	s_cmp_lg_u32 s86, 0
	s_cbranch_scc0 .Lspf2_pre
	s_add_i32 m0, s3, 0xc000
	s_nop 0
	global_load_lds_dwordx4 v146, s[10:11]
	s_add_u32 s98, s10, 0x20000
	s_addc_u32 s99, s11, 0
	s_add_i32 m0, s3, 0xd000
	s_nop 0
	global_load_lds_dwordx4 v146, s[98:99]
	s_add_u32 s98, s10, 0xfff80000
	s_addc_u32 s99, s11, -1
	s_add_i32 m0, s3, 0x8000
	s_nop 0
	global_load_lds_dwordx4 v146, s[98:99]
	s_add_u32 s98, s10, 0xfffa0000
	s_addc_u32 s99, s11, -1
	s_add_i32 m0, s3, 0x9000
	s_nop 0
	global_load_lds_dwordx4 v146, s[98:99]
.Lspf2_pre:
.LBB0_403:
	s_add_u32 s67, s10, 0xfff80080
	s_addc_u32 s74, s11, -1
	s_cmp_eq_u32 s66, 28
	s_cselect_b32 vcc_hi, s12, s74
	s_cselect_b32 vcc_lo, s13, s67
	s_cselect_b32 s97, s47, s95
	s_cselect_b32 s96, s89, s91
	s_cmp_lg_u32 s86, 0
	s_cbranch_scc0 .Lspf2_a_h1
	s_add_u32 s98, s91, 0xffffff80
	s_addc_u32 s99, s95, -1
	s_add_i32 m0, s3, 0x18000
	ds_read_b128 v[128:131], v143
	ds_read_b128 v[132:135], v143 offset:1024
	ds_read_b128 v[154:157], v143 offset:2048
	global_load_lds_dwordx4 v138, s[98:99]
	s_add_i32 m0, s3, 0x1a000
	ds_read_b128 v[158:161], v143 offset:3072
	ds_read_b128 v[162:165], v147
	ds_read_b128 v[166:169], v147 offset:1024
	global_load_lds_dwordx4 v142, s[98:99]
	s_add_u32 s98, s91, 0x1ff80
	s_addc_u32 s99, s95, 0
	s_add_i32 m0, s3, 0x19000
	ds_read_b128 v[170:173], v147 offset:2048
	ds_read_b128 v[186:189], v147 offset:3072
	ds_read_b128 v[190:193], v149
	global_load_lds_dwordx4 v138, s[98:99]
	s_add_i32 m0, s3, 0x1b000
	ds_read_b128 v[194:197], v149 offset:1024
	ds_read_b128 v[198:201], v149 offset:2048
	ds_read_b128 v[202:205], v149 offset:3072
	global_load_lds_dwordx4 v142, s[98:99]
	s_add_u32 s98, s91, 0x7ff80
	s_addc_u32 s99, s95, 0
	s_add_i32 m0, s3, 0x1c000
	ds_read_b128 v[206:209], v149 offset:4096
	ds_read_b128 v[210:213], v149 offset:5120
	ds_read_b128 v[218:221], v149 offset:6144
	global_load_lds_dwordx4 v138, s[98:99]
	s_add_i32 m0, s3, 0x1e000
	ds_read_b128 v[224:227], v149 offset:7168
	ds_read_b128 v[174:177], v149 offset:16384
	ds_read_b128 v[178:181], v149 offset:17408
	global_load_lds_dwordx4 v142, s[98:99]
	s_add_u32 s98, s91, 0x9ff80
	s_addc_u32 s99, s95, 0
	s_add_i32 m0, s3, 0x1d000
	ds_read_b128 v[228:231], v149 offset:18432
	ds_read_b128 v[232:235], v149 offset:19456
	ds_read_b128 v[236:239], v149 offset:20480
	global_load_lds_dwordx4 v138, s[98:99]
	s_add_i32 m0, s3, 0x1f000
	ds_read_b128 v[240:243], v149 offset:21504
	ds_read_b128 v[244:247], v149 offset:22528
	ds_read_b128 v[248:251], v149 offset:23552
	global_load_lds_dwordx4 v142, s[98:99]
	s_branch .Lspf2_a_rd
; #define PG8_STAGE(bufoff, gbase, voff) do { _Pragma("unroll") for (int _i = 0; _i < 2; ++_i) \
;         __builtin_amdgcn_global_load_lds((const unsigned*)((const char*)(gbase) + (voff)[_i]), (PG8_LAS unsigned*)(lds + (bufoff) + ldsw + _i * 8192), 16, 0, 0); } while (0)
; #define PG8_LDA(dst, b, h) do { _Pragma("unroll") for (int m = 0; m < 4; ++m) _Pragma("unroll") for (int k = 0; k < 2; ++k) dst[m][k] = *(const PG8_LAS bf16x8*)(lds + PG8_SA(b, h) + aoff + m * 2048 + k * 1024); } while (0)
; #define PG8_LDB(dst, b, h) do { _Pragma("unroll") for (int n = 0; n < 2; ++n) _Pragma("unroll") for (int k = 0; k < 2; ++k) dst[n][k] = *(const PG8_LAS bf16x8*)(lds + PG8_SB(b, h) + boff + n * 2048 + k * 1024); } while (0)
; #define PG8_MMA(ai, bj, At, Bt) do { __builtin_amdgcn_s_setprio(1); _Pragma("unroll") for (int m = 0; m < 4; ++m) _Pragma("unroll") for (int n = 0; n < 2; ++n) _Pragma("unroll") for (int k = 0; k < 2; ++k) \
;         acc[ai][bj][m][n] = __builtin_amdgcn_mfma_f32_16x16x32_bf16(Bt[n][k], At[m][k], acc[ai][bj][m][n], 0, 0, 0); __builtin_amdgcn_s_setprio(0); } while (0)
; #define PG8_WAIT_V(n) asm volatile("s_waitcnt vmcnt(" #n ")" ::: "memory")
; #define PG8_WAIT_L(n) asm volatile("s_waitcnt lgkmcnt(" #n ")" ::: "memory")
; #define PG8_BAR __builtin_amdgcn_s_barrier()
; #define PG8_SCHED __builtin_amdgcn_sched_barrier(0)
; template <class Epi, class Sched, bool ALIGN_EPI = false, bool SP2 = false>
; __device__ __forceinline__ void gemm_phase(PG8_LAS unsigned char* lds, const Gemm g, const Sched& S, const Epi& E) {
;     ...
;             PG8_LDB(B0, 0, 0); PG8_LDB(B1, 0, 1); PG8_SCHED; PG8_LDA(At, 0, 0); PG8_STAGE(PG8_SA(1, 1), a1 + hstep, voffA);
;             PG8_WAIT_V(8); PG8_WAIT_L(0); PG8_BAR; PG8_MMA(0, 0, At, B0); PG8_MMA(0, 1, At, B1); PG8_BAR; PG8_SCHED;
;             PG8_LDA(At, 0, 1); PG8_STAGE(PG8_SB(0, 0), b2, voffB); PG8_STAGE(PG8_SB(0, 1), b2 + hstep, voffB); PG8_STAGE(PG8_SA(0, 0), a2, voffA);
;             PG8_WAIT_V(8); PG8_WAIT_L(0); PG8_BAR; PG8_MMA(1, 0, At, B0); PG8_MMA(1, 1, At, B1); PG8_BAR; PG8_SCHED;
.Lspf2_a_h1:
	s_add_u32 s98, s10, 0xfff80000
	s_addc_u32 s99, s11, -1
	s_add_i32 m0, s3, 0xa000
	ds_read_b128 v[128:131], v143
	ds_read_b128 v[132:135], v143 offset:1024
	ds_read_b128 v[154:157], v143 offset:2048
	global_load_lds_dwordx4 v148, s[98:99]
	s_add_u32 s98, s10, 0xfff60000
	s_addc_u32 s99, s11, -1
	s_add_i32 m0, s3, 0x9000
	ds_read_b128 v[158:161], v143 offset:3072
	ds_read_b128 v[162:165], v147
	ds_read_b128 v[166:169], v147 offset:1024
	global_load_lds_dwordx4 v148, s[98:99]
	s_add_i32 m0, s3, 0xe000
	ds_read_b128 v[170:173], v147 offset:2048
	ds_read_b128 v[186:189], v147 offset:3072
	ds_read_b128 v[190:193], v149
	global_load_lds_dwordx4 v148, s[10:11]
	s_add_u32 s98, s10, 0xfffe0000
	s_addc_u32 s99, s11, -1
	s_add_i32 m0, s3, 0xd000
	ds_read_b128 v[194:197], v149 offset:1024
	ds_read_b128 v[198:201], v149 offset:2048
	ds_read_b128 v[202:205], v149 offset:3072
	global_load_lds_dwordx4 v148, s[98:99]
	s_add_i32 m0, s3, 0x0
	ds_read_b128 v[206:209], v149 offset:4096
	ds_read_b128 v[210:213], v149 offset:5120
	ds_read_b128 v[218:221], v149 offset:6144
	global_load_lds_dwordx4 v136, vcc
	s_add_u32 s98, vcc_lo, 0xfffe0000
	s_addc_u32 s99, vcc_hi, -1
	s_add_i32 m0, s3, 0xfffff000
	ds_read_b128 v[224:227], v149 offset:7168
	ds_read_b128 v[174:177], v149 offset:16384
	ds_read_b128 v[178:181], v149 offset:17408
	global_load_lds_dwordx4 v136, s[98:99]
	s_add_u32 s98, vcc_lo, 0x80000
	s_addc_u32 s99, vcc_hi, 0
	s_add_i32 m0, s3, 0x4000
	ds_read_b128 v[228:231], v149 offset:18432
	ds_read_b128 v[232:235], v149 offset:19456
	ds_read_b128 v[236:239], v149 offset:20480
	global_load_lds_dwordx4 v136, s[98:99]
	s_add_u32 s98, vcc_lo, 0x60000
	s_addc_u32 s99, vcc_hi, 0
	s_add_i32 m0, s3, 0x3000
	ds_read_b128 v[240:243], v149 offset:21504
	ds_read_b128 v[244:247], v149 offset:22528
	ds_read_b128 v[248:251], v149 offset:23552
	global_load_lds_dwordx4 v136, s[98:99]
.Lspf2_a_rd:
	s_waitcnt lgkmcnt(0)
	s_setprio 1
	s_barrier
	v_mfma_f32_16x16x32_bf16 v[72:75], v[128:131], v[190:193], v[72:75]
	v_mfma_f32_16x16x32_bf16 v[80:83], v[154:157], v[190:193], v[80:83]
	v_mfma_f32_16x16x32_bf16 v[104:107], v[128:131], v[198:201], v[104:107]
	v_mfma_f32_16x16x32_bf16 v[108:111], v[154:157], v[198:201], v[108:111]
	v_mfma_f32_16x16x32_bf16 v[124:127], v[128:131], v[206:209], v[124:127]
	v_mfma_f32_16x16x32_bf16 v[120:123], v[154:157], v[206:209], v[120:123]
	v_mfma_f32_16x16x32_bf16 v[100:103], v[128:131], v[218:221], v[100:103]
	v_mfma_f32_16x16x32_bf16 v[96:99], v[154:157], v[218:221], v[96:99]
	v_mfma_f32_16x16x32_bf16 v[72:75], v[132:135], v[194:197], v[72:75]
	v_mfma_f32_16x16x32_bf16 v[80:83], v[158:161], v[194:197], v[80:83]
	v_mfma_f32_16x16x32_bf16 v[104:107], v[132:135], v[202:205], v[104:107]
	v_mfma_f32_16x16x32_bf16 v[108:111], v[158:161], v[202:205], v[108:111]
	v_mfma_f32_16x16x32_bf16 v[124:127], v[132:135], v[210:213], v[124:127]
	v_mfma_f32_16x16x32_bf16 v[120:123], v[158:161], v[210:213], v[120:123]
	v_mfma_f32_16x16x32_bf16 v[100:103], v[132:135], v[224:227], v[100:103]
	v_mfma_f32_16x16x32_bf16 v[96:99], v[158:161], v[224:227], v[96:99]
	v_mfma_f32_16x16x32_bf16 v[64:67], v[162:165], v[190:193], v[64:67]
	v_mfma_f32_16x16x32_bf16 v[68:71], v[170:173], v[190:193], v[68:71]
	v_mfma_f32_16x16x32_bf16 v[88:91], v[162:165], v[198:201], v[88:91]
	v_mfma_f32_16x16x32_bf16 v[92:95], v[170:173], v[198:201], v[92:95]
	v_mfma_f32_16x16x32_bf16 v[116:119], v[162:165], v[206:209], v[116:119]
	v_mfma_f32_16x16x32_bf16 v[112:115], v[170:173], v[206:209], v[112:115]
	v_mfma_f32_16x16x32_bf16 v[84:87], v[162:165], v[218:221], v[84:87]
	v_mfma_f32_16x16x32_bf16 v[76:79], v[170:173], v[218:221], v[76:79]
	v_mfma_f32_16x16x32_bf16 v[64:67], v[166:169], v[194:197], v[64:67]
	v_mfma_f32_16x16x32_bf16 v[68:71], v[186:189], v[194:197], v[68:71]
	v_mfma_f32_16x16x32_bf16 v[88:91], v[166:169], v[202:205], v[88:91]
	v_mfma_f32_16x16x32_bf16 v[92:95], v[186:189], v[202:205], v[92:95]
	v_mfma_f32_16x16x32_bf16 v[116:119], v[166:169], v[210:213], v[116:119]
	v_mfma_f32_16x16x32_bf16 v[112:115], v[186:189], v[210:213], v[112:115]
	v_mfma_f32_16x16x32_bf16 v[84:87], v[166:169], v[224:227], v[84:87]
	v_mfma_f32_16x16x32_bf16 v[76:79], v[186:189], v[224:227], v[76:79]
	v_mfma_f32_16x16x32_bf16 v[60:63], v[128:131], v[174:177], v[60:63]
	v_mfma_f32_16x16x32_bf16 v[56:59], v[154:157], v[174:177], v[56:59]
	v_mfma_f32_16x16x32_bf16 v[44:47], v[128:131], v[228:231], v[44:47]
	v_mfma_f32_16x16x32_bf16 v[40:43], v[154:157], v[228:231], v[40:43]
	v_mfma_f32_16x16x32_bf16 v[28:31], v[128:131], v[236:239], v[28:31]
	v_mfma_f32_16x16x32_bf16 v[24:27], v[154:157], v[236:239], v[24:27]
	v_mfma_f32_16x16x32_bf16 v[12:15], v[128:131], v[244:247], v[12:15]
	v_mfma_f32_16x16x32_bf16 v[8:11], v[154:157], v[244:247], v[8:11]
	v_mfma_f32_16x16x32_bf16 v[60:63], v[132:135], v[178:181], v[60:63]
	v_mfma_f32_16x16x32_bf16 v[56:59], v[158:161], v[178:181], v[56:59]
	v_mfma_f32_16x16x32_bf16 v[44:47], v[132:135], v[232:235], v[44:47]
	v_mfma_f32_16x16x32_bf16 v[40:43], v[158:161], v[232:235], v[40:43]
	v_mfma_f32_16x16x32_bf16 v[28:31], v[132:135], v[240:243], v[28:31]
	v_mfma_f32_16x16x32_bf16 v[24:27], v[158:161], v[240:243], v[24:27]
	v_mfma_f32_16x16x32_bf16 v[12:15], v[132:135], v[248:251], v[12:15]
	v_mfma_f32_16x16x32_bf16 v[8:11], v[158:161], v[248:251], v[8:11]
	v_mfma_f32_16x16x32_bf16 v[52:55], v[162:165], v[174:177], v[52:55]
	v_mfma_f32_16x16x32_bf16 v[48:51], v[170:173], v[174:177], v[48:51]
	v_mfma_f32_16x16x32_bf16 v[36:39], v[162:165], v[228:231], v[36:39]
	v_mfma_f32_16x16x32_bf16 v[32:35], v[170:173], v[228:231], v[32:35]
	v_mfma_f32_16x16x32_bf16 v[20:23], v[162:165], v[236:239], v[20:23]
	v_mfma_f32_16x16x32_bf16 v[16:19], v[170:173], v[236:239], v[16:19]
	v_mfma_f32_16x16x32_bf16 v[4:7], v[162:165], v[244:247], v[4:7]
	v_mfma_f32_16x16x32_bf16 v[0:3], v[170:173], v[244:247], v[0:3]
	v_mfma_f32_16x16x32_bf16 v[52:55], v[166:169], v[178:181], v[52:55]
	v_mfma_f32_16x16x32_bf16 v[48:51], v[186:189], v[178:181], v[48:51]
	v_mfma_f32_16x16x32_bf16 v[36:39], v[166:169], v[232:235], v[36:39]
	v_mfma_f32_16x16x32_bf16 v[32:35], v[186:189], v[232:235], v[32:35]
	v_mfma_f32_16x16x32_bf16 v[20:23], v[166:169], v[240:243], v[20:23]
	v_mfma_f32_16x16x32_bf16 v[16:19], v[186:189], v[240:243], v[16:19]
	v_mfma_f32_16x16x32_bf16 v[4:7], v[166:169], v[248:251], v[4:7]
	v_mfma_f32_16x16x32_bf16 v[0:3], v[186:189], v[248:251], v[0:3]
	s_waitcnt vmcnt(0)
	s_barrier
; #define PG8_STAGE(bufoff, gbase, voff) do { _Pragma("unroll") for (int _i = 0; _i < 2; ++_i) \
;         __builtin_amdgcn_global_load_lds((const unsigned*)((const char*)(gbase) + (voff)[_i]), (PG8_LAS unsigned*)(lds + (bufoff) + ldsw + _i * 8192), 16, 0, 0); } while (0)
; #define PG8_LDA(dst, b, h) do { _Pragma("unroll") for (int m = 0; m < 4; ++m) _Pragma("unroll") for (int k = 0; k < 2; ++k) dst[m][k] = *(const PG8_LAS bf16x8*)(lds + PG8_SA(b, h) + aoff + m * 2048 + k * 1024); } while (0)
; #define PG8_LDB(dst, b, h) do { _Pragma("unroll") for (int n = 0; n < 2; ++n) _Pragma("unroll") for (int k = 0; k < 2; ++k) dst[n][k] = *(const PG8_LAS bf16x8*)(lds + PG8_SB(b, h) + boff + n * 2048 + k * 1024); } while (0)
; #define PG8_MMA(ai, bj, At, Bt) do { __builtin_amdgcn_s_setprio(1); _Pragma("unroll") for (int m = 0; m < 4; ++m) _Pragma("unroll") for (int n = 0; n < 2; ++n) _Pragma("unroll") for (int k = 0; k < 2; ++k) \
;         acc[ai][bj][m][n] = __builtin_amdgcn_mfma_f32_16x16x32_bf16(Bt[n][k], At[m][k], acc[ai][bj][m][n], 0, 0, 0); __builtin_amdgcn_s_setprio(0); } while (0)
; #define PG8_WAIT_V(n) asm volatile("s_waitcnt vmcnt(" #n ")" ::: "memory")
; #define PG8_WAIT_L(n) asm volatile("s_waitcnt lgkmcnt(" #n ")" ::: "memory")
; #define PG8_BAR __builtin_amdgcn_s_barrier()
; #define PG8_SCHED __builtin_amdgcn_sched_barrier(0)
; template <class Epi, class Sched, bool ALIGN_EPI = false, bool SP2 = false>
; __device__ __forceinline__ void gemm_phase(PG8_LAS unsigned char* lds, const Gemm g, const Sched& S, const Epi& E) {
;     ...
;             PG8_LDA(At, 0, 1); PG8_STAGE(PG8_SB(0, 0), b2, voffB); PG8_STAGE(PG8_SB(0, 1), b2 + hstep, voffB); PG8_STAGE(PG8_SA(0, 0), a2, voffA);
;             PG8_WAIT_V(8); PG8_WAIT_L(0); PG8_BAR; PG8_MMA(1, 0, At, B0); PG8_MMA(1, 1, At, B1); PG8_BAR; PG8_SCHED;
;             PG8_LDB(B0, 1, 0); PG8_LDB(B1, 1, 1); PG8_SCHED; PG8_LDA(At, 1, 0); PG8_STAGE(PG8_SA(0, 1), a2 + hstep, voffA);
;             PG8_WAIT_V(8); PG8_WAIT_L(0); PG8_BAR; PG8_MMA(0, 0, At, B0); PG8_MMA(0, 1, At, B1); PG8_BAR; PG8_SCHED;
;             PG8_LDA(At, 1, 1); PG8_STAGE(PG8_SB(1, 0), b3, voffB); PG8_STAGE(PG8_SB(1, 1), b3 + hstep, voffB); PG8_STAGE(PG8_SA(1, 0), a3, voffA);
	s_setprio 0
	s_cmp_lg_u32 s86, 0
	s_cbranch_scc0 .Lspf2_b_h1
	s_add_i32 m0, s3, 0x10000
	ds_read_b128 v[128:131], v214
	ds_read_b128 v[132:135], v214 offset:1024
	ds_read_b128 v[154:157], v214 offset:2048
	global_load_lds_dwordx4 v138, s[96:97]
	s_add_i32 m0, s3, 0x12000
	ds_read_b128 v[158:161], v214 offset:3072
	ds_read_b128 v[162:165], v215
	ds_read_b128 v[166:169], v215 offset:1024
	global_load_lds_dwordx4 v142, s[96:97]
	s_add_u32 s98, s96, 0x20000
	s_addc_u32 s99, s97, 0
	s_add_i32 m0, s3, 0x11000
	ds_read_b128 v[170:173], v215 offset:2048
	ds_read_b128 v[186:189], v215 offset:3072
	ds_read_b128 v[190:193], v149 offset:32768
	global_load_lds_dwordx4 v138, s[98:99]
	s_add_i32 m0, s3, 0x13000
	ds_read_b128 v[194:197], v149 offset:33792
	ds_read_b128 v[198:201], v149 offset:34816
	ds_read_b128 v[202:205], v149 offset:35840
	global_load_lds_dwordx4 v142, s[98:99]
	s_add_u32 s98, s96, 0x80000
	s_addc_u32 s99, s97, 0
	s_add_i32 m0, s3, 0x14000
	ds_read_b128 v[206:209], v149 offset:36864
	ds_read_b128 v[210:213], v149 offset:37888
	ds_read_b128 v[218:221], v149 offset:38912
	global_load_lds_dwordx4 v138, s[98:99]
	s_add_i32 m0, s3, 0x16000
	ds_read_b128 v[224:227], v149 offset:39936
	ds_read_b128 v[174:177], v149 offset:49152
	ds_read_b128 v[178:181], v149 offset:50176
	global_load_lds_dwordx4 v142, s[98:99]
	s_add_u32 s98, s96, 0xa0000
	s_addc_u32 s99, s97, 0
	s_add_i32 m0, s3, 0x15000
	ds_read_b128 v[228:231], v149 offset:51200
	ds_read_b128 v[232:235], v149 offset:52224
	ds_read_b128 v[236:239], v149 offset:53248
	global_load_lds_dwordx4 v138, s[98:99]
	s_add_i32 m0, s3, 0x17000
	ds_read_b128 v[240:243], v149 offset:54272
	ds_read_b128 v[244:247], v149 offset:55296
	ds_read_b128 v[248:251], v149 offset:56320
	global_load_lds_dwordx4 v142, s[98:99]
	s_branch .Lspf2_b_rd
.Lspf2_b_h1:
	s_add_i32 m0, s3, 0x2000
	ds_read_b128 v[128:131], v214
	ds_read_b128 v[132:135], v214 offset:1024
	ds_read_b128 v[154:157], v214 offset:2048
	global_load_lds_dwordx4 v140, vcc
	s_add_u32 s98, vcc_lo, 0xfffe0000
	s_addc_u32 s99, vcc_hi, -1
	s_add_i32 m0, s3, 0x1000
	ds_read_b128 v[158:161], v214 offset:3072
	ds_read_b128 v[162:165], v215
	ds_read_b128 v[166:169], v215 offset:1024
	global_load_lds_dwordx4 v140, s[98:99]
	s_add_u32 s98, vcc_lo, 0x80000
	s_addc_u32 s99, vcc_hi, 0
	s_add_i32 m0, s3, 0x6000
	ds_read_b128 v[170:173], v215 offset:2048
	ds_read_b128 v[186:189], v215 offset:3072
	ds_read_b128 v[190:193], v149 offset:32768
	global_load_lds_dwordx4 v140, s[98:99]
	s_add_u32 s98, vcc_lo, 0x60000
	s_addc_u32 s99, vcc_hi, 0
	s_add_i32 m0, s3, 0x5000
	ds_read_b128 v[194:197], v149 offset:33792
	ds_read_b128 v[198:201], v149 offset:34816
	ds_read_b128 v[202:205], v149 offset:35840
	global_load_lds_dwordx4 v140, s[98:99]
	s_add_u32 s98, vcc_lo, 0x80
	s_addc_u32 s99, vcc_hi, 0
	s_add_i32 m0, s3, 0x8000
	ds_read_b128 v[206:209], v149 offset:36864
	ds_read_b128 v[210:213], v149 offset:37888
	ds_read_b128 v[218:221], v149 offset:38912
	global_load_lds_dwordx4 v136, s[98:99]
	s_add_u32 s98, vcc_lo, 0xfffe0080
	s_addc_u32 s99, vcc_hi, -1
	s_add_i32 m0, s3, 0x7000
	ds_read_b128 v[224:227], v149 offset:39936
	ds_read_b128 v[174:177], v149 offset:49152
	ds_read_b128 v[178:181], v149 offset:50176
	global_load_lds_dwordx4 v136, s[98:99]
	s_add_u32 s98, vcc_lo, 0x80080
	s_addc_u32 s99, vcc_hi, 0
	s_add_i32 m0, s3, 0xc000
	ds_read_b128 v[228:231], v149 offset:51200
	ds_read_b128 v[232:235], v149 offset:52224
	ds_read_b128 v[236:239], v149 offset:53248
	global_load_lds_dwordx4 v136, s[98:99]
	s_add_u32 s98, vcc_lo, 0x60080
	s_addc_u32 s99, vcc_hi, 0
	s_add_i32 m0, s3, 0xb000
	ds_read_b128 v[240:243], v149 offset:54272
	ds_read_b128 v[244:247], v149 offset:55296
	ds_read_b128 v[248:251], v149 offset:56320
	global_load_lds_dwordx4 v136, s[98:99]
; #define PG8_STAGE(bufoff, gbase, voff) do { _Pragma("unroll") for (int _i = 0; _i < 2; ++_i) \
;         __builtin_amdgcn_global_load_lds((const unsigned*)((const char*)(gbase) + (voff)[_i]), (PG8_LAS unsigned*)(lds + (bufoff) + ldsw + _i * 8192), 16, 0, 0); } while (0)
; #define PG8_LDA(dst, b, h) do { _Pragma("unroll") for (int m = 0; m < 4; ++m) _Pragma("unroll") for (int k = 0; k < 2; ++k) dst[m][k] = *(const PG8_LAS bf16x8*)(lds + PG8_SA(b, h) + aoff + m * 2048 + k * 1024); } while (0)
; #define PG8_LDB(dst, b, h) do { _Pragma("unroll") for (int n = 0; n < 2; ++n) _Pragma("unroll") for (int k = 0; k < 2; ++k) dst[n][k] = *(const PG8_LAS bf16x8*)(lds + PG8_SB(b, h) + boff + n * 2048 + k * 1024); } while (0)
; #define PG8_MMA(ai, bj, At, Bt) do { __builtin_amdgcn_s_setprio(1); _Pragma("unroll") for (int m = 0; m < 4; ++m) _Pragma("unroll") for (int n = 0; n < 2; ++n) _Pragma("unroll") for (int k = 0; k < 2; ++k) \
;         acc[ai][bj][m][n] = __builtin_amdgcn_mfma_f32_16x16x32_bf16(Bt[n][k], At[m][k], acc[ai][bj][m][n], 0, 0, 0); __builtin_amdgcn_s_setprio(0); } while (0)
; #define PG8_WAIT_V(n) asm volatile("s_waitcnt vmcnt(" #n ")" ::: "memory")
; template <class Epi, class Sched, bool ALIGN_EPI = false, bool SP2 = false>
; __device__ __forceinline__ void gemm_phase(PG8_LAS unsigned char* lds, const Gemm g, const Sched& S, const Epi& E) {
;     ...
;             PG8_LDB(B0, 0, 0); PG8_LDB(B1, 0, 1); PG8_SCHED; PG8_LDA(At, 0, 0); PG8_STAGE(PG8_SA(1, 1), a1 + hstep, voffA);
;             PG8_WAIT_V(8); PG8_WAIT_L(0); PG8_BAR; PG8_MMA(0, 0, At, B0); PG8_MMA(0, 1, At, B1); PG8_BAR; PG8_SCHED;
;             PG8_LDA(At, 0, 1); PG8_STAGE(PG8_SB(0, 0), b2, voffB); PG8_STAGE(PG8_SB(0, 1), b2 + hstep, voffB); PG8_STAGE(PG8_SA(0, 0), a2, voffA);
;             PG8_WAIT_V(8); PG8_WAIT_L(0); PG8_BAR; PG8_MMA(1, 0, At, B0); PG8_MMA(1, 1, At, B1); PG8_BAR; PG8_SCHED;
;             PG8_LDB(B0, 1, 0); PG8_LDB(B1, 1, 1); PG8_SCHED; PG8_LDA(At, 1, 0); PG8_STAGE(PG8_SA(0, 1), a2 + hstep, voffA);
;             PG8_WAIT_V(8); PG8_WAIT_L(0); PG8_BAR; PG8_MMA(0, 0, At, B0); PG8_MMA(0, 1, At, B1); PG8_BAR; PG8_SCHED;
;             PG8_LDA(At, 1, 1); PG8_STAGE(PG8_SB(1, 0), b3, voffB); PG8_STAGE(PG8_SB(1, 1), b3 + hstep, voffB); PG8_STAGE(PG8_SA(1, 0), a3, voffA);
;             PG8_WAIT_V(8); PG8_WAIT_L(0); PG8_BAR; PG8_MMA(1, 0, At, B0); PG8_MMA(1, 1, At, B1); PG8_BAR; PG8_SCHED;
.Lspf2_b_rd:
	s_waitcnt lgkmcnt(0)
	s_setprio 1
	s_barrier
	v_mfma_f32_16x16x32_bf16 v[72:75], v[128:131], v[190:193], v[72:75]
	v_mfma_f32_16x16x32_bf16 v[80:83], v[154:157], v[190:193], v[80:83]
	v_mfma_f32_16x16x32_bf16 v[104:107], v[128:131], v[198:201], v[104:107]
	v_mfma_f32_16x16x32_bf16 v[108:111], v[154:157], v[198:201], v[108:111]
	v_mfma_f32_16x16x32_bf16 v[124:127], v[128:131], v[206:209], v[124:127]
	v_mfma_f32_16x16x32_bf16 v[120:123], v[154:157], v[206:209], v[120:123]
	v_mfma_f32_16x16x32_bf16 v[100:103], v[128:131], v[218:221], v[100:103]
	v_mfma_f32_16x16x32_bf16 v[96:99], v[154:157], v[218:221], v[96:99]
	v_mfma_f32_16x16x32_bf16 v[72:75], v[132:135], v[194:197], v[72:75]
	v_mfma_f32_16x16x32_bf16 v[80:83], v[158:161], v[194:197], v[80:83]
	v_mfma_f32_16x16x32_bf16 v[104:107], v[132:135], v[202:205], v[104:107]
	v_mfma_f32_16x16x32_bf16 v[108:111], v[158:161], v[202:205], v[108:111]
	v_mfma_f32_16x16x32_bf16 v[124:127], v[132:135], v[210:213], v[124:127]
	v_mfma_f32_16x16x32_bf16 v[120:123], v[158:161], v[210:213], v[120:123]
	v_mfma_f32_16x16x32_bf16 v[100:103], v[132:135], v[224:227], v[100:103]
	v_mfma_f32_16x16x32_bf16 v[96:99], v[158:161], v[224:227], v[96:99]
	v_mfma_f32_16x16x32_bf16 v[64:67], v[162:165], v[190:193], v[64:67]
	v_mfma_f32_16x16x32_bf16 v[68:71], v[170:173], v[190:193], v[68:71]
	v_mfma_f32_16x16x32_bf16 v[88:91], v[162:165], v[198:201], v[88:91]
	v_mfma_f32_16x16x32_bf16 v[92:95], v[170:173], v[198:201], v[92:95]
	v_mfma_f32_16x16x32_bf16 v[116:119], v[162:165], v[206:209], v[116:119]
	v_mfma_f32_16x16x32_bf16 v[112:115], v[170:173], v[206:209], v[112:115]
	v_mfma_f32_16x16x32_bf16 v[84:87], v[162:165], v[218:221], v[84:87]
	v_mfma_f32_16x16x32_bf16 v[76:79], v[170:173], v[218:221], v[76:79]
	v_mfma_f32_16x16x32_bf16 v[64:67], v[166:169], v[194:197], v[64:67]
	v_mfma_f32_16x16x32_bf16 v[68:71], v[186:189], v[194:197], v[68:71]
	v_mfma_f32_16x16x32_bf16 v[88:91], v[166:169], v[202:205], v[88:91]
	v_mfma_f32_16x16x32_bf16 v[92:95], v[186:189], v[202:205], v[92:95]
	v_mfma_f32_16x16x32_bf16 v[116:119], v[166:169], v[210:213], v[116:119]
	v_mfma_f32_16x16x32_bf16 v[112:115], v[186:189], v[210:213], v[112:115]
	v_mfma_f32_16x16x32_bf16 v[84:87], v[166:169], v[224:227], v[84:87]
	v_mfma_f32_16x16x32_bf16 v[76:79], v[186:189], v[224:227], v[76:79]
	v_mfma_f32_16x16x32_bf16 v[60:63], v[128:131], v[174:177], v[60:63]
	v_mfma_f32_16x16x32_bf16 v[56:59], v[154:157], v[174:177], v[56:59]
	v_mfma_f32_16x16x32_bf16 v[44:47], v[128:131], v[228:231], v[44:47]
	v_mfma_f32_16x16x32_bf16 v[40:43], v[154:157], v[228:231], v[40:43]
	v_mfma_f32_16x16x32_bf16 v[28:31], v[128:131], v[236:239], v[28:31]
	v_mfma_f32_16x16x32_bf16 v[24:27], v[154:157], v[236:239], v[24:27]
	v_mfma_f32_16x16x32_bf16 v[12:15], v[128:131], v[244:247], v[12:15]
	v_mfma_f32_16x16x32_bf16 v[8:11], v[154:157], v[244:247], v[8:11]
	v_mfma_f32_16x16x32_bf16 v[60:63], v[132:135], v[178:181], v[60:63]
	v_mfma_f32_16x16x32_bf16 v[56:59], v[158:161], v[178:181], v[56:59]
	v_mfma_f32_16x16x32_bf16 v[44:47], v[132:135], v[232:235], v[44:47]
	v_mfma_f32_16x16x32_bf16 v[40:43], v[158:161], v[232:235], v[40:43]
	v_mfma_f32_16x16x32_bf16 v[28:31], v[132:135], v[240:243], v[28:31]
	v_mfma_f32_16x16x32_bf16 v[24:27], v[158:161], v[240:243], v[24:27]
	v_mfma_f32_16x16x32_bf16 v[12:15], v[132:135], v[248:251], v[12:15]
	v_mfma_f32_16x16x32_bf16 v[8:11], v[158:161], v[248:251], v[8:11]
	v_mfma_f32_16x16x32_bf16 v[52:55], v[162:165], v[174:177], v[52:55]
	v_mfma_f32_16x16x32_bf16 v[48:51], v[170:173], v[174:177], v[48:51]
	v_mfma_f32_16x16x32_bf16 v[36:39], v[162:165], v[228:231], v[36:39]
	v_mfma_f32_16x16x32_bf16 v[32:35], v[170:173], v[228:231], v[32:35]
	v_mfma_f32_16x16x32_bf16 v[20:23], v[162:165], v[236:239], v[20:23]
	v_mfma_f32_16x16x32_bf16 v[16:19], v[170:173], v[236:239], v[16:19]
	v_mfma_f32_16x16x32_bf16 v[4:7], v[162:165], v[244:247], v[4:7]
	v_mfma_f32_16x16x32_bf16 v[0:3], v[170:173], v[244:247], v[0:3]
	v_mfma_f32_16x16x32_bf16 v[52:55], v[166:169], v[178:181], v[52:55]
	v_mfma_f32_16x16x32_bf16 v[48:51], v[186:189], v[178:181], v[48:51]
	v_mfma_f32_16x16x32_bf16 v[36:39], v[166:169], v[232:235], v[36:39]
	v_mfma_f32_16x16x32_bf16 v[32:35], v[186:189], v[232:235], v[32:35]
	v_mfma_f32_16x16x32_bf16 v[20:23], v[166:169], v[240:243], v[20:23]
	v_mfma_f32_16x16x32_bf16 v[16:19], v[186:189], v[240:243], v[16:19]
	v_mfma_f32_16x16x32_bf16 v[4:7], v[166:169], v[248:251], v[4:7]
	v_mfma_f32_16x16x32_bf16 v[0:3], v[186:189], v[248:251], v[0:3]
	s_waitcnt vmcnt(0)
	s_barrier
	s_setprio 0
	s_add_i32 s66, s66, 2
	s_add_u32 s10, s10, 0x100
	s_addc_u32 s11, s11, 0
	s_add_u32 s91, s91, 0x100
	s_addc_u32 s95, s95, 0
	s_cmp_gt_u32 s66, 29
	s_cbranch_scc0 .LBB0_403
	v_mov_b32_e32 v181, v149
	v_mov_b32_e32 v180, v147
	v_mov_b32_e32 v179, v143
	v_mov_b32_e32 v178, v141
	v_mov_b32_e32 v177, v139
	v_mov_b32_e32 v176, v137
	s_and_b64 vcc, exec, s[86:87]
	s_cbranch_vccz .LBB0_406
	s_barrier

; #define PG8_STAGE(bufoff, gbase, voff) do { _Pragma("unroll") for (int _i = 0; _i < 2; ++_i) \
;         __builtin_amdgcn_global_load_lds((const unsigned*)((const char*)(gbase) + (voff)[_i]), (PG8_LAS unsigned*)(lds + (bufoff) + ldsw + _i * 8192), 16, 0, 0); } while (0)
; #define PG8_WAIT_V(n) asm volatile("s_waitcnt vmcnt(" #n ")" ::: "memory")
; #define PG8_BAR __builtin_amdgcn_s_barrier()
; template <class Epi, class Sched, bool ALIGN_EPI = false, bool SP2 = false>
; __device__ __forceinline__ void gemm_phase(PG8_LAS unsigned char* lds, const Gemm g, const Sched& S, const Epi& E) {
;     ...
;     const int tid = tid_o, wid = __builtin_amdgcn_readfirstlane(tid >> 6), lane = tid & 63, wr = wid >> 2, wc = wid & 3, fr = lane & 15, fq = lane >> 4;
;     const int K = g.K, nt = K / BK;
;     unsigned voffA[2], voffB[2];
; #pragma unroll
;     for (int i = 0; i < 2; ++i) { int R, C; stage_rc(tid * 16 + i * 8192, R, C); const int Rb = Epi::PERM ? ((R & ~31) + perm32(R & 31)) : R;
;         voffA[i] = (unsigned)(R * K + C) * 2u; voffB[i] = (unsigned)(Rb * K + C) * 2u; }
;     const size_t kstep = (size_t)(BK * 2);
;     const size_t hstep = (size_t)HALF * K * 2;
;     const size_t tstep = 2 * hstep;
;     const unsigned ldsw = (unsigned)wid * 1024u;
;     const int aoff = lds_byte(wr * 64 + fr, fq * 8), boff = lds_byte(wc * 32 + fr, fq * 8);
;     ...
;     if constexpr (SP2) {
;         PG8_STAGE(PG8_SB(0, 0), cB, voffB); PG8_STAGE(PG8_SB(0, 1), cB + hstep, voffB); PG8_STAGE(PG8_SA(0, 0), cA, voffA); PG8_STAGE(PG8_SA(0, 1), cA + hstep, voffA);
;         if (wr == 1) PG8_BAR;
;         PG8_WAIT_V(2); PG8_BAR;
;         PG8_STAGE(PG8_SB(1, 0), cB + kstep, voffB); PG8_STAGE(PG8_SA(1, 0), cA + kstep, voffA); PG8_STAGE(PG8_SB(1, 1), cB + hstep + kstep, voffB);
;         PG8_WAIT_V(6); PG8_BAR;
.LBB0_483:
	v_bfe_u32 v17, v8, 4, 2
	v_and_b32_e32 v16, 15, v8
	v_lshlrev_b32_e32 v18, 4, v17
	v_lshl_or_b32 v162, s11, 6, v16
	v_lshl_or_b32 v16, v16, 6, v18
	v_lshlrev_b32_e32 v18, 2, v8
	s_sext_i32_i16 s80, s6
	s_lshl_b32 s6, s11, 13
	v_and_b32_e32 v18, 32, v18
	v_bitop3_b32 v19, v16, s6, v18 bitop3:0xde
	s_lshl_b32 s6, s10, 5
	s_and_b32 s6, s6, 0x60
	s_lshl_b32 s10, s6, 7
	v_bitop3_b32 v163, v16, s10, v18 bitop3:0xde
	s_mov_b64 s[10:11], 0x80
	s_add_i32 m0, s14, 0x18000
	v_lshl_add_u64 v[6:7], v[6:7], 0, s[10:11]
	s_waitcnt vmcnt(0)
	s_barrier
	global_load_lds_dwordx4 v[6:7], off
	v_lshl_add_u64 v[4:5], v[4:5], 0, s[10:11]
	s_add_i32 m0, s14, 0x1a000
	s_add_i32 s68, s14, 0x8000
	s_add_i32 s69, s14, 0xa000
	global_load_lds_dwordx4 v[4:5], off
	v_lshl_add_u64 v[0:1], v[0:1], 0, s[10:11]
	s_mov_b32 m0, s68
	s_add_u32 s12, s94, 0x80080
	global_load_lds_dwordx4 v[0:1], off
	v_lshl_add_u64 v[0:1], v[2:3], 0, s[10:11]
	s_mov_b32 m0, s69
	s_addc_u32 s13, s95, 0
	global_load_lds_dwordx4 v[0:1], off
	s_add_i32 m0, s14, 0x1c000
	v_lshl_add_u64 v[0:1], s[12:13], 0, v[132:133]
	global_load_lds_dwordx4 v[0:1], off
	v_lshl_add_u64 v[0:1], s[12:13], 0, v[128:129]
	s_add_i32 m0, s14, 0x1e000
	v_lshl_or_b32 v164, v17, 3, s6
	global_load_lds_dwordx4 v[0:1], off
	v_and_b32_e32 v0, 0x80, v11
	v_and_b32_e32 v1, 7, v8
	v_or3_b32 v165, v0, v1, v164
	v_lshlrev_b32_e32 v1, 15, v14
	v_and_b32_e32 v1, 0xffff0000, v1
	v_lshl_add_u32 v1, v13, 12, v1
	v_and_b32_e32 v2, 1, v14
	v_lshl_or_b32 v1, v2, 6, v1
	v_lshl_add_u32 v136, v15, 1, v1
	v_lshlrev_b32_e32 v1, 15, v9
	v_and_b32_e32 v1, 0xffff0000, v1
	v_lshl_add_u32 v1, v10, 12, v1
	v_and_b32_e32 v2, 1, v9
	v_lshl_or_b32 v1, v2, 6, v1
	s_waitcnt vmcnt(6)
	s_cmpk_lt_u32 s7, 0x100
	v_lshl_add_u32 v138, v12, 1, v1
	v_mbcnt_hi_u32_b32 v1, -1, v216
	s_movk_i32 s6, 0x100
	s_cselect_b64 s[44:45], -1, 0
	v_lshlrev_b32_e32 v0, 6, v17
	s_add_i32 s70, 0, 0x10000
	s_add_i32 s71, 0, 0x14000
	v_lshlrev_b32_e32 v1, 2, v1
	v_mov_b32_e32 v137, v133
	v_mov_b32_e32 v139, v133
	v_mov_b64_e32 v[140:141], 0x100
	v_mov_b64_e32 v[142:143], 0xff
	v_add_u32_e32 v166, s70, v163
	v_add_u32_e32 v167, s71, v163
	v_add_u32_e32 v168, 0, v19
	v_mov_b32_e32 v169, 0x358637bd
	v_and_or_b32 v170, v1, s6, v0
	s_barrier
	s_branch .LBB0_486

; #define PG8_STAGE(bufoff, gbase, voff) do { _Pragma("unroll") for (int _i = 0; _i < 2; ++_i) \
;         __builtin_amdgcn_global_load_lds((const unsigned*)((const char*)(gbase) + (voff)[_i]), (PG8_LAS unsigned*)(lds + (bufoff) + ldsw + _i * 8192), 16, 0, 0); } while (0)
; #define PG8_LDA(dst, b, h) do { _Pragma("unroll") for (int m = 0; m < 4; ++m) _Pragma("unroll") for (int k = 0; k < 2; ++k) dst[m][k] = *(const PG8_LAS bf16x8*)(lds + PG8_SA(b, h) + aoff + m * 2048 + k * 1024); } while (0)
; #define PG8_LDB(dst, b, h) do { _Pragma("unroll") for (int n = 0; n < 2; ++n) _Pragma("unroll") for (int k = 0; k < 2; ++k) dst[n][k] = *(const PG8_LAS bf16x8*)(lds + PG8_SB(b, h) + boff + n * 2048 + k * 1024); } while (0)
; template <class Epi, class Sched, bool ALIGN_EPI = false, bool SP2 = false>
; __device__ __forceinline__ void gemm_phase(PG8_LAS unsigned char* lds, const Gemm g, const Sched& S, const Epi& E) {
;     ...
;     for (;;) {
;         const bool has_next = S.next(ui + 1, nxt);
;         const char* nA = has_next ? (const char*)g.A + (size_t)nxt.pm * tstep : cA; const char* nB = has_next ? (const char*)g.Bt + (size_t)nxt.pn * tstep : cB;
;         for (int t = 0; t < nt; t += 2) {
;             const bool last = (t == nt - 2);
;             const char* a1 = cA + (size_t)(t + 1) * kstep;
;             const char* a2 = last ? nA : cA + (size_t)(t + 2) * kstep; const char* b2 = last ? nB : cB + (size_t)(t + 2) * kstep;
;             const char* a3 = a2 + kstep; const char* b3 = b2 + kstep;
;             if (last && has_next) S.a_ready(nxt);
;             if constexpr (SP2) {
;             PG8_LDB(B0, 0, 0); PG8_LDB(B1, 0, 1); PG8_SCHED; PG8_LDA(At, 0, 0); PG8_STAGE(PG8_SA(1, 1), a1 + hstep, voffA);
;             PG8_WAIT_V(8); PG8_WAIT_L(0); PG8_BAR; PG8_MMA(0, 0, At, B0); PG8_MMA(0, 1, At, B1); PG8_BAR; PG8_SCHED;
;             PG8_LDA(At, 0, 1); PG8_STAGE(PG8_SB(0, 0), b2, voffB); PG8_STAGE(PG8_SB(0, 1), b2 + hstep, voffB); PG8_STAGE(PG8_SA(0, 0), a2, voffA);
;     ...
;         if (!has_next) break;
; #pragma unroll
;         for (int a = 0; a < 2; ++a)
; #pragma unroll
;             for (int b = 0; b < 2; ++b)
; #pragma unroll
;                 for (int m = 0; m < 4; ++m)
; #pragma unroll
;                     for (int n = 0; n < 2; ++n) acc[a][b][m][n] = (f32x4){0.f, 0.f, 0.f, 0.f};
;         cur = nxt; cA = nA; cB = nB; ++ui;
.LBB0_492:
	s_ashr_i32 s85, s84, 31
	s_lshl_b64 s[12:13], s[84:85], 20
	s_add_u32 s86, s0, s12
	s_addc_u32 s87, s1, s13
	s_and_b64 s[12:13], s[6:7], exec
	s_cselect_b32 s12, s87, s83
	s_cselect_b32 s13, s86, s82
	s_ashr_i32 s47, s46, 31
	s_lshl_b64 s[66:67], s[46:47], 20
	s_add_u32 s88, s40, s66
	s_addc_u32 s89, s41, s67
	s_and_b64 s[66:67], s[6:7], exec
	s_cselect_b32 s47, s89, s95
	s_cselect_b32 s81, s88, s94
	s_add_u32 s92, s82, 0x80080
	s_addc_u32 s93, s83, 0
	s_add_u32 s85, s94, 0x100
	v_mov_b64_e32 v[0:1], 0
	v_mov_b64_e32 v[2:3], 0
	v_mov_b64_e32 v[4:5], 0
	v_mov_b64_e32 v[6:7], 0
	v_mov_b64_e32 v[8:9], 0
	v_mov_b64_e32 v[10:11], 0
	v_mov_b64_e32 v[12:13], 0
	v_mov_b64_e32 v[14:15], 0
	v_mov_b64_e32 v[16:17], 0
	v_mov_b64_e32 v[18:19], 0
	v_mov_b64_e32 v[20:21], 0
	v_mov_b64_e32 v[22:23], 0
	v_mov_b64_e32 v[24:25], 0
	v_mov_b64_e32 v[26:27], 0
	v_mov_b64_e32 v[28:29], 0
	v_mov_b64_e32 v[30:31], 0
	v_mov_b64_e32 v[32:33], 0
	v_mov_b64_e32 v[34:35], 0
	v_mov_b64_e32 v[36:37], 0
	v_mov_b64_e32 v[38:39], 0
	v_mov_b64_e32 v[40:41], 0
	v_mov_b64_e32 v[42:43], 0
	v_mov_b64_e32 v[44:45], 0
	v_mov_b64_e32 v[46:47], 0
	v_mov_b64_e32 v[48:49], 0
	v_mov_b64_e32 v[50:51], 0
	v_mov_b64_e32 v[52:53], 0
	v_mov_b64_e32 v[54:55], 0
	v_mov_b64_e32 v[56:57], 0
	v_mov_b64_e32 v[58:59], 0
	v_mov_b64_e32 v[60:61], 0
	v_mov_b64_e32 v[62:63], 0
	v_mov_b64_e32 v[64:65], 0
	v_mov_b64_e32 v[66:67], 0
	v_mov_b64_e32 v[68:69], 0
	v_mov_b64_e32 v[70:71], 0
	v_mov_b64_e32 v[72:73], 0
	v_mov_b64_e32 v[74:75], 0
	v_mov_b64_e32 v[76:77], 0
	v_mov_b64_e32 v[78:79], 0
	v_mov_b64_e32 v[80:81], 0
	v_mov_b64_e32 v[82:83], 0
	v_mov_b64_e32 v[84:85], 0
	v_mov_b64_e32 v[86:87], 0
	v_mov_b64_e32 v[88:89], 0
	v_mov_b64_e32 v[90:91], 0
	v_mov_b64_e32 v[92:93], 0
	v_mov_b64_e32 v[94:95], 0
	v_mov_b64_e32 v[96:97], 0
	v_mov_b64_e32 v[98:99], 0
	v_mov_b64_e32 v[100:101], 0
	v_mov_b64_e32 v[102:103], 0
	v_mov_b64_e32 v[104:105], 0
	v_mov_b64_e32 v[106:107], 0
	v_mov_b64_e32 v[108:109], 0
	v_mov_b64_e32 v[110:111], 0
	v_mov_b64_e32 v[112:113], 0
	v_mov_b64_e32 v[114:115], 0
	v_mov_b64_e32 v[116:117], 0
	v_mov_b64_e32 v[118:119], 0
	v_mov_b64_e32 v[120:121], 0
	v_mov_b64_e32 v[122:123], 0
	v_mov_b64_e32 v[124:125], 0
	v_mov_b64_e32 v[126:127], 0
	s_addc_u32 s91, s95, 0
	s_mov_b32 s66, -2
	v_mov_b32_e32 v131, v162
	v_mov_b32_e32 v135, v163
	v_mov_b32_e32 v137, v166
	v_mov_b32_e32 v139, v167
	v_mov_b32_e32 v171, v168
	v_add_u32_e32 v217, 0x18000, v135
	v_add_u32_e32 v223, 0x1c000, v135
	s_cmp_lg_u32 s44, 0
	s_cbranch_scc0 .Lspf3_pre
	s_add_i32 m0, s3, 0xc000
	s_nop 0
	global_load_lds_dwordx4 v136, s[92:93]
	s_add_u32 s98, s92, 0x20000
	s_addc_u32 s99, s93, 0
	s_add_i32 m0, s3, 0xd000
	s_nop 0
	global_load_lds_dwordx4 v136, s[98:99]
	s_add_u32 s98, s92, 0xfff80000
	s_addc_u32 s99, s93, -1
	s_add_i32 m0, s3, 0x8000
	s_nop 0
	global_load_lds_dwordx4 v136, s[98:99]
	s_add_u32 s98, s92, 0xfffa0000
	s_addc_u32 s99, s93, -1
	s_add_i32 m0, s3, 0x9000
	s_nop 0
	global_load_lds_dwordx4 v136, s[98:99]
.Lspf3_pre:
.LBB0_493:
	s_add_u32 s67, s92, 0xfff80080
	s_addc_u32 s74, s93, -1
	s_cmp_eq_u32 s66, 28
	s_cselect_b32 s95, s12, s74
	s_cselect_b32 s94, s13, s67
	s_cselect_b32 s83, s47, s91
	s_cselect_b32 s82, s81, s85
	s_cmp_lg_u32 s44, 0
	s_cbranch_scc0 .Lspf3_a_h1
	s_add_u32 s98, s85, 0xffffff80
	s_addc_u32 s99, s91, -1
	s_add_i32 m0, s3, 0x18000
	ds_read_b128 v[144:147], v137
	ds_read_b128 v[148:151], v137 offset:1024
	ds_read_b128 v[152:155], v137 offset:2048
	global_load_lds_dwordx4 v132, s[98:99]
	s_add_i32 m0, s3, 0x1a000
	ds_read_b128 v[156:159], v137 offset:3072
	ds_read_b128 v[172:175], v139
	ds_read_b128 v[176:179], v139 offset:1024
	global_load_lds_dwordx4 v128, s[98:99]
	s_add_u32 s98, s85, 0x1ff80
	s_addc_u32 s99, s91, 0
	s_add_i32 m0, s3, 0x19000
	ds_read_b128 v[180:183], v139 offset:2048
	ds_read_b128 v[184:187], v139 offset:3072
	ds_read_b128 v[188:191], v171
	global_load_lds_dwordx4 v132, s[98:99]
	s_add_i32 m0, s3, 0x1b000
	ds_read_b128 v[192:195], v171 offset:1024
	ds_read_b128 v[196:199], v171 offset:2048
	ds_read_b128 v[200:203], v171 offset:3072
	global_load_lds_dwordx4 v128, s[98:99]
	s_add_u32 s98, s85, 0x7ff80
	s_addc_u32 s99, s91, 0
	s_add_i32 m0, s3, 0x1c000
	ds_read_b128 v[204:207], v171 offset:4096
	ds_read_b128 v[208:211], v171 offset:5120
	ds_read_b128 v[212:215], v171 offset:6144
	global_load_lds_dwordx4 v132, s[98:99]
	s_add_i32 m0, s3, 0x1e000
	ds_read_b128 v[218:221], v171 offset:7168
	ds_read_b128 v[160:163], v171 offset:16384
	ds_read_b128 v[224:227], v171 offset:17408
	global_load_lds_dwordx4 v128, s[98:99]
	s_add_u32 s98, s85, 0x9ff80
	s_addc_u32 s99, s91, 0
	s_add_i32 m0, s3, 0x1d000
	ds_read_b128 v[228:231], v171 offset:18432
	ds_read_b128 v[232:235], v171 offset:19456
	ds_read_b128 v[236:239], v171 offset:20480
	global_load_lds_dwordx4 v132, s[98:99]
	s_add_i32 m0, s3, 0x1f000
	ds_read_b128 v[240:243], v171 offset:21504
	ds_read_b128 v[244:247], v171 offset:22528
	ds_read_b128 v[248:251], v171 offset:23552
	global_load_lds_dwordx4 v128, s[98:99]
	s_branch .Lspf3_a_rd
; #define PG8_STAGE(bufoff, gbase, voff) do { _Pragma("unroll") for (int _i = 0; _i < 2; ++_i) \
;         __builtin_amdgcn_global_load_lds((const unsigned*)((const char*)(gbase) + (voff)[_i]), (PG8_LAS unsigned*)(lds + (bufoff) + ldsw + _i * 8192), 16, 0, 0); } while (0)
; #define PG8_LDA(dst, b, h) do { _Pragma("unroll") for (int m = 0; m < 4; ++m) _Pragma("unroll") for (int k = 0; k < 2; ++k) dst[m][k] = *(const PG8_LAS bf16x8*)(lds + PG8_SA(b, h) + aoff + m * 2048 + k * 1024); } while (0)
; #define PG8_LDB(dst, b, h) do { _Pragma("unroll") for (int n = 0; n < 2; ++n) _Pragma("unroll") for (int k = 0; k < 2; ++k) dst[n][k] = *(const PG8_LAS bf16x8*)(lds + PG8_SB(b, h) + boff + n * 2048 + k * 1024); } while (0)
; #define PG8_MMA(ai, bj, At, Bt) do { __builtin_amdgcn_s_setprio(1); _Pragma("unroll") for (int m = 0; m < 4; ++m) _Pragma("unroll") for (int n = 0; n < 2; ++n) _Pragma("unroll") for (int k = 0; k < 2; ++k) \
;         acc[ai][bj][m][n] = __builtin_amdgcn_mfma_f32_16x16x32_bf16(Bt[n][k], At[m][k], acc[ai][bj][m][n], 0, 0, 0); __builtin_amdgcn_s_setprio(0); } while (0)
; #define PG8_WAIT_V(n) asm volatile("s_waitcnt vmcnt(" #n ")" ::: "memory")
; #define PG8_WAIT_L(n) asm volatile("s_waitcnt lgkmcnt(" #n ")" ::: "memory")
; #define PG8_BAR __builtin_amdgcn_s_barrier()
; #define PG8_SCHED __builtin_amdgcn_sched_barrier(0)
; template <class Epi, class Sched, bool ALIGN_EPI = false, bool SP2 = false>
; __device__ __forceinline__ void gemm_phase(PG8_LAS unsigned char* lds, const Gemm g, const Sched& S, const Epi& E) {
;     ...
;             if constexpr (SP2) {
;             PG8_LDB(B0, 0, 0); PG8_LDB(B1, 0, 1); PG8_SCHED; PG8_LDA(At, 0, 0); PG8_STAGE(PG8_SA(1, 1), a1 + hstep, voffA);
;             PG8_WAIT_V(8); PG8_WAIT_L(0); PG8_BAR; PG8_MMA(0, 0, At, B0); PG8_MMA(0, 1, At, B1); PG8_BAR; PG8_SCHED;
;             PG8_LDA(At, 0, 1); PG8_STAGE(PG8_SB(0, 0), b2, voffB); PG8_STAGE(PG8_SB(0, 1), b2 + hstep, voffB); PG8_STAGE(PG8_SA(0, 0), a2, voffA);
;             PG8_WAIT_V(8); PG8_WAIT_L(0); PG8_BAR; PG8_MMA(1, 0, At, B0); PG8_MMA(1, 1, At, B1); PG8_BAR; PG8_SCHED;
.Lspf3_a_h1:
	s_add_u32 s98, s92, 0xfff80000
	s_addc_u32 s99, s93, -1
	s_add_i32 m0, s3, 0xa000
	ds_read_b128 v[144:147], v137
	ds_read_b128 v[148:151], v137 offset:1024
	ds_read_b128 v[152:155], v137 offset:2048
	global_load_lds_dwordx4 v138, s[98:99]
	s_add_u32 s98, s92, 0xfff60000
	s_addc_u32 s99, s93, -1
	s_add_i32 m0, s3, 0x9000
	ds_read_b128 v[156:159], v137 offset:3072
	ds_read_b128 v[172:175], v139
	ds_read_b128 v[176:179], v139 offset:1024
	global_load_lds_dwordx4 v138, s[98:99]
	s_add_i32 m0, s3, 0xe000
	ds_read_b128 v[180:183], v139 offset:2048
	ds_read_b128 v[184:187], v139 offset:3072
	ds_read_b128 v[188:191], v171
	global_load_lds_dwordx4 v138, s[92:93]
	s_add_u32 s98, s92, 0xfffe0000
	s_addc_u32 s99, s93, -1
	s_add_i32 m0, s3, 0xd000
	ds_read_b128 v[192:195], v171 offset:1024
	ds_read_b128 v[196:199], v171 offset:2048
	ds_read_b128 v[200:203], v171 offset:3072
	global_load_lds_dwordx4 v138, s[98:99]
	s_add_i32 m0, s3, 0x0
	ds_read_b128 v[204:207], v171 offset:4096
	ds_read_b128 v[208:211], v171 offset:5120
	ds_read_b128 v[212:215], v171 offset:6144
	global_load_lds_dwordx4 v134, s[94:95]
	s_add_u32 s98, s94, 0xfffe0000
	s_addc_u32 s99, s95, -1
	s_add_i32 m0, s3, 0xfffff000
	ds_read_b128 v[218:221], v171 offset:7168
	ds_read_b128 v[160:163], v171 offset:16384
	ds_read_b128 v[224:227], v171 offset:17408
	global_load_lds_dwordx4 v134, s[98:99]
	s_add_u32 s98, s94, 0x80000
	s_addc_u32 s99, s95, 0
	s_add_i32 m0, s3, 0x4000
	ds_read_b128 v[228:231], v171 offset:18432
	ds_read_b128 v[232:235], v171 offset:19456
	ds_read_b128 v[236:239], v171 offset:20480
	global_load_lds_dwordx4 v134, s[98:99]
	s_add_u32 s98, s94, 0x60000
	s_addc_u32 s99, s95, 0
	s_add_i32 m0, s3, 0x3000
	ds_read_b128 v[240:243], v171 offset:21504
	ds_read_b128 v[244:247], v171 offset:22528
	ds_read_b128 v[248:251], v171 offset:23552
	global_load_lds_dwordx4 v134, s[98:99]
.Lspf3_a_rd:
	s_waitcnt lgkmcnt(0)
	s_setprio 1
	s_barrier
	v_mfma_f32_16x16x32_bf16 v[124:127], v[144:147], v[188:191], v[124:127]
	v_mfma_f32_16x16x32_bf16 v[120:123], v[152:155], v[188:191], v[120:123]
	v_mfma_f32_16x16x32_bf16 v[108:111], v[144:147], v[196:199], v[108:111]
	v_mfma_f32_16x16x32_bf16 v[104:107], v[152:155], v[196:199], v[104:107]
	v_mfma_f32_16x16x32_bf16 v[100:103], v[144:147], v[204:207], v[100:103]
	v_mfma_f32_16x16x32_bf16 v[92:95], v[152:155], v[204:207], v[92:95]
	v_mfma_f32_16x16x32_bf16 v[84:87], v[144:147], v[212:215], v[84:87]
	v_mfma_f32_16x16x32_bf16 v[76:79], v[152:155], v[212:215], v[76:79]
	v_mfma_f32_16x16x32_bf16 v[124:127], v[148:151], v[192:195], v[124:127]
	v_mfma_f32_16x16x32_bf16 v[120:123], v[156:159], v[192:195], v[120:123]
	v_mfma_f32_16x16x32_bf16 v[108:111], v[148:151], v[200:203], v[108:111]
	v_mfma_f32_16x16x32_bf16 v[104:107], v[156:159], v[200:203], v[104:107]
	v_mfma_f32_16x16x32_bf16 v[100:103], v[148:151], v[208:211], v[100:103]
	v_mfma_f32_16x16x32_bf16 v[92:95], v[156:159], v[208:211], v[92:95]
	v_mfma_f32_16x16x32_bf16 v[84:87], v[148:151], v[218:221], v[84:87]
	v_mfma_f32_16x16x32_bf16 v[76:79], v[156:159], v[218:221], v[76:79]
	v_mfma_f32_16x16x32_bf16 v[116:119], v[172:175], v[188:191], v[116:119]
	v_mfma_f32_16x16x32_bf16 v[112:115], v[180:183], v[188:191], v[112:115]
	v_mfma_f32_16x16x32_bf16 v[96:99], v[172:175], v[196:199], v[96:99]
	v_mfma_f32_16x16x32_bf16 v[88:91], v[180:183], v[196:199], v[88:91]
	v_mfma_f32_16x16x32_bf16 v[80:83], v[172:175], v[204:207], v[80:83]
	v_mfma_f32_16x16x32_bf16 v[72:75], v[180:183], v[204:207], v[72:75]
	v_mfma_f32_16x16x32_bf16 v[68:71], v[172:175], v[212:215], v[68:71]
	v_mfma_f32_16x16x32_bf16 v[64:67], v[180:183], v[212:215], v[64:67]
	v_mfma_f32_16x16x32_bf16 v[116:119], v[176:179], v[192:195], v[116:119]
	v_mfma_f32_16x16x32_bf16 v[112:115], v[184:187], v[192:195], v[112:115]
	v_mfma_f32_16x16x32_bf16 v[96:99], v[176:179], v[200:203], v[96:99]
	v_mfma_f32_16x16x32_bf16 v[88:91], v[184:187], v[200:203], v[88:91]
	v_mfma_f32_16x16x32_bf16 v[80:83], v[176:179], v[208:211], v[80:83]
	v_mfma_f32_16x16x32_bf16 v[72:75], v[184:187], v[208:211], v[72:75]
	v_mfma_f32_16x16x32_bf16 v[68:71], v[176:179], v[218:221], v[68:71]
	v_mfma_f32_16x16x32_bf16 v[64:67], v[184:187], v[218:221], v[64:67]
	v_mfma_f32_16x16x32_bf16 v[60:63], v[144:147], v[160:163], v[60:63]
	v_mfma_f32_16x16x32_bf16 v[56:59], v[152:155], v[160:163], v[56:59]
	v_mfma_f32_16x16x32_bf16 v[52:55], v[144:147], v[228:231], v[52:55]
	v_mfma_f32_16x16x32_bf16 v[44:47], v[152:155], v[228:231], v[44:47]
	v_mfma_f32_16x16x32_bf16 v[36:39], v[144:147], v[236:239], v[36:39]
	v_mfma_f32_16x16x32_bf16 v[28:31], v[152:155], v[236:239], v[28:31]
	v_mfma_f32_16x16x32_bf16 v[20:23], v[144:147], v[244:247], v[20:23]
	v_mfma_f32_16x16x32_bf16 v[12:15], v[152:155], v[244:247], v[12:15]
	v_mfma_f32_16x16x32_bf16 v[60:63], v[148:151], v[224:227], v[60:63]
	v_mfma_f32_16x16x32_bf16 v[56:59], v[156:159], v[224:227], v[56:59]
	v_mfma_f32_16x16x32_bf16 v[52:55], v[148:151], v[232:235], v[52:55]
	v_mfma_f32_16x16x32_bf16 v[44:47], v[156:159], v[232:235], v[44:47]
	v_mfma_f32_16x16x32_bf16 v[36:39], v[148:151], v[240:243], v[36:39]
	v_mfma_f32_16x16x32_bf16 v[28:31], v[156:159], v[240:243], v[28:31]
	v_mfma_f32_16x16x32_bf16 v[20:23], v[148:151], v[248:251], v[20:23]
	v_mfma_f32_16x16x32_bf16 v[12:15], v[156:159], v[248:251], v[12:15]
	v_mfma_f32_16x16x32_bf16 v[48:51], v[172:175], v[160:163], v[48:51]
	v_mfma_f32_16x16x32_bf16 v[40:43], v[180:183], v[160:163], v[40:43]
	v_mfma_f32_16x16x32_bf16 v[32:35], v[172:175], v[228:231], v[32:35]
	v_mfma_f32_16x16x32_bf16 v[24:27], v[180:183], v[228:231], v[24:27]
	v_mfma_f32_16x16x32_bf16 v[16:19], v[172:175], v[236:239], v[16:19]
	v_mfma_f32_16x16x32_bf16 v[8:11], v[180:183], v[236:239], v[8:11]
	v_mfma_f32_16x16x32_bf16 v[4:7], v[172:175], v[244:247], v[4:7]
	v_mfma_f32_16x16x32_bf16 v[0:3], v[180:183], v[244:247], v[0:3]
	v_mfma_f32_16x16x32_bf16 v[48:51], v[176:179], v[224:227], v[48:51]
	v_mfma_f32_16x16x32_bf16 v[40:43], v[184:187], v[224:227], v[40:43]
	v_mfma_f32_16x16x32_bf16 v[32:35], v[176:179], v[232:235], v[32:35]
	v_mfma_f32_16x16x32_bf16 v[24:27], v[184:187], v[232:235], v[24:27]
	v_mfma_f32_16x16x32_bf16 v[16:19], v[176:179], v[240:243], v[16:19]
	v_mfma_f32_16x16x32_bf16 v[8:11], v[184:187], v[240:243], v[8:11]
	v_mfma_f32_16x16x32_bf16 v[4:7], v[176:179], v[248:251], v[4:7]
	v_mfma_f32_16x16x32_bf16 v[0:3], v[184:187], v[248:251], v[0:3]
	s_waitcnt vmcnt(0)
	s_barrier
; #define PG8_STAGE(bufoff, gbase, voff) do { _Pragma("unroll") for (int _i = 0; _i < 2; ++_i) \
;         __builtin_amdgcn_global_load_lds((const unsigned*)((const char*)(gbase) + (voff)[_i]), (PG8_LAS unsigned*)(lds + (bufoff) + ldsw + _i * 8192), 16, 0, 0); } while (0)
; #define PG8_LDA(dst, b, h) do { _Pragma("unroll") for (int m = 0; m < 4; ++m) _Pragma("unroll") for (int k = 0; k < 2; ++k) dst[m][k] = *(const PG8_LAS bf16x8*)(lds + PG8_SA(b, h) + aoff + m * 2048 + k * 1024); } while (0)
; #define PG8_LDB(dst, b, h) do { _Pragma("unroll") for (int n = 0; n < 2; ++n) _Pragma("unroll") for (int k = 0; k < 2; ++k) dst[n][k] = *(const PG8_LAS bf16x8*)(lds + PG8_SB(b, h) + boff + n * 2048 + k * 1024); } while (0)
; #define PG8_MMA(ai, bj, At, Bt) do { __builtin_amdgcn_s_setprio(1); _Pragma("unroll") for (int m = 0; m < 4; ++m) _Pragma("unroll") for (int n = 0; n < 2; ++n) _Pragma("unroll") for (int k = 0; k < 2; ++k) \
;         acc[ai][bj][m][n] = __builtin_amdgcn_mfma_f32_16x16x32_bf16(Bt[n][k], At[m][k], acc[ai][bj][m][n], 0, 0, 0); __builtin_amdgcn_s_setprio(0); } while (0)
; #define PG8_WAIT_V(n) asm volatile("s_waitcnt vmcnt(" #n ")" ::: "memory")
; #define PG8_WAIT_L(n) asm volatile("s_waitcnt lgkmcnt(" #n ")" ::: "memory")
; #define PG8_BAR __builtin_amdgcn_s_barrier()
; #define PG8_SCHED __builtin_amdgcn_sched_barrier(0)
; template <class Epi, class Sched, bool ALIGN_EPI = false, bool SP2 = false>
; __device__ __forceinline__ void gemm_phase(PG8_LAS unsigned char* lds, const Gemm g, const Sched& S, const Epi& E) {
;     ...
;             PG8_LDB(B0, 1, 0); PG8_LDB(B1, 1, 1); PG8_SCHED; PG8_LDA(At, 1, 0); PG8_STAGE(PG8_SA(0, 1), a2 + hstep, voffA);
;             PG8_WAIT_V(8); PG8_WAIT_L(0); PG8_BAR; PG8_MMA(0, 0, At, B0); PG8_MMA(0, 1, At, B1); PG8_BAR; PG8_SCHED;
;             PG8_LDA(At, 1, 1); PG8_STAGE(PG8_SB(1, 0), b3, voffB); PG8_STAGE(PG8_SB(1, 1), b3 + hstep, voffB); PG8_STAGE(PG8_SA(1, 0), a3, voffA);
	s_setprio 0
	s_cmp_lg_u32 s44, 0
	s_cbranch_scc0 .Lspf3_b_h1
	s_add_i32 m0, s3, 0x10000
	ds_read_b128 v[144:147], v217
	ds_read_b128 v[148:151], v217 offset:1024
	ds_read_b128 v[152:155], v217 offset:2048
	global_load_lds_dwordx4 v132, s[82:83]
	s_add_i32 m0, s3, 0x12000
	ds_read_b128 v[156:159], v217 offset:3072
	ds_read_b128 v[172:175], v223
	ds_read_b128 v[176:179], v223 offset:1024
	global_load_lds_dwordx4 v128, s[82:83]
	s_add_u32 s98, s82, 0x20000
	s_addc_u32 s99, s83, 0
	s_add_i32 m0, s3, 0x11000
	ds_read_b128 v[180:183], v223 offset:2048
	ds_read_b128 v[184:187], v223 offset:3072
	ds_read_b128 v[188:191], v171 offset:32768
	global_load_lds_dwordx4 v132, s[98:99]
	s_add_i32 m0, s3, 0x13000
	ds_read_b128 v[192:195], v171 offset:33792
	ds_read_b128 v[196:199], v171 offset:34816
	ds_read_b128 v[200:203], v171 offset:35840
	global_load_lds_dwordx4 v128, s[98:99]
	s_add_u32 s98, s82, 0x80000
	s_addc_u32 s99, s83, 0
	s_add_i32 m0, s3, 0x14000
	ds_read_b128 v[204:207], v171 offset:36864
	ds_read_b128 v[208:211], v171 offset:37888
	ds_read_b128 v[212:215], v171 offset:38912
	global_load_lds_dwordx4 v132, s[98:99]
	s_add_i32 m0, s3, 0x16000
	ds_read_b128 v[218:221], v171 offset:39936
	ds_read_b128 v[160:163], v171 offset:49152
	ds_read_b128 v[224:227], v171 offset:50176
	global_load_lds_dwordx4 v128, s[98:99]
	s_add_u32 s98, s82, 0xa0000
	s_addc_u32 s99, s83, 0
	s_add_i32 m0, s3, 0x15000
	ds_read_b128 v[228:231], v171 offset:51200
	ds_read_b128 v[232:235], v171 offset:52224
	ds_read_b128 v[236:239], v171 offset:53248
	global_load_lds_dwordx4 v132, s[98:99]
	s_add_i32 m0, s3, 0x17000
	ds_read_b128 v[240:243], v171 offset:54272
	ds_read_b128 v[244:247], v171 offset:55296
	ds_read_b128 v[248:251], v171 offset:56320
	global_load_lds_dwordx4 v128, s[98:99]
	s_branch .Lspf3_b_rd
.Lspf3_b_h1:
	s_add_i32 m0, s3, 0x2000
	ds_read_b128 v[144:147], v217
	ds_read_b128 v[148:151], v217 offset:1024
	ds_read_b128 v[152:155], v217 offset:2048
	global_load_lds_dwordx4 v130, s[94:95]
	s_add_u32 s98, s94, 0xfffe0000
	s_addc_u32 s99, s95, -1
	s_add_i32 m0, s3, 0x1000
	ds_read_b128 v[156:159], v217 offset:3072
	ds_read_b128 v[172:175], v223
	ds_read_b128 v[176:179], v223 offset:1024
	global_load_lds_dwordx4 v130, s[98:99]
	s_add_u32 s98, s94, 0x80000
	s_addc_u32 s99, s95, 0
	s_add_i32 m0, s3, 0x6000
	ds_read_b128 v[180:183], v223 offset:2048
	ds_read_b128 v[184:187], v223 offset:3072
	ds_read_b128 v[188:191], v171 offset:32768
	global_load_lds_dwordx4 v130, s[98:99]
	s_add_u32 s98, s94, 0x60000
	s_addc_u32 s99, s95, 0
	s_add_i32 m0, s3, 0x5000
	ds_read_b128 v[192:195], v171 offset:33792
	ds_read_b128 v[196:199], v171 offset:34816
	ds_read_b128 v[200:203], v171 offset:35840
	global_load_lds_dwordx4 v130, s[98:99]
	s_add_u32 s98, s94, 0x80
	s_addc_u32 s99, s95, 0
	s_add_i32 m0, s3, 0x8000
	ds_read_b128 v[204:207], v171 offset:36864
	ds_read_b128 v[208:211], v171 offset:37888
	ds_read_b128 v[212:215], v171 offset:38912
	global_load_lds_dwordx4 v134, s[98:99]
	s_add_u32 s98, s94, 0xfffe0080
	s_addc_u32 s99, s95, -1
	s_add_i32 m0, s3, 0x7000
	ds_read_b128 v[218:221], v171 offset:39936
	ds_read_b128 v[160:163], v171 offset:49152
	ds_read_b128 v[224:227], v171 offset:50176
	global_load_lds_dwordx4 v134, s[98:99]
	s_add_u32 s98, s94, 0x80080
	s_addc_u32 s99, s95, 0
	s_add_i32 m0, s3, 0xc000
	ds_read_b128 v[228:231], v171 offset:51200
	ds_read_b128 v[232:235], v171 offset:52224
	ds_read_b128 v[236:239], v171 offset:53248
	global_load_lds_dwordx4 v134, s[98:99]
	s_add_u32 s98, s94, 0x60080
	s_addc_u32 s99, s95, 0
	s_add_i32 m0, s3, 0xb000
	ds_read_b128 v[240:243], v171 offset:54272
	ds_read_b128 v[244:247], v171 offset:55296
	ds_read_b128 v[248:251], v171 offset:56320
	global_load_lds_dwordx4 v134, s[98:99]
; #define PG8_STAGE(bufoff, gbase, voff) do { _Pragma("unroll") for (int _i = 0; _i < 2; ++_i) \
;         __builtin_amdgcn_global_load_lds((const unsigned*)((const char*)(gbase) + (voff)[_i]), (PG8_LAS unsigned*)(lds + (bufoff) + ldsw + _i * 8192), 16, 0, 0); } while (0)
; #define PG8_LDA(dst, b, h) do { _Pragma("unroll") for (int m = 0; m < 4; ++m) _Pragma("unroll") for (int k = 0; k < 2; ++k) dst[m][k] = *(const PG8_LAS bf16x8*)(lds + PG8_SA(b, h) + aoff + m * 2048 + k * 1024); } while (0)
; #define PG8_LDB(dst, b, h) do { _Pragma("unroll") for (int n = 0; n < 2; ++n) _Pragma("unroll") for (int k = 0; k < 2; ++k) dst[n][k] = *(const PG8_LAS bf16x8*)(lds + PG8_SB(b, h) + boff + n * 2048 + k * 1024); } while (0)
; #define PG8_MMA(ai, bj, At, Bt) do { __builtin_amdgcn_s_setprio(1); _Pragma("unroll") for (int m = 0; m < 4; ++m) _Pragma("unroll") for (int n = 0; n < 2; ++n) _Pragma("unroll") for (int k = 0; k < 2; ++k) \
;         acc[ai][bj][m][n] = __builtin_amdgcn_mfma_f32_16x16x32_bf16(Bt[n][k], At[m][k], acc[ai][bj][m][n], 0, 0, 0); __builtin_amdgcn_s_setprio(0); } while (0)
; #define PG8_WAIT_V(n) asm volatile("s_waitcnt vmcnt(" #n ")" ::: "memory")
; #define PG8_WAIT_L(n) asm volatile("s_waitcnt lgkmcnt(" #n ")" ::: "memory")
; #define PG8_BAR __builtin_amdgcn_s_barrier()
; #define PG8_SCHED __builtin_amdgcn_sched_barrier(0)
; template <class Epi, class Sched, bool ALIGN_EPI = false, bool SP2 = false>
; __device__ __forceinline__ void gemm_phase(PG8_LAS unsigned char* lds, const Gemm g, const Sched& S, const Epi& E) {
;     ...
;         for (int t = 0; t < nt; t += 2) {
;     ...
;             PG8_LDB(B0, 1, 0); PG8_LDB(B1, 1, 1); PG8_SCHED; PG8_LDA(At, 1, 0); PG8_STAGE(PG8_SA(0, 1), a2 + hstep, voffA);
;             PG8_WAIT_V(8); PG8_WAIT_L(0); PG8_BAR; PG8_MMA(0, 0, At, B0); PG8_MMA(0, 1, At, B1); PG8_BAR; PG8_SCHED;
;             PG8_LDA(At, 1, 1); PG8_STAGE(PG8_SB(1, 0), b3, voffB); PG8_STAGE(PG8_SB(1, 1), b3 + hstep, voffB); PG8_STAGE(PG8_SA(1, 0), a3, voffA);
;             PG8_WAIT_V(8); PG8_WAIT_L(0); PG8_BAR; PG8_MMA(1, 0, At, B0); PG8_MMA(1, 1, At, B1); PG8_BAR; PG8_SCHED;
.Lspf3_b_rd:
	s_waitcnt lgkmcnt(0)
	s_setprio 1
	s_barrier
	v_mfma_f32_16x16x32_bf16 v[124:127], v[144:147], v[188:191], v[124:127]
	v_mfma_f32_16x16x32_bf16 v[120:123], v[152:155], v[188:191], v[120:123]
	v_mfma_f32_16x16x32_bf16 v[108:111], v[144:147], v[196:199], v[108:111]
	v_mfma_f32_16x16x32_bf16 v[104:107], v[152:155], v[196:199], v[104:107]
	v_mfma_f32_16x16x32_bf16 v[100:103], v[144:147], v[204:207], v[100:103]
	v_mfma_f32_16x16x32_bf16 v[92:95], v[152:155], v[204:207], v[92:95]
	v_mfma_f32_16x16x32_bf16 v[84:87], v[144:147], v[212:215], v[84:87]
	v_mfma_f32_16x16x32_bf16 v[76:79], v[152:155], v[212:215], v[76:79]
	v_mfma_f32_16x16x32_bf16 v[124:127], v[148:151], v[192:195], v[124:127]
	v_mfma_f32_16x16x32_bf16 v[120:123], v[156:159], v[192:195], v[120:123]
	v_mfma_f32_16x16x32_bf16 v[108:111], v[148:151], v[200:203], v[108:111]
	v_mfma_f32_16x16x32_bf16 v[104:107], v[156:159], v[200:203], v[104:107]
	v_mfma_f32_16x16x32_bf16 v[100:103], v[148:151], v[208:211], v[100:103]
	v_mfma_f32_16x16x32_bf16 v[92:95], v[156:159], v[208:211], v[92:95]
	v_mfma_f32_16x16x32_bf16 v[84:87], v[148:151], v[218:221], v[84:87]
	v_mfma_f32_16x16x32_bf16 v[76:79], v[156:159], v[218:221], v[76:79]
	v_mfma_f32_16x16x32_bf16 v[116:119], v[172:175], v[188:191], v[116:119]
	v_mfma_f32_16x16x32_bf16 v[112:115], v[180:183], v[188:191], v[112:115]
	v_mfma_f32_16x16x32_bf16 v[96:99], v[172:175], v[196:199], v[96:99]
	v_mfma_f32_16x16x32_bf16 v[88:91], v[180:183], v[196:199], v[88:91]
	v_mfma_f32_16x16x32_bf16 v[80:83], v[172:175], v[204:207], v[80:83]
	v_mfma_f32_16x16x32_bf16 v[72:75], v[180:183], v[204:207], v[72:75]
	v_mfma_f32_16x16x32_bf16 v[68:71], v[172:175], v[212:215], v[68:71]
	v_mfma_f32_16x16x32_bf16 v[64:67], v[180:183], v[212:215], v[64:67]
	v_mfma_f32_16x16x32_bf16 v[116:119], v[176:179], v[192:195], v[116:119]
	v_mfma_f32_16x16x32_bf16 v[112:115], v[184:187], v[192:195], v[112:115]
	v_mfma_f32_16x16x32_bf16 v[96:99], v[176:179], v[200:203], v[96:99]
	v_mfma_f32_16x16x32_bf16 v[88:91], v[184:187], v[200:203], v[88:91]
	v_mfma_f32_16x16x32_bf16 v[80:83], v[176:179], v[208:211], v[80:83]
	v_mfma_f32_16x16x32_bf16 v[72:75], v[184:187], v[208:211], v[72:75]
	v_mfma_f32_16x16x32_bf16 v[68:71], v[176:179], v[218:221], v[68:71]
	v_mfma_f32_16x16x32_bf16 v[64:67], v[184:187], v[218:221], v[64:67]
	v_mfma_f32_16x16x32_bf16 v[60:63], v[144:147], v[160:163], v[60:63]
	v_mfma_f32_16x16x32_bf16 v[56:59], v[152:155], v[160:163], v[56:59]
	v_mfma_f32_16x16x32_bf16 v[52:55], v[144:147], v[228:231], v[52:55]
	v_mfma_f32_16x16x32_bf16 v[44:47], v[152:155], v[228:231], v[44:47]
	v_mfma_f32_16x16x32_bf16 v[36:39], v[144:147], v[236:239], v[36:39]
	v_mfma_f32_16x16x32_bf16 v[28:31], v[152:155], v[236:239], v[28:31]
	v_mfma_f32_16x16x32_bf16 v[20:23], v[144:147], v[244:247], v[20:23]
	v_mfma_f32_16x16x32_bf16 v[12:15], v[152:155], v[244:247], v[12:15]
	v_mfma_f32_16x16x32_bf16 v[60:63], v[148:151], v[224:227], v[60:63]
	v_mfma_f32_16x16x32_bf16 v[56:59], v[156:159], v[224:227], v[56:59]
	v_mfma_f32_16x16x32_bf16 v[52:55], v[148:151], v[232:235], v[52:55]
	v_mfma_f32_16x16x32_bf16 v[44:47], v[156:159], v[232:235], v[44:47]
	v_mfma_f32_16x16x32_bf16 v[36:39], v[148:151], v[240:243], v[36:39]
	v_mfma_f32_16x16x32_bf16 v[28:31], v[156:159], v[240:243], v[28:31]
	v_mfma_f32_16x16x32_bf16 v[20:23], v[148:151], v[248:251], v[20:23]
	v_mfma_f32_16x16x32_bf16 v[12:15], v[156:159], v[248:251], v[12:15]
	v_mfma_f32_16x16x32_bf16 v[48:51], v[172:175], v[160:163], v[48:51]
	v_mfma_f32_16x16x32_bf16 v[40:43], v[180:183], v[160:163], v[40:43]
	v_mfma_f32_16x16x32_bf16 v[32:35], v[172:175], v[228:231], v[32:35]
	v_mfma_f32_16x16x32_bf16 v[24:27], v[180:183], v[228:231], v[24:27]
	v_mfma_f32_16x16x32_bf16 v[16:19], v[172:175], v[236:239], v[16:19]
	v_mfma_f32_16x16x32_bf16 v[8:11], v[180:183], v[236:239], v[8:11]
	v_mfma_f32_16x16x32_bf16 v[4:7], v[172:175], v[244:247], v[4:7]
	v_mfma_f32_16x16x32_bf16 v[0:3], v[180:183], v[244:247], v[0:3]
	v_mfma_f32_16x16x32_bf16 v[48:51], v[176:179], v[224:227], v[48:51]
	v_mfma_f32_16x16x32_bf16 v[40:43], v[184:187], v[224:227], v[40:43]
	v_mfma_f32_16x16x32_bf16 v[32:35], v[176:179], v[232:235], v[32:35]
	v_mfma_f32_16x16x32_bf16 v[24:27], v[184:187], v[232:235], v[24:27]
	v_mfma_f32_16x16x32_bf16 v[16:19], v[176:179], v[240:243], v[16:19]
	v_mfma_f32_16x16x32_bf16 v[8:11], v[184:187], v[240:243], v[8:11]
	v_mfma_f32_16x16x32_bf16 v[4:7], v[176:179], v[248:251], v[4:7]
	v_mfma_f32_16x16x32_bf16 v[0:3], v[184:187], v[248:251], v[0:3]
	s_waitcnt vmcnt(0)
	s_barrier
	s_setprio 0
	s_add_i32 s66, s66, 2
	s_add_u32 s92, s92, 0x100
	s_addc_u32 s93, s93, 0
	s_add_u32 s85, s85, 0x100
	s_addc_u32 s91, s91, 0
	s_cmp_gt_u32 s66, 29
	s_cbranch_scc0 .LBB0_493
	v_mov_b32_e32 v168, v171
	v_mov_b32_e32 v167, v139
	v_mov_b32_e32 v166, v137
	v_mov_b32_e32 v163, v135
	v_mov_b32_e32 v162, v131
	s_and_b64 vcc, exec, s[44:45]
	s_cbranch_vccz .LBB0_496
	s_barrier

; #define PG8_STAGE(bufoff, gbase, voff) do { _Pragma("unroll") for (int _i = 0; _i < 2; ++_i) \
;         __builtin_amdgcn_global_load_lds((const unsigned*)((const char*)(gbase) + (voff)[_i]), (PG8_LAS unsigned*)(lds + (bufoff) + ldsw + _i * 8192), 16, 0, 0); } while (0)
; #define PG8_WAIT_V(n) asm volatile("s_waitcnt vmcnt(" #n ")" ::: "memory")
; #define PG8_BAR __builtin_amdgcn_s_barrier()
; template <class Epi, class Sched, bool ALIGN_EPI = false, bool SP2 = false>
; __device__ __forceinline__ void gemm_phase(PG8_LAS unsigned char* lds, const Gemm g, const Sched& S, const Epi& E) {
;     ...
;     const int tid = tid_o, wid = __builtin_amdgcn_readfirstlane(tid >> 6), lane = tid & 63, wr = wid >> 2, wc = wid & 3, fr = lane & 15, fq = lane >> 4;
;     const int K = g.K, nt = K / BK;
;     unsigned voffA[2], voffB[2];
; #pragma unroll
;     for (int i = 0; i < 2; ++i) { int R, C; stage_rc(tid * 16 + i * 8192, R, C); const int Rb = Epi::PERM ? ((R & ~31) + perm32(R & 31)) : R;
;         voffA[i] = (unsigned)(R * K + C) * 2u; voffB[i] = (unsigned)(Rb * K + C) * 2u; }
;     const size_t kstep = (size_t)(BK * 2);
;     const size_t hstep = (size_t)HALF * K * 2;
;     const size_t tstep = 2 * hstep;
;     const unsigned ldsw = (unsigned)wid * 1024u;
;     const int aoff = lds_byte(wr * 64 + fr, fq * 8), boff = lds_byte(wc * 32 + fr, fq * 8);
;     ...
;     if constexpr (SP2) {
;         PG8_STAGE(PG8_SB(0, 0), cB, voffB); PG8_STAGE(PG8_SB(0, 1), cB + hstep, voffB); PG8_STAGE(PG8_SA(0, 0), cA, voffA); PG8_STAGE(PG8_SA(0, 1), cA + hstep, voffA);
;         if (wr == 1) PG8_BAR;
;         PG8_WAIT_V(2); PG8_BAR;
;         PG8_STAGE(PG8_SB(1, 0), cB + kstep, voffB); PG8_STAGE(PG8_SA(1, 0), cA + kstep, voffA); PG8_STAGE(PG8_SB(1, 1), cB + hstep + kstep, voffB);
;         PG8_WAIT_V(6); PG8_BAR;
.LBB0_771:
	s_add_u32 s10, s58, 0xfa02000
	s_addc_u32 s11, s59, 0
	s_lshl_b32 s13, s13, 5
	s_mov_b64 s[16:17], 0x80
	s_and_b32 s13, s13, 0x60
	s_add_i32 m0, s14, 0x18000
	v_lshl_add_u64 v[6:7], v[6:7], 0, s[16:17]
	s_lshl_b32 s20, s12, 13
	s_lshl_b32 s21, s13, 7
	s_waitcnt vmcnt(0)
	s_barrier
	global_load_lds_dwordx4 v[6:7], off
	v_lshl_add_u64 v[4:5], v[4:5], 0, s[16:17]
	s_add_i32 m0, s14, 0x1a000
	s_add_i32 s35, s14, 0x8000
	s_add_i32 s45, s14, 0xa000
	global_load_lds_dwordx4 v[4:5], off
	v_lshl_add_u64 v[0:1], v[0:1], 0, s[16:17]
	s_mov_b32 m0, s35
	s_add_u32 s18, s48, 0x40080
	global_load_lds_dwordx4 v[0:1], off
	v_lshl_add_u64 v[0:1], v[2:3], 0, s[16:17]
	s_mov_b32 m0, s45
	s_addc_u32 s19, s49, 0
	global_load_lds_dwordx4 v[0:1], off
	s_add_i32 m0, s14, 0x1c000
	v_lshl_add_u64 v[0:1], s[18:19], 0, v[132:133]
	global_load_lds_dwordx4 v[0:1], off
	v_lshl_add_u64 v[0:1], s[18:19], 0, v[128:129]
	s_add_i32 m0, s14, 0x1e000
	s_cmpk_lt_u32 s7, 0x100
	global_load_lds_dwordx4 v[0:1], off
	v_lshrrev_b32_e32 v1, 1, v9
	v_and_b32_e32 v1, 24, v1
	v_and_b32_e32 v0, 15, v9
	v_lshlrev_b32_e32 v2, 1, v1
	v_lshl_or_b32 v150, s12, 6, v0
	v_lshl_or_b32 v0, v0, 6, v2
	v_lshlrev_b32_e32 v2, 2, v9
	v_and_b32_e32 v2, 32, v2
	v_bitop3_b32 v3, v0, s20, v2 bitop3:0xde
	v_bitop3_b32 v151, v0, s21, v2 bitop3:0xde
	v_lshlrev_b32_e32 v0, 14, v13
	v_and_b32_e32 v0, 0xffff8000, v0
	v_or_b32_e32 v152, s13, v1
	v_lshl_add_u32 v0, v12, 11, v0
	v_and_b32_e32 v1, 1, v13
	v_lshl_or_b32 v0, v1, 6, v0
	v_lshl_add_u32 v136, v14, 1, v0
	v_lshlrev_b32_e32 v0, 14, v8
	v_and_b32_e32 v0, 0xffff8000, v0
	s_waitcnt vmcnt(6)
	v_lshl_add_u32 v0, v10, 11, v0
	v_and_b32_e32 v1, 1, v8
	s_cselect_b64 s[18:19], -1, 0
	v_lshl_or_b32 v0, v1, 6, v0
	s_add_i32 s68, 0, 0x10000
	s_add_i32 s69, 0, 0x14000
	s_sext_i32_i8 s70, s6
	v_mov_b32_e32 v137, v133
	v_lshl_add_u32 v138, v11, 1, v0
	v_mov_b32_e32 v139, v133
	v_mov_b64_e32 v[140:141], 0x100
	v_mov_b64_e32 v[142:143], 0xff
	v_add_u32_e32 v153, s68, v151
	v_add_u32_e32 v154, s69, v151
	v_add_u32_e32 v155, 0, v3
	s_barrier
	s_branch .LBB0_774

; #define PG8_STAGE(bufoff, gbase, voff) do { _Pragma("unroll") for (int _i = 0; _i < 2; ++_i) \
;         __builtin_amdgcn_global_load_lds((const unsigned*)((const char*)(gbase) + (voff)[_i]), (PG8_LAS unsigned*)(lds + (bufoff) + ldsw + _i * 8192), 16, 0, 0); } while (0)
; #define PG8_LDA(dst, b, h) do { _Pragma("unroll") for (int m = 0; m < 4; ++m) _Pragma("unroll") for (int k = 0; k < 2; ++k) dst[m][k] = *(const PG8_LAS bf16x8*)(lds + PG8_SA(b, h) + aoff + m * 2048 + k * 1024); } while (0)
; #define PG8_LDB(dst, b, h) do { _Pragma("unroll") for (int n = 0; n < 2; ++n) _Pragma("unroll") for (int k = 0; k < 2; ++k) dst[n][k] = *(const PG8_LAS bf16x8*)(lds + PG8_SB(b, h) + boff + n * 2048 + k * 1024); } while (0)
; template <class Epi, class Sched, bool ALIGN_EPI = false, bool SP2 = false>
; __device__ __forceinline__ void gemm_phase(PG8_LAS unsigned char* lds, const Gemm g, const Sched& S, const Epi& E) {
;     ...
;     for (;;) {
;         const bool has_next = S.next(ui + 1, nxt);
;         const char* nA = has_next ? (const char*)g.A + (size_t)nxt.pm * tstep : cA; const char* nB = has_next ? (const char*)g.Bt + (size_t)nxt.pn * tstep : cB;
;         for (int t = 0; t < nt; t += 2) {
;             const bool last = (t == nt - 2);
;             const char* a1 = cA + (size_t)(t + 1) * kstep;
;             const char* a2 = last ? nA : cA + (size_t)(t + 2) * kstep; const char* b2 = last ? nB : cB + (size_t)(t + 2) * kstep;
;             const char* a3 = a2 + kstep; const char* b3 = b2 + kstep;
;             if (last && has_next) S.a_ready(nxt);
;             if constexpr (SP2) {
;             PG8_LDB(B0, 0, 0); PG8_LDB(B1, 0, 1); PG8_SCHED; PG8_LDA(At, 0, 0); PG8_STAGE(PG8_SA(1, 1), a1 + hstep, voffA);
;             PG8_WAIT_V(8); PG8_WAIT_L(0); PG8_BAR; PG8_MMA(0, 0, At, B0); PG8_MMA(0, 1, At, B1); PG8_BAR; PG8_SCHED;
;             PG8_LDA(At, 0, 1); PG8_STAGE(PG8_SB(0, 0), b2, voffB); PG8_STAGE(PG8_SB(0, 1), b2 + hstep, voffB); PG8_STAGE(PG8_SA(0, 0), a2, voffA);
;     ...
;         if (!has_next) break;
; #pragma unroll
;         for (int a = 0; a < 2; ++a)
; #pragma unroll
;             for (int b = 0; b < 2; ++b)
; #pragma unroll
;                 for (int m = 0; m < 4; ++m)
; #pragma unroll
;                     for (int n = 0; n < 2; ++n) acc[a][b][m][n] = (f32x4){0.f, 0.f, 0.f, 0.f};
;         cur = nxt; cA = nA; cB = nB; ++ui;
.LBB0_780:
	s_ashr_i32 s29, s28, 31
	s_lshl_b64 s[12:13], s[28:29], 19
	s_add_u32 s30, s38, s12
	s_addc_u32 s31, s39, s13
	s_and_b64 s[12:13], s[6:7], exec
	s_cselect_b32 s12, s31, s47
	s_cselect_b32 s13, s30, s46
	s_ashr_i32 s21, s20, 31
	s_lshl_b64 s[42:43], s[20:21], 19
	v_readlane_b32 s50, v252, 4
	v_readlane_b32 s51, v252, 5
	s_add_u32 s42, s50, s42
	s_addc_u32 s43, s51, s43
	s_and_b64 s[50:51], s[6:7], exec
	s_cselect_b32 s21, s43, s49
	s_cselect_b32 s29, s42, s48
	s_add_u32 s46, s46, 0x40080
	s_addc_u32 s47, s47, 0
	s_add_u32 s71, s48, 0x100
	v_mov_b64_e32 v[0:1], 0
	v_mov_b64_e32 v[2:3], 0
	v_mov_b64_e32 v[4:5], 0
	v_mov_b64_e32 v[6:7], 0
	v_mov_b64_e32 v[8:9], 0
	v_mov_b64_e32 v[10:11], 0
	v_mov_b64_e32 v[12:13], 0
	v_mov_b64_e32 v[14:15], 0
	v_mov_b64_e32 v[16:17], 0
	v_mov_b64_e32 v[18:19], 0
	v_mov_b64_e32 v[20:21], 0
	v_mov_b64_e32 v[22:23], 0
	v_mov_b64_e32 v[24:25], 0
	v_mov_b64_e32 v[26:27], 0
	v_mov_b64_e32 v[28:29], 0
	v_mov_b64_e32 v[30:31], 0
	v_mov_b64_e32 v[32:33], 0
	v_mov_b64_e32 v[34:35], 0
	v_mov_b64_e32 v[36:37], 0
	v_mov_b64_e32 v[38:39], 0
	v_mov_b64_e32 v[40:41], 0
	v_mov_b64_e32 v[42:43], 0
	v_mov_b64_e32 v[44:45], 0
	v_mov_b64_e32 v[46:47], 0
	v_mov_b64_e32 v[48:49], 0
	v_mov_b64_e32 v[50:51], 0
	v_mov_b64_e32 v[52:53], 0
	v_mov_b64_e32 v[54:55], 0
	v_mov_b64_e32 v[56:57], 0
	v_mov_b64_e32 v[58:59], 0
	v_mov_b64_e32 v[60:61], 0
	v_mov_b64_e32 v[62:63], 0
	v_mov_b64_e32 v[64:65], 0
	v_mov_b64_e32 v[66:67], 0
	v_mov_b64_e32 v[68:69], 0
	v_mov_b64_e32 v[70:71], 0
	v_mov_b64_e32 v[72:73], 0
	v_mov_b64_e32 v[74:75], 0
	v_mov_b64_e32 v[76:77], 0
	v_mov_b64_e32 v[78:79], 0
	v_mov_b64_e32 v[80:81], 0
	v_mov_b64_e32 v[82:83], 0
	v_mov_b64_e32 v[84:85], 0
	v_mov_b64_e32 v[86:87], 0
	v_mov_b64_e32 v[88:89], 0
	v_mov_b64_e32 v[90:91], 0
	v_mov_b64_e32 v[92:93], 0
	v_mov_b64_e32 v[94:95], 0
	v_mov_b64_e32 v[96:97], 0
	v_mov_b64_e32 v[98:99], 0
	v_mov_b64_e32 v[100:101], 0
	v_mov_b64_e32 v[102:103], 0
	v_mov_b64_e32 v[104:105], 0
	v_mov_b64_e32 v[106:107], 0
	v_mov_b64_e32 v[108:109], 0
	v_mov_b64_e32 v[110:111], 0
	v_mov_b64_e32 v[112:113], 0
	v_mov_b64_e32 v[114:115], 0
	v_mov_b64_e32 v[116:117], 0
	v_mov_b64_e32 v[118:119], 0
	v_mov_b64_e32 v[120:121], 0
	v_mov_b64_e32 v[122:123], 0
	v_mov_b64_e32 v[124:125], 0
	v_mov_b64_e32 v[126:127], 0
	s_addc_u32 s72, s49, 0
	s_mov_b32 s66, -2
	v_mov_b32_e32 v129, v150
	v_mov_b32_e32 v131, v151
	v_mov_b32_e32 v133, v153
	v_mov_b32_e32 v135, v154
	v_mov_b32_e32 v137, v155
	v_add_u32_e32 v139, 0x18000, v131
	v_add_u32_e32 v220, 0x1c000, v131
	s_cmp_lg_u32 s18, 0
	s_cbranch_scc0 .Lspf4_pre
	s_add_i32 m0, s3, 0xc000
	s_nop 0
	global_load_lds_dwordx4 v136, s[46:47]
	s_add_u32 s98, s46, 0x10000
	s_addc_u32 s99, s47, 0
	s_add_i32 m0, s3, 0xd000
	s_nop 0
	global_load_lds_dwordx4 v136, s[98:99]
	s_add_u32 s98, s46, 0xfffc0000
	s_addc_u32 s99, s47, -1
	s_add_i32 m0, s3, 0x8000
	s_nop 0
	global_load_lds_dwordx4 v136, s[98:99]
	s_add_u32 s98, s46, 0xfffd0000
	s_addc_u32 s99, s47, -1
	s_add_i32 m0, s3, 0x9000
	s_nop 0
	global_load_lds_dwordx4 v136, s[98:99]
.Lspf4_pre:
.LBB0_781:
	s_add_u32 s48, s46, 0xfffc0080
	s_addc_u32 s49, s47, -1
	s_cmp_eq_u32 s66, 12
	s_cselect_b32 s51, s12, s49
	s_cselect_b32 s50, s13, s48
	s_cselect_b32 s49, s21, s72
	s_cselect_b32 s48, s29, s71
	s_cmp_lg_u32 s18, 0
	s_cbranch_scc0 .Lspf4_a_h1
	s_add_u32 s98, s71, 0xffffff80
	s_addc_u32 s99, s72, -1
	s_add_i32 m0, s3, 0x18000
	ds_read_b128 v[144:147], v133
	ds_read_b128 v[156:159], v133 offset:1024
	ds_read_b128 v[160:163], v133 offset:2048
	global_load_lds_dwordx4 v132, s[98:99]
	s_add_i32 m0, s3, 0x1a000
	ds_read_b128 v[164:167], v133 offset:3072
	ds_read_b128 v[168:171], v135
	ds_read_b128 v[172:175], v135 offset:1024
	global_load_lds_dwordx4 v128, s[98:99]
	s_add_u32 s98, s71, 0xff80
	s_addc_u32 s99, s72, 0
	s_add_i32 m0, s3, 0x19000
	ds_read_b128 v[176:179], v135 offset:2048
	ds_read_b128 v[180:183], v135 offset:3072
	ds_read_b128 v[184:187], v137
	global_load_lds_dwordx4 v132, s[98:99]
	s_add_i32 m0, s3, 0x1b000
	ds_read_b128 v[188:191], v137 offset:1024
	ds_read_b128 v[192:195], v137 offset:2048
	ds_read_b128 v[196:199], v137 offset:3072
	global_load_lds_dwordx4 v128, s[98:99]
	s_add_u32 s98, s71, 0x3ff80
	s_addc_u32 s99, s72, 0
	s_add_i32 m0, s3, 0x1c000
	ds_read_b128 v[200:203], v137 offset:4096
	ds_read_b128 v[204:207], v137 offset:5120
	ds_read_b128 v[208:211], v137 offset:6144
	global_load_lds_dwordx4 v132, s[98:99]
	s_add_i32 m0, s3, 0x1e000
	ds_read_b128 v[212:215], v137 offset:7168
	ds_read_b128 v[148:151], v137 offset:16384
	ds_read_b128 v[216:219], v137 offset:17408
	global_load_lds_dwordx4 v128, s[98:99]
	s_add_u32 s98, s71, 0x4ff80
	s_addc_u32 s99, s72, 0
	s_add_i32 m0, s3, 0x1d000
	ds_read_b128 v[226:229], v137 offset:18432
	ds_read_b128 v[230:233], v137 offset:19456
	ds_read_b128 v[234:237], v137 offset:20480
	global_load_lds_dwordx4 v132, s[98:99]
	s_add_i32 m0, s3, 0x1f000
	ds_read_b128 v[238:241], v137 offset:21504
	ds_read_b128 v[242:245], v137 offset:22528
	ds_read_b128 v[246:249], v137 offset:23552
	global_load_lds_dwordx4 v128, s[98:99]
	s_branch .Lspf4_a_rd
; #define PG8_STAGE(bufoff, gbase, voff) do { _Pragma("unroll") for (int _i = 0; _i < 2; ++_i) \
;         __builtin_amdgcn_global_load_lds((const unsigned*)((const char*)(gbase) + (voff)[_i]), (PG8_LAS unsigned*)(lds + (bufoff) + ldsw + _i * 8192), 16, 0, 0); } while (0)
; #define PG8_LDA(dst, b, h) do { _Pragma("unroll") for (int m = 0; m < 4; ++m) _Pragma("unroll") for (int k = 0; k < 2; ++k) dst[m][k] = *(const PG8_LAS bf16x8*)(lds + PG8_SA(b, h) + aoff + m * 2048 + k * 1024); } while (0)
; #define PG8_LDB(dst, b, h) do { _Pragma("unroll") for (int n = 0; n < 2; ++n) _Pragma("unroll") for (int k = 0; k < 2; ++k) dst[n][k] = *(const PG8_LAS bf16x8*)(lds + PG8_SB(b, h) + boff + n * 2048 + k * 1024); } while (0)
; #define PG8_MMA(ai, bj, At, Bt) do { __builtin_amdgcn_s_setprio(1); _Pragma("unroll") for (int m = 0; m < 4; ++m) _Pragma("unroll") for (int n = 0; n < 2; ++n) _Pragma("unroll") for (int k = 0; k < 2; ++k) \
;         acc[ai][bj][m][n] = __builtin_amdgcn_mfma_f32_16x16x32_bf16(Bt[n][k], At[m][k], acc[ai][bj][m][n], 0, 0, 0); __builtin_amdgcn_s_setprio(0); } while (0)
; #define PG8_WAIT_V(n) asm volatile("s_waitcnt vmcnt(" #n ")" ::: "memory")
; #define PG8_WAIT_L(n) asm volatile("s_waitcnt lgkmcnt(" #n ")" ::: "memory")
; #define PG8_BAR __builtin_amdgcn_s_barrier()
; #define PG8_SCHED __builtin_amdgcn_sched_barrier(0)
; template <class Epi, class Sched, bool ALIGN_EPI = false, bool SP2 = false>
; __device__ __forceinline__ void gemm_phase(PG8_LAS unsigned char* lds, const Gemm g, const Sched& S, const Epi& E) {
;     ...
;             if constexpr (SP2) {
;             PG8_LDB(B0, 0, 0); PG8_LDB(B1, 0, 1); PG8_SCHED; PG8_LDA(At, 0, 0); PG8_STAGE(PG8_SA(1, 1), a1 + hstep, voffA);
;             PG8_WAIT_V(8); PG8_WAIT_L(0); PG8_BAR; PG8_MMA(0, 0, At, B0); PG8_MMA(0, 1, At, B1); PG8_BAR; PG8_SCHED;
;             PG8_LDA(At, 0, 1); PG8_STAGE(PG8_SB(0, 0), b2, voffB); PG8_STAGE(PG8_SB(0, 1), b2 + hstep, voffB); PG8_STAGE(PG8_SA(0, 0), a2, voffA);
;             PG8_WAIT_V(8); PG8_WAIT_L(0); PG8_BAR; PG8_MMA(1, 0, At, B0); PG8_MMA(1, 1, At, B1); PG8_BAR; PG8_SCHED;
.Lspf4_a_h1:
	s_add_u32 s98, s46, 0xfffc0000
	s_addc_u32 s99, s47, -1
	s_add_i32 m0, s3, 0xa000
	ds_read_b128 v[144:147], v133
	ds_read_b128 v[156:159], v133 offset:1024
	ds_read_b128 v[160:163], v133 offset:2048
	global_load_lds_dwordx4 v138, s[98:99]
	s_add_u32 s98, s46, 0xfffb0000
	s_addc_u32 s99, s47, -1
	s_add_i32 m0, s3, 0x9000
	ds_read_b128 v[164:167], v133 offset:3072
	ds_read_b128 v[168:171], v135
	ds_read_b128 v[172:175], v135 offset:1024
	global_load_lds_dwordx4 v138, s[98:99]
	s_add_i32 m0, s3, 0xe000
	ds_read_b128 v[176:179], v135 offset:2048
	ds_read_b128 v[180:183], v135 offset:3072
	ds_read_b128 v[184:187], v137
	global_load_lds_dwordx4 v138, s[46:47]
	s_add_u32 s98, s46, 0xffff0000
	s_addc_u32 s99, s47, -1
	s_add_i32 m0, s3, 0xd000
	ds_read_b128 v[188:191], v137 offset:1024
	ds_read_b128 v[192:195], v137 offset:2048
	ds_read_b128 v[196:199], v137 offset:3072
	global_load_lds_dwordx4 v138, s[98:99]
	s_add_i32 m0, s3, 0x0
	ds_read_b128 v[200:203], v137 offset:4096
	ds_read_b128 v[204:207], v137 offset:5120
	ds_read_b128 v[208:211], v137 offset:6144
	global_load_lds_dwordx4 v134, s[50:51]
	s_add_u32 s98, s50, 0xffff0000
	s_addc_u32 s99, s51, -1
	s_add_i32 m0, s3, 0xfffff000
	ds_read_b128 v[212:215], v137 offset:7168
	ds_read_b128 v[148:151], v137 offset:16384
	ds_read_b128 v[216:219], v137 offset:17408
	global_load_lds_dwordx4 v134, s[98:99]
	s_add_u32 s98, s50, 0x40000
	s_addc_u32 s99, s51, 0
	s_add_i32 m0, s3, 0x4000
	ds_read_b128 v[226:229], v137 offset:18432
	ds_read_b128 v[230:233], v137 offset:19456
	ds_read_b128 v[234:237], v137 offset:20480
	global_load_lds_dwordx4 v134, s[98:99]
	s_add_u32 s98, s50, 0x30000
	s_addc_u32 s99, s51, 0
	s_add_i32 m0, s3, 0x3000
	ds_read_b128 v[238:241], v137 offset:21504
	ds_read_b128 v[242:245], v137 offset:22528
	ds_read_b128 v[246:249], v137 offset:23552
	global_load_lds_dwordx4 v134, s[98:99]
.Lspf4_a_rd:
	s_waitcnt lgkmcnt(0)
	s_setprio 1
	s_barrier
	v_mfma_f32_16x16x32_bf16 v[124:127], v[144:147], v[184:187], v[124:127]
	v_mfma_f32_16x16x32_bf16 v[120:123], v[160:163], v[184:187], v[120:123]
	v_mfma_f32_16x16x32_bf16 v[108:111], v[144:147], v[192:195], v[108:111]
	v_mfma_f32_16x16x32_bf16 v[104:107], v[160:163], v[192:195], v[104:107]
	v_mfma_f32_16x16x32_bf16 v[96:99], v[144:147], v[200:203], v[96:99]
	v_mfma_f32_16x16x32_bf16 v[88:91], v[160:163], v[200:203], v[88:91]
	v_mfma_f32_16x16x32_bf16 v[80:83], v[144:147], v[208:211], v[80:83]
	v_mfma_f32_16x16x32_bf16 v[72:75], v[160:163], v[208:211], v[72:75]
	v_mfma_f32_16x16x32_bf16 v[124:127], v[156:159], v[188:191], v[124:127]
	v_mfma_f32_16x16x32_bf16 v[120:123], v[164:167], v[188:191], v[120:123]
	v_mfma_f32_16x16x32_bf16 v[108:111], v[156:159], v[196:199], v[108:111]
	v_mfma_f32_16x16x32_bf16 v[104:107], v[164:167], v[196:199], v[104:107]
	v_mfma_f32_16x16x32_bf16 v[96:99], v[156:159], v[204:207], v[96:99]
	v_mfma_f32_16x16x32_bf16 v[88:91], v[164:167], v[204:207], v[88:91]
	v_mfma_f32_16x16x32_bf16 v[80:83], v[156:159], v[212:215], v[80:83]
	v_mfma_f32_16x16x32_bf16 v[72:75], v[164:167], v[212:215], v[72:75]
	v_mfma_f32_16x16x32_bf16 v[116:119], v[168:171], v[184:187], v[116:119]
	v_mfma_f32_16x16x32_bf16 v[112:115], v[176:179], v[184:187], v[112:115]
	v_mfma_f32_16x16x32_bf16 v[100:103], v[168:171], v[192:195], v[100:103]
	v_mfma_f32_16x16x32_bf16 v[92:95], v[176:179], v[192:195], v[92:95]
	v_mfma_f32_16x16x32_bf16 v[84:87], v[168:171], v[200:203], v[84:87]
	v_mfma_f32_16x16x32_bf16 v[76:79], v[176:179], v[200:203], v[76:79]
	v_mfma_f32_16x16x32_bf16 v[68:71], v[168:171], v[208:211], v[68:71]
	v_mfma_f32_16x16x32_bf16 v[64:67], v[176:179], v[208:211], v[64:67]
	v_mfma_f32_16x16x32_bf16 v[116:119], v[172:175], v[188:191], v[116:119]
	v_mfma_f32_16x16x32_bf16 v[112:115], v[180:183], v[188:191], v[112:115]
	v_mfma_f32_16x16x32_bf16 v[100:103], v[172:175], v[196:199], v[100:103]
	v_mfma_f32_16x16x32_bf16 v[92:95], v[180:183], v[196:199], v[92:95]
	v_mfma_f32_16x16x32_bf16 v[84:87], v[172:175], v[204:207], v[84:87]
	v_mfma_f32_16x16x32_bf16 v[76:79], v[180:183], v[204:207], v[76:79]
	v_mfma_f32_16x16x32_bf16 v[68:71], v[172:175], v[212:215], v[68:71]
	v_mfma_f32_16x16x32_bf16 v[64:67], v[180:183], v[212:215], v[64:67]
	v_mfma_f32_16x16x32_bf16 v[60:63], v[144:147], v[148:151], v[60:63]
	v_mfma_f32_16x16x32_bf16 v[56:59], v[160:163], v[148:151], v[56:59]
	v_mfma_f32_16x16x32_bf16 v[48:51], v[144:147], v[226:229], v[48:51]
	v_mfma_f32_16x16x32_bf16 v[40:43], v[160:163], v[226:229], v[40:43]
	v_mfma_f32_16x16x32_bf16 v[32:35], v[144:147], v[234:237], v[32:35]
	v_mfma_f32_16x16x32_bf16 v[24:27], v[160:163], v[234:237], v[24:27]
	v_mfma_f32_16x16x32_bf16 v[16:19], v[144:147], v[242:245], v[16:19]
	v_mfma_f32_16x16x32_bf16 v[8:11], v[160:163], v[242:245], v[8:11]
	v_mfma_f32_16x16x32_bf16 v[60:63], v[156:159], v[216:219], v[60:63]
	v_mfma_f32_16x16x32_bf16 v[56:59], v[164:167], v[216:219], v[56:59]
	v_mfma_f32_16x16x32_bf16 v[48:51], v[156:159], v[230:233], v[48:51]
	v_mfma_f32_16x16x32_bf16 v[40:43], v[164:167], v[230:233], v[40:43]
	v_mfma_f32_16x16x32_bf16 v[32:35], v[156:159], v[238:241], v[32:35]
	v_mfma_f32_16x16x32_bf16 v[24:27], v[164:167], v[238:241], v[24:27]
	v_mfma_f32_16x16x32_bf16 v[16:19], v[156:159], v[246:249], v[16:19]
	v_mfma_f32_16x16x32_bf16 v[8:11], v[164:167], v[246:249], v[8:11]
	v_mfma_f32_16x16x32_bf16 v[52:55], v[168:171], v[148:151], v[52:55]
	v_mfma_f32_16x16x32_bf16 v[44:47], v[176:179], v[148:151], v[44:47]
	v_mfma_f32_16x16x32_bf16 v[36:39], v[168:171], v[226:229], v[36:39]
	v_mfma_f32_16x16x32_bf16 v[28:31], v[176:179], v[226:229], v[28:31]
	v_mfma_f32_16x16x32_bf16 v[20:23], v[168:171], v[234:237], v[20:23]
	v_mfma_f32_16x16x32_bf16 v[12:15], v[176:179], v[234:237], v[12:15]
	v_mfma_f32_16x16x32_bf16 v[4:7], v[168:171], v[242:245], v[4:7]
	v_mfma_f32_16x16x32_bf16 v[0:3], v[176:179], v[242:245], v[0:3]
	v_mfma_f32_16x16x32_bf16 v[52:55], v[172:175], v[216:219], v[52:55]
	v_mfma_f32_16x16x32_bf16 v[44:47], v[180:183], v[216:219], v[44:47]
	v_mfma_f32_16x16x32_bf16 v[36:39], v[172:175], v[230:233], v[36:39]
	v_mfma_f32_16x16x32_bf16 v[28:31], v[180:183], v[230:233], v[28:31]
	v_mfma_f32_16x16x32_bf16 v[20:23], v[172:175], v[238:241], v[20:23]
	v_mfma_f32_16x16x32_bf16 v[12:15], v[180:183], v[238:241], v[12:15]
	v_mfma_f32_16x16x32_bf16 v[4:7], v[172:175], v[246:249], v[4:7]
	v_mfma_f32_16x16x32_bf16 v[0:3], v[180:183], v[246:249], v[0:3]
	s_waitcnt vmcnt(0)
	s_barrier
; #define PG8_STAGE(bufoff, gbase, voff) do { _Pragma("unroll") for (int _i = 0; _i < 2; ++_i) \
;         __builtin_amdgcn_global_load_lds((const unsigned*)((const char*)(gbase) + (voff)[_i]), (PG8_LAS unsigned*)(lds + (bufoff) + ldsw + _i * 8192), 16, 0, 0); } while (0)
; #define PG8_LDA(dst, b, h) do { _Pragma("unroll") for (int m = 0; m < 4; ++m) _Pragma("unroll") for (int k = 0; k < 2; ++k) dst[m][k] = *(const PG8_LAS bf16x8*)(lds + PG8_SA(b, h) + aoff + m * 2048 + k * 1024); } while (0)
; #define PG8_LDB(dst, b, h) do { _Pragma("unroll") for (int n = 0; n < 2; ++n) _Pragma("unroll") for (int k = 0; k < 2; ++k) dst[n][k] = *(const PG8_LAS bf16x8*)(lds + PG8_SB(b, h) + boff + n * 2048 + k * 1024); } while (0)
; #define PG8_MMA(ai, bj, At, Bt) do { __builtin_amdgcn_s_setprio(1); _Pragma("unroll") for (int m = 0; m < 4; ++m) _Pragma("unroll") for (int n = 0; n < 2; ++n) _Pragma("unroll") for (int k = 0; k < 2; ++k) \
;         acc[ai][bj][m][n] = __builtin_amdgcn_mfma_f32_16x16x32_bf16(Bt[n][k], At[m][k], acc[ai][bj][m][n], 0, 0, 0); __builtin_amdgcn_s_setprio(0); } while (0)
; #define PG8_WAIT_V(n) asm volatile("s_waitcnt vmcnt(" #n ")" ::: "memory")
; #define PG8_WAIT_L(n) asm volatile("s_waitcnt lgkmcnt(" #n ")" ::: "memory")
; #define PG8_BAR __builtin_amdgcn_s_barrier()
; #define PG8_SCHED __builtin_amdgcn_sched_barrier(0)
; template <class Epi, class Sched, bool ALIGN_EPI = false, bool SP2 = false>
; __device__ __forceinline__ void gemm_phase(PG8_LAS unsigned char* lds, const Gemm g, const Sched& S, const Epi& E) {
;     ...
;             PG8_LDB(B0, 1, 0); PG8_LDB(B1, 1, 1); PG8_SCHED; PG8_LDA(At, 1, 0); PG8_STAGE(PG8_SA(0, 1), a2 + hstep, voffA);
;             PG8_WAIT_V(8); PG8_WAIT_L(0); PG8_BAR; PG8_MMA(0, 0, At, B0); PG8_MMA(0, 1, At, B1); PG8_BAR; PG8_SCHED;
;             PG8_LDA(At, 1, 1); PG8_STAGE(PG8_SB(1, 0), b3, voffB); PG8_STAGE(PG8_SB(1, 1), b3 + hstep, voffB); PG8_STAGE(PG8_SA(1, 0), a3, voffA);
	s_setprio 0
	s_cmp_lg_u32 s18, 0
	s_cbranch_scc0 .Lspf4_b_h1
	s_add_i32 m0, s3, 0x10000
	ds_read_b128 v[144:147], v139
	ds_read_b128 v[156:159], v139 offset:1024
	ds_read_b128 v[160:163], v139 offset:2048
	global_load_lds_dwordx4 v132, s[48:49]
	s_add_i32 m0, s3, 0x12000
	ds_read_b128 v[164:167], v139 offset:3072
	ds_read_b128 v[168:171], v220
	ds_read_b128 v[172:175], v220 offset:1024
	global_load_lds_dwordx4 v128, s[48:49]
	s_add_u32 s98, s48, 0x10000
	s_addc_u32 s99, s49, 0
	s_add_i32 m0, s3, 0x11000
	ds_read_b128 v[176:179], v220 offset:2048
	ds_read_b128 v[180:183], v220 offset:3072
	ds_read_b128 v[184:187], v137 offset:32768
	global_load_lds_dwordx4 v132, s[98:99]
	s_add_i32 m0, s3, 0x13000
	ds_read_b128 v[188:191], v137 offset:33792
	ds_read_b128 v[192:195], v137 offset:34816
	ds_read_b128 v[196:199], v137 offset:35840
	global_load_lds_dwordx4 v128, s[98:99]
	s_add_u32 s98, s48, 0x40000
	s_addc_u32 s99, s49, 0
	s_add_i32 m0, s3, 0x14000
	ds_read_b128 v[200:203], v137 offset:36864
	ds_read_b128 v[204:207], v137 offset:37888
	ds_read_b128 v[208:211], v137 offset:38912
	global_load_lds_dwordx4 v132, s[98:99]
	s_add_i32 m0, s3, 0x16000
	ds_read_b128 v[212:215], v137 offset:39936
	ds_read_b128 v[148:151], v137 offset:49152
	ds_read_b128 v[216:219], v137 offset:50176
	global_load_lds_dwordx4 v128, s[98:99]
	s_add_u32 s98, s48, 0x50000
	s_addc_u32 s99, s49, 0
	s_add_i32 m0, s3, 0x15000
	ds_read_b128 v[226:229], v137 offset:51200
	ds_read_b128 v[230:233], v137 offset:52224
	ds_read_b128 v[234:237], v137 offset:53248
	global_load_lds_dwordx4 v132, s[98:99]
	s_add_i32 m0, s3, 0x17000
	ds_read_b128 v[238:241], v137 offset:54272
	ds_read_b128 v[242:245], v137 offset:55296
	ds_read_b128 v[246:249], v137 offset:56320
	global_load_lds_dwordx4 v128, s[98:99]
	s_branch .Lspf4_b_rd
.Lspf4_b_h1:
	s_add_i32 m0, s3, 0x2000
	ds_read_b128 v[144:147], v139
	ds_read_b128 v[156:159], v139 offset:1024
	ds_read_b128 v[160:163], v139 offset:2048
	global_load_lds_dwordx4 v130, s[50:51]
	s_add_u32 s98, s50, 0xffff0000
	s_addc_u32 s99, s51, -1
	s_add_i32 m0, s3, 0x1000
	ds_read_b128 v[164:167], v139 offset:3072
	ds_read_b128 v[168:171], v220
	ds_read_b128 v[172:175], v220 offset:1024
	global_load_lds_dwordx4 v130, s[98:99]
	s_add_u32 s98, s50, 0x40000
	s_addc_u32 s99, s51, 0
	s_add_i32 m0, s3, 0x6000
	ds_read_b128 v[176:179], v220 offset:2048
	ds_read_b128 v[180:183], v220 offset:3072
	ds_read_b128 v[184:187], v137 offset:32768
	global_load_lds_dwordx4 v130, s[98:99]
	s_add_u32 s98, s50, 0x30000
	s_addc_u32 s99, s51, 0
	s_add_i32 m0, s3, 0x5000
	ds_read_b128 v[188:191], v137 offset:33792
	ds_read_b128 v[192:195], v137 offset:34816
	ds_read_b128 v[196:199], v137 offset:35840
	global_load_lds_dwordx4 v130, s[98:99]
	s_add_u32 s98, s50, 0x80
	s_addc_u32 s99, s51, 0
	s_add_i32 m0, s3, 0x8000
	ds_read_b128 v[200:203], v137 offset:36864
	ds_read_b128 v[204:207], v137 offset:37888
	ds_read_b128 v[208:211], v137 offset:38912
	global_load_lds_dwordx4 v134, s[98:99]
	s_add_u32 s98, s50, 0xffff0080
	s_addc_u32 s99, s51, -1
	s_add_i32 m0, s3, 0x7000
	ds_read_b128 v[212:215], v137 offset:39936
	ds_read_b128 v[148:151], v137 offset:49152
	ds_read_b128 v[216:219], v137 offset:50176
	global_load_lds_dwordx4 v134, s[98:99]
	s_add_u32 s98, s50, 0x40080
	s_addc_u32 s99, s51, 0
	s_add_i32 m0, s3, 0xc000
	ds_read_b128 v[226:229], v137 offset:51200
	ds_read_b128 v[230:233], v137 offset:52224
	ds_read_b128 v[234:237], v137 offset:53248
	global_load_lds_dwordx4 v134, s[98:99]
	s_add_u32 s98, s50, 0x30080
	s_addc_u32 s99, s51, 0
	s_add_i32 m0, s3, 0xb000
	ds_read_b128 v[238:241], v137 offset:54272
	ds_read_b128 v[242:245], v137 offset:55296
	ds_read_b128 v[246:249], v137 offset:56320
	global_load_lds_dwordx4 v134, s[98:99]
; #define PG8_STAGE(bufoff, gbase, voff) do { _Pragma("unroll") for (int _i = 0; _i < 2; ++_i) \
;         __builtin_amdgcn_global_load_lds((const unsigned*)((const char*)(gbase) + (voff)[_i]), (PG8_LAS unsigned*)(lds + (bufoff) + ldsw + _i * 8192), 16, 0, 0); } while (0)
; #define PG8_LDA(dst, b, h) do { _Pragma("unroll") for (int m = 0; m < 4; ++m) _Pragma("unroll") for (int k = 0; k < 2; ++k) dst[m][k] = *(const PG8_LAS bf16x8*)(lds + PG8_SA(b, h) + aoff + m * 2048 + k * 1024); } while (0)
; #define PG8_LDB(dst, b, h) do { _Pragma("unroll") for (int n = 0; n < 2; ++n) _Pragma("unroll") for (int k = 0; k < 2; ++k) dst[n][k] = *(const PG8_LAS bf16x8*)(lds + PG8_SB(b, h) + boff + n * 2048 + k * 1024); } while (0)
; #define PG8_MMA(ai, bj, At, Bt) do { __builtin_amdgcn_s_setprio(1); _Pragma("unroll") for (int m = 0; m < 4; ++m) _Pragma("unroll") for (int n = 0; n < 2; ++n) _Pragma("unroll") for (int k = 0; k < 2; ++k) \
;         acc[ai][bj][m][n] = __builtin_amdgcn_mfma_f32_16x16x32_bf16(Bt[n][k], At[m][k], acc[ai][bj][m][n], 0, 0, 0); __builtin_amdgcn_s_setprio(0); } while (0)
; #define PG8_WAIT_V(n) asm volatile("s_waitcnt vmcnt(" #n ")" ::: "memory")
; #define PG8_WAIT_L(n) asm volatile("s_waitcnt lgkmcnt(" #n ")" ::: "memory")
; #define PG8_BAR __builtin_amdgcn_s_barrier()
; #define PG8_SCHED __builtin_amdgcn_sched_barrier(0)
; template <class Epi, class Sched, bool ALIGN_EPI = false, bool SP2 = false>
; __device__ __forceinline__ void gemm_phase(PG8_LAS unsigned char* lds, const Gemm g, const Sched& S, const Epi& E) {
;     ...
;         for (int t = 0; t < nt; t += 2) {
;     ...
;             PG8_LDB(B0, 1, 0); PG8_LDB(B1, 1, 1); PG8_SCHED; PG8_LDA(At, 1, 0); PG8_STAGE(PG8_SA(0, 1), a2 + hstep, voffA);
;             PG8_WAIT_V(8); PG8_WAIT_L(0); PG8_BAR; PG8_MMA(0, 0, At, B0); PG8_MMA(0, 1, At, B1); PG8_BAR; PG8_SCHED;
;             PG8_LDA(At, 1, 1); PG8_STAGE(PG8_SB(1, 0), b3, voffB); PG8_STAGE(PG8_SB(1, 1), b3 + hstep, voffB); PG8_STAGE(PG8_SA(1, 0), a3, voffA);
;             PG8_WAIT_V(8); PG8_WAIT_L(0); PG8_BAR; PG8_MMA(1, 0, At, B0); PG8_MMA(1, 1, At, B1); PG8_BAR; PG8_SCHED;
.Lspf4_b_rd:
	s_waitcnt lgkmcnt(0)
	s_setprio 1
	s_barrier
	v_mfma_f32_16x16x32_bf16 v[124:127], v[144:147], v[184:187], v[124:127]
	v_mfma_f32_16x16x32_bf16 v[120:123], v[160:163], v[184:187], v[120:123]
	v_mfma_f32_16x16x32_bf16 v[108:111], v[144:147], v[192:195], v[108:111]
	v_mfma_f32_16x16x32_bf16 v[104:107], v[160:163], v[192:195], v[104:107]
	v_mfma_f32_16x16x32_bf16 v[96:99], v[144:147], v[200:203], v[96:99]
	v_mfma_f32_16x16x32_bf16 v[88:91], v[160:163], v[200:203], v[88:91]
	v_mfma_f32_16x16x32_bf16 v[80:83], v[144:147], v[208:211], v[80:83]
	v_mfma_f32_16x16x32_bf16 v[72:75], v[160:163], v[208:211], v[72:75]
	v_mfma_f32_16x16x32_bf16 v[124:127], v[156:159], v[188:191], v[124:127]
	v_mfma_f32_16x16x32_bf16 v[120:123], v[164:167], v[188:191], v[120:123]
	v_mfma_f32_16x16x32_bf16 v[108:111], v[156:159], v[196:199], v[108:111]
	v_mfma_f32_16x16x32_bf16 v[104:107], v[164:167], v[196:199], v[104:107]
	v_mfma_f32_16x16x32_bf16 v[96:99], v[156:159], v[204:207], v[96:99]
	v_mfma_f32_16x16x32_bf16 v[88:91], v[164:167], v[204:207], v[88:91]
	v_mfma_f32_16x16x32_bf16 v[80:83], v[156:159], v[212:215], v[80:83]
	v_mfma_f32_16x16x32_bf16 v[72:75], v[164:167], v[212:215], v[72:75]
	v_mfma_f32_16x16x32_bf16 v[116:119], v[168:171], v[184:187], v[116:119]
	v_mfma_f32_16x16x32_bf16 v[112:115], v[176:179], v[184:187], v[112:115]
	v_mfma_f32_16x16x32_bf16 v[100:103], v[168:171], v[192:195], v[100:103]
	v_mfma_f32_16x16x32_bf16 v[92:95], v[176:179], v[192:195], v[92:95]
	v_mfma_f32_16x16x32_bf16 v[84:87], v[168:171], v[200:203], v[84:87]
	v_mfma_f32_16x16x32_bf16 v[76:79], v[176:179], v[200:203], v[76:79]
	v_mfma_f32_16x16x32_bf16 v[68:71], v[168:171], v[208:211], v[68:71]
	v_mfma_f32_16x16x32_bf16 v[64:67], v[176:179], v[208:211], v[64:67]
	v_mfma_f32_16x16x32_bf16 v[116:119], v[172:175], v[188:191], v[116:119]
	v_mfma_f32_16x16x32_bf16 v[112:115], v[180:183], v[188:191], v[112:115]
	v_mfma_f32_16x16x32_bf16 v[100:103], v[172:175], v[196:199], v[100:103]
	v_mfma_f32_16x16x32_bf16 v[92:95], v[180:183], v[196:199], v[92:95]
	v_mfma_f32_16x16x32_bf16 v[84:87], v[172:175], v[204:207], v[84:87]
	v_mfma_f32_16x16x32_bf16 v[76:79], v[180:183], v[204:207], v[76:79]
	v_mfma_f32_16x16x32_bf16 v[68:71], v[172:175], v[212:215], v[68:71]
	v_mfma_f32_16x16x32_bf16 v[64:67], v[180:183], v[212:215], v[64:67]
	v_mfma_f32_16x16x32_bf16 v[60:63], v[144:147], v[148:151], v[60:63]
	v_mfma_f32_16x16x32_bf16 v[56:59], v[160:163], v[148:151], v[56:59]
	v_mfma_f32_16x16x32_bf16 v[48:51], v[144:147], v[226:229], v[48:51]
	v_mfma_f32_16x16x32_bf16 v[40:43], v[160:163], v[226:229], v[40:43]
	v_mfma_f32_16x16x32_bf16 v[32:35], v[144:147], v[234:237], v[32:35]
	v_mfma_f32_16x16x32_bf16 v[24:27], v[160:163], v[234:237], v[24:27]
	v_mfma_f32_16x16x32_bf16 v[16:19], v[144:147], v[242:245], v[16:19]
	v_mfma_f32_16x16x32_bf16 v[8:11], v[160:163], v[242:245], v[8:11]
	v_mfma_f32_16x16x32_bf16 v[60:63], v[156:159], v[216:219], v[60:63]
	v_mfma_f32_16x16x32_bf16 v[56:59], v[164:167], v[216:219], v[56:59]
	v_mfma_f32_16x16x32_bf16 v[48:51], v[156:159], v[230:233], v[48:51]
	v_mfma_f32_16x16x32_bf16 v[40:43], v[164:167], v[230:233], v[40:43]
	v_mfma_f32_16x16x32_bf16 v[32:35], v[156:159], v[238:241], v[32:35]
	v_mfma_f32_16x16x32_bf16 v[24:27], v[164:167], v[238:241], v[24:27]
	v_mfma_f32_16x16x32_bf16 v[16:19], v[156:159], v[246:249], v[16:19]
	v_mfma_f32_16x16x32_bf16 v[8:11], v[164:167], v[246:249], v[8:11]
	v_mfma_f32_16x16x32_bf16 v[52:55], v[168:171], v[148:151], v[52:55]
	v_mfma_f32_16x16x32_bf16 v[44:47], v[176:179], v[148:151], v[44:47]
	v_mfma_f32_16x16x32_bf16 v[36:39], v[168:171], v[226:229], v[36:39]
	v_mfma_f32_16x16x32_bf16 v[28:31], v[176:179], v[226:229], v[28:31]
	v_mfma_f32_16x16x32_bf16 v[20:23], v[168:171], v[234:237], v[20:23]
	v_mfma_f32_16x16x32_bf16 v[12:15], v[176:179], v[234:237], v[12:15]
	v_mfma_f32_16x16x32_bf16 v[4:7], v[168:171], v[242:245], v[4:7]
	v_mfma_f32_16x16x32_bf16 v[0:3], v[176:179], v[242:245], v[0:3]
	v_mfma_f32_16x16x32_bf16 v[52:55], v[172:175], v[216:219], v[52:55]
	v_mfma_f32_16x16x32_bf16 v[44:47], v[180:183], v[216:219], v[44:47]
	v_mfma_f32_16x16x32_bf16 v[36:39], v[172:175], v[230:233], v[36:39]
	v_mfma_f32_16x16x32_bf16 v[28:31], v[180:183], v[230:233], v[28:31]
	v_mfma_f32_16x16x32_bf16 v[20:23], v[172:175], v[238:241], v[20:23]
	v_mfma_f32_16x16x32_bf16 v[12:15], v[180:183], v[238:241], v[12:15]
	v_mfma_f32_16x16x32_bf16 v[4:7], v[172:175], v[246:249], v[4:7]
	v_mfma_f32_16x16x32_bf16 v[0:3], v[180:183], v[246:249], v[0:3]
	s_waitcnt vmcnt(0)
	s_barrier
	s_setprio 0
	s_add_i32 s66, s66, 2
	s_add_u32 s46, s46, 0x100
	s_addc_u32 s47, s47, 0
	s_add_u32 s71, s71, 0x100
	s_addc_u32 s72, s72, 0
	s_cmp_gt_u32 s66, 13
	s_cbranch_scc0 .LBB0_781
	v_mov_b32_e32 v155, v137
	v_mov_b32_e32 v154, v135
	v_mov_b32_e32 v153, v133
	v_mov_b32_e32 v151, v131
	v_mov_b32_e32 v150, v129
	s_and_b64 vcc, exec, s[18:19]
	s_cbranch_vccz .LBB0_784
	s_barrier

; #define PG8_STAGE(bufoff, gbase, voff) do { _Pragma("unroll") for (int _i = 0; _i < 2; ++_i) \
;         __builtin_amdgcn_global_load_lds((const unsigned*)((const char*)(gbase) + (voff)[_i]), (PG8_LAS unsigned*)(lds + (bufoff) + ldsw + _i * 8192), 16, 0, 0); } while (0)
; #define PG8_WAIT_V(n) asm volatile("s_waitcnt vmcnt(" #n ")" ::: "memory")
; #define PG8_BAR __builtin_amdgcn_s_barrier()
; template <class Epi, class Sched, bool ALIGN_EPI = false, bool SP2 = false>
; __device__ __forceinline__ void gemm_phase(PG8_LAS unsigned char* lds, const Gemm g, const Sched& S, const Epi& E) {
;     ...
;     const int tid = tid_o, wid = __builtin_amdgcn_readfirstlane(tid >> 6), lane = tid & 63, wr = wid >> 2, wc = wid & 3, fr = lane & 15, fq = lane >> 4;
;     const int K = g.K, nt = K / BK;
;     unsigned voffA[2], voffB[2];
; #pragma unroll
;     for (int i = 0; i < 2; ++i) { int R, C; stage_rc(tid * 16 + i * 8192, R, C); const int Rb = Epi::PERM ? ((R & ~31) + perm32(R & 31)) : R;
;         voffA[i] = (unsigned)(R * K + C) * 2u; voffB[i] = (unsigned)(Rb * K + C) * 2u; }
;     const size_t kstep = (size_t)(BK * 2);
;     const size_t hstep = (size_t)HALF * K * 2;
;     const size_t tstep = 2 * hstep;
;     const unsigned ldsw = (unsigned)wid * 1024u;
;     const int aoff = lds_byte(wr * 64 + fr, fq * 8), boff = lds_byte(wc * 32 + fr, fq * 8);
;     ...
;     if constexpr (SP2) {
;         PG8_STAGE(PG8_SB(0, 0), cB, voffB); PG8_STAGE(PG8_SB(0, 1), cB + hstep, voffB); PG8_STAGE(PG8_SA(0, 0), cA, voffA); PG8_STAGE(PG8_SA(0, 1), cA + hstep, voffA);
;         if (wr == 1) PG8_BAR;
;         PG8_WAIT_V(2); PG8_BAR;
;         PG8_STAGE(PG8_SB(1, 0), cB + kstep, voffB); PG8_STAGE(PG8_SA(1, 0), cA + kstep, voffA); PG8_STAGE(PG8_SB(1, 1), cB + hstep + kstep, voffB);
;         PG8_WAIT_V(6); PG8_BAR;
.LBB0_791:
	s_lshl_b32 s10, s10, 5
	s_and_b32 s20, s10, 0x60
	s_lshl_b32 s13, s12, 13
	s_lshl_b32 s21, s20, 7
	s_add_u32 s10, s58, 0xfa03000
	s_mov_b64 s[16:17], 0x80
	s_addc_u32 s11, s59, 0
	s_add_i32 m0, s14, 0x18000
	v_lshl_add_u64 v[6:7], v[6:7], 0, s[16:17]
	s_waitcnt vmcnt(0)
	s_barrier
	global_load_lds_dwordx4 v[6:7], off
	v_lshl_add_u64 v[4:5], v[4:5], 0, s[16:17]
	s_add_i32 m0, s14, 0x1a000
	s_add_i32 s35, s14, 0x8000
	s_add_i32 s45, s14, 0xa000
	global_load_lds_dwordx4 v[4:5], off
	v_lshl_add_u64 v[0:1], v[0:1], 0, s[16:17]
	s_mov_b32 m0, s35
	s_add_u32 s18, s48, 0x40080
	global_load_lds_dwordx4 v[0:1], off
	v_lshl_add_u64 v[0:1], v[2:3], 0, s[16:17]
	s_mov_b32 m0, s45
	s_addc_u32 s19, s49, 0
	global_load_lds_dwordx4 v[0:1], off
	s_add_i32 m0, s14, 0x1c000
	v_lshl_add_u64 v[0:1], s[18:19], 0, v[156:157]
	global_load_lds_dwordx4 v[0:1], off
	v_lshl_add_u64 v[0:1], s[18:19], 0, v[152:153]
	s_add_i32 m0, s14, 0x1e000
	s_cmpk_lt_u32 s7, 0x100
	global_load_lds_dwordx4 v[0:1], off
	v_lshrrev_b32_e32 v1, 1, v9
	v_and_b32_e32 v1, 24, v1
	v_and_b32_e32 v0, 15, v9
	v_lshlrev_b32_e32 v2, 1, v1
	v_lshl_or_b32 v176, s12, 6, v0
	v_lshl_or_b32 v0, v0, 6, v2
	v_lshlrev_b32_e32 v2, 2, v9
	v_and_b32_e32 v2, 32, v2
	v_bitop3_b32 v3, v0, s13, v2 bitop3:0xde
	v_bitop3_b32 v177, v0, s21, v2 bitop3:0xde
	v_lshlrev_b32_e32 v0, 14, v13
	v_and_b32_e32 v0, 0xffff8000, v0
	v_or_b32_e32 v178, s20, v1
	v_lshl_add_u32 v0, v12, 11, v0
	v_and_b32_e32 v1, 1, v13
	v_lshl_or_b32 v0, v1, 6, v0
	v_lshl_add_u32 v160, v14, 1, v0
	v_lshlrev_b32_e32 v0, 14, v8
	v_and_b32_e32 v0, 0xffff8000, v0
	s_waitcnt vmcnt(6)
	v_lshl_add_u32 v0, v10, 11, v0
	v_and_b32_e32 v1, 1, v8
	s_cselect_b64 s[18:19], -1, 0
	v_lshl_or_b32 v0, v1, 6, v0
	s_add_i32 s68, 0, 0x10000
	s_add_i32 s69, 0, 0x14000
	s_sext_i32_i8 s70, s6
	v_mov_b32_e32 v161, v157
	v_lshl_add_u32 v162, v11, 1, v0
	v_mov_b32_e32 v163, v157
	v_mov_b64_e32 v[164:165], 0x100
	v_mov_b64_e32 v[166:167], 0xff
	v_add_u32_e32 v179, s68, v177
	v_add_u32_e32 v180, s69, v177
	v_add_u32_e32 v181, 0, v3
	s_barrier
	s_branch .LBB0_794

; #define PG8_STAGE(bufoff, gbase, voff) do { _Pragma("unroll") for (int _i = 0; _i < 2; ++_i) \
;         __builtin_amdgcn_global_load_lds((const unsigned*)((const char*)(gbase) + (voff)[_i]), (PG8_LAS unsigned*)(lds + (bufoff) + ldsw + _i * 8192), 16, 0, 0); } while (0)
; #define PG8_LDA(dst, b, h) do { _Pragma("unroll") for (int m = 0; m < 4; ++m) _Pragma("unroll") for (int k = 0; k < 2; ++k) dst[m][k] = *(const PG8_LAS bf16x8*)(lds + PG8_SA(b, h) + aoff + m * 2048 + k * 1024); } while (0)
; #define PG8_LDB(dst, b, h) do { _Pragma("unroll") for (int n = 0; n < 2; ++n) _Pragma("unroll") for (int k = 0; k < 2; ++k) dst[n][k] = *(const PG8_LAS bf16x8*)(lds + PG8_SB(b, h) + boff + n * 2048 + k * 1024); } while (0)
; template <class Epi, class Sched, bool ALIGN_EPI = false, bool SP2 = false>
; __device__ __forceinline__ void gemm_phase(PG8_LAS unsigned char* lds, const Gemm g, const Sched& S, const Epi& E) {
;     ...
;     for (;;) {
;         const bool has_next = S.next(ui + 1, nxt);
;         const char* nA = has_next ? (const char*)g.A + (size_t)nxt.pm * tstep : cA; const char* nB = has_next ? (const char*)g.Bt + (size_t)nxt.pn * tstep : cB;
;         for (int t = 0; t < nt; t += 2) {
;             const bool last = (t == nt - 2);
;             const char* a1 = cA + (size_t)(t + 1) * kstep;
;             const char* a2 = last ? nA : cA + (size_t)(t + 2) * kstep; const char* b2 = last ? nB : cB + (size_t)(t + 2) * kstep;
;             const char* a3 = a2 + kstep; const char* b3 = b2 + kstep;
;             if (last && has_next) S.a_ready(nxt);
;             if constexpr (SP2) {
;             PG8_LDB(B0, 0, 0); PG8_LDB(B1, 0, 1); PG8_SCHED; PG8_LDA(At, 0, 0); PG8_STAGE(PG8_SA(1, 1), a1 + hstep, voffA);
;             PG8_WAIT_V(8); PG8_WAIT_L(0); PG8_BAR; PG8_MMA(0, 0, At, B0); PG8_MMA(0, 1, At, B1); PG8_BAR; PG8_SCHED;
;             PG8_LDA(At, 0, 1); PG8_STAGE(PG8_SB(0, 0), b2, voffB); PG8_STAGE(PG8_SB(0, 1), b2 + hstep, voffB); PG8_STAGE(PG8_SA(0, 0), a2, voffA);
;     ...
;         if (!has_next) break;
; #pragma unroll
;         for (int a = 0; a < 2; ++a)
; #pragma unroll
;             for (int b = 0; b < 2; ++b)
; #pragma unroll
;                 for (int m = 0; m < 4; ++m)
; #pragma unroll
;                     for (int n = 0; n < 2; ++n) acc[a][b][m][n] = (f32x4){0.f, 0.f, 0.f, 0.f};
;         cur = nxt; cA = nA; cB = nB; ++ui;
.LBB0_800:
	s_ashr_i32 s29, s28, 31
	s_lshl_b64 s[12:13], s[28:29], 19
	s_add_u32 s30, s8, s12
	s_addc_u32 s31, s9, s13
	s_and_b64 s[12:13], s[6:7], exec
	s_cselect_b32 s12, s31, s47
	s_cselect_b32 s13, s30, s46
	s_ashr_i32 s21, s20, 31
	s_lshl_b64 s[42:43], s[20:21], 19
	v_readlane_b32 s50, v252, 6
	v_readlane_b32 s51, v252, 7
	s_add_u32 s42, s50, s42
	s_addc_u32 s43, s51, s43
	s_and_b64 s[50:51], s[6:7], exec
	s_cselect_b32 s21, s43, s49
	s_cselect_b32 s29, s42, s48
	s_add_u32 s46, s46, 0x40080
	s_addc_u32 s47, s47, 0
	s_add_u32 s71, s48, 0x100
	v_mov_b64_e32 v[0:1], 0
	v_mov_b64_e32 v[2:3], 0
	v_mov_b64_e32 v[4:5], 0
	v_mov_b64_e32 v[6:7], 0
	v_mov_b64_e32 v[8:9], 0
	v_mov_b64_e32 v[10:11], 0
	v_mov_b64_e32 v[12:13], 0
	v_mov_b64_e32 v[14:15], 0
	v_mov_b64_e32 v[16:17], 0
	v_mov_b64_e32 v[18:19], 0
	v_mov_b64_e32 v[20:21], 0
	v_mov_b64_e32 v[22:23], 0
	v_mov_b64_e32 v[24:25], 0
	v_mov_b64_e32 v[26:27], 0
	v_mov_b64_e32 v[28:29], 0
	v_mov_b64_e32 v[30:31], 0
	v_mov_b64_e32 v[32:33], 0
	v_mov_b64_e32 v[34:35], 0
	v_mov_b64_e32 v[36:37], 0
	v_mov_b64_e32 v[38:39], 0
	v_mov_b64_e32 v[40:41], 0
	v_mov_b64_e32 v[42:43], 0
	v_mov_b64_e32 v[44:45], 0
	v_mov_b64_e32 v[46:47], 0
	v_mov_b64_e32 v[48:49], 0
	v_mov_b64_e32 v[50:51], 0
	v_mov_b64_e32 v[52:53], 0
	v_mov_b64_e32 v[54:55], 0
	v_mov_b64_e32 v[56:57], 0
	v_mov_b64_e32 v[58:59], 0
	v_mov_b64_e32 v[60:61], 0
	v_mov_b64_e32 v[62:63], 0
	v_mov_b64_e32 v[64:65], 0
	v_mov_b64_e32 v[66:67], 0
	v_mov_b64_e32 v[68:69], 0
	v_mov_b64_e32 v[70:71], 0
	v_mov_b64_e32 v[72:73], 0
	v_mov_b64_e32 v[74:75], 0
	v_mov_b64_e32 v[76:77], 0
	v_mov_b64_e32 v[78:79], 0
	v_mov_b64_e32 v[80:81], 0
	v_mov_b64_e32 v[82:83], 0
	v_mov_b64_e32 v[84:85], 0
	v_mov_b64_e32 v[86:87], 0
	v_mov_b64_e32 v[88:89], 0
	v_mov_b64_e32 v[90:91], 0
	v_mov_b64_e32 v[92:93], 0
	v_mov_b64_e32 v[94:95], 0
	v_mov_b64_e32 v[96:97], 0
	v_mov_b64_e32 v[98:99], 0
	v_mov_b64_e32 v[100:101], 0
	v_mov_b64_e32 v[102:103], 0
	v_mov_b64_e32 v[104:105], 0
	v_mov_b64_e32 v[106:107], 0
	v_mov_b64_e32 v[108:109], 0
	v_mov_b64_e32 v[110:111], 0
	v_mov_b64_e32 v[112:113], 0
	v_mov_b64_e32 v[114:115], 0
	v_mov_b64_e32 v[116:117], 0
	v_mov_b64_e32 v[118:119], 0
	v_mov_b64_e32 v[120:121], 0
	v_mov_b64_e32 v[122:123], 0
	v_mov_b64_e32 v[124:125], 0
	v_mov_b64_e32 v[126:127], 0
	s_addc_u32 s72, s49, 0
	s_mov_b32 s66, -2
	v_mov_b32_e32 v153, v177
	v_mov_b32_e32 v155, v179
	v_mov_b32_e32 v157, v180
	v_mov_b32_e32 v159, v181
	v_add_u32_e32 v161, 0x18000, v153
	v_add_u32_e32 v163, 0x1c000, v153
	s_cmp_lg_u32 s18, 0
	s_cbranch_scc0 .Lspf5_pre
	s_add_i32 m0, s3, 0xc000
	s_nop 0
	global_load_lds_dwordx4 v160, s[46:47]
	s_add_u32 s98, s46, 0x10000
	s_addc_u32 s99, s47, 0
	s_add_i32 m0, s3, 0xd000
	s_nop 0
	global_load_lds_dwordx4 v160, s[98:99]
	s_add_u32 s98, s46, 0xfffc0000
	s_addc_u32 s99, s47, -1
	s_add_i32 m0, s3, 0x8000
	s_nop 0
	global_load_lds_dwordx4 v160, s[98:99]
	s_add_u32 s98, s46, 0xfffd0000
	s_addc_u32 s99, s47, -1
	s_add_i32 m0, s3, 0x9000
	s_nop 0
	global_load_lds_dwordx4 v160, s[98:99]
.Lspf5_pre:
.LBB0_801:
	s_add_u32 s48, s46, 0xfffc0080
	s_addc_u32 s49, s47, -1
	s_cmp_eq_u32 s66, 12
	s_cselect_b32 s51, s12, s49
	s_cselect_b32 s50, s13, s48
	s_cselect_b32 s49, s21, s72
	s_cselect_b32 s48, s29, s71
	s_cmp_lg_u32 s18, 0
	s_cbranch_scc0 .Lspf5_a_h1
	s_add_u32 s98, s71, 0xffffff80
	s_addc_u32 s99, s72, -1
	s_add_i32 m0, s3, 0x18000
	ds_read_b128 v[128:131], v155
	ds_read_b128 v[132:135], v155 offset:1024
	ds_read_b128 v[136:139], v155 offset:2048
	global_load_lds_dwordx4 v156, s[98:99]
	s_add_i32 m0, s3, 0x1a000
	ds_read_b128 v[140:143], v155 offset:3072
	ds_read_b128 v[144:147], v157
	ds_read_b128 v[148:151], v157 offset:1024
	global_load_lds_dwordx4 v152, s[98:99]
	s_add_u32 s98, s71, 0xff80
	s_addc_u32 s99, s72, 0
	s_add_i32 m0, s3, 0x19000
	ds_read_b128 v[168:171], v157 offset:2048
	ds_read_b128 v[172:175], v157 offset:3072
	ds_read_b128 v[182:185], v159
	global_load_lds_dwordx4 v156, s[98:99]
	s_add_i32 m0, s3, 0x1b000
	ds_read_b128 v[186:189], v159 offset:1024
	ds_read_b128 v[190:193], v159 offset:2048
	ds_read_b128 v[194:197], v159 offset:3072
	global_load_lds_dwordx4 v152, s[98:99]
	s_add_u32 s98, s71, 0x3ff80
	s_addc_u32 s99, s72, 0
	s_add_i32 m0, s3, 0x1c000
	ds_read_b128 v[198:201], v159 offset:4096
	ds_read_b128 v[202:205], v159 offset:5120
	ds_read_b128 v[206:209], v159 offset:6144
	global_load_lds_dwordx4 v156, s[98:99]
	s_add_i32 m0, s3, 0x1e000
	ds_read_b128 v[210:213], v159 offset:7168
	ds_read_b128 v[214:217], v159 offset:16384
	ds_read_b128 v[218:221], v159 offset:17408
	global_load_lds_dwordx4 v152, s[98:99]
	s_add_u32 s98, s71, 0x4ff80
	s_addc_u32 s99, s72, 0
	s_add_i32 m0, s3, 0x1d000
	ds_read_b128 v[226:229], v159 offset:18432
	ds_read_b128 v[230:233], v159 offset:19456
	ds_read_b128 v[234:237], v159 offset:20480
	global_load_lds_dwordx4 v156, s[98:99]
	s_add_i32 m0, s3, 0x1f000
	ds_read_b128 v[238:241], v159 offset:21504
	ds_read_b128 v[242:245], v159 offset:22528
	ds_read_b128 v[246:249], v159 offset:23552
	global_load_lds_dwordx4 v152, s[98:99]
	s_branch .Lspf5_a_rd
; #define PG8_STAGE(bufoff, gbase, voff) do { _Pragma("unroll") for (int _i = 0; _i < 2; ++_i) \
;         __builtin_amdgcn_global_load_lds((const unsigned*)((const char*)(gbase) + (voff)[_i]), (PG8_LAS unsigned*)(lds + (bufoff) + ldsw + _i * 8192), 16, 0, 0); } while (0)
; #define PG8_LDA(dst, b, h) do { _Pragma("unroll") for (int m = 0; m < 4; ++m) _Pragma("unroll") for (int k = 0; k < 2; ++k) dst[m][k] = *(const PG8_LAS bf16x8*)(lds + PG8_SA(b, h) + aoff + m * 2048 + k * 1024); } while (0)
; #define PG8_LDB(dst, b, h) do { _Pragma("unroll") for (int n = 0; n < 2; ++n) _Pragma("unroll") for (int k = 0; k < 2; ++k) dst[n][k] = *(const PG8_LAS bf16x8*)(lds + PG8_SB(b, h) + boff + n * 2048 + k * 1024); } while (0)
; #define PG8_MMA(ai, bj, At, Bt) do { __builtin_amdgcn_s_setprio(1); _Pragma("unroll") for (int m = 0; m < 4; ++m) _Pragma("unroll") for (int n = 0; n < 2; ++n) _Pragma("unroll") for (int k = 0; k < 2; ++k) \
;         acc[ai][bj][m][n] = __builtin_amdgcn_mfma_f32_16x16x32_bf16(Bt[n][k], At[m][k], acc[ai][bj][m][n], 0, 0, 0); __builtin_amdgcn_s_setprio(0); } while (0)
; #define PG8_WAIT_V(n) asm volatile("s_waitcnt vmcnt(" #n ")" ::: "memory")
; #define PG8_WAIT_L(n) asm volatile("s_waitcnt lgkmcnt(" #n ")" ::: "memory")
; #define PG8_BAR __builtin_amdgcn_s_barrier()
; #define PG8_SCHED __builtin_amdgcn_sched_barrier(0)
; template <class Epi, class Sched, bool ALIGN_EPI = false, bool SP2 = false>
; __device__ __forceinline__ void gemm_phase(PG8_LAS unsigned char* lds, const Gemm g, const Sched& S, const Epi& E) {
;     ...
;             if constexpr (SP2) {
;             PG8_LDB(B0, 0, 0); PG8_LDB(B1, 0, 1); PG8_SCHED; PG8_LDA(At, 0, 0); PG8_STAGE(PG8_SA(1, 1), a1 + hstep, voffA);
;             PG8_WAIT_V(8); PG8_WAIT_L(0); PG8_BAR; PG8_MMA(0, 0, At, B0); PG8_MMA(0, 1, At, B1); PG8_BAR; PG8_SCHED;
;             PG8_LDA(At, 0, 1); PG8_STAGE(PG8_SB(0, 0), b2, voffB); PG8_STAGE(PG8_SB(0, 1), b2 + hstep, voffB); PG8_STAGE(PG8_SA(0, 0), a2, voffA);
;             PG8_WAIT_V(8); PG8_WAIT_L(0); PG8_BAR; PG8_MMA(1, 0, At, B0); PG8_MMA(1, 1, At, B1); PG8_BAR; PG8_SCHED;
.Lspf5_a_h1:
	s_add_u32 s98, s46, 0xfffc0000
	s_addc_u32 s99, s47, -1
	s_add_i32 m0, s3, 0xa000
	ds_read_b128 v[128:131], v155
	ds_read_b128 v[132:135], v155 offset:1024
	ds_read_b128 v[136:139], v155 offset:2048
	global_load_lds_dwordx4 v162, s[98:99]
	s_add_u32 s98, s46, 0xfffb0000
	s_addc_u32 s99, s47, -1
	s_add_i32 m0, s3, 0x9000
	ds_read_b128 v[140:143], v155 offset:3072
	ds_read_b128 v[144:147], v157
	ds_read_b128 v[148:151], v157 offset:1024
	global_load_lds_dwordx4 v162, s[98:99]
	s_add_i32 m0, s3, 0xe000
	ds_read_b128 v[168:171], v157 offset:2048
	ds_read_b128 v[172:175], v157 offset:3072
	ds_read_b128 v[182:185], v159
	global_load_lds_dwordx4 v162, s[46:47]
	s_add_u32 s98, s46, 0xffff0000
	s_addc_u32 s99, s47, -1
	s_add_i32 m0, s3, 0xd000
	ds_read_b128 v[186:189], v159 offset:1024
	ds_read_b128 v[190:193], v159 offset:2048
	ds_read_b128 v[194:197], v159 offset:3072
	global_load_lds_dwordx4 v162, s[98:99]
	s_add_i32 m0, s3, 0x0
	ds_read_b128 v[198:201], v159 offset:4096
	ds_read_b128 v[202:205], v159 offset:5120
	ds_read_b128 v[206:209], v159 offset:6144
	global_load_lds_dwordx4 v158, s[50:51]
	s_add_u32 s98, s50, 0xffff0000
	s_addc_u32 s99, s51, -1
	s_add_i32 m0, s3, 0xfffff000
	ds_read_b128 v[210:213], v159 offset:7168
	ds_read_b128 v[214:217], v159 offset:16384
	ds_read_b128 v[218:221], v159 offset:17408
	global_load_lds_dwordx4 v158, s[98:99]
	s_add_u32 s98, s50, 0x40000
	s_addc_u32 s99, s51, 0
	s_add_i32 m0, s3, 0x4000
	ds_read_b128 v[226:229], v159 offset:18432
	ds_read_b128 v[230:233], v159 offset:19456
	ds_read_b128 v[234:237], v159 offset:20480
	global_load_lds_dwordx4 v158, s[98:99]
	s_add_u32 s98, s50, 0x30000
	s_addc_u32 s99, s51, 0
	s_add_i32 m0, s3, 0x3000
	ds_read_b128 v[238:241], v159 offset:21504
	ds_read_b128 v[242:245], v159 offset:22528
	ds_read_b128 v[246:249], v159 offset:23552
	global_load_lds_dwordx4 v158, s[98:99]
.Lspf5_a_rd:
	s_waitcnt lgkmcnt(0)
	s_setprio 1
	s_barrier
	v_mfma_f32_16x16x32_bf16 v[124:127], v[128:131], v[182:185], v[124:127]
	v_mfma_f32_16x16x32_bf16 v[120:123], v[136:139], v[182:185], v[120:123]
	v_mfma_f32_16x16x32_bf16 v[108:111], v[128:131], v[190:193], v[108:111]
	v_mfma_f32_16x16x32_bf16 v[104:107], v[136:139], v[190:193], v[104:107]
	v_mfma_f32_16x16x32_bf16 v[92:95], v[128:131], v[198:201], v[92:95]
	v_mfma_f32_16x16x32_bf16 v[88:91], v[136:139], v[198:201], v[88:91]
	v_mfma_f32_16x16x32_bf16 v[76:79], v[128:131], v[206:209], v[76:79]
	v_mfma_f32_16x16x32_bf16 v[72:75], v[136:139], v[206:209], v[72:75]
	v_mfma_f32_16x16x32_bf16 v[124:127], v[132:135], v[186:189], v[124:127]
	v_mfma_f32_16x16x32_bf16 v[120:123], v[140:143], v[186:189], v[120:123]
	v_mfma_f32_16x16x32_bf16 v[108:111], v[132:135], v[194:197], v[108:111]
	v_mfma_f32_16x16x32_bf16 v[104:107], v[140:143], v[194:197], v[104:107]
	v_mfma_f32_16x16x32_bf16 v[92:95], v[132:135], v[202:205], v[92:95]
	v_mfma_f32_16x16x32_bf16 v[88:91], v[140:143], v[202:205], v[88:91]
	v_mfma_f32_16x16x32_bf16 v[76:79], v[132:135], v[210:213], v[76:79]
	v_mfma_f32_16x16x32_bf16 v[72:75], v[140:143], v[210:213], v[72:75]
	v_mfma_f32_16x16x32_bf16 v[116:119], v[144:147], v[182:185], v[116:119]
	v_mfma_f32_16x16x32_bf16 v[112:115], v[168:171], v[182:185], v[112:115]
	v_mfma_f32_16x16x32_bf16 v[100:103], v[144:147], v[190:193], v[100:103]
	v_mfma_f32_16x16x32_bf16 v[96:99], v[168:171], v[190:193], v[96:99]
	v_mfma_f32_16x16x32_bf16 v[84:87], v[144:147], v[198:201], v[84:87]
	v_mfma_f32_16x16x32_bf16 v[80:83], v[168:171], v[198:201], v[80:83]
	v_mfma_f32_16x16x32_bf16 v[68:71], v[144:147], v[206:209], v[68:71]
	v_mfma_f32_16x16x32_bf16 v[64:67], v[168:171], v[206:209], v[64:67]
	v_mfma_f32_16x16x32_bf16 v[116:119], v[148:151], v[186:189], v[116:119]
	v_mfma_f32_16x16x32_bf16 v[112:115], v[172:175], v[186:189], v[112:115]
	v_mfma_f32_16x16x32_bf16 v[100:103], v[148:151], v[194:197], v[100:103]
	v_mfma_f32_16x16x32_bf16 v[96:99], v[172:175], v[194:197], v[96:99]
	v_mfma_f32_16x16x32_bf16 v[84:87], v[148:151], v[202:205], v[84:87]
	v_mfma_f32_16x16x32_bf16 v[80:83], v[172:175], v[202:205], v[80:83]
	v_mfma_f32_16x16x32_bf16 v[68:71], v[148:151], v[210:213], v[68:71]
	v_mfma_f32_16x16x32_bf16 v[64:67], v[172:175], v[210:213], v[64:67]
	v_mfma_f32_16x16x32_bf16 v[60:63], v[128:131], v[214:217], v[60:63]
	v_mfma_f32_16x16x32_bf16 v[56:59], v[136:139], v[214:217], v[56:59]
	v_mfma_f32_16x16x32_bf16 v[44:47], v[128:131], v[226:229], v[44:47]
	v_mfma_f32_16x16x32_bf16 v[40:43], v[136:139], v[226:229], v[40:43]
	v_mfma_f32_16x16x32_bf16 v[28:31], v[128:131], v[234:237], v[28:31]
	v_mfma_f32_16x16x32_bf16 v[24:27], v[136:139], v[234:237], v[24:27]
	v_mfma_f32_16x16x32_bf16 v[12:15], v[128:131], v[242:245], v[12:15]
	v_mfma_f32_16x16x32_bf16 v[8:11], v[136:139], v[242:245], v[8:11]
	v_mfma_f32_16x16x32_bf16 v[60:63], v[132:135], v[218:221], v[60:63]
	v_mfma_f32_16x16x32_bf16 v[56:59], v[140:143], v[218:221], v[56:59]
	v_mfma_f32_16x16x32_bf16 v[44:47], v[132:135], v[230:233], v[44:47]
	v_mfma_f32_16x16x32_bf16 v[40:43], v[140:143], v[230:233], v[40:43]
	v_mfma_f32_16x16x32_bf16 v[28:31], v[132:135], v[238:241], v[28:31]
	v_mfma_f32_16x16x32_bf16 v[24:27], v[140:143], v[238:241], v[24:27]
	v_mfma_f32_16x16x32_bf16 v[12:15], v[132:135], v[246:249], v[12:15]
	v_mfma_f32_16x16x32_bf16 v[8:11], v[140:143], v[246:249], v[8:11]
	v_mfma_f32_16x16x32_bf16 v[52:55], v[144:147], v[214:217], v[52:55]
	v_mfma_f32_16x16x32_bf16 v[48:51], v[168:171], v[214:217], v[48:51]
	v_mfma_f32_16x16x32_bf16 v[36:39], v[144:147], v[226:229], v[36:39]
	v_mfma_f32_16x16x32_bf16 v[32:35], v[168:171], v[226:229], v[32:35]
	v_mfma_f32_16x16x32_bf16 v[20:23], v[144:147], v[234:237], v[20:23]
	v_mfma_f32_16x16x32_bf16 v[16:19], v[168:171], v[234:237], v[16:19]
	v_mfma_f32_16x16x32_bf16 v[4:7], v[144:147], v[242:245], v[4:7]
	v_mfma_f32_16x16x32_bf16 v[0:3], v[168:171], v[242:245], v[0:3]
	v_mfma_f32_16x16x32_bf16 v[52:55], v[148:151], v[218:221], v[52:55]
	v_mfma_f32_16x16x32_bf16 v[48:51], v[172:175], v[218:221], v[48:51]
	v_mfma_f32_16x16x32_bf16 v[36:39], v[148:151], v[230:233], v[36:39]
	v_mfma_f32_16x16x32_bf16 v[32:35], v[172:175], v[230:233], v[32:35]
	v_mfma_f32_16x16x32_bf16 v[20:23], v[148:151], v[238:241], v[20:23]
	v_mfma_f32_16x16x32_bf16 v[16:19], v[172:175], v[238:241], v[16:19]
	v_mfma_f32_16x16x32_bf16 v[4:7], v[148:151], v[246:249], v[4:7]
	v_mfma_f32_16x16x32_bf16 v[0:3], v[172:175], v[246:249], v[0:3]
	s_waitcnt vmcnt(0)
	s_barrier
; #define PG8_STAGE(bufoff, gbase, voff) do { _Pragma("unroll") for (int _i = 0; _i < 2; ++_i) \
;         __builtin_amdgcn_global_load_lds((const unsigned*)((const char*)(gbase) + (voff)[_i]), (PG8_LAS unsigned*)(lds + (bufoff) + ldsw + _i * 8192), 16, 0, 0); } while (0)
; #define PG8_LDA(dst, b, h) do { _Pragma("unroll") for (int m = 0; m < 4; ++m) _Pragma("unroll") for (int k = 0; k < 2; ++k) dst[m][k] = *(const PG8_LAS bf16x8*)(lds + PG8_SA(b, h) + aoff + m * 2048 + k * 1024); } while (0)
; #define PG8_LDB(dst, b, h) do { _Pragma("unroll") for (int n = 0; n < 2; ++n) _Pragma("unroll") for (int k = 0; k < 2; ++k) dst[n][k] = *(const PG8_LAS bf16x8*)(lds + PG8_SB(b, h) + boff + n * 2048 + k * 1024); } while (0)
; #define PG8_MMA(ai, bj, At, Bt) do { __builtin_amdgcn_s_setprio(1); _Pragma("unroll") for (int m = 0; m < 4; ++m) _Pragma("unroll") for (int n = 0; n < 2; ++n) _Pragma("unroll") for (int k = 0; k < 2; ++k) \
;         acc[ai][bj][m][n] = __builtin_amdgcn_mfma_f32_16x16x32_bf16(Bt[n][k], At[m][k], acc[ai][bj][m][n], 0, 0, 0); __builtin_amdgcn_s_setprio(0); } while (0)
; #define PG8_WAIT_V(n) asm volatile("s_waitcnt vmcnt(" #n ")" ::: "memory")
; #define PG8_WAIT_L(n) asm volatile("s_waitcnt lgkmcnt(" #n ")" ::: "memory")
; #define PG8_BAR __builtin_amdgcn_s_barrier()
; #define PG8_SCHED __builtin_amdgcn_sched_barrier(0)
; template <class Epi, class Sched, bool ALIGN_EPI = false, bool SP2 = false>
; __device__ __forceinline__ void gemm_phase(PG8_LAS unsigned char* lds, const Gemm g, const Sched& S, const Epi& E) {
;     ...
;             PG8_LDB(B0, 1, 0); PG8_LDB(B1, 1, 1); PG8_SCHED; PG8_LDA(At, 1, 0); PG8_STAGE(PG8_SA(0, 1), a2 + hstep, voffA);
;             PG8_WAIT_V(8); PG8_WAIT_L(0); PG8_BAR; PG8_MMA(0, 0, At, B0); PG8_MMA(0, 1, At, B1); PG8_BAR; PG8_SCHED;
;             PG8_LDA(At, 1, 1); PG8_STAGE(PG8_SB(1, 0), b3, voffB); PG8_STAGE(PG8_SB(1, 1), b3 + hstep, voffB); PG8_STAGE(PG8_SA(1, 0), a3, voffA);
	s_setprio 0
	s_cmp_lg_u32 s18, 0
	s_cbranch_scc0 .Lspf5_b_h1
	s_add_i32 m0, s3, 0x10000
	ds_read_b128 v[128:131], v161
	ds_read_b128 v[132:135], v161 offset:1024
	ds_read_b128 v[136:139], v161 offset:2048
	global_load_lds_dwordx4 v156, s[48:49]
	s_add_i32 m0, s3, 0x12000
	ds_read_b128 v[140:143], v161 offset:3072
	ds_read_b128 v[144:147], v163
	ds_read_b128 v[148:151], v163 offset:1024
	global_load_lds_dwordx4 v152, s[48:49]
	s_add_u32 s98, s48, 0x10000
	s_addc_u32 s99, s49, 0
	s_add_i32 m0, s3, 0x11000
	ds_read_b128 v[168:171], v163 offset:2048
	ds_read_b128 v[172:175], v163 offset:3072
	ds_read_b128 v[182:185], v159 offset:32768
	global_load_lds_dwordx4 v156, s[98:99]
	s_add_i32 m0, s3, 0x13000
	ds_read_b128 v[186:189], v159 offset:33792
	ds_read_b128 v[190:193], v159 offset:34816
	ds_read_b128 v[194:197], v159 offset:35840
	global_load_lds_dwordx4 v152, s[98:99]
	s_add_u32 s98, s48, 0x40000
	s_addc_u32 s99, s49, 0
	s_add_i32 m0, s3, 0x14000
	ds_read_b128 v[198:201], v159 offset:36864
	ds_read_b128 v[202:205], v159 offset:37888
	ds_read_b128 v[206:209], v159 offset:38912
	global_load_lds_dwordx4 v156, s[98:99]
	s_add_i32 m0, s3, 0x16000
	ds_read_b128 v[210:213], v159 offset:39936
	ds_read_b128 v[214:217], v159 offset:49152
	ds_read_b128 v[218:221], v159 offset:50176
	global_load_lds_dwordx4 v152, s[98:99]
	s_add_u32 s98, s48, 0x50000
	s_addc_u32 s99, s49, 0
	s_add_i32 m0, s3, 0x15000
	ds_read_b128 v[226:229], v159 offset:51200
	ds_read_b128 v[230:233], v159 offset:52224
	ds_read_b128 v[234:237], v159 offset:53248
	global_load_lds_dwordx4 v156, s[98:99]
	s_add_i32 m0, s3, 0x17000
	ds_read_b128 v[238:241], v159 offset:54272
	ds_read_b128 v[242:245], v159 offset:55296
	ds_read_b128 v[246:249], v159 offset:56320
	global_load_lds_dwordx4 v152, s[98:99]
	s_branch .Lspf5_b_rd
.Lspf5_b_h1:
	s_add_i32 m0, s3, 0x2000
	ds_read_b128 v[128:131], v161
	ds_read_b128 v[132:135], v161 offset:1024
	ds_read_b128 v[136:139], v161 offset:2048
	global_load_lds_dwordx4 v154, s[50:51]
	s_add_u32 s98, s50, 0xffff0000
	s_addc_u32 s99, s51, -1
	s_add_i32 m0, s3, 0x1000
	ds_read_b128 v[140:143], v161 offset:3072
	ds_read_b128 v[144:147], v163
	ds_read_b128 v[148:151], v163 offset:1024
	global_load_lds_dwordx4 v154, s[98:99]
	s_add_u32 s98, s50, 0x40000
	s_addc_u32 s99, s51, 0
	s_add_i32 m0, s3, 0x6000
	ds_read_b128 v[168:171], v163 offset:2048
	ds_read_b128 v[172:175], v163 offset:3072
	ds_read_b128 v[182:185], v159 offset:32768
	global_load_lds_dwordx4 v154, s[98:99]
	s_add_u32 s98, s50, 0x30000
	s_addc_u32 s99, s51, 0
	s_add_i32 m0, s3, 0x5000
	ds_read_b128 v[186:189], v159 offset:33792
	ds_read_b128 v[190:193], v159 offset:34816
	ds_read_b128 v[194:197], v159 offset:35840
	global_load_lds_dwordx4 v154, s[98:99]
	s_add_u32 s98, s50, 0x80
	s_addc_u32 s99, s51, 0
	s_add_i32 m0, s3, 0x8000
	ds_read_b128 v[198:201], v159 offset:36864
	ds_read_b128 v[202:205], v159 offset:37888
	ds_read_b128 v[206:209], v159 offset:38912
	global_load_lds_dwordx4 v158, s[98:99]
	s_add_u32 s98, s50, 0xffff0080
	s_addc_u32 s99, s51, -1
	s_add_i32 m0, s3, 0x7000
	ds_read_b128 v[210:213], v159 offset:39936
	ds_read_b128 v[214:217], v159 offset:49152
	ds_read_b128 v[218:221], v159 offset:50176
	global_load_lds_dwordx4 v158, s[98:99]
	s_add_u32 s98, s50, 0x40080
	s_addc_u32 s99, s51, 0
	s_add_i32 m0, s3, 0xc000
	ds_read_b128 v[226:229], v159 offset:51200
	ds_read_b128 v[230:233], v159 offset:52224
	ds_read_b128 v[234:237], v159 offset:53248
	global_load_lds_dwordx4 v158, s[98:99]
	s_add_u32 s98, s50, 0x30080
	s_addc_u32 s99, s51, 0
	s_add_i32 m0, s3, 0xb000
	ds_read_b128 v[238:241], v159 offset:54272
	ds_read_b128 v[242:245], v159 offset:55296
	ds_read_b128 v[246:249], v159 offset:56320
	global_load_lds_dwordx4 v158, s[98:99]
; #define PG8_STAGE(bufoff, gbase, voff) do { _Pragma("unroll") for (int _i = 0; _i < 2; ++_i) \
;         __builtin_amdgcn_global_load_lds((const unsigned*)((const char*)(gbase) + (voff)[_i]), (PG8_LAS unsigned*)(lds + (bufoff) + ldsw + _i * 8192), 16, 0, 0); } while (0)
; #define PG8_LDA(dst, b, h) do { _Pragma("unroll") for (int m = 0; m < 4; ++m) _Pragma("unroll") for (int k = 0; k < 2; ++k) dst[m][k] = *(const PG8_LAS bf16x8*)(lds + PG8_SA(b, h) + aoff + m * 2048 + k * 1024); } while (0)
; #define PG8_LDB(dst, b, h) do { _Pragma("unroll") for (int n = 0; n < 2; ++n) _Pragma("unroll") for (int k = 0; k < 2; ++k) dst[n][k] = *(const PG8_LAS bf16x8*)(lds + PG8_SB(b, h) + boff + n * 2048 + k * 1024); } while (0)
; #define PG8_MMA(ai, bj, At, Bt) do { __builtin_amdgcn_s_setprio(1); _Pragma("unroll") for (int m = 0; m < 4; ++m) _Pragma("unroll") for (int n = 0; n < 2; ++n) _Pragma("unroll") for (int k = 0; k < 2; ++k) \
;         acc[ai][bj][m][n] = __builtin_amdgcn_mfma_f32_16x16x32_bf16(Bt[n][k], At[m][k], acc[ai][bj][m][n], 0, 0, 0); __builtin_amdgcn_s_setprio(0); } while (0)
; #define PG8_WAIT_V(n) asm volatile("s_waitcnt vmcnt(" #n ")" ::: "memory")
; #define PG8_WAIT_L(n) asm volatile("s_waitcnt lgkmcnt(" #n ")" ::: "memory")
; #define PG8_BAR __builtin_amdgcn_s_barrier()
; #define PG8_SCHED __builtin_amdgcn_sched_barrier(0)
; template <class Epi, class Sched, bool ALIGN_EPI = false, bool SP2 = false>
; __device__ __forceinline__ void gemm_phase(PG8_LAS unsigned char* lds, const Gemm g, const Sched& S, const Epi& E) {
;     ...
;         for (int t = 0; t < nt; t += 2) {
;     ...
;             PG8_LDB(B0, 1, 0); PG8_LDB(B1, 1, 1); PG8_SCHED; PG8_LDA(At, 1, 0); PG8_STAGE(PG8_SA(0, 1), a2 + hstep, voffA);
;             PG8_WAIT_V(8); PG8_WAIT_L(0); PG8_BAR; PG8_MMA(0, 0, At, B0); PG8_MMA(0, 1, At, B1); PG8_BAR; PG8_SCHED;
;             PG8_LDA(At, 1, 1); PG8_STAGE(PG8_SB(1, 0), b3, voffB); PG8_STAGE(PG8_SB(1, 1), b3 + hstep, voffB); PG8_STAGE(PG8_SA(1, 0), a3, voffA);
;             PG8_WAIT_V(8); PG8_WAIT_L(0); PG8_BAR; PG8_MMA(1, 0, At, B0); PG8_MMA(1, 1, At, B1); PG8_BAR; PG8_SCHED;
.Lspf5_b_rd:
	s_waitcnt lgkmcnt(0)
	s_setprio 1
	s_barrier
	v_mfma_f32_16x16x32_bf16 v[124:127], v[128:131], v[182:185], v[124:127]
	v_mfma_f32_16x16x32_bf16 v[120:123], v[136:139], v[182:185], v[120:123]
	v_mfma_f32_16x16x32_bf16 v[108:111], v[128:131], v[190:193], v[108:111]
	v_mfma_f32_16x16x32_bf16 v[104:107], v[136:139], v[190:193], v[104:107]
	v_mfma_f32_16x16x32_bf16 v[92:95], v[128:131], v[198:201], v[92:95]
	v_mfma_f32_16x16x32_bf16 v[88:91], v[136:139], v[198:201], v[88:91]
	v_mfma_f32_16x16x32_bf16 v[76:79], v[128:131], v[206:209], v[76:79]
	v_mfma_f32_16x16x32_bf16 v[72:75], v[136:139], v[206:209], v[72:75]
	v_mfma_f32_16x16x32_bf16 v[124:127], v[132:135], v[186:189], v[124:127]
	v_mfma_f32_16x16x32_bf16 v[120:123], v[140:143], v[186:189], v[120:123]
	v_mfma_f32_16x16x32_bf16 v[108:111], v[132:135], v[194:197], v[108:111]
	v_mfma_f32_16x16x32_bf16 v[104:107], v[140:143], v[194:197], v[104:107]
	v_mfma_f32_16x16x32_bf16 v[92:95], v[132:135], v[202:205], v[92:95]
	v_mfma_f32_16x16x32_bf16 v[88:91], v[140:143], v[202:205], v[88:91]
	v_mfma_f32_16x16x32_bf16 v[76:79], v[132:135], v[210:213], v[76:79]
	v_mfma_f32_16x16x32_bf16 v[72:75], v[140:143], v[210:213], v[72:75]
	v_mfma_f32_16x16x32_bf16 v[116:119], v[144:147], v[182:185], v[116:119]
	v_mfma_f32_16x16x32_bf16 v[112:115], v[168:171], v[182:185], v[112:115]
	v_mfma_f32_16x16x32_bf16 v[100:103], v[144:147], v[190:193], v[100:103]
	v_mfma_f32_16x16x32_bf16 v[96:99], v[168:171], v[190:193], v[96:99]
	v_mfma_f32_16x16x32_bf16 v[84:87], v[144:147], v[198:201], v[84:87]
	v_mfma_f32_16x16x32_bf16 v[80:83], v[168:171], v[198:201], v[80:83]
	v_mfma_f32_16x16x32_bf16 v[68:71], v[144:147], v[206:209], v[68:71]
	v_mfma_f32_16x16x32_bf16 v[64:67], v[168:171], v[206:209], v[64:67]
	v_mfma_f32_16x16x32_bf16 v[116:119], v[148:151], v[186:189], v[116:119]
	v_mfma_f32_16x16x32_bf16 v[112:115], v[172:175], v[186:189], v[112:115]
	v_mfma_f32_16x16x32_bf16 v[100:103], v[148:151], v[194:197], v[100:103]
	v_mfma_f32_16x16x32_bf16 v[96:99], v[172:175], v[194:197], v[96:99]
	v_mfma_f32_16x16x32_bf16 v[84:87], v[148:151], v[202:205], v[84:87]
	v_mfma_f32_16x16x32_bf16 v[80:83], v[172:175], v[202:205], v[80:83]
	v_mfma_f32_16x16x32_bf16 v[68:71], v[148:151], v[210:213], v[68:71]
	v_mfma_f32_16x16x32_bf16 v[64:67], v[172:175], v[210:213], v[64:67]
	v_mfma_f32_16x16x32_bf16 v[60:63], v[128:131], v[214:217], v[60:63]
	v_mfma_f32_16x16x32_bf16 v[56:59], v[136:139], v[214:217], v[56:59]
	v_mfma_f32_16x16x32_bf16 v[44:47], v[128:131], v[226:229], v[44:47]
	v_mfma_f32_16x16x32_bf16 v[40:43], v[136:139], v[226:229], v[40:43]
	v_mfma_f32_16x16x32_bf16 v[28:31], v[128:131], v[234:237], v[28:31]
	v_mfma_f32_16x16x32_bf16 v[24:27], v[136:139], v[234:237], v[24:27]
	v_mfma_f32_16x16x32_bf16 v[12:15], v[128:131], v[242:245], v[12:15]
	v_mfma_f32_16x16x32_bf16 v[8:11], v[136:139], v[242:245], v[8:11]
	v_mfma_f32_16x16x32_bf16 v[60:63], v[132:135], v[218:221], v[60:63]
	v_mfma_f32_16x16x32_bf16 v[56:59], v[140:143], v[218:221], v[56:59]
	v_mfma_f32_16x16x32_bf16 v[44:47], v[132:135], v[230:233], v[44:47]
	v_mfma_f32_16x16x32_bf16 v[40:43], v[140:143], v[230:233], v[40:43]
	v_mfma_f32_16x16x32_bf16 v[28:31], v[132:135], v[238:241], v[28:31]
	v_mfma_f32_16x16x32_bf16 v[24:27], v[140:143], v[238:241], v[24:27]
	v_mfma_f32_16x16x32_bf16 v[12:15], v[132:135], v[246:249], v[12:15]
	v_mfma_f32_16x16x32_bf16 v[8:11], v[140:143], v[246:249], v[8:11]
	v_mfma_f32_16x16x32_bf16 v[52:55], v[144:147], v[214:217], v[52:55]
	v_mfma_f32_16x16x32_bf16 v[48:51], v[168:171], v[214:217], v[48:51]
	v_mfma_f32_16x16x32_bf16 v[36:39], v[144:147], v[226:229], v[36:39]
	v_mfma_f32_16x16x32_bf16 v[32:35], v[168:171], v[226:229], v[32:35]
	v_mfma_f32_16x16x32_bf16 v[20:23], v[144:147], v[234:237], v[20:23]
	v_mfma_f32_16x16x32_bf16 v[16:19], v[168:171], v[234:237], v[16:19]
	v_mfma_f32_16x16x32_bf16 v[4:7], v[144:147], v[242:245], v[4:7]
	v_mfma_f32_16x16x32_bf16 v[0:3], v[168:171], v[242:245], v[0:3]
	v_mfma_f32_16x16x32_bf16 v[52:55], v[148:151], v[218:221], v[52:55]
	v_mfma_f32_16x16x32_bf16 v[48:51], v[172:175], v[218:221], v[48:51]
	v_mfma_f32_16x16x32_bf16 v[36:39], v[148:151], v[230:233], v[36:39]
	v_mfma_f32_16x16x32_bf16 v[32:35], v[172:175], v[230:233], v[32:35]
	v_mfma_f32_16x16x32_bf16 v[20:23], v[148:151], v[238:241], v[20:23]
	v_mfma_f32_16x16x32_bf16 v[16:19], v[172:175], v[238:241], v[16:19]
	v_mfma_f32_16x16x32_bf16 v[4:7], v[148:151], v[246:249], v[4:7]
	v_mfma_f32_16x16x32_bf16 v[0:3], v[172:175], v[246:249], v[0:3]
	s_waitcnt vmcnt(0)
	s_barrier
	s_setprio 0
	s_add_i32 s66, s66, 2
	s_add_u32 s46, s46, 0x100
	s_addc_u32 s47, s47, 0
	s_add_u32 s71, s71, 0x100
	s_addc_u32 s72, s72, 0
	s_cmp_gt_u32 s66, 13
	s_cbranch_scc0 .LBB0_801
	v_mov_b32_e32 v181, v159
	v_mov_b32_e32 v180, v157
	v_mov_b32_e32 v179, v155
	v_mov_b32_e32 v177, v153
	s_and_b64 vcc, exec, s[18:19]
	s_cbranch_vccz .LBB0_804
	s_barrier

; #define PG8_STAGE(bufoff, gbase, voff) do { _Pragma("unroll") for (int _i = 0; _i < 2; ++_i) \
;         __builtin_amdgcn_global_load_lds((const unsigned*)((const char*)(gbase) + (voff)[_i]), (PG8_LAS unsigned*)(lds + (bufoff) + ldsw + _i * 8192), 16, 0, 0); } while (0)
; #define PG8_WAIT_V(n) asm volatile("s_waitcnt vmcnt(" #n ")" ::: "memory")
; #define PG8_BAR __builtin_amdgcn_s_barrier()
; template <class Epi, class Sched, bool ALIGN_EPI = false, bool SP2 = false>
; __device__ __forceinline__ void gemm_phase(PG8_LAS unsigned char* lds, const Gemm g, const Sched& S, const Epi& E) {
;     ...
;     const int tid = tid_o, wid = __builtin_amdgcn_readfirstlane(tid >> 6), lane = tid & 63, wr = wid >> 2, wc = wid & 3, fr = lane & 15, fq = lane >> 4;
;     const int K = g.K, nt = K / BK;
;     unsigned voffA[2], voffB[2];
; #pragma unroll
;     for (int i = 0; i < 2; ++i) { int R, C; stage_rc(tid * 16 + i * 8192, R, C); const int Rb = Epi::PERM ? ((R & ~31) + perm32(R & 31)) : R;
;         voffA[i] = (unsigned)(R * K + C) * 2u; voffB[i] = (unsigned)(Rb * K + C) * 2u; }
;     const size_t kstep = (size_t)(BK * 2);
;     const size_t hstep = (size_t)HALF * K * 2;
;     const size_t tstep = 2 * hstep;
;     const unsigned ldsw = (unsigned)wid * 1024u;
;     const int aoff = lds_byte(wr * 64 + fr, fq * 8), boff = lds_byte(wc * 32 + fr, fq * 8);
;     ...
;     if constexpr (SP2) {
;         PG8_STAGE(PG8_SB(0, 0), cB, voffB); PG8_STAGE(PG8_SB(0, 1), cB + hstep, voffB); PG8_STAGE(PG8_SA(0, 0), cA, voffA); PG8_STAGE(PG8_SA(0, 1), cA + hstep, voffA);
;         if (wr == 1) PG8_BAR;
;         PG8_WAIT_V(2); PG8_BAR;
;         PG8_STAGE(PG8_SB(1, 0), cB + kstep, voffB); PG8_STAGE(PG8_SA(1, 0), cA + kstep, voffA); PG8_STAGE(PG8_SB(1, 1), cB + hstep + kstep, voffB);
;         PG8_WAIT_V(6); PG8_BAR;
.LBB0_866:
	s_mov_b64 s[20:21], 0x80
	s_and_b32 s34, s7, 3
	s_add_i32 m0, s14, 0x18000
	v_lshl_add_u64 v[6:7], v[6:7], 0, s[20:21]
	s_lshl_b32 s7, s8, 13
	s_lshl_b32 s9, s34, 12
	s_waitcnt vmcnt(0)
	s_barrier
	global_load_lds_dwordx4 v[6:7], off
	v_lshl_add_u64 v[4:5], v[4:5], 0, s[20:21]
	s_add_i32 m0, s14, 0x1a000
	s_add_i32 s35, s14, 0x8000
	s_add_i32 s68, s14, 0xa000
	global_load_lds_dwordx4 v[4:5], off
	v_lshl_add_u64 v[0:1], v[0:1], 0, s[20:21]
	s_mov_b32 m0, s35
	s_add_u32 s12, s48, 0x80080
	global_load_lds_dwordx4 v[0:1], off
	v_lshl_add_u64 v[0:1], v[2:3], 0, s[20:21]
	s_mov_b32 m0, s68
	s_addc_u32 s13, s49, 0
	global_load_lds_dwordx4 v[0:1], off
	s_add_i32 m0, s14, 0x1c000
	v_lshl_add_u64 v[0:1], s[12:13], 0, v[188:189]
	global_load_lds_dwordx4 v[0:1], off
	v_lshl_add_u64 v[0:1], s[12:13], 0, v[190:191]
	s_add_i32 m0, s14, 0x1e000
	s_cmpk_lt_u32 s6, 0x100
	global_load_lds_dwordx4 v[0:1], off
	v_bfe_u32 v0, v8, 4, 2
	v_and_b32_e32 v1, 15, v8
	v_lshlrev_b32_e32 v2, 4, v0
	v_lshl_or_b32 v225, s8, 6, v1
	v_lshl_or_b32 v1, v1, 6, v2
	v_lshlrev_b32_e32 v2, 2, v8
	v_and_b32_e32 v2, 32, v2
	v_bitop3_b32 v3, v1, s7, v2 bitop3:0xde
	v_bitop3_b32 v226, v1, s9, v2 bitop3:0xde
	v_lshlrev_b32_e32 v1, 2, v0
	v_cmp_eq_u32_e64 s[6:7], 0, v0
	v_lshlrev_b32_e32 v0, 14, v9
	v_and_b32_e32 v0, 0x7fff8000, v0
	v_lshl_add_u32 v0, v10, 11, v0
	v_or_b32_e32 v0, v0, v11
	s_mov_b64 s[8:9], 0x80080
	v_lshl_or_b32 v227, s34, 5, v1
	v_add_lshl_u32 v0, v0, v12, 1
	v_mov_b32_e32 v1, v189
	v_lshl_add_u64 v[192:193], v[0:1], 0, s[8:9]
	v_lshlrev_b32_e32 v0, 14, v13
	v_and_b32_e32 v0, 0x7fff8000, v0
	v_lshl_add_u32 v0, v14, 11, v0
	s_waitcnt vmcnt(6)
	v_or_b32_e32 v0, v0, v15
	s_cselect_b64 s[26:27], -1, 0
	v_add_lshl_u32 v0, v0, v16, 1
	s_add_i32 s69, 0, 0x10000
	s_add_i32 s70, 0, 0x14000
	v_lshl_add_u64 v[194:195], v[0:1], 0, s[8:9]
	v_mov_b64_e32 v[196:197], 0x100
	v_mov_b64_e32 v[198:199], 0xff
	v_add_u32_e32 v228, s69, v226
	v_add_u32_e32 v229, s70, v226
	v_add_u32_e32 v230, 0, v3
	s_mov_b32 s71, 0
	s_barrier
	s_branch .LBB0_869

; #define PG8_STAGE(bufoff, gbase, voff) do { _Pragma("unroll") for (int _i = 0; _i < 2; ++_i) \
;         __builtin_amdgcn_global_load_lds((const unsigned*)((const char*)(gbase) + (voff)[_i]), (PG8_LAS unsigned*)(lds + (bufoff) + ldsw + _i * 8192), 16, 0, 0); } while (0)
; #define PG8_LDA(dst, b, h) do { _Pragma("unroll") for (int m = 0; m < 4; ++m) _Pragma("unroll") for (int k = 0; k < 2; ++k) dst[m][k] = *(const PG8_LAS bf16x8*)(lds + PG8_SA(b, h) + aoff + m * 2048 + k * 1024); } while (0)
; #define PG8_LDB(dst, b, h) do { _Pragma("unroll") for (int n = 0; n < 2; ++n) _Pragma("unroll") for (int k = 0; k < 2; ++k) dst[n][k] = *(const PG8_LAS bf16x8*)(lds + PG8_SB(b, h) + boff + n * 2048 + k * 1024); } while (0)
; template <class Epi, class Sched, bool ALIGN_EPI = false, bool SP2 = false>
; __device__ __forceinline__ void gemm_phase(PG8_LAS unsigned char* lds, const Gemm g, const Sched& S, const Epi& E) {
;     ...
;     for (;;) {
;         const bool has_next = S.next(ui + 1, nxt);
;         const char* nA = has_next ? (const char*)g.A + (size_t)nxt.pm * tstep : cA; const char* nB = has_next ? (const char*)g.Bt + (size_t)nxt.pn * tstep : cB;
;         for (int t = 0; t < nt; t += 2) {
;             const bool last = (t == nt - 2);
;             const char* a1 = cA + (size_t)(t + 1) * kstep;
;             const char* a2 = last ? nA : cA + (size_t)(t + 2) * kstep; const char* b2 = last ? nB : cB + (size_t)(t + 2) * kstep;
;             const char* a3 = a2 + kstep; const char* b3 = b2 + kstep;
;             if (last && has_next) S.a_ready(nxt);
;             if constexpr (SP2) {
;             PG8_LDB(B0, 0, 0); PG8_LDB(B1, 0, 1); PG8_SCHED; PG8_LDA(At, 0, 0); PG8_STAGE(PG8_SA(1, 1), a1 + hstep, voffA);
;             PG8_WAIT_V(8); PG8_WAIT_L(0); PG8_BAR; PG8_MMA(0, 0, At, B0); PG8_MMA(0, 1, At, B1); PG8_BAR; PG8_SCHED;
;             PG8_LDA(At, 0, 1); PG8_STAGE(PG8_SB(0, 0), b2, voffB); PG8_STAGE(PG8_SB(0, 1), b2 + hstep, voffB); PG8_STAGE(PG8_SA(0, 0), a2, voffA);
;     ...
;         if (!has_next) break;
; #pragma unroll
;         for (int a = 0; a < 2; ++a)
; #pragma unroll
;             for (int b = 0; b < 2; ++b)
; #pragma unroll
;                 for (int m = 0; m < 4; ++m)
; #pragma unroll
;                     for (int n = 0; n < 2; ++n) acc[a][b][m][n] = (f32x4){0.f, 0.f, 0.f, 0.f};
;         cur = nxt; cA = nA; cB = nB; ++ui;
.LBB0_875:
	s_ashr_i32 s31, s30, 31
	s_lshl_b64 s[12:13], s[30:31], 20
	s_add_u32 s42, s36, s12
	s_addc_u32 s43, s37, s13
	s_and_b64 s[12:13], s[8:9], exec
	s_cselect_b32 s11, s43, s47
	s_cselect_b32 s12, s42, s46
	s_ashr_i32 s29, s28, 31
	s_lshl_b64 s[44:45], s[28:29], 20
	v_readlane_b32 s50, v252, 8
	v_readlane_b32 s51, v252, 9
	s_add_u32 s44, s50, s44
	s_addc_u32 s45, s51, s45
	s_and_b64 s[50:51], s[8:9], exec
	s_cselect_b32 s13, s45, s49
	s_cselect_b32 s29, s44, s48
	s_add_u32 s31, s48, 0x100
	v_mov_b64_e32 v[0:1], 0
	v_mov_b64_e32 v[2:3], 0
	v_mov_b64_e32 v[4:5], 0
	v_mov_b64_e32 v[6:7], 0
	v_mov_b64_e32 v[8:9], 0
	v_mov_b64_e32 v[10:11], 0
	v_mov_b64_e32 v[12:13], 0
	v_mov_b64_e32 v[14:15], 0
	v_mov_b64_e32 v[16:17], 0
	v_mov_b64_e32 v[18:19], 0
	v_mov_b64_e32 v[20:21], 0
	v_mov_b64_e32 v[22:23], 0
	v_mov_b64_e32 v[24:25], 0
	v_mov_b64_e32 v[26:27], 0
	v_mov_b64_e32 v[28:29], 0
	v_mov_b64_e32 v[30:31], 0
	v_mov_b64_e32 v[32:33], 0
	v_mov_b64_e32 v[34:35], 0
	v_mov_b64_e32 v[36:37], 0
	v_mov_b64_e32 v[38:39], 0
	v_mov_b64_e32 v[40:41], 0
	v_mov_b64_e32 v[42:43], 0
	v_mov_b64_e32 v[44:45], 0
	v_mov_b64_e32 v[46:47], 0
	v_mov_b64_e32 v[48:49], 0
	v_mov_b64_e32 v[50:51], 0
	v_mov_b64_e32 v[52:53], 0
	v_mov_b64_e32 v[54:55], 0
	v_mov_b64_e32 v[56:57], 0
	v_mov_b64_e32 v[58:59], 0
	v_mov_b64_e32 v[60:61], 0
	v_mov_b64_e32 v[62:63], 0
	v_mov_b64_e32 v[64:65], 0
	v_mov_b64_e32 v[66:67], 0
	v_mov_b64_e32 v[68:69], 0
	v_mov_b64_e32 v[70:71], 0
	v_mov_b64_e32 v[72:73], 0
	v_mov_b64_e32 v[74:75], 0
	v_mov_b64_e32 v[76:77], 0
	v_mov_b64_e32 v[78:79], 0
	v_mov_b64_e32 v[80:81], 0
	v_mov_b64_e32 v[82:83], 0
	v_mov_b64_e32 v[84:85], 0
	v_mov_b64_e32 v[86:87], 0
	v_mov_b64_e32 v[88:89], 0
	v_mov_b64_e32 v[90:91], 0
	v_mov_b64_e32 v[92:93], 0
	v_mov_b64_e32 v[94:95], 0
	v_mov_b64_e32 v[96:97], 0
	v_mov_b64_e32 v[98:99], 0
	v_mov_b64_e32 v[100:101], 0
	v_mov_b64_e32 v[102:103], 0
	v_mov_b64_e32 v[104:105], 0
	v_mov_b64_e32 v[106:107], 0
	v_mov_b64_e32 v[108:109], 0
	v_mov_b64_e32 v[110:111], 0
	v_mov_b64_e32 v[112:113], 0
	v_mov_b64_e32 v[114:115], 0
	v_mov_b64_e32 v[116:117], 0
	v_mov_b64_e32 v[118:119], 0
	v_mov_b64_e32 v[120:121], 0
	v_mov_b64_e32 v[122:123], 0
	v_mov_b64_e32 v[124:125], 0
	v_mov_b64_e32 v[126:127], 0
	s_addc_u32 s72, s49, 0
	s_mov_b32 s66, -2
	s_waitcnt lgkmcnt(0)
	v_mov_b32_e32 v189, v226
	v_mov_b32_e32 v191, v228
	v_mov_b32_e32 v193, v229
	v_mov_b32_e32 v195, v230
	v_add_u32_e32 v220, 0x18000, v189
	v_add_u32_e32 v221, 0x1c000, v189
	s_cmp_lg_u32 s26, 0
	s_cbranch_scc0 .Lspf6_pre
	s_add_i32 m0, s3, 0xc000
	s_nop 0
	global_load_lds_dwordx4 v192, s[46:47]
	s_add_u32 s98, s46, 0x20000
	s_addc_u32 s99, s47, 0
	s_add_i32 m0, s3, 0xd000
	s_nop 0
	global_load_lds_dwordx4 v192, s[98:99]
	s_add_u32 s98, s46, 0xfff80000
	s_addc_u32 s99, s47, -1
	s_add_i32 m0, s3, 0x8000
	s_nop 0
	global_load_lds_dwordx4 v192, s[98:99]
	s_add_u32 s98, s46, 0xfffa0000
	s_addc_u32 s99, s47, -1
	s_add_i32 m0, s3, 0x9000
	s_nop 0
	global_load_lds_dwordx4 v192, s[98:99]
.Lspf6_pre:
.LBB0_876:
	s_add_u32 s48, s46, 0x100
	s_addc_u32 s49, s47, 0
	s_cmp_eq_u32 s66, 28
	s_cselect_b32 s75, s11, s49
	s_cselect_b32 s74, s12, s48
	s_cselect_b32 s51, s13, s72
	s_cselect_b32 s50, s29, s31
	s_cmp_lg_u32 s26, 0
	s_cbranch_scc0 .Lspf6_a_h1
	s_add_u32 s98, s31, 0xffffff80
	s_addc_u32 s99, s72, -1
	s_add_i32 m0, s3, 0x18000
	ds_read_b128 v[128:131], v191
	ds_read_b128 v[132:135], v191 offset:1024
	ds_read_b128 v[136:139], v191 offset:2048
	global_load_lds_dwordx4 v188, s[98:99]
	s_add_i32 m0, s3, 0x1a000
	ds_read_b128 v[140:143], v191 offset:3072
	ds_read_b128 v[144:147], v193
	ds_read_b128 v[148:151], v193 offset:1024
	global_load_lds_dwordx4 v190, s[98:99]
	s_add_u32 s98, s31, 0x1ff80
	s_addc_u32 s99, s72, 0
	s_add_i32 m0, s3, 0x19000
	ds_read_b128 v[152:155], v193 offset:2048
	ds_read_b128 v[156:159], v193 offset:3072
	ds_read_b128 v[160:163], v195
	global_load_lds_dwordx4 v188, s[98:99]
	s_add_i32 m0, s3, 0x1b000
	ds_read_b128 v[164:167], v195 offset:1024
	ds_read_b128 v[168:171], v195 offset:2048
	ds_read_b128 v[172:175], v195 offset:3072
	global_load_lds_dwordx4 v190, s[98:99]
	s_add_u32 s98, s31, 0x7ff80
	s_addc_u32 s99, s72, 0
	s_add_i32 m0, s3, 0x1c000
	ds_read_b128 v[176:179], v195 offset:4096
	ds_read_b128 v[180:183], v195 offset:5120
	ds_read_b128 v[184:187], v195 offset:6144
	global_load_lds_dwordx4 v188, s[98:99]
	s_add_i32 m0, s3, 0x1e000
	ds_read_b128 v[200:203], v195 offset:7168
	ds_read_b128 v[204:207], v195 offset:16384
	ds_read_b128 v[208:211], v195 offset:17408
	global_load_lds_dwordx4 v190, s[98:99]
	s_add_u32 s98, s31, 0x9ff80
	s_addc_u32 s99, s72, 0
	s_add_i32 m0, s3, 0x1d000
	ds_read_b128 v[212:215], v195 offset:18432
	ds_read_b128 v[216:219], v195 offset:19456
	ds_read_b128 v[228:231], v195 offset:20480
	global_load_lds_dwordx4 v188, s[98:99]
	s_add_i32 m0, s3, 0x1f000
	ds_read_b128 v[232:235], v195 offset:21504
	ds_read_b128 v[236:239], v195 offset:22528
	ds_read_b128 v[240:243], v195 offset:23552
	global_load_lds_dwordx4 v190, s[98:99]
	s_branch .Lspf6_a_rd
; #define PG8_STAGE(bufoff, gbase, voff) do { _Pragma("unroll") for (int _i = 0; _i < 2; ++_i) \
;         __builtin_amdgcn_global_load_lds((const unsigned*)((const char*)(gbase) + (voff)[_i]), (PG8_LAS unsigned*)(lds + (bufoff) + ldsw + _i * 8192), 16, 0, 0); } while (0)
; #define PG8_LDA(dst, b, h) do { _Pragma("unroll") for (int m = 0; m < 4; ++m) _Pragma("unroll") for (int k = 0; k < 2; ++k) dst[m][k] = *(const PG8_LAS bf16x8*)(lds + PG8_SA(b, h) + aoff + m * 2048 + k * 1024); } while (0)
; #define PG8_LDB(dst, b, h) do { _Pragma("unroll") for (int n = 0; n < 2; ++n) _Pragma("unroll") for (int k = 0; k < 2; ++k) dst[n][k] = *(const PG8_LAS bf16x8*)(lds + PG8_SB(b, h) + boff + n * 2048 + k * 1024); } while (0)
; #define PG8_MMA(ai, bj, At, Bt) do { __builtin_amdgcn_s_setprio(1); _Pragma("unroll") for (int m = 0; m < 4; ++m) _Pragma("unroll") for (int n = 0; n < 2; ++n) _Pragma("unroll") for (int k = 0; k < 2; ++k) \
;         acc[ai][bj][m][n] = __builtin_amdgcn_mfma_f32_16x16x32_bf16(Bt[n][k], At[m][k], acc[ai][bj][m][n], 0, 0, 0); __builtin_amdgcn_s_setprio(0); } while (0)
; #define PG8_WAIT_V(n) asm volatile("s_waitcnt vmcnt(" #n ")" ::: "memory")
; #define PG8_WAIT_L(n) asm volatile("s_waitcnt lgkmcnt(" #n ")" ::: "memory")
; #define PG8_BAR __builtin_amdgcn_s_barrier()
; #define PG8_SCHED __builtin_amdgcn_sched_barrier(0)
; template <class Epi, class Sched, bool ALIGN_EPI = false, bool SP2 = false>
; __device__ __forceinline__ void gemm_phase(PG8_LAS unsigned char* lds, const Gemm g, const Sched& S, const Epi& E) {
;     ...
;             if constexpr (SP2) {
;             PG8_LDB(B0, 0, 0); PG8_LDB(B1, 0, 1); PG8_SCHED; PG8_LDA(At, 0, 0); PG8_STAGE(PG8_SA(1, 1), a1 + hstep, voffA);
;             PG8_WAIT_V(8); PG8_WAIT_L(0); PG8_BAR; PG8_MMA(0, 0, At, B0); PG8_MMA(0, 1, At, B1); PG8_BAR; PG8_SCHED;
;             PG8_LDA(At, 0, 1); PG8_STAGE(PG8_SB(0, 0), b2, voffB); PG8_STAGE(PG8_SB(0, 1), b2 + hstep, voffB); PG8_STAGE(PG8_SA(0, 0), a2, voffA);
;             PG8_WAIT_V(8); PG8_WAIT_L(0); PG8_BAR; PG8_MMA(1, 0, At, B0); PG8_MMA(1, 1, At, B1); PG8_BAR; PG8_SCHED;
.Lspf6_a_h1:
	s_add_u32 s98, s46, 0xfff80000
	s_addc_u32 s99, s47, -1
	s_add_i32 m0, s3, 0xa000
	ds_read_b128 v[128:131], v191
	ds_read_b128 v[132:135], v191 offset:1024
	ds_read_b128 v[136:139], v191 offset:2048
	global_load_lds_dwordx4 v194, s[98:99]
	s_add_u32 s98, s46, 0xfff60000
	s_addc_u32 s99, s47, -1
	s_add_i32 m0, s3, 0x9000
	ds_read_b128 v[140:143], v191 offset:3072
	ds_read_b128 v[144:147], v193
	ds_read_b128 v[148:151], v193 offset:1024
	global_load_lds_dwordx4 v194, s[98:99]
	s_add_i32 m0, s3, 0xe000
	ds_read_b128 v[152:155], v193 offset:2048
	ds_read_b128 v[156:159], v193 offset:3072
	ds_read_b128 v[160:163], v195
	global_load_lds_dwordx4 v194, s[46:47]
	s_add_u32 s98, s46, 0xfffe0000
	s_addc_u32 s99, s47, -1
	s_add_i32 m0, s3, 0xd000
	ds_read_b128 v[164:167], v195 offset:1024
	ds_read_b128 v[168:171], v195 offset:2048
	ds_read_b128 v[172:175], v195 offset:3072
	global_load_lds_dwordx4 v194, s[98:99]
	s_add_i32 m0, s3, 0x0
	ds_read_b128 v[176:179], v195 offset:4096
	ds_read_b128 v[180:183], v195 offset:5120
	ds_read_b128 v[184:187], v195 offset:6144
	global_load_lds_dwordx4 v188, s[74:75]
	s_add_u32 s98, s74, 0xfffe0000
	s_addc_u32 s99, s75, -1
	s_add_i32 m0, s3, 0xfffff000
	ds_read_b128 v[200:203], v195 offset:7168
	ds_read_b128 v[204:207], v195 offset:16384
	ds_read_b128 v[208:211], v195 offset:17408
	global_load_lds_dwordx4 v188, s[98:99]
	s_add_u32 s98, s74, 0x80000
	s_addc_u32 s99, s75, 0
	s_add_i32 m0, s3, 0x4000
	ds_read_b128 v[212:215], v195 offset:18432
	ds_read_b128 v[216:219], v195 offset:19456
	ds_read_b128 v[228:231], v195 offset:20480
	global_load_lds_dwordx4 v188, s[98:99]
	s_add_u32 s98, s74, 0x60000
	s_addc_u32 s99, s75, 0
	s_add_i32 m0, s3, 0x3000
	ds_read_b128 v[232:235], v195 offset:21504
	ds_read_b128 v[236:239], v195 offset:22528
	ds_read_b128 v[240:243], v195 offset:23552
	global_load_lds_dwordx4 v188, s[98:99]
.Lspf6_a_rd:
	s_waitcnt lgkmcnt(0)
	s_setprio 1
	s_barrier
	v_mfma_f32_16x16x32_bf16 v[124:127], v[128:131], v[160:163], v[124:127]
	v_mfma_f32_16x16x32_bf16 v[120:123], v[136:139], v[160:163], v[120:123]
	v_mfma_f32_16x16x32_bf16 v[108:111], v[128:131], v[168:171], v[108:111]
	v_mfma_f32_16x16x32_bf16 v[104:107], v[136:139], v[168:171], v[104:107]
	v_mfma_f32_16x16x32_bf16 v[92:95], v[128:131], v[176:179], v[92:95]
	v_mfma_f32_16x16x32_bf16 v[88:91], v[136:139], v[176:179], v[88:91]
	v_mfma_f32_16x16x32_bf16 v[76:79], v[128:131], v[184:187], v[76:79]
	v_mfma_f32_16x16x32_bf16 v[72:75], v[136:139], v[184:187], v[72:75]
	v_mfma_f32_16x16x32_bf16 v[124:127], v[132:135], v[164:167], v[124:127]
	v_mfma_f32_16x16x32_bf16 v[120:123], v[140:143], v[164:167], v[120:123]
	v_mfma_f32_16x16x32_bf16 v[108:111], v[132:135], v[172:175], v[108:111]
	v_mfma_f32_16x16x32_bf16 v[104:107], v[140:143], v[172:175], v[104:107]
	v_mfma_f32_16x16x32_bf16 v[92:95], v[132:135], v[180:183], v[92:95]
	v_mfma_f32_16x16x32_bf16 v[88:91], v[140:143], v[180:183], v[88:91]
	v_mfma_f32_16x16x32_bf16 v[76:79], v[132:135], v[200:203], v[76:79]
	v_mfma_f32_16x16x32_bf16 v[72:75], v[140:143], v[200:203], v[72:75]
	v_mfma_f32_16x16x32_bf16 v[116:119], v[144:147], v[160:163], v[116:119]
	v_mfma_f32_16x16x32_bf16 v[112:115], v[152:155], v[160:163], v[112:115]
	v_mfma_f32_16x16x32_bf16 v[100:103], v[144:147], v[168:171], v[100:103]
	v_mfma_f32_16x16x32_bf16 v[96:99], v[152:155], v[168:171], v[96:99]
	v_mfma_f32_16x16x32_bf16 v[84:87], v[144:147], v[176:179], v[84:87]
	v_mfma_f32_16x16x32_bf16 v[80:83], v[152:155], v[176:179], v[80:83]
	v_mfma_f32_16x16x32_bf16 v[68:71], v[144:147], v[184:187], v[68:71]
	v_mfma_f32_16x16x32_bf16 v[64:67], v[152:155], v[184:187], v[64:67]
	v_mfma_f32_16x16x32_bf16 v[116:119], v[148:151], v[164:167], v[116:119]
	v_mfma_f32_16x16x32_bf16 v[112:115], v[156:159], v[164:167], v[112:115]
	v_mfma_f32_16x16x32_bf16 v[100:103], v[148:151], v[172:175], v[100:103]
	v_mfma_f32_16x16x32_bf16 v[96:99], v[156:159], v[172:175], v[96:99]
	v_mfma_f32_16x16x32_bf16 v[84:87], v[148:151], v[180:183], v[84:87]
	v_mfma_f32_16x16x32_bf16 v[80:83], v[156:159], v[180:183], v[80:83]
	v_mfma_f32_16x16x32_bf16 v[68:71], v[148:151], v[200:203], v[68:71]
	v_mfma_f32_16x16x32_bf16 v[64:67], v[156:159], v[200:203], v[64:67]
	v_mfma_f32_16x16x32_bf16 v[60:63], v[128:131], v[204:207], v[60:63]
	v_mfma_f32_16x16x32_bf16 v[56:59], v[136:139], v[204:207], v[56:59]
	v_mfma_f32_16x16x32_bf16 v[44:47], v[128:131], v[212:215], v[44:47]
	v_mfma_f32_16x16x32_bf16 v[40:43], v[136:139], v[212:215], v[40:43]
	v_mfma_f32_16x16x32_bf16 v[28:31], v[128:131], v[228:231], v[28:31]
	v_mfma_f32_16x16x32_bf16 v[24:27], v[136:139], v[228:231], v[24:27]
	v_mfma_f32_16x16x32_bf16 v[12:15], v[128:131], v[236:239], v[12:15]
	v_mfma_f32_16x16x32_bf16 v[8:11], v[136:139], v[236:239], v[8:11]
	v_mfma_f32_16x16x32_bf16 v[60:63], v[132:135], v[208:211], v[60:63]
	v_mfma_f32_16x16x32_bf16 v[56:59], v[140:143], v[208:211], v[56:59]
	v_mfma_f32_16x16x32_bf16 v[44:47], v[132:135], v[216:219], v[44:47]
	v_mfma_f32_16x16x32_bf16 v[40:43], v[140:143], v[216:219], v[40:43]
	v_mfma_f32_16x16x32_bf16 v[28:31], v[132:135], v[232:235], v[28:31]
	v_mfma_f32_16x16x32_bf16 v[24:27], v[140:143], v[232:235], v[24:27]
	v_mfma_f32_16x16x32_bf16 v[12:15], v[132:135], v[240:243], v[12:15]
	v_mfma_f32_16x16x32_bf16 v[8:11], v[140:143], v[240:243], v[8:11]
	v_mfma_f32_16x16x32_bf16 v[52:55], v[144:147], v[204:207], v[52:55]
	v_mfma_f32_16x16x32_bf16 v[48:51], v[152:155], v[204:207], v[48:51]
	v_mfma_f32_16x16x32_bf16 v[36:39], v[144:147], v[212:215], v[36:39]
	v_mfma_f32_16x16x32_bf16 v[32:35], v[152:155], v[212:215], v[32:35]
	v_mfma_f32_16x16x32_bf16 v[20:23], v[144:147], v[228:231], v[20:23]
	v_mfma_f32_16x16x32_bf16 v[16:19], v[152:155], v[228:231], v[16:19]
	v_mfma_f32_16x16x32_bf16 v[4:7], v[144:147], v[236:239], v[4:7]
	v_mfma_f32_16x16x32_bf16 v[0:3], v[152:155], v[236:239], v[0:3]
	v_mfma_f32_16x16x32_bf16 v[52:55], v[148:151], v[208:211], v[52:55]
	v_mfma_f32_16x16x32_bf16 v[48:51], v[156:159], v[208:211], v[48:51]
	v_mfma_f32_16x16x32_bf16 v[36:39], v[148:151], v[216:219], v[36:39]
	v_mfma_f32_16x16x32_bf16 v[32:35], v[156:159], v[216:219], v[32:35]
	v_mfma_f32_16x16x32_bf16 v[20:23], v[148:151], v[232:235], v[20:23]
	v_mfma_f32_16x16x32_bf16 v[16:19], v[156:159], v[232:235], v[16:19]
	v_mfma_f32_16x16x32_bf16 v[4:7], v[148:151], v[240:243], v[4:7]
	v_mfma_f32_16x16x32_bf16 v[0:3], v[156:159], v[240:243], v[0:3]
	s_waitcnt vmcnt(0)
	s_barrier
; #define PG8_STAGE(bufoff, gbase, voff) do { _Pragma("unroll") for (int _i = 0; _i < 2; ++_i) \
;         __builtin_amdgcn_global_load_lds((const unsigned*)((const char*)(gbase) + (voff)[_i]), (PG8_LAS unsigned*)(lds + (bufoff) + ldsw + _i * 8192), 16, 0, 0); } while (0)
; #define PG8_LDA(dst, b, h) do { _Pragma("unroll") for (int m = 0; m < 4; ++m) _Pragma("unroll") for (int k = 0; k < 2; ++k) dst[m][k] = *(const PG8_LAS bf16x8*)(lds + PG8_SA(b, h) + aoff + m * 2048 + k * 1024); } while (0)
; #define PG8_LDB(dst, b, h) do { _Pragma("unroll") for (int n = 0; n < 2; ++n) _Pragma("unroll") for (int k = 0; k < 2; ++k) dst[n][k] = *(const PG8_LAS bf16x8*)(lds + PG8_SB(b, h) + boff + n * 2048 + k * 1024); } while (0)
; #define PG8_MMA(ai, bj, At, Bt) do { __builtin_amdgcn_s_setprio(1); _Pragma("unroll") for (int m = 0; m < 4; ++m) _Pragma("unroll") for (int n = 0; n < 2; ++n) _Pragma("unroll") for (int k = 0; k < 2; ++k) \
;         acc[ai][bj][m][n] = __builtin_amdgcn_mfma_f32_16x16x32_bf16(Bt[n][k], At[m][k], acc[ai][bj][m][n], 0, 0, 0); __builtin_amdgcn_s_setprio(0); } while (0)
; #define PG8_WAIT_V(n) asm volatile("s_waitcnt vmcnt(" #n ")" ::: "memory")
; #define PG8_WAIT_L(n) asm volatile("s_waitcnt lgkmcnt(" #n ")" ::: "memory")
; #define PG8_BAR __builtin_amdgcn_s_barrier()
; #define PG8_SCHED __builtin_amdgcn_sched_barrier(0)
; template <class Epi, class Sched, bool ALIGN_EPI = false, bool SP2 = false>
; __device__ __forceinline__ void gemm_phase(PG8_LAS unsigned char* lds, const Gemm g, const Sched& S, const Epi& E) {
;     ...
;             PG8_LDB(B0, 1, 0); PG8_LDB(B1, 1, 1); PG8_SCHED; PG8_LDA(At, 1, 0); PG8_STAGE(PG8_SA(0, 1), a2 + hstep, voffA);
;             PG8_WAIT_V(8); PG8_WAIT_L(0); PG8_BAR; PG8_MMA(0, 0, At, B0); PG8_MMA(0, 1, At, B1); PG8_BAR; PG8_SCHED;
;             PG8_LDA(At, 1, 1); PG8_STAGE(PG8_SB(1, 0), b3, voffB); PG8_STAGE(PG8_SB(1, 1), b3 + hstep, voffB); PG8_STAGE(PG8_SA(1, 0), a3, voffA);
	s_setprio 0
	s_cmp_lg_u32 s26, 0
	s_cbranch_scc0 .Lspf6_b_h1
	s_add_i32 m0, s3, 0x10000
	ds_read_b128 v[128:131], v220
	ds_read_b128 v[132:135], v220 offset:1024
	ds_read_b128 v[136:139], v220 offset:2048
	global_load_lds_dwordx4 v188, s[50:51]
	s_add_i32 m0, s3, 0x12000
	ds_read_b128 v[140:143], v220 offset:3072
	ds_read_b128 v[144:147], v221
	ds_read_b128 v[148:151], v221 offset:1024
	global_load_lds_dwordx4 v190, s[50:51]
	s_add_u32 s98, s50, 0x20000
	s_addc_u32 s99, s51, 0
	s_add_i32 m0, s3, 0x11000
	ds_read_b128 v[152:155], v221 offset:2048
	ds_read_b128 v[156:159], v221 offset:3072
	ds_read_b128 v[160:163], v195 offset:32768
	global_load_lds_dwordx4 v188, s[98:99]
	s_add_i32 m0, s3, 0x13000
	ds_read_b128 v[164:167], v195 offset:33792
	ds_read_b128 v[168:171], v195 offset:34816
	ds_read_b128 v[172:175], v195 offset:35840
	global_load_lds_dwordx4 v190, s[98:99]
	s_add_u32 s98, s50, 0x80000
	s_addc_u32 s99, s51, 0
	s_add_i32 m0, s3, 0x14000
	ds_read_b128 v[176:179], v195 offset:36864
	ds_read_b128 v[180:183], v195 offset:37888
	ds_read_b128 v[184:187], v195 offset:38912
	global_load_lds_dwordx4 v188, s[98:99]
	s_add_i32 m0, s3, 0x16000
	ds_read_b128 v[200:203], v195 offset:39936
	ds_read_b128 v[204:207], v195 offset:49152
	ds_read_b128 v[208:211], v195 offset:50176
	global_load_lds_dwordx4 v190, s[98:99]
	s_add_u32 s98, s50, 0xa0000
	s_addc_u32 s99, s51, 0
	s_add_i32 m0, s3, 0x15000
	ds_read_b128 v[212:215], v195 offset:51200
	ds_read_b128 v[216:219], v195 offset:52224
	ds_read_b128 v[228:231], v195 offset:53248
	global_load_lds_dwordx4 v188, s[98:99]
	s_add_i32 m0, s3, 0x17000
	ds_read_b128 v[232:235], v195 offset:54272
	ds_read_b128 v[236:239], v195 offset:55296
	ds_read_b128 v[240:243], v195 offset:56320
	global_load_lds_dwordx4 v190, s[98:99]
	s_branch .Lspf6_b_rd
.Lspf6_b_h1:
	s_add_i32 m0, s3, 0x2000
	ds_read_b128 v[128:131], v220
	ds_read_b128 v[132:135], v220 offset:1024
	ds_read_b128 v[136:139], v220 offset:2048
	global_load_lds_dwordx4 v190, s[74:75]
	s_add_u32 s98, s74, 0xfffe0000
	s_addc_u32 s99, s75, -1
	s_add_i32 m0, s3, 0x1000
	ds_read_b128 v[140:143], v220 offset:3072
	ds_read_b128 v[144:147], v221
	ds_read_b128 v[148:151], v221 offset:1024
	global_load_lds_dwordx4 v190, s[98:99]
	s_add_u32 s98, s74, 0x80000
	s_addc_u32 s99, s75, 0
	s_add_i32 m0, s3, 0x6000
	ds_read_b128 v[152:155], v221 offset:2048
	ds_read_b128 v[156:159], v221 offset:3072
	ds_read_b128 v[160:163], v195 offset:32768
	global_load_lds_dwordx4 v190, s[98:99]
	s_add_u32 s98, s74, 0x60000
	s_addc_u32 s99, s75, 0
	s_add_i32 m0, s3, 0x5000
	ds_read_b128 v[164:167], v195 offset:33792
	ds_read_b128 v[168:171], v195 offset:34816
	ds_read_b128 v[172:175], v195 offset:35840
	global_load_lds_dwordx4 v190, s[98:99]
	s_add_u32 s98, s74, 0x80
	s_addc_u32 s99, s75, 0
	s_add_i32 m0, s3, 0x8000
	ds_read_b128 v[176:179], v195 offset:36864
	ds_read_b128 v[180:183], v195 offset:37888
	ds_read_b128 v[184:187], v195 offset:38912
	global_load_lds_dwordx4 v188, s[98:99]
	s_add_u32 s98, s74, 0xfffe0080
	s_addc_u32 s99, s75, -1
	s_add_i32 m0, s3, 0x7000
	ds_read_b128 v[200:203], v195 offset:39936
	ds_read_b128 v[204:207], v195 offset:49152
	ds_read_b128 v[208:211], v195 offset:50176
	global_load_lds_dwordx4 v188, s[98:99]
	s_add_u32 s98, s74, 0x80080
	s_addc_u32 s99, s75, 0
	s_add_i32 m0, s3, 0xc000
	ds_read_b128 v[212:215], v195 offset:51200
	ds_read_b128 v[216:219], v195 offset:52224
	ds_read_b128 v[228:231], v195 offset:53248
	global_load_lds_dwordx4 v188, s[98:99]
	s_add_u32 s98, s74, 0x60080
	s_addc_u32 s99, s75, 0
	s_add_i32 m0, s3, 0xb000
	ds_read_b128 v[232:235], v195 offset:54272
	ds_read_b128 v[236:239], v195 offset:55296
	ds_read_b128 v[240:243], v195 offset:56320
	global_load_lds_dwordx4 v188, s[98:99]
; #define PG8_STAGE(bufoff, gbase, voff) do { _Pragma("unroll") for (int _i = 0; _i < 2; ++_i) \
;         __builtin_amdgcn_global_load_lds((const unsigned*)((const char*)(gbase) + (voff)[_i]), (PG8_LAS unsigned*)(lds + (bufoff) + ldsw + _i * 8192), 16, 0, 0); } while (0)
; #define PG8_LDA(dst, b, h) do { _Pragma("unroll") for (int m = 0; m < 4; ++m) _Pragma("unroll") for (int k = 0; k < 2; ++k) dst[m][k] = *(const PG8_LAS bf16x8*)(lds + PG8_SA(b, h) + aoff + m * 2048 + k * 1024); } while (0)
; #define PG8_LDB(dst, b, h) do { _Pragma("unroll") for (int n = 0; n < 2; ++n) _Pragma("unroll") for (int k = 0; k < 2; ++k) dst[n][k] = *(const PG8_LAS bf16x8*)(lds + PG8_SB(b, h) + boff + n * 2048 + k * 1024); } while (0)
; #define PG8_MMA(ai, bj, At, Bt) do { __builtin_amdgcn_s_setprio(1); _Pragma("unroll") for (int m = 0; m < 4; ++m) _Pragma("unroll") for (int n = 0; n < 2; ++n) _Pragma("unroll") for (int k = 0; k < 2; ++k) \
;         acc[ai][bj][m][n] = __builtin_amdgcn_mfma_f32_16x16x32_bf16(Bt[n][k], At[m][k], acc[ai][bj][m][n], 0, 0, 0); __builtin_amdgcn_s_setprio(0); } while (0)
; #define PG8_WAIT_V(n) asm volatile("s_waitcnt vmcnt(" #n ")" ::: "memory")
; #define PG8_WAIT_L(n) asm volatile("s_waitcnt lgkmcnt(" #n ")" ::: "memory")
; #define PG8_BAR __builtin_amdgcn_s_barrier()
; #define PG8_SCHED __builtin_amdgcn_sched_barrier(0)
; template <class Epi, class Sched, bool ALIGN_EPI = false, bool SP2 = false>
; __device__ __forceinline__ void gemm_phase(PG8_LAS unsigned char* lds, const Gemm g, const Sched& S, const Epi& E) {
;     ...
;         for (int t = 0; t < nt; t += 2) {
;     ...
;             PG8_LDB(B0, 1, 0); PG8_LDB(B1, 1, 1); PG8_SCHED; PG8_LDA(At, 1, 0); PG8_STAGE(PG8_SA(0, 1), a2 + hstep, voffA);
;             PG8_WAIT_V(8); PG8_WAIT_L(0); PG8_BAR; PG8_MMA(0, 0, At, B0); PG8_MMA(0, 1, At, B1); PG8_BAR; PG8_SCHED;
;             PG8_LDA(At, 1, 1); PG8_STAGE(PG8_SB(1, 0), b3, voffB); PG8_STAGE(PG8_SB(1, 1), b3 + hstep, voffB); PG8_STAGE(PG8_SA(1, 0), a3, voffA);
;             PG8_WAIT_V(8); PG8_WAIT_L(0); PG8_BAR; PG8_MMA(1, 0, At, B0); PG8_MMA(1, 1, At, B1); PG8_BAR; PG8_SCHED;
.Lspf6_b_rd:
	s_waitcnt lgkmcnt(0)
	s_setprio 1
	s_barrier
	v_mfma_f32_16x16x32_bf16 v[124:127], v[128:131], v[160:163], v[124:127]
	v_mfma_f32_16x16x32_bf16 v[120:123], v[136:139], v[160:163], v[120:123]
	v_mfma_f32_16x16x32_bf16 v[108:111], v[128:131], v[168:171], v[108:111]
	v_mfma_f32_16x16x32_bf16 v[104:107], v[136:139], v[168:171], v[104:107]
	v_mfma_f32_16x16x32_bf16 v[92:95], v[128:131], v[176:179], v[92:95]
	v_mfma_f32_16x16x32_bf16 v[88:91], v[136:139], v[176:179], v[88:91]
	v_mfma_f32_16x16x32_bf16 v[76:79], v[128:131], v[184:187], v[76:79]
	v_mfma_f32_16x16x32_bf16 v[72:75], v[136:139], v[184:187], v[72:75]
	v_mfma_f32_16x16x32_bf16 v[124:127], v[132:135], v[164:167], v[124:127]
	v_mfma_f32_16x16x32_bf16 v[120:123], v[140:143], v[164:167], v[120:123]
	v_mfma_f32_16x16x32_bf16 v[108:111], v[132:135], v[172:175], v[108:111]
	v_mfma_f32_16x16x32_bf16 v[104:107], v[140:143], v[172:175], v[104:107]
	v_mfma_f32_16x16x32_bf16 v[92:95], v[132:135], v[180:183], v[92:95]
	v_mfma_f32_16x16x32_bf16 v[88:91], v[140:143], v[180:183], v[88:91]
	v_mfma_f32_16x16x32_bf16 v[76:79], v[132:135], v[200:203], v[76:79]
	v_mfma_f32_16x16x32_bf16 v[72:75], v[140:143], v[200:203], v[72:75]
	v_mfma_f32_16x16x32_bf16 v[116:119], v[144:147], v[160:163], v[116:119]
	v_mfma_f32_16x16x32_bf16 v[112:115], v[152:155], v[160:163], v[112:115]
	v_mfma_f32_16x16x32_bf16 v[100:103], v[144:147], v[168:171], v[100:103]
	v_mfma_f32_16x16x32_bf16 v[96:99], v[152:155], v[168:171], v[96:99]
	v_mfma_f32_16x16x32_bf16 v[84:87], v[144:147], v[176:179], v[84:87]
	v_mfma_f32_16x16x32_bf16 v[80:83], v[152:155], v[176:179], v[80:83]
	v_mfma_f32_16x16x32_bf16 v[68:71], v[144:147], v[184:187], v[68:71]
	v_mfma_f32_16x16x32_bf16 v[64:67], v[152:155], v[184:187], v[64:67]
	v_mfma_f32_16x16x32_bf16 v[116:119], v[148:151], v[164:167], v[116:119]
	v_mfma_f32_16x16x32_bf16 v[112:115], v[156:159], v[164:167], v[112:115]
	v_mfma_f32_16x16x32_bf16 v[100:103], v[148:151], v[172:175], v[100:103]
	v_mfma_f32_16x16x32_bf16 v[96:99], v[156:159], v[172:175], v[96:99]
	v_mfma_f32_16x16x32_bf16 v[84:87], v[148:151], v[180:183], v[84:87]
	v_mfma_f32_16x16x32_bf16 v[80:83], v[156:159], v[180:183], v[80:83]
	v_mfma_f32_16x16x32_bf16 v[68:71], v[148:151], v[200:203], v[68:71]
	v_mfma_f32_16x16x32_bf16 v[64:67], v[156:159], v[200:203], v[64:67]
	v_mfma_f32_16x16x32_bf16 v[60:63], v[128:131], v[204:207], v[60:63]
	v_mfma_f32_16x16x32_bf16 v[56:59], v[136:139], v[204:207], v[56:59]
	v_mfma_f32_16x16x32_bf16 v[44:47], v[128:131], v[212:215], v[44:47]
	v_mfma_f32_16x16x32_bf16 v[40:43], v[136:139], v[212:215], v[40:43]
	v_mfma_f32_16x16x32_bf16 v[28:31], v[128:131], v[228:231], v[28:31]
	v_mfma_f32_16x16x32_bf16 v[24:27], v[136:139], v[228:231], v[24:27]
	v_mfma_f32_16x16x32_bf16 v[12:15], v[128:131], v[236:239], v[12:15]
	v_mfma_f32_16x16x32_bf16 v[8:11], v[136:139], v[236:239], v[8:11]
	v_mfma_f32_16x16x32_bf16 v[60:63], v[132:135], v[208:211], v[60:63]
	v_mfma_f32_16x16x32_bf16 v[56:59], v[140:143], v[208:211], v[56:59]
	v_mfma_f32_16x16x32_bf16 v[44:47], v[132:135], v[216:219], v[44:47]
	v_mfma_f32_16x16x32_bf16 v[40:43], v[140:143], v[216:219], v[40:43]
	v_mfma_f32_16x16x32_bf16 v[28:31], v[132:135], v[232:235], v[28:31]
	v_mfma_f32_16x16x32_bf16 v[24:27], v[140:143], v[232:235], v[24:27]
	v_mfma_f32_16x16x32_bf16 v[12:15], v[132:135], v[240:243], v[12:15]
	v_mfma_f32_16x16x32_bf16 v[8:11], v[140:143], v[240:243], v[8:11]
	v_mfma_f32_16x16x32_bf16 v[52:55], v[144:147], v[204:207], v[52:55]
	v_mfma_f32_16x16x32_bf16 v[48:51], v[152:155], v[204:207], v[48:51]
	v_mfma_f32_16x16x32_bf16 v[36:39], v[144:147], v[212:215], v[36:39]
	v_mfma_f32_16x16x32_bf16 v[32:35], v[152:155], v[212:215], v[32:35]
	v_mfma_f32_16x16x32_bf16 v[20:23], v[144:147], v[228:231], v[20:23]
	v_mfma_f32_16x16x32_bf16 v[16:19], v[152:155], v[228:231], v[16:19]
	v_mfma_f32_16x16x32_bf16 v[4:7], v[144:147], v[236:239], v[4:7]
	v_mfma_f32_16x16x32_bf16 v[0:3], v[152:155], v[236:239], v[0:3]
	v_mfma_f32_16x16x32_bf16 v[52:55], v[148:151], v[208:211], v[52:55]
	v_mfma_f32_16x16x32_bf16 v[48:51], v[156:159], v[208:211], v[48:51]
	v_mfma_f32_16x16x32_bf16 v[36:39], v[148:151], v[216:219], v[36:39]
	v_mfma_f32_16x16x32_bf16 v[32:35], v[156:159], v[216:219], v[32:35]
	v_mfma_f32_16x16x32_bf16 v[20:23], v[148:151], v[232:235], v[20:23]
	v_mfma_f32_16x16x32_bf16 v[16:19], v[156:159], v[232:235], v[16:19]
	v_mfma_f32_16x16x32_bf16 v[4:7], v[148:151], v[240:243], v[4:7]
	v_mfma_f32_16x16x32_bf16 v[0:3], v[156:159], v[240:243], v[0:3]
	s_waitcnt vmcnt(0)
	s_barrier
	s_setprio 0
	s_add_i32 s66, s66, 2
	s_add_u32 s31, s31, 0x100
	s_addc_u32 s72, s72, 0
	s_cmp_gt_u32 s66, 29
	s_mov_b64 s[46:47], s[48:49]
	s_cbranch_scc0 .LBB0_876
	v_mov_b32_e32 v230, v195
	v_mov_b32_e32 v229, v193
	v_mov_b32_e32 v228, v191
	v_mov_b32_e32 v226, v189
	s_and_b64 vcc, exec, s[26:27]
	s_cbranch_vccz .LBB0_879
	s_barrier

; #define PG8_STAGE(bufoff, gbase, voff) do { _Pragma("unroll") for (int _i = 0; _i < 2; ++_i) \
;         __builtin_amdgcn_global_load_lds((const unsigned*)((const char*)(gbase) + (voff)[_i]), (PG8_LAS unsigned*)(lds + (bufoff) + ldsw + _i * 8192), 16, 0, 0); } while (0)
; #define PG8_WAIT_V(n) asm volatile("s_waitcnt vmcnt(" #n ")" ::: "memory")
; #define PG8_BAR __builtin_amdgcn_s_barrier()
; template <class Epi, class Sched, bool ALIGN_EPI = false, bool SP2 = false>
; __device__ __forceinline__ void gemm_phase(PG8_LAS unsigned char* lds, const Gemm g, const Sched& S, const Epi& E) {
;     ...
;     const int tid = tid_o, wid = __builtin_amdgcn_readfirstlane(tid >> 6), lane = tid & 63, wr = wid >> 2, wc = wid & 3, fr = lane & 15, fq = lane >> 4;
;     const int K = g.K, nt = K / BK;
;     unsigned voffA[2], voffB[2];
; #pragma unroll
;     for (int i = 0; i < 2; ++i) { int R, C; stage_rc(tid * 16 + i * 8192, R, C); const int Rb = Epi::PERM ? ((R & ~31) + perm32(R & 31)) : R;
;         voffA[i] = (unsigned)(R * K + C) * 2u; voffB[i] = (unsigned)(Rb * K + C) * 2u; }
;     const size_t kstep = (size_t)(BK * 2);
;     const size_t hstep = (size_t)HALF * K * 2;
;     const size_t tstep = 2 * hstep;
;     const unsigned ldsw = (unsigned)wid * 1024u;
;     const int aoff = lds_byte(wr * 64 + fr, fq * 8), boff = lds_byte(wc * 32 + fr, fq * 8);
;     ...
;     if constexpr (SP2) {
;         PG8_STAGE(PG8_SB(0, 0), cB, voffB); PG8_STAGE(PG8_SB(0, 1), cB + hstep, voffB); PG8_STAGE(PG8_SA(0, 0), cA, voffA); PG8_STAGE(PG8_SA(0, 1), cA + hstep, voffA);
;         if (wr == 1) PG8_BAR;
;         PG8_WAIT_V(2); PG8_BAR;
;         PG8_STAGE(PG8_SB(1, 0), cB + kstep, voffB); PG8_STAGE(PG8_SA(1, 0), cA + kstep, voffA); PG8_STAGE(PG8_SB(1, 1), cB + hstep + kstep, voffB);
;         PG8_WAIT_V(6); PG8_BAR;
.LBB0_1019:
	s_lshl_b32 s10, s10, 5
	s_and_b32 s18, s10, 0x60
	s_mov_b64 s[10:11], 0x80
	s_add_i32 m0, s15, 0x18000
	v_lshl_add_u64 v[6:7], v[6:7], 0, s[10:11]
	s_lshl_b32 s13, s12, 13
	s_lshl_b32 s19, s18, 7
	s_waitcnt vmcnt(0)
	s_barrier
	global_load_lds_dwordx4 v[6:7], off
	v_lshl_add_u64 v[4:5], v[4:5], 0, s[10:11]
	s_add_i32 m0, s15, 0x1a000
	s_add_i32 s35, s15, 0x8000
	s_add_i32 s42, s15, 0xa000
	global_load_lds_dwordx4 v[4:5], off
	v_lshl_add_u64 v[0:1], v[0:1], 0, s[10:11]
	s_mov_b32 m0, s35
	s_add_u32 s16, s30, 0x80080
	global_load_lds_dwordx4 v[0:1], off
	v_lshl_add_u64 v[0:1], v[2:3], 0, s[10:11]
	s_mov_b32 m0, s42
	s_addc_u32 s17, s31, 0
	global_load_lds_dwordx4 v[0:1], off
	s_add_i32 m0, s15, 0x1c000
	v_lshl_add_u64 v[0:1], s[16:17], 0, v[132:133]
	global_load_lds_dwordx4 v[0:1], off
	v_lshl_add_u64 v[0:1], s[16:17], 0, v[128:129]
	s_add_i32 m0, s15, 0x1e000
	s_cmpk_lt_u32 s7, 0x100
	global_load_lds_dwordx4 v[0:1], off
	v_lshrrev_b32_e32 v1, 1, v9
	v_and_b32_e32 v2, 24, v1
	v_and_b32_e32 v0, 15, v9
	v_lshlrev_b32_e32 v1, 1, v2
	v_lshl_or_b32 v155, s12, 6, v0
	v_lshl_or_b32 v0, v0, 6, v1
	v_lshlrev_b32_e32 v1, 2, v9
	v_and_b32_e32 v1, 32, v1
	v_bitop3_b32 v3, v0, s13, v1 bitop3:0xde
	v_bitop3_b32 v159, v0, s19, v1 bitop3:0xde
	v_lshlrev_b32_e32 v0, 2, v2
	v_mov_b32_e32 v1, v133
	v_lshl_add_u64 v[136:137], s[0:1], 0, v[0:1]
	v_lshlrev_b32_e32 v0, 15, v13
	v_and_b32_e32 v0, 0xffff0000, v0
	v_lshl_add_u32 v0, v12, 12, v0
	v_and_b32_e32 v1, 1, v13
	v_lshl_or_b32 v0, v1, 6, v0
	v_lshl_add_u32 v138, v14, 1, v0
	v_lshlrev_b32_e32 v0, 15, v8
	v_and_b32_e32 v0, 0xffff0000, v0
	s_waitcnt vmcnt(6)
	v_lshl_add_u32 v0, v10, 12, v0
	v_and_b32_e32 v1, 1, v8
	s_cselect_b64 s[16:17], -1, 0
	v_lshl_or_b32 v0, v1, 6, v0
	s_add_i32 s43, 0, 0x10000
	s_add_i32 s44, 0, 0x14000
	s_sext_i32_i16 s46, s6
	v_or_b32_e32 v163, s18, v2
	v_mov_b32_e32 v139, v133
	v_lshl_add_u32 v140, v11, 1, v0
	v_mov_b32_e32 v141, v133
	v_mov_b64_e32 v[142:143], 0x580
	v_mov_b64_e32 v[144:145], 0x57f
	v_add_u32_e32 v167, s43, v159
	v_add_u32_e32 v171, s44, v159
	v_add_u32_e32 v175, 0, v3
	v_mov_b32_e32 v176, 0x358637bd
	s_movk_i32 s45, 0x2c00
	s_barrier
	s_branch .LBB0_1022

; #define PG8_STAGE(bufoff, gbase, voff) do { _Pragma("unroll") for (int _i = 0; _i < 2; ++_i) \
;         __builtin_amdgcn_global_load_lds((const unsigned*)((const char*)(gbase) + (voff)[_i]), (PG8_LAS unsigned*)(lds + (bufoff) + ldsw + _i * 8192), 16, 0, 0); } while (0)
; #define PG8_LDA(dst, b, h) do { _Pragma("unroll") for (int m = 0; m < 4; ++m) _Pragma("unroll") for (int k = 0; k < 2; ++k) dst[m][k] = *(const PG8_LAS bf16x8*)(lds + PG8_SA(b, h) + aoff + m * 2048 + k * 1024); } while (0)
; #define PG8_LDB(dst, b, h) do { _Pragma("unroll") for (int n = 0; n < 2; ++n) _Pragma("unroll") for (int k = 0; k < 2; ++k) dst[n][k] = *(const PG8_LAS bf16x8*)(lds + PG8_SB(b, h) + boff + n * 2048 + k * 1024); } while (0)
; template <class Epi, class Sched, bool ALIGN_EPI = false, bool SP2 = false>
; __device__ __forceinline__ void gemm_phase(PG8_LAS unsigned char* lds, const Gemm g, const Sched& S, const Epi& E) {
;     ...
;     for (;;) {
;         const bool has_next = S.next(ui + 1, nxt);
;         const char* nA = has_next ? (const char*)g.A + (size_t)nxt.pm * tstep : cA; const char* nB = has_next ? (const char*)g.Bt + (size_t)nxt.pn * tstep : cB;
;         for (int t = 0; t < nt; t += 2) {
;             const bool last = (t == nt - 2);
;             const char* a1 = cA + (size_t)(t + 1) * kstep;
;             const char* a2 = last ? nA : cA + (size_t)(t + 2) * kstep; const char* b2 = last ? nB : cB + (size_t)(t + 2) * kstep;
;             const char* a3 = a2 + kstep; const char* b3 = b2 + kstep;
;             if (last && has_next) S.a_ready(nxt);
;             if constexpr (SP2) {
;             PG8_LDB(B0, 0, 0); PG8_LDB(B1, 0, 1); PG8_SCHED; PG8_LDA(At, 0, 0); PG8_STAGE(PG8_SA(1, 1), a1 + hstep, voffA);
;             PG8_WAIT_V(8); PG8_WAIT_L(0); PG8_BAR; PG8_MMA(0, 0, At, B0); PG8_MMA(0, 1, At, B1); PG8_BAR; PG8_SCHED;
;             PG8_LDA(At, 0, 1); PG8_STAGE(PG8_SB(0, 0), b2, voffB); PG8_STAGE(PG8_SB(0, 1), b2 + hstep, voffB); PG8_STAGE(PG8_SA(0, 0), a2, voffA);
;     ...
;         if (!has_next) break;
; #pragma unroll
;         for (int a = 0; a < 2; ++a)
; #pragma unroll
;             for (int b = 0; b < 2; ++b)
; #pragma unroll
;                 for (int m = 0; m < 4; ++m)
; #pragma unroll
;                     for (int n = 0; n < 2; ++n) acc[a][b][m][n] = (f32x4){0.f, 0.f, 0.f, 0.f};
;         cur = nxt; cA = nA; cB = nB; ++ui;
.LBB0_1024:
	s_ashr_i32 s19, s18, 31
	s_lshl_b64 s[12:13], s[18:19], 20
	s_add_u32 s20, s40, s12
	s_addc_u32 s21, s41, s13
	s_and_b64 s[12:13], s[6:7], exec
	s_cselect_b32 s12, s21, s29
	s_cselect_b32 s13, s20, s28
	s_ashr_i32 s1, s0, 31
	s_lshl_b64 s[24:25], s[0:1], 20
	s_add_u32 s24, s64, s24
	s_addc_u32 s25, s65, s25
	s_and_b64 s[36:37], s[6:7], exec
	s_cselect_b32 s1, s25, s31
	s_cselect_b32 s19, s24, s30
	s_add_u32 s28, s28, 0x80080
	s_addc_u32 s29, s29, 0
	s_add_u32 s47, s30, 0x100
	v_mov_b64_e32 v[0:1], 0
	v_mov_b64_e32 v[2:3], 0
	v_mov_b64_e32 v[4:5], 0
	v_mov_b64_e32 v[6:7], 0
	v_mov_b64_e32 v[8:9], 0
	v_mov_b64_e32 v[10:11], 0
	v_mov_b64_e32 v[12:13], 0
	v_mov_b64_e32 v[14:15], 0
	v_mov_b64_e32 v[16:17], 0
	v_mov_b64_e32 v[18:19], 0
	v_mov_b64_e32 v[20:21], 0
	v_mov_b64_e32 v[22:23], 0
	v_mov_b64_e32 v[24:25], 0
	v_mov_b64_e32 v[26:27], 0
	v_mov_b64_e32 v[28:29], 0
	v_mov_b64_e32 v[30:31], 0
	v_mov_b64_e32 v[32:33], 0
	v_mov_b64_e32 v[34:35], 0
	v_mov_b64_e32 v[36:37], 0
	v_mov_b64_e32 v[38:39], 0
	v_mov_b64_e32 v[40:41], 0
	v_mov_b64_e32 v[42:43], 0
	v_mov_b64_e32 v[44:45], 0
	v_mov_b64_e32 v[46:47], 0
	v_mov_b64_e32 v[48:49], 0
	v_mov_b64_e32 v[50:51], 0
	v_mov_b64_e32 v[52:53], 0
	v_mov_b64_e32 v[54:55], 0
	v_mov_b64_e32 v[56:57], 0
	v_mov_b64_e32 v[58:59], 0
	v_mov_b64_e32 v[60:61], 0
	v_mov_b64_e32 v[62:63], 0
	v_mov_b64_e32 v[64:65], 0
	v_mov_b64_e32 v[66:67], 0
	v_mov_b64_e32 v[68:69], 0
	v_mov_b64_e32 v[70:71], 0
	v_mov_b64_e32 v[72:73], 0
	v_mov_b64_e32 v[74:75], 0
	v_mov_b64_e32 v[76:77], 0
	v_mov_b64_e32 v[78:79], 0
	v_mov_b64_e32 v[80:81], 0
	v_mov_b64_e32 v[82:83], 0
	v_mov_b64_e32 v[84:85], 0
	v_mov_b64_e32 v[86:87], 0
	v_mov_b64_e32 v[88:89], 0
	v_mov_b64_e32 v[90:91], 0
	v_mov_b64_e32 v[92:93], 0
	v_mov_b64_e32 v[94:95], 0
	v_mov_b64_e32 v[96:97], 0
	v_mov_b64_e32 v[98:99], 0
	v_mov_b64_e32 v[100:101], 0
	v_mov_b64_e32 v[102:103], 0
	v_mov_b64_e32 v[104:105], 0
	v_mov_b64_e32 v[106:107], 0
	v_mov_b64_e32 v[108:109], 0
	v_mov_b64_e32 v[110:111], 0
	v_mov_b64_e32 v[112:113], 0
	v_mov_b64_e32 v[114:115], 0
	v_mov_b64_e32 v[116:117], 0
	v_mov_b64_e32 v[118:119], 0
	v_mov_b64_e32 v[120:121], 0
	v_mov_b64_e32 v[122:123], 0
	v_mov_b64_e32 v[124:125], 0
	v_mov_b64_e32 v[126:127], 0
	s_addc_u32 s48, s31, 0
	s_mov_b32 s49, -2
	v_mov_b32_e32 v129, v155
	v_mov_b32_e32 v131, v159
	v_mov_b32_e32 v133, v163
	v_mov_b32_e32 v135, v167
	v_mov_b32_e32 v139, v171
	v_mov_b32_e32 v141, v175
	v_add_u32_e32 v174, 0x18000, v131
	v_add_u32_e32 v177, 0x1c000, v131
	s_cmp_lg_u32 s16, 0
	s_cbranch_scc0 .Lspf7_pre
	s_add_i32 m0, s3, 0xc000
	s_nop 0
	global_load_lds_dwordx4 v138, s[28:29]
	s_add_u32 s98, s28, 0x20000
	s_addc_u32 s99, s29, 0
	s_add_i32 m0, s3, 0xd000
	s_nop 0
	global_load_lds_dwordx4 v138, s[98:99]
	s_add_u32 s98, s28, 0xfff80000
	s_addc_u32 s99, s29, -1
	s_add_i32 m0, s3, 0x8000
	s_nop 0
	global_load_lds_dwordx4 v138, s[98:99]
	s_add_u32 s98, s28, 0xfffa0000
	s_addc_u32 s99, s29, -1
	s_add_i32 m0, s3, 0x9000
	s_nop 0
	global_load_lds_dwordx4 v138, s[98:99]
.Lspf7_pre:
.LBB0_1025:
	s_add_u32 s30, s28, 0xfff80080
	s_addc_u32 s31, s29, -1
	s_cmp_eq_u32 s49, 28
	s_cselect_b32 s37, s12, s31
	s_cselect_b32 s36, s13, s30
	s_cselect_b32 s31, s1, s48
	s_cselect_b32 s30, s19, s47
	s_cmp_lg_u32 s16, 0
	s_cbranch_scc0 .Lspf7_a_h1
	s_add_u32 s98, s47, 0xffffff80
	s_addc_u32 s99, s48, -1
	s_add_i32 m0, s3, 0x18000
	ds_read_b128 v[146:149], v135
	ds_read_b128 v[150:153], v135 offset:1024
	ds_read_b128 v[178:181], v135 offset:2048
	global_load_lds_dwordx4 v132, s[98:99]
	s_add_i32 m0, s3, 0x1a000
	ds_read_b128 v[182:185], v135 offset:3072
	ds_read_b128 v[186:189], v139
	ds_read_b128 v[190:193], v139 offset:1024
	global_load_lds_dwordx4 v128, s[98:99]
	s_add_u32 s98, s47, 0x1ff80
	s_addc_u32 s99, s48, 0
	s_add_i32 m0, s3, 0x19000
	ds_read_b128 v[194:197], v139 offset:2048
	ds_read_b128 v[198:201], v139 offset:3072
	ds_read_b128 v[202:205], v141
	global_load_lds_dwordx4 v132, s[98:99]
	s_add_i32 m0, s3, 0x1b000
	ds_read_b128 v[206:209], v141 offset:1024
	ds_read_b128 v[210:213], v141 offset:2048
	ds_read_b128 v[214:217], v141 offset:3072
	global_load_lds_dwordx4 v128, s[98:99]
	s_add_u32 s98, s47, 0x7ff80
	s_addc_u32 s99, s48, 0
	s_add_i32 m0, s3, 0x1c000
	ds_read_b128 v[218:221], v141 offset:4096
	ds_read_b128 v[226:229], v141 offset:5120
	ds_read_b128 v[230:233], v141 offset:6144
	global_load_lds_dwordx4 v132, s[98:99]
	s_add_i32 m0, s3, 0x1e000
	ds_read_b128 v[234:237], v141 offset:7168
	ds_read_b128 v[154:157], v141 offset:16384
	ds_read_b128 v[158:161], v141 offset:17408
	global_load_lds_dwordx4 v128, s[98:99]
	s_add_u32 s98, s47, 0x9ff80
	s_addc_u32 s99, s48, 0
	s_add_i32 m0, s3, 0x1d000
	ds_read_b128 v[162:165], v141 offset:18432
	ds_read_b128 v[166:169], v141 offset:19456
	ds_read_b128 v[170:173], v141 offset:20480
	global_load_lds_dwordx4 v132, s[98:99]
	s_add_i32 m0, s3, 0x1f000
	ds_read_b128 v[238:241], v141 offset:21504
	ds_read_b128 v[242:245], v141 offset:22528
	ds_read_b128 v[246:249], v141 offset:23552
	global_load_lds_dwordx4 v128, s[98:99]
	s_branch .Lspf7_a_rd
; #define PG8_STAGE(bufoff, gbase, voff) do { _Pragma("unroll") for (int _i = 0; _i < 2; ++_i) \
;         __builtin_amdgcn_global_load_lds((const unsigned*)((const char*)(gbase) + (voff)[_i]), (PG8_LAS unsigned*)(lds + (bufoff) + ldsw + _i * 8192), 16, 0, 0); } while (0)
; #define PG8_LDA(dst, b, h) do { _Pragma("unroll") for (int m = 0; m < 4; ++m) _Pragma("unroll") for (int k = 0; k < 2; ++k) dst[m][k] = *(const PG8_LAS bf16x8*)(lds + PG8_SA(b, h) + aoff + m * 2048 + k * 1024); } while (0)
; #define PG8_LDB(dst, b, h) do { _Pragma("unroll") for (int n = 0; n < 2; ++n) _Pragma("unroll") for (int k = 0; k < 2; ++k) dst[n][k] = *(const PG8_LAS bf16x8*)(lds + PG8_SB(b, h) + boff + n * 2048 + k * 1024); } while (0)
; #define PG8_MMA(ai, bj, At, Bt) do { __builtin_amdgcn_s_setprio(1); _Pragma("unroll") for (int m = 0; m < 4; ++m) _Pragma("unroll") for (int n = 0; n < 2; ++n) _Pragma("unroll") for (int k = 0; k < 2; ++k) \
;         acc[ai][bj][m][n] = __builtin_amdgcn_mfma_f32_16x16x32_bf16(Bt[n][k], At[m][k], acc[ai][bj][m][n], 0, 0, 0); __builtin_amdgcn_s_setprio(0); } while (0)
; #define PG8_WAIT_V(n) asm volatile("s_waitcnt vmcnt(" #n ")" ::: "memory")
; #define PG8_WAIT_L(n) asm volatile("s_waitcnt lgkmcnt(" #n ")" ::: "memory")
; #define PG8_BAR __builtin_amdgcn_s_barrier()
; #define PG8_SCHED __builtin_amdgcn_sched_barrier(0)
; template <class Epi, class Sched, bool ALIGN_EPI = false, bool SP2 = false>
; __device__ __forceinline__ void gemm_phase(PG8_LAS unsigned char* lds, const Gemm g, const Sched& S, const Epi& E) {
;     ...
;             if constexpr (SP2) {
;             PG8_LDB(B0, 0, 0); PG8_LDB(B1, 0, 1); PG8_SCHED; PG8_LDA(At, 0, 0); PG8_STAGE(PG8_SA(1, 1), a1 + hstep, voffA);
;             PG8_WAIT_V(8); PG8_WAIT_L(0); PG8_BAR; PG8_MMA(0, 0, At, B0); PG8_MMA(0, 1, At, B1); PG8_BAR; PG8_SCHED;
;             PG8_LDA(At, 0, 1); PG8_STAGE(PG8_SB(0, 0), b2, voffB); PG8_STAGE(PG8_SB(0, 1), b2 + hstep, voffB); PG8_STAGE(PG8_SA(0, 0), a2, voffA);
;             PG8_WAIT_V(8); PG8_WAIT_L(0); PG8_BAR; PG8_MMA(1, 0, At, B0); PG8_MMA(1, 1, At, B1); PG8_BAR; PG8_SCHED;
.Lspf7_a_h1:
	s_add_u32 s98, s28, 0xfff80000
	s_addc_u32 s99, s29, -1
	s_add_i32 m0, s3, 0xa000
	ds_read_b128 v[146:149], v135
	ds_read_b128 v[150:153], v135 offset:1024
	ds_read_b128 v[178:181], v135 offset:2048
	global_load_lds_dwordx4 v140, s[98:99]
	s_add_u32 s98, s28, 0xfff60000
	s_addc_u32 s99, s29, -1
	s_add_i32 m0, s3, 0x9000
	ds_read_b128 v[182:185], v135 offset:3072
	ds_read_b128 v[186:189], v139
	ds_read_b128 v[190:193], v139 offset:1024
	global_load_lds_dwordx4 v140, s[98:99]
	s_add_i32 m0, s3, 0xe000
	ds_read_b128 v[194:197], v139 offset:2048
	ds_read_b128 v[198:201], v139 offset:3072
	ds_read_b128 v[202:205], v141
	global_load_lds_dwordx4 v140, s[28:29]
	s_add_u32 s98, s28, 0xfffe0000
	s_addc_u32 s99, s29, -1
	s_add_i32 m0, s3, 0xd000
	ds_read_b128 v[206:209], v141 offset:1024
	ds_read_b128 v[210:213], v141 offset:2048
	ds_read_b128 v[214:217], v141 offset:3072
	global_load_lds_dwordx4 v140, s[98:99]
	s_add_i32 m0, s3, 0x0
	ds_read_b128 v[218:221], v141 offset:4096
	ds_read_b128 v[226:229], v141 offset:5120
	ds_read_b128 v[230:233], v141 offset:6144
	global_load_lds_dwordx4 v134, s[36:37]
	s_add_u32 s98, s36, 0xfffe0000
	s_addc_u32 s99, s37, -1
	s_add_i32 m0, s3, 0xfffff000
	ds_read_b128 v[234:237], v141 offset:7168
	ds_read_b128 v[154:157], v141 offset:16384
	ds_read_b128 v[158:161], v141 offset:17408
	global_load_lds_dwordx4 v134, s[98:99]
	s_add_u32 s98, s36, 0x80000
	s_addc_u32 s99, s37, 0
	s_add_i32 m0, s3, 0x4000
	ds_read_b128 v[162:165], v141 offset:18432
	ds_read_b128 v[166:169], v141 offset:19456
	ds_read_b128 v[170:173], v141 offset:20480
	global_load_lds_dwordx4 v134, s[98:99]
	s_add_u32 s98, s36, 0x60000
	s_addc_u32 s99, s37, 0
	s_add_i32 m0, s3, 0x3000
	ds_read_b128 v[238:241], v141 offset:21504
	ds_read_b128 v[242:245], v141 offset:22528
	ds_read_b128 v[246:249], v141 offset:23552
	global_load_lds_dwordx4 v134, s[98:99]
.Lspf7_a_rd:
	s_waitcnt lgkmcnt(0)
	s_setprio 1
	s_barrier
	v_mfma_f32_16x16x32_bf16 v[124:127], v[146:149], v[202:205], v[124:127]
	v_mfma_f32_16x16x32_bf16 v[120:123], v[178:181], v[202:205], v[120:123]
	v_mfma_f32_16x16x32_bf16 v[108:111], v[146:149], v[210:213], v[108:111]
	v_mfma_f32_16x16x32_bf16 v[104:107], v[178:181], v[210:213], v[104:107]
	v_mfma_f32_16x16x32_bf16 v[92:95], v[146:149], v[218:221], v[92:95]
	v_mfma_f32_16x16x32_bf16 v[88:91], v[178:181], v[218:221], v[88:91]
	v_mfma_f32_16x16x32_bf16 v[76:79], v[146:149], v[230:233], v[76:79]
	v_mfma_f32_16x16x32_bf16 v[72:75], v[178:181], v[230:233], v[72:75]
	v_mfma_f32_16x16x32_bf16 v[124:127], v[150:153], v[206:209], v[124:127]
	v_mfma_f32_16x16x32_bf16 v[120:123], v[182:185], v[206:209], v[120:123]
	v_mfma_f32_16x16x32_bf16 v[108:111], v[150:153], v[214:217], v[108:111]
	v_mfma_f32_16x16x32_bf16 v[104:107], v[182:185], v[214:217], v[104:107]
	v_mfma_f32_16x16x32_bf16 v[92:95], v[150:153], v[226:229], v[92:95]
	v_mfma_f32_16x16x32_bf16 v[88:91], v[182:185], v[226:229], v[88:91]
	v_mfma_f32_16x16x32_bf16 v[76:79], v[150:153], v[234:237], v[76:79]
	v_mfma_f32_16x16x32_bf16 v[72:75], v[182:185], v[234:237], v[72:75]
	v_mfma_f32_16x16x32_bf16 v[116:119], v[186:189], v[202:205], v[116:119]
	v_mfma_f32_16x16x32_bf16 v[112:115], v[194:197], v[202:205], v[112:115]
	v_mfma_f32_16x16x32_bf16 v[100:103], v[186:189], v[210:213], v[100:103]
	v_mfma_f32_16x16x32_bf16 v[96:99], v[194:197], v[210:213], v[96:99]
	v_mfma_f32_16x16x32_bf16 v[84:87], v[186:189], v[218:221], v[84:87]
	v_mfma_f32_16x16x32_bf16 v[80:83], v[194:197], v[218:221], v[80:83]
	v_mfma_f32_16x16x32_bf16 v[68:71], v[186:189], v[230:233], v[68:71]
	v_mfma_f32_16x16x32_bf16 v[64:67], v[194:197], v[230:233], v[64:67]
	v_mfma_f32_16x16x32_bf16 v[116:119], v[190:193], v[206:209], v[116:119]
	v_mfma_f32_16x16x32_bf16 v[112:115], v[198:201], v[206:209], v[112:115]
	v_mfma_f32_16x16x32_bf16 v[100:103], v[190:193], v[214:217], v[100:103]
	v_mfma_f32_16x16x32_bf16 v[96:99], v[198:201], v[214:217], v[96:99]
	v_mfma_f32_16x16x32_bf16 v[84:87], v[190:193], v[226:229], v[84:87]
	v_mfma_f32_16x16x32_bf16 v[80:83], v[198:201], v[226:229], v[80:83]
	v_mfma_f32_16x16x32_bf16 v[68:71], v[190:193], v[234:237], v[68:71]
	v_mfma_f32_16x16x32_bf16 v[64:67], v[198:201], v[234:237], v[64:67]
	v_mfma_f32_16x16x32_bf16 v[60:63], v[146:149], v[154:157], v[60:63]
	v_mfma_f32_16x16x32_bf16 v[56:59], v[178:181], v[154:157], v[56:59]
	v_mfma_f32_16x16x32_bf16 v[44:47], v[146:149], v[162:165], v[44:47]
	v_mfma_f32_16x16x32_bf16 v[40:43], v[178:181], v[162:165], v[40:43]
	v_mfma_f32_16x16x32_bf16 v[28:31], v[146:149], v[170:173], v[28:31]
	v_mfma_f32_16x16x32_bf16 v[24:27], v[178:181], v[170:173], v[24:27]
	v_mfma_f32_16x16x32_bf16 v[12:15], v[146:149], v[242:245], v[12:15]
	v_mfma_f32_16x16x32_bf16 v[8:11], v[178:181], v[242:245], v[8:11]
	v_mfma_f32_16x16x32_bf16 v[60:63], v[150:153], v[158:161], v[60:63]
	v_mfma_f32_16x16x32_bf16 v[56:59], v[182:185], v[158:161], v[56:59]
	v_mfma_f32_16x16x32_bf16 v[44:47], v[150:153], v[166:169], v[44:47]
	v_mfma_f32_16x16x32_bf16 v[40:43], v[182:185], v[166:169], v[40:43]
	v_mfma_f32_16x16x32_bf16 v[28:31], v[150:153], v[238:241], v[28:31]
	v_mfma_f32_16x16x32_bf16 v[24:27], v[182:185], v[238:241], v[24:27]
	v_mfma_f32_16x16x32_bf16 v[12:15], v[150:153], v[246:249], v[12:15]
	v_mfma_f32_16x16x32_bf16 v[8:11], v[182:185], v[246:249], v[8:11]
	v_mfma_f32_16x16x32_bf16 v[52:55], v[186:189], v[154:157], v[52:55]
	v_mfma_f32_16x16x32_bf16 v[48:51], v[194:197], v[154:157], v[48:51]
	v_mfma_f32_16x16x32_bf16 v[36:39], v[186:189], v[162:165], v[36:39]
	v_mfma_f32_16x16x32_bf16 v[32:35], v[194:197], v[162:165], v[32:35]
	v_mfma_f32_16x16x32_bf16 v[20:23], v[186:189], v[170:173], v[20:23]
	v_mfma_f32_16x16x32_bf16 v[16:19], v[194:197], v[170:173], v[16:19]
	v_mfma_f32_16x16x32_bf16 v[4:7], v[186:189], v[242:245], v[4:7]
	v_mfma_f32_16x16x32_bf16 v[0:3], v[194:197], v[242:245], v[0:3]
	v_mfma_f32_16x16x32_bf16 v[52:55], v[190:193], v[158:161], v[52:55]
	v_mfma_f32_16x16x32_bf16 v[48:51], v[198:201], v[158:161], v[48:51]
	v_mfma_f32_16x16x32_bf16 v[36:39], v[190:193], v[166:169], v[36:39]
	v_mfma_f32_16x16x32_bf16 v[32:35], v[198:201], v[166:169], v[32:35]
	v_mfma_f32_16x16x32_bf16 v[20:23], v[190:193], v[238:241], v[20:23]
	v_mfma_f32_16x16x32_bf16 v[16:19], v[198:201], v[238:241], v[16:19]
	v_mfma_f32_16x16x32_bf16 v[4:7], v[190:193], v[246:249], v[4:7]
	v_mfma_f32_16x16x32_bf16 v[0:3], v[198:201], v[246:249], v[0:3]
	s_waitcnt vmcnt(0)
	s_barrier
; #define PG8_STAGE(bufoff, gbase, voff) do { _Pragma("unroll") for (int _i = 0; _i < 2; ++_i) \
;         __builtin_amdgcn_global_load_lds((const unsigned*)((const char*)(gbase) + (voff)[_i]), (PG8_LAS unsigned*)(lds + (bufoff) + ldsw + _i * 8192), 16, 0, 0); } while (0)
; #define PG8_LDA(dst, b, h) do { _Pragma("unroll") for (int m = 0; m < 4; ++m) _Pragma("unroll") for (int k = 0; k < 2; ++k) dst[m][k] = *(const PG8_LAS bf16x8*)(lds + PG8_SA(b, h) + aoff + m * 2048 + k * 1024); } while (0)
; #define PG8_LDB(dst, b, h) do { _Pragma("unroll") for (int n = 0; n < 2; ++n) _Pragma("unroll") for (int k = 0; k < 2; ++k) dst[n][k] = *(const PG8_LAS bf16x8*)(lds + PG8_SB(b, h) + boff + n * 2048 + k * 1024); } while (0)
; #define PG8_MMA(ai, bj, At, Bt) do { __builtin_amdgcn_s_setprio(1); _Pragma("unroll") for (int m = 0; m < 4; ++m) _Pragma("unroll") for (int n = 0; n < 2; ++n) _Pragma("unroll") for (int k = 0; k < 2; ++k) \
;         acc[ai][bj][m][n] = __builtin_amdgcn_mfma_f32_16x16x32_bf16(Bt[n][k], At[m][k], acc[ai][bj][m][n], 0, 0, 0); __builtin_amdgcn_s_setprio(0); } while (0)
; #define PG8_WAIT_V(n) asm volatile("s_waitcnt vmcnt(" #n ")" ::: "memory")
; template <class Epi, class Sched, bool ALIGN_EPI = false, bool SP2 = false>
; __device__ __forceinline__ void gemm_phase(PG8_LAS unsigned char* lds, const Gemm g, const Sched& S, const Epi& E) {
;     ...
;             PG8_LDB(B0, 0, 0); PG8_LDB(B1, 0, 1); PG8_SCHED; PG8_LDA(At, 0, 0); PG8_STAGE(PG8_SA(1, 1), a1 + hstep, voffA);
;             PG8_WAIT_V(8); PG8_WAIT_L(0); PG8_BAR; PG8_MMA(0, 0, At, B0); PG8_MMA(0, 1, At, B1); PG8_BAR; PG8_SCHED;
;             PG8_LDA(At, 0, 1); PG8_STAGE(PG8_SB(0, 0), b2, voffB); PG8_STAGE(PG8_SB(0, 1), b2 + hstep, voffB); PG8_STAGE(PG8_SA(0, 0), a2, voffA);
;             PG8_WAIT_V(8); PG8_WAIT_L(0); PG8_BAR; PG8_MMA(1, 0, At, B0); PG8_MMA(1, 1, At, B1); PG8_BAR; PG8_SCHED;
;             PG8_LDB(B0, 1, 0); PG8_LDB(B1, 1, 1); PG8_SCHED; PG8_LDA(At, 1, 0); PG8_STAGE(PG8_SA(0, 1), a2 + hstep, voffA);
;             PG8_WAIT_V(8); PG8_WAIT_L(0); PG8_BAR; PG8_MMA(0, 0, At, B0); PG8_MMA(0, 1, At, B1); PG8_BAR; PG8_SCHED;
;             PG8_LDA(At, 1, 1); PG8_STAGE(PG8_SB(1, 0), b3, voffB); PG8_STAGE(PG8_SB(1, 1), b3 + hstep, voffB); PG8_STAGE(PG8_SA(1, 0), a3, voffA);
;             PG8_WAIT_V(8); PG8_WAIT_L(0); PG8_BAR; PG8_MMA(1, 0, At, B0); PG8_MMA(1, 1, At, B1); PG8_BAR; PG8_SCHED;
	s_setprio 0
	s_cmp_lg_u32 s16, 0
	s_cbranch_scc0 .Lspf7_b_h1
	s_add_i32 m0, s3, 0x10000
	ds_read_b128 v[146:149], v174
	ds_read_b128 v[150:153], v174 offset:1024
	ds_read_b128 v[178:181], v174 offset:2048
	global_load_lds_dwordx4 v132, s[30:31]
	s_add_i32 m0, s3, 0x12000
	ds_read_b128 v[182:185], v174 offset:3072
	ds_read_b128 v[186:189], v177
	ds_read_b128 v[190:193], v177 offset:1024
	global_load_lds_dwordx4 v128, s[30:31]
	s_add_u32 s98, s30, 0x20000
	s_addc_u32 s99, s31, 0
	s_add_i32 m0, s3, 0x11000
	ds_read_b128 v[194:197], v177 offset:2048
	ds_read_b128 v[198:201], v177 offset:3072
	ds_read_b128 v[202:205], v141 offset:32768
	global_load_lds_dwordx4 v132, s[98:99]
	s_add_i32 m0, s3, 0x13000
	ds_read_b128 v[206:209], v141 offset:33792
	ds_read_b128 v[210:213], v141 offset:34816
	ds_read_b128 v[214:217], v141 offset:35840
	global_load_lds_dwordx4 v128, s[98:99]
	s_add_u32 s98, s30, 0x80000
	s_addc_u32 s99, s31, 0
	s_add_i32 m0, s3, 0x14000
	ds_read_b128 v[218:221], v141 offset:36864
	ds_read_b128 v[226:229], v141 offset:37888
	ds_read_b128 v[230:233], v141 offset:38912
	global_load_lds_dwordx4 v132, s[98:99]
	s_add_i32 m0, s3, 0x16000
	ds_read_b128 v[234:237], v141 offset:39936
	ds_read_b128 v[154:157], v141 offset:49152
	ds_read_b128 v[158:161], v141 offset:50176
	global_load_lds_dwordx4 v128, s[98:99]
	s_add_u32 s98, s30, 0xa0000
	s_addc_u32 s99, s31, 0
	s_add_i32 m0, s3, 0x15000
	ds_read_b128 v[162:165], v141 offset:51200
	ds_read_b128 v[166:169], v141 offset:52224
	ds_read_b128 v[170:173], v141 offset:53248
	global_load_lds_dwordx4 v132, s[98:99]
	s_add_i32 m0, s3, 0x17000
	ds_read_b128 v[238:241], v141 offset:54272
	ds_read_b128 v[242:245], v141 offset:55296
	ds_read_b128 v[246:249], v141 offset:56320
	global_load_lds_dwordx4 v128, s[98:99]
	s_branch .Lspf7_b_rd
.Lspf7_b_h1:
	s_add_i32 m0, s3, 0x2000
	ds_read_b128 v[146:149], v174
	ds_read_b128 v[150:153], v174 offset:1024
	ds_read_b128 v[178:181], v174 offset:2048
	global_load_lds_dwordx4 v130, s[36:37]
	s_add_u32 s98, s36, 0xfffe0000
	s_addc_u32 s99, s37, -1
	s_add_i32 m0, s3, 0x1000
	ds_read_b128 v[182:185], v174 offset:3072
	ds_read_b128 v[186:189], v177
	ds_read_b128 v[190:193], v177 offset:1024
	global_load_lds_dwordx4 v130, s[98:99]
	s_add_u32 s98, s36, 0x80000
	s_addc_u32 s99, s37, 0
	s_add_i32 m0, s3, 0x6000
	ds_read_b128 v[194:197], v177 offset:2048
	ds_read_b128 v[198:201], v177 offset:3072
	ds_read_b128 v[202:205], v141 offset:32768
	global_load_lds_dwordx4 v130, s[98:99]
	s_add_u32 s98, s36, 0x60000
	s_addc_u32 s99, s37, 0
	s_add_i32 m0, s3, 0x5000
	ds_read_b128 v[206:209], v141 offset:33792
	ds_read_b128 v[210:213], v141 offset:34816
	ds_read_b128 v[214:217], v141 offset:35840
	global_load_lds_dwordx4 v130, s[98:99]
	s_add_u32 s98, s36, 0x80
	s_addc_u32 s99, s37, 0
	s_add_i32 m0, s3, 0x8000
	ds_read_b128 v[218:221], v141 offset:36864
	ds_read_b128 v[226:229], v141 offset:37888
	ds_read_b128 v[230:233], v141 offset:38912
	global_load_lds_dwordx4 v134, s[98:99]
	s_add_u32 s98, s36, 0xfffe0080
	s_addc_u32 s99, s37, -1
	s_add_i32 m0, s3, 0x7000
	ds_read_b128 v[234:237], v141 offset:39936
	ds_read_b128 v[154:157], v141 offset:49152
	ds_read_b128 v[158:161], v141 offset:50176
	global_load_lds_dwordx4 v134, s[98:99]
	s_add_u32 s98, s36, 0x80080
	s_addc_u32 s99, s37, 0
	s_add_i32 m0, s3, 0xc000
	ds_read_b128 v[162:165], v141 offset:51200
	ds_read_b128 v[166:169], v141 offset:52224
	ds_read_b128 v[170:173], v141 offset:53248
	global_load_lds_dwordx4 v134, s[98:99]
	s_add_u32 s98, s36, 0x60080
	s_addc_u32 s99, s37, 0
	s_add_i32 m0, s3, 0xb000
	ds_read_b128 v[238:241], v141 offset:54272
	ds_read_b128 v[242:245], v141 offset:55296
	ds_read_b128 v[246:249], v141 offset:56320
	global_load_lds_dwordx4 v134, s[98:99]
; #define PG8_STAGE(bufoff, gbase, voff) do { _Pragma("unroll") for (int _i = 0; _i < 2; ++_i) \
;         __builtin_amdgcn_global_load_lds((const unsigned*)((const char*)(gbase) + (voff)[_i]), (PG8_LAS unsigned*)(lds + (bufoff) + ldsw + _i * 8192), 16, 0, 0); } while (0)
; #define PG8_LDA(dst, b, h) do { _Pragma("unroll") for (int m = 0; m < 4; ++m) _Pragma("unroll") for (int k = 0; k < 2; ++k) dst[m][k] = *(const PG8_LAS bf16x8*)(lds + PG8_SA(b, h) + aoff + m * 2048 + k * 1024); } while (0)
; #define PG8_LDB(dst, b, h) do { _Pragma("unroll") for (int n = 0; n < 2; ++n) _Pragma("unroll") for (int k = 0; k < 2; ++k) dst[n][k] = *(const PG8_LAS bf16x8*)(lds + PG8_SB(b, h) + boff + n * 2048 + k * 1024); } while (0)
; #define PG8_MMA(ai, bj, At, Bt) do { __builtin_amdgcn_s_setprio(1); _Pragma("unroll") for (int m = 0; m < 4; ++m) _Pragma("unroll") for (int n = 0; n < 2; ++n) _Pragma("unroll") for (int k = 0; k < 2; ++k) \
;         acc[ai][bj][m][n] = __builtin_amdgcn_mfma_f32_16x16x32_bf16(Bt[n][k], At[m][k], acc[ai][bj][m][n], 0, 0, 0); __builtin_amdgcn_s_setprio(0); } while (0)
; #define PG8_WAIT_V(n) asm volatile("s_waitcnt vmcnt(" #n ")" ::: "memory")
; template <class Epi, class Sched, bool ALIGN_EPI = false, bool SP2 = false>
; __device__ __forceinline__ void gemm_phase(PG8_LAS unsigned char* lds, const Gemm g, const Sched& S, const Epi& E) {
;     ...
;             PG8_LDB(B0, 0, 0); PG8_LDB(B1, 0, 1); PG8_SCHED; PG8_LDA(At, 0, 0); PG8_STAGE(PG8_SA(1, 1), a1 + hstep, voffA);
;             PG8_WAIT_V(8); PG8_WAIT_L(0); PG8_BAR; PG8_MMA(0, 0, At, B0); PG8_MMA(0, 1, At, B1); PG8_BAR; PG8_SCHED;
;             PG8_LDA(At, 0, 1); PG8_STAGE(PG8_SB(0, 0), b2, voffB); PG8_STAGE(PG8_SB(0, 1), b2 + hstep, voffB); PG8_STAGE(PG8_SA(0, 0), a2, voffA);
;             PG8_WAIT_V(8); PG8_WAIT_L(0); PG8_BAR; PG8_MMA(1, 0, At, B0); PG8_MMA(1, 1, At, B1); PG8_BAR; PG8_SCHED;
;             PG8_LDB(B0, 1, 0); PG8_LDB(B1, 1, 1); PG8_SCHED; PG8_LDA(At, 1, 0); PG8_STAGE(PG8_SA(0, 1), a2 + hstep, voffA);
;             PG8_WAIT_V(8); PG8_WAIT_L(0); PG8_BAR; PG8_MMA(0, 0, At, B0); PG8_MMA(0, 1, At, B1); PG8_BAR; PG8_SCHED;
;             PG8_LDA(At, 1, 1); PG8_STAGE(PG8_SB(1, 0), b3, voffB); PG8_STAGE(PG8_SB(1, 1), b3 + hstep, voffB); PG8_STAGE(PG8_SA(1, 0), a3, voffA);
;             PG8_WAIT_V(8); PG8_WAIT_L(0); PG8_BAR; PG8_MMA(1, 0, At, B0); PG8_MMA(1, 1, At, B1); PG8_BAR; PG8_SCHED;
.Lspf7_b_rd:
	s_waitcnt lgkmcnt(0)
	s_setprio 1
	s_barrier
	v_mfma_f32_16x16x32_bf16 v[124:127], v[146:149], v[202:205], v[124:127]
	v_mfma_f32_16x16x32_bf16 v[120:123], v[178:181], v[202:205], v[120:123]
	v_mfma_f32_16x16x32_bf16 v[108:111], v[146:149], v[210:213], v[108:111]
	v_mfma_f32_16x16x32_bf16 v[104:107], v[178:181], v[210:213], v[104:107]
	v_mfma_f32_16x16x32_bf16 v[92:95], v[146:149], v[218:221], v[92:95]
	v_mfma_f32_16x16x32_bf16 v[88:91], v[178:181], v[218:221], v[88:91]
	v_mfma_f32_16x16x32_bf16 v[76:79], v[146:149], v[230:233], v[76:79]
	v_mfma_f32_16x16x32_bf16 v[72:75], v[178:181], v[230:233], v[72:75]
	v_mfma_f32_16x16x32_bf16 v[124:127], v[150:153], v[206:209], v[124:127]
	v_mfma_f32_16x16x32_bf16 v[120:123], v[182:185], v[206:209], v[120:123]
	v_mfma_f32_16x16x32_bf16 v[108:111], v[150:153], v[214:217], v[108:111]
	v_mfma_f32_16x16x32_bf16 v[104:107], v[182:185], v[214:217], v[104:107]
	v_mfma_f32_16x16x32_bf16 v[92:95], v[150:153], v[226:229], v[92:95]
	v_mfma_f32_16x16x32_bf16 v[88:91], v[182:185], v[226:229], v[88:91]
	v_mfma_f32_16x16x32_bf16 v[76:79], v[150:153], v[234:237], v[76:79]
	v_mfma_f32_16x16x32_bf16 v[72:75], v[182:185], v[234:237], v[72:75]
	v_mfma_f32_16x16x32_bf16 v[116:119], v[186:189], v[202:205], v[116:119]
	v_mfma_f32_16x16x32_bf16 v[112:115], v[194:197], v[202:205], v[112:115]
	v_mfma_f32_16x16x32_bf16 v[100:103], v[186:189], v[210:213], v[100:103]
	v_mfma_f32_16x16x32_bf16 v[96:99], v[194:197], v[210:213], v[96:99]
	v_mfma_f32_16x16x32_bf16 v[84:87], v[186:189], v[218:221], v[84:87]
	v_mfma_f32_16x16x32_bf16 v[80:83], v[194:197], v[218:221], v[80:83]
	v_mfma_f32_16x16x32_bf16 v[68:71], v[186:189], v[230:233], v[68:71]
	v_mfma_f32_16x16x32_bf16 v[64:67], v[194:197], v[230:233], v[64:67]
	v_mfma_f32_16x16x32_bf16 v[116:119], v[190:193], v[206:209], v[116:119]
	v_mfma_f32_16x16x32_bf16 v[112:115], v[198:201], v[206:209], v[112:115]
	v_mfma_f32_16x16x32_bf16 v[100:103], v[190:193], v[214:217], v[100:103]
	v_mfma_f32_16x16x32_bf16 v[96:99], v[198:201], v[214:217], v[96:99]
	v_mfma_f32_16x16x32_bf16 v[84:87], v[190:193], v[226:229], v[84:87]
	v_mfma_f32_16x16x32_bf16 v[80:83], v[198:201], v[226:229], v[80:83]
	v_mfma_f32_16x16x32_bf16 v[68:71], v[190:193], v[234:237], v[68:71]
	v_mfma_f32_16x16x32_bf16 v[64:67], v[198:201], v[234:237], v[64:67]
	v_mfma_f32_16x16x32_bf16 v[60:63], v[146:149], v[154:157], v[60:63]
	v_mfma_f32_16x16x32_bf16 v[56:59], v[178:181], v[154:157], v[56:59]
	v_mfma_f32_16x16x32_bf16 v[44:47], v[146:149], v[162:165], v[44:47]
	v_mfma_f32_16x16x32_bf16 v[40:43], v[178:181], v[162:165], v[40:43]
	v_mfma_f32_16x16x32_bf16 v[28:31], v[146:149], v[170:173], v[28:31]
	v_mfma_f32_16x16x32_bf16 v[24:27], v[178:181], v[170:173], v[24:27]
	v_mfma_f32_16x16x32_bf16 v[12:15], v[146:149], v[242:245], v[12:15]
	v_mfma_f32_16x16x32_bf16 v[8:11], v[178:181], v[242:245], v[8:11]
	v_mfma_f32_16x16x32_bf16 v[60:63], v[150:153], v[158:161], v[60:63]
	v_mfma_f32_16x16x32_bf16 v[56:59], v[182:185], v[158:161], v[56:59]
	v_mfma_f32_16x16x32_bf16 v[44:47], v[150:153], v[166:169], v[44:47]
	v_mfma_f32_16x16x32_bf16 v[40:43], v[182:185], v[166:169], v[40:43]
	v_mfma_f32_16x16x32_bf16 v[28:31], v[150:153], v[238:241], v[28:31]
	v_mfma_f32_16x16x32_bf16 v[24:27], v[182:185], v[238:241], v[24:27]
	v_mfma_f32_16x16x32_bf16 v[12:15], v[150:153], v[246:249], v[12:15]
	v_mfma_f32_16x16x32_bf16 v[8:11], v[182:185], v[246:249], v[8:11]
	v_mfma_f32_16x16x32_bf16 v[52:55], v[186:189], v[154:157], v[52:55]
	v_mfma_f32_16x16x32_bf16 v[48:51], v[194:197], v[154:157], v[48:51]
	v_mfma_f32_16x16x32_bf16 v[36:39], v[186:189], v[162:165], v[36:39]
	v_mfma_f32_16x16x32_bf16 v[32:35], v[194:197], v[162:165], v[32:35]
	v_mfma_f32_16x16x32_bf16 v[20:23], v[186:189], v[170:173], v[20:23]
	v_mfma_f32_16x16x32_bf16 v[16:19], v[194:197], v[170:173], v[16:19]
	v_mfma_f32_16x16x32_bf16 v[4:7], v[186:189], v[242:245], v[4:7]
	v_mfma_f32_16x16x32_bf16 v[0:3], v[194:197], v[242:245], v[0:3]
	v_mfma_f32_16x16x32_bf16 v[52:55], v[190:193], v[158:161], v[52:55]
	v_mfma_f32_16x16x32_bf16 v[48:51], v[198:201], v[158:161], v[48:51]
	v_mfma_f32_16x16x32_bf16 v[36:39], v[190:193], v[166:169], v[36:39]
	v_mfma_f32_16x16x32_bf16 v[32:35], v[198:201], v[166:169], v[32:35]
	v_mfma_f32_16x16x32_bf16 v[20:23], v[190:193], v[238:241], v[20:23]
	v_mfma_f32_16x16x32_bf16 v[16:19], v[198:201], v[238:241], v[16:19]
	v_mfma_f32_16x16x32_bf16 v[4:7], v[190:193], v[246:249], v[4:7]
	v_mfma_f32_16x16x32_bf16 v[0:3], v[198:201], v[246:249], v[0:3]
	s_waitcnt vmcnt(0)
	s_barrier
	s_setprio 0
	s_add_i32 s49, s49, 2
	s_add_u32 s28, s28, 0x100
	s_addc_u32 s29, s29, 0
	s_add_u32 s47, s47, 0x100
	s_addc_u32 s48, s48, 0
	s_cmp_gt_u32 s49, 29
	s_cbranch_scc0 .LBB0_1025
	v_mov_b32_e32 v175, v141
	v_mov_b32_e32 v171, v139
	v_mov_b32_e32 v167, v135
	v_mov_b32_e32 v163, v133
	v_mov_b32_e32 v159, v131
	v_mov_b32_e32 v155, v129
	s_and_b64 vcc, exec, s[16:17]
	s_cbranch_vccz .LBB0_1028
	s_barrier

; #define PG8_STAGE(bufoff, gbase, voff) do { _Pragma("unroll") for (int _i = 0; _i < 2; ++_i) \
;         __builtin_amdgcn_global_load_lds((const unsigned*)((const char*)(gbase) + (voff)[_i]), (PG8_LAS unsigned*)(lds + (bufoff) + ldsw + _i * 8192), 16, 0, 0); } while (0)
; #define PG8_WAIT_V(n) asm volatile("s_waitcnt vmcnt(" #n ")" ::: "memory")
; #define PG8_BAR __builtin_amdgcn_s_barrier()
; template <class Epi, class Sched, bool ALIGN_EPI = false, bool SP2 = false>
; __device__ __forceinline__ void gemm_phase(PG8_LAS unsigned char* lds, const Gemm g, const Sched& S, const Epi& E) {
;     ...
;     for (int i = 0; i < 2; ++i) { int R, C; stage_rc(tid * 16 + i * 8192, R, C); const int Rb = Epi::PERM ? ((R & ~31) + perm32(R & 31)) : R;
;         voffA[i] = (unsigned)(R * K + C) * 2u; voffB[i] = (unsigned)(Rb * K + C) * 2u; }
;     const size_t kstep = (size_t)(BK * 2);
;     const size_t hstep = (size_t)HALF * K * 2;
;     const size_t tstep = 2 * hstep;
;     const unsigned ldsw = (unsigned)wid * 1024u;
;     const int aoff = lds_byte(wr * 64 + fr, fq * 8), boff = lds_byte(wc * 32 + fr, fq * 8);
;     ...
;     if constexpr (SP2) {
;         PG8_STAGE(PG8_SB(0, 0), cB, voffB); PG8_STAGE(PG8_SB(0, 1), cB + hstep, voffB); PG8_STAGE(PG8_SA(0, 0), cA, voffA); PG8_STAGE(PG8_SA(0, 1), cA + hstep, voffA);
;         if (wr == 1) PG8_BAR;
;         PG8_WAIT_V(2); PG8_BAR;
;         PG8_STAGE(PG8_SB(1, 0), cB + kstep, voffB); PG8_STAGE(PG8_SA(1, 0), cA + kstep, voffA); PG8_STAGE(PG8_SB(1, 1), cB + hstep + kstep, voffB);
;         PG8_WAIT_V(6); PG8_BAR;
.LBB0_1094:
	s_and_b32 s35, s7, 3
	s_lshl_b32 s7, s9, 13
	s_lshl_b32 s11, s35, 12
	s_add_u32 s18, s58, 0x300000
	s_mov_b64 s[20:21], 0x80
	s_addc_u32 s19, s59, 0
	s_add_i32 m0, s15, 0x18000
	v_lshl_add_u64 v[6:7], v[6:7], 0, s[20:21]
	s_waitcnt vmcnt(0)
	s_barrier
	global_load_lds_dwordx4 v[6:7], off
	v_lshl_add_u64 v[4:5], v[4:5], 0, s[20:21]
	s_add_i32 m0, s15, 0x1a000
	s_add_i32 s42, s15, 0x8000
	s_add_i32 s43, s15, 0xa000
	global_load_lds_dwordx4 v[4:5], off
	v_lshl_add_u64 v[0:1], v[0:1], 0, s[20:21]
	s_mov_b32 m0, s42
	s_add_u32 s24, s30, 0x160080
	global_load_lds_dwordx4 v[0:1], off
	v_lshl_add_u64 v[0:1], v[2:3], 0, s[20:21]
	s_mov_b32 m0, s43
	s_addc_u32 s25, s31, 0
	global_load_lds_dwordx4 v[0:1], off
	s_add_i32 m0, s15, 0x1c000
	v_lshl_add_u64 v[0:1], s[24:25], 0, v[176:177]
	global_load_lds_dwordx4 v[0:1], off
	v_lshl_add_u64 v[0:1], s[24:25], 0, v[178:179]
	s_add_i32 m0, s15, 0x1e000
	s_cmpk_lt_u32 s6, 0x100
	global_load_lds_dwordx4 v[0:1], off
	v_bfe_u32 v0, v8, 4, 2
	v_and_b32_e32 v1, 15, v8
	v_lshlrev_b32_e32 v2, 4, v0
	v_lshl_or_b32 v206, s9, 6, v1
	v_lshl_or_b32 v1, v1, 6, v2
	v_lshlrev_b32_e32 v2, 2, v8
	v_and_b32_e32 v2, 32, v2
	v_bitop3_b32 v3, v1, s7, v2 bitop3:0xde
	v_bitop3_b32 v207, v1, s11, v2 bitop3:0xde
	v_lshlrev_b32_e32 v1, 2, v0
	v_lshl_or_b32 v208, s35, 5, v1
	v_cmp_eq_u32_e64 s[6:7], 0, v0
	v_lshrrev_b32_e32 v1, 1, v9
	v_mul_lo_u32 v0, v10, s8
	v_mad_u64_u32 v[0:1], s[36:37], v1, s10, v[0:1]
	v_or_b32_e32 v0, v0, v11
	s_mov_b64 s[26:27], 0x160080
	v_add_lshl_u32 v0, v0, v12, 1
	v_mov_b32_e32 v1, v177
	v_lshl_add_u64 v[180:181], v[0:1], 0, s[26:27]
	v_lshrrev_b32_e32 v1, 1, v13
	v_mul_lo_u32 v0, v14, s8
	v_mad_u64_u32 v[0:1], s[8:9], v1, s10, v[0:1]
	s_waitcnt vmcnt(6)
	v_or_b32_e32 v0, v0, v15
	s_cselect_b64 s[24:25], -1, 0
	v_add_lshl_u32 v0, v0, v16, 1
	v_mov_b32_e32 v1, v177
	s_add_i32 s44, 0, 0x10000
	s_add_i32 s45, 0, 0x14000
	v_lshl_add_u64 v[182:183], v[0:1], 0, s[26:27]
	v_mov_b64_e32 v[184:185], 0x100
	v_mov_b64_e32 v[186:187], 0xff
	v_add_u32_e32 v209, s44, v207
	v_add_u32_e32 v210, s45, v207
	v_add_u32_e32 v211, 0, v3
	s_mov_b32 s46, 0
	s_barrier
	s_branch .LBB0_1097

; #define PG8_STAGE(bufoff, gbase, voff) do { _Pragma("unroll") for (int _i = 0; _i < 2; ++_i) \
;         __builtin_amdgcn_global_load_lds((const unsigned*)((const char*)(gbase) + (voff)[_i]), (PG8_LAS unsigned*)(lds + (bufoff) + ldsw + _i * 8192), 16, 0, 0); } while (0)
; #define PG8_LDA(dst, b, h) do { _Pragma("unroll") for (int m = 0; m < 4; ++m) _Pragma("unroll") for (int k = 0; k < 2; ++k) dst[m][k] = *(const PG8_LAS bf16x8*)(lds + PG8_SA(b, h) + aoff + m * 2048 + k * 1024); } while (0)
; #define PG8_LDB(dst, b, h) do { _Pragma("unroll") for (int n = 0; n < 2; ++n) _Pragma("unroll") for (int k = 0; k < 2; ++k) dst[n][k] = *(const PG8_LAS bf16x8*)(lds + PG8_SB(b, h) + boff + n * 2048 + k * 1024); } while (0)
; #define PG8_WAIT_V(n) asm volatile("s_waitcnt vmcnt(" #n ")" ::: "memory")
; #define PG8_WAIT_L(n) asm volatile("s_waitcnt lgkmcnt(" #n ")" ::: "memory")
; #define PG8_BAR __builtin_amdgcn_s_barrier()
; #define PG8_SCHED __builtin_amdgcn_sched_barrier(0)
; template <class Epi, class Sched, bool ALIGN_EPI = false, bool SP2 = false>
; __device__ __forceinline__ void gemm_phase(PG8_LAS unsigned char* lds, const Gemm g, const Sched& S, const Epi& E) {
;     ...
;         for (int t = 0; t < nt; t += 2) {
;             const bool last = (t == nt - 2);
;             const char* a1 = cA + (size_t)(t + 1) * kstep;
;             const char* a2 = last ? nA : cA + (size_t)(t + 2) * kstep; const char* b2 = last ? nB : cB + (size_t)(t + 2) * kstep;
;             const char* a3 = a2 + kstep; const char* b3 = b2 + kstep;
;             if (last && has_next) S.a_ready(nxt);
;             if constexpr (SP2) {
;             PG8_LDB(B0, 0, 0); PG8_LDB(B1, 0, 1); PG8_SCHED; PG8_LDA(At, 0, 0); PG8_STAGE(PG8_SA(1, 1), a1 + hstep, voffA);
;             PG8_WAIT_V(8); PG8_WAIT_L(0); PG8_BAR; PG8_MMA(0, 0, At, B0); PG8_MMA(0, 1, At, B1); PG8_BAR; PG8_SCHED;
;             PG8_LDA(At, 0, 1); PG8_STAGE(PG8_SB(0, 0), b2, voffB); PG8_STAGE(PG8_SB(0, 1), b2 + hstep, voffB); PG8_STAGE(PG8_SA(0, 0), a2, voffA);
;     ...
; #pragma unroll
;         for (int a = 0; a < 2; ++a)
; #pragma unroll
;             for (int b = 0; b < 2; ++b)
; #pragma unroll
;                 for (int m = 0; m < 4; ++m)
; #pragma unroll
;                     for (int n = 0; n < 2; ++n) acc[a][b][m][n] = (f32x4){0.f, 0.f, 0.f, 0.f};
.LBB0_1107:
	s_add_u32 s13, s30, 0x100
	v_mov_b64_e32 v[0:1], 0
	v_mov_b64_e32 v[2:3], 0
	v_mov_b64_e32 v[4:5], 0
	v_mov_b64_e32 v[6:7], 0
	v_mov_b64_e32 v[8:9], 0
	v_mov_b64_e32 v[10:11], 0
	v_mov_b64_e32 v[12:13], 0
	v_mov_b64_e32 v[14:15], 0
	v_mov_b64_e32 v[16:17], 0
	v_mov_b64_e32 v[18:19], 0
	v_mov_b64_e32 v[20:21], 0
	v_mov_b64_e32 v[22:23], 0
	v_mov_b64_e32 v[24:25], 0
	v_mov_b64_e32 v[26:27], 0
	v_mov_b64_e32 v[28:29], 0
	v_mov_b64_e32 v[30:31], 0
	v_mov_b64_e32 v[32:33], 0
	v_mov_b64_e32 v[34:35], 0
	v_mov_b64_e32 v[36:37], 0
	v_mov_b64_e32 v[38:39], 0
	v_mov_b64_e32 v[40:41], 0
	v_mov_b64_e32 v[42:43], 0
	v_mov_b64_e32 v[44:45], 0
	v_mov_b64_e32 v[46:47], 0
	v_mov_b64_e32 v[48:49], 0
	v_mov_b64_e32 v[50:51], 0
	v_mov_b64_e32 v[52:53], 0
	v_mov_b64_e32 v[54:55], 0
	v_mov_b64_e32 v[56:57], 0
	v_mov_b64_e32 v[58:59], 0
	v_mov_b64_e32 v[60:61], 0
	v_mov_b64_e32 v[62:63], 0
	v_mov_b64_e32 v[64:65], 0
	v_mov_b64_e32 v[66:67], 0
	v_mov_b64_e32 v[68:69], 0
	v_mov_b64_e32 v[70:71], 0
	v_mov_b64_e32 v[72:73], 0
	v_mov_b64_e32 v[74:75], 0
	v_mov_b64_e32 v[76:77], 0
	v_mov_b64_e32 v[78:79], 0
	v_mov_b64_e32 v[80:81], 0
	v_mov_b64_e32 v[82:83], 0
	v_mov_b64_e32 v[84:85], 0
	v_mov_b64_e32 v[86:87], 0
	v_mov_b64_e32 v[88:89], 0
	v_mov_b64_e32 v[90:91], 0
	v_mov_b64_e32 v[92:93], 0
	v_mov_b64_e32 v[94:95], 0
	v_mov_b64_e32 v[96:97], 0
	v_mov_b64_e32 v[98:99], 0
	v_mov_b64_e32 v[100:101], 0
	v_mov_b64_e32 v[102:103], 0
	v_mov_b64_e32 v[104:105], 0
	v_mov_b64_e32 v[106:107], 0
	v_mov_b64_e32 v[108:109], 0
	v_mov_b64_e32 v[110:111], 0
	v_mov_b64_e32 v[112:113], 0
	v_mov_b64_e32 v[114:115], 0
	v_mov_b64_e32 v[116:117], 0
	v_mov_b64_e32 v[118:119], 0
	v_mov_b64_e32 v[120:121], 0
	v_mov_b64_e32 v[122:123], 0
	v_mov_b64_e32 v[124:125], 0
	v_mov_b64_e32 v[126:127], 0
	s_addc_u32 s49, s31, 0
	s_mov_b32 s50, -2
	s_waitcnt lgkmcnt(0)
	v_mov_b32_e32 v177, v207
	v_mov_b32_e32 v179, v209
	v_mov_b32_e32 v181, v210
	v_mov_b32_e32 v183, v211
	v_add_u32_e32 v204, 0x18000, v177
	v_add_u32_e32 v205, 0x1c000, v177
	s_cmp_lg_u32 s24, 0
	s_cbranch_scc0 .Lspf8_pre
	s_add_i32 m0, s14, 0xc000
	s_nop 0
	global_load_lds_dwordx4 v180, s[28:29]
	s_add_u32 s98, s28, 0x58000
	s_addc_u32 s99, s29, 0
	s_add_i32 m0, s14, 0xd000
	s_nop 0
	global_load_lds_dwordx4 v180, s[98:99]
	s_add_u32 s98, s28, 0xffea0000
	s_addc_u32 s99, s29, -1
	s_add_i32 m0, s14, 0x8000
	s_nop 0
	global_load_lds_dwordx4 v180, s[98:99]
	s_add_u32 s98, s28, 0xffef8000
	s_addc_u32 s99, s29, -1
	s_add_i32 m0, s14, 0x9000
	s_nop 0
	global_load_lds_dwordx4 v180, s[98:99]
.Lspf8_pre:
.LBB0_1108:
	s_add_u32 s30, s28, 0x100
	s_addc_u32 s31, s29, 0
	s_cmpk_eq_i32 s50, 0x54
	s_cselect_b32 s41, s11, s31
	s_cselect_b32 s40, s10, s30
	s_cselect_b32 s37, s27, s49
	s_cselect_b32 s36, s26, s13
	s_cmp_lg_u32 s24, 0
	s_cbranch_scc0 .Lspf8_a_h1
	s_add_u32 s98, s13, 0xffffff80
	s_addc_u32 s99, s49, -1
	s_add_i32 m0, s14, 0x18000
	ds_read_b128 v[128:131], v179
	ds_read_b128 v[132:135], v179 offset:1024
	ds_read_b128 v[136:139], v179 offset:2048
	global_load_lds_dwordx4 v176, s[98:99]
	s_add_i32 m0, s14, 0x1a000
	ds_read_b128 v[140:143], v179 offset:3072
	ds_read_b128 v[144:147], v181
	ds_read_b128 v[148:151], v181 offset:1024
	global_load_lds_dwordx4 v178, s[98:99]
	s_add_u32 s98, s13, 0x57f80
	s_addc_u32 s99, s49, 0
	s_add_i32 m0, s14, 0x19000
	ds_read_b128 v[152:155], v181 offset:2048
	ds_read_b128 v[156:159], v181 offset:3072
	ds_read_b128 v[160:163], v183
	global_load_lds_dwordx4 v176, s[98:99]
	s_add_i32 m0, s14, 0x1b000
	ds_read_b128 v[164:167], v183 offset:1024
	ds_read_b128 v[168:171], v183 offset:2048
	ds_read_b128 v[172:175], v183 offset:3072
	global_load_lds_dwordx4 v178, s[98:99]
	s_add_u32 s98, s13, 0x15ff80
	s_addc_u32 s99, s49, 0
	s_add_i32 m0, s14, 0x1c000
	ds_read_b128 v[188:191], v183 offset:4096
	ds_read_b128 v[192:195], v183 offset:5120
	ds_read_b128 v[196:199], v183 offset:6144
	global_load_lds_dwordx4 v176, s[98:99]
	s_add_i32 m0, s14, 0x1e000
	ds_read_b128 v[200:203], v183 offset:7168
	ds_read_b128 v[210:213], v183 offset:16384
	ds_read_b128 v[214:217], v183 offset:17408
	global_load_lds_dwordx4 v178, s[98:99]
	s_add_u32 s98, s13, 0x1b7f80
	s_addc_u32 s99, s49, 0
	s_add_i32 m0, s14, 0x1d000
	ds_read_b128 v[218:221], v183 offset:18432
	ds_read_b128 v[226:229], v183 offset:19456
	ds_read_b128 v[230:233], v183 offset:20480
	global_load_lds_dwordx4 v176, s[98:99]
	s_add_i32 m0, s14, 0x1f000
	ds_read_b128 v[234:237], v183 offset:21504
	ds_read_b128 v[238:241], v183 offset:22528
	ds_read_b128 v[242:245], v183 offset:23552
	global_load_lds_dwordx4 v178, s[98:99]
	s_branch .Lspf8_a_rd
.Lspf8_a_h1:
	s_add_u32 s98, s28, 0xffea0000
	s_addc_u32 s99, s29, -1
	s_add_i32 m0, s14, 0xa000
	ds_read_b128 v[128:131], v179
	ds_read_b128 v[132:135], v179 offset:1024
	ds_read_b128 v[136:139], v179 offset:2048
	global_load_lds_dwordx4 v182, s[98:99]
	s_add_u32 s98, s28, 0xffe48000
	s_addc_u32 s99, s29, -1
	s_add_i32 m0, s14, 0x9000
	ds_read_b128 v[140:143], v179 offset:3072
	ds_read_b128 v[144:147], v181
	ds_read_b128 v[148:151], v181 offset:1024
	global_load_lds_dwordx4 v182, s[98:99]
	s_add_i32 m0, s14, 0xe000
	ds_read_b128 v[152:155], v181 offset:2048
	ds_read_b128 v[156:159], v181 offset:3072
	ds_read_b128 v[160:163], v183
	global_load_lds_dwordx4 v182, s[28:29]
	s_add_u32 s98, s28, 0xfffa8000
	s_addc_u32 s99, s29, -1
	s_add_i32 m0, s14, 0xd000
	ds_read_b128 v[164:167], v183 offset:1024
	ds_read_b128 v[168:171], v183 offset:2048
	ds_read_b128 v[172:175], v183 offset:3072
	global_load_lds_dwordx4 v182, s[98:99]
	s_add_i32 m0, s14, 0x0
	ds_read_b128 v[188:191], v183 offset:4096
	ds_read_b128 v[192:195], v183 offset:5120
	ds_read_b128 v[196:199], v183 offset:6144
	global_load_lds_dwordx4 v176, s[40:41]
	s_add_u32 s98, s40, 0xfffa8000
	s_addc_u32 s99, s41, -1
	s_add_i32 m0, s14, 0xfffff000
	ds_read_b128 v[200:203], v183 offset:7168
	ds_read_b128 v[210:213], v183 offset:16384
	ds_read_b128 v[214:217], v183 offset:17408
	global_load_lds_dwordx4 v176, s[98:99]
	s_add_u32 s98, s40, 0x160000
	s_addc_u32 s99, s41, 0
	s_add_i32 m0, s14, 0x4000
	ds_read_b128 v[218:221], v183 offset:18432
	ds_read_b128 v[226:229], v183 offset:19456
	ds_read_b128 v[230:233], v183 offset:20480
	global_load_lds_dwordx4 v176, s[98:99]
	s_add_u32 s98, s40, 0x108000
	s_addc_u32 s99, s41, 0
	s_add_i32 m0, s14, 0x3000
	ds_read_b128 v[234:237], v183 offset:21504
	ds_read_b128 v[238:241], v183 offset:22528
	ds_read_b128 v[242:245], v183 offset:23552
	global_load_lds_dwordx4 v176, s[98:99]
; #define PG8_STAGE(bufoff, gbase, voff) do { _Pragma("unroll") for (int _i = 0; _i < 2; ++_i) \
;         __builtin_amdgcn_global_load_lds((const unsigned*)((const char*)(gbase) + (voff)[_i]), (PG8_LAS unsigned*)(lds + (bufoff) + ldsw + _i * 8192), 16, 0, 0); } while (0)
; #define PG8_LDA(dst, b, h) do { _Pragma("unroll") for (int m = 0; m < 4; ++m) _Pragma("unroll") for (int k = 0; k < 2; ++k) dst[m][k] = *(const PG8_LAS bf16x8*)(lds + PG8_SA(b, h) + aoff + m * 2048 + k * 1024); } while (0)
; #define PG8_LDB(dst, b, h) do { _Pragma("unroll") for (int n = 0; n < 2; ++n) _Pragma("unroll") for (int k = 0; k < 2; ++k) dst[n][k] = *(const PG8_LAS bf16x8*)(lds + PG8_SB(b, h) + boff + n * 2048 + k * 1024); } while (0)
; #define PG8_MMA(ai, bj, At, Bt) do { __builtin_amdgcn_s_setprio(1); _Pragma("unroll") for (int m = 0; m < 4; ++m) _Pragma("unroll") for (int n = 0; n < 2; ++n) _Pragma("unroll") for (int k = 0; k < 2; ++k) \
;         acc[ai][bj][m][n] = __builtin_amdgcn_mfma_f32_16x16x32_bf16(Bt[n][k], At[m][k], acc[ai][bj][m][n], 0, 0, 0); __builtin_amdgcn_s_setprio(0); } while (0)
; #define PG8_WAIT_V(n) asm volatile("s_waitcnt vmcnt(" #n ")" ::: "memory")
; #define PG8_WAIT_L(n) asm volatile("s_waitcnt lgkmcnt(" #n ")" ::: "memory")
; #define PG8_BAR __builtin_amdgcn_s_barrier()
; #define PG8_SCHED __builtin_amdgcn_sched_barrier(0)
; template <class Epi, class Sched, bool ALIGN_EPI = false, bool SP2 = false>
; __device__ __forceinline__ void gemm_phase(PG8_LAS unsigned char* lds, const Gemm g, const Sched& S, const Epi& E) {
;     ...
;             PG8_WAIT_V(8); PG8_WAIT_L(0); PG8_BAR; PG8_MMA(0, 0, At, B0); PG8_MMA(0, 1, At, B1); PG8_BAR; PG8_SCHED;
;             PG8_LDA(At, 0, 1); PG8_STAGE(PG8_SB(0, 0), b2, voffB); PG8_STAGE(PG8_SB(0, 1), b2 + hstep, voffB); PG8_STAGE(PG8_SA(0, 0), a2, voffA);
;             PG8_WAIT_V(8); PG8_WAIT_L(0); PG8_BAR; PG8_MMA(1, 0, At, B0); PG8_MMA(1, 1, At, B1); PG8_BAR; PG8_SCHED;
;             PG8_LDB(B0, 1, 0); PG8_LDB(B1, 1, 1); PG8_SCHED; PG8_LDA(At, 1, 0); PG8_STAGE(PG8_SA(0, 1), a2 + hstep, voffA);
;             PG8_WAIT_V(8); PG8_WAIT_L(0); PG8_BAR; PG8_MMA(0, 0, At, B0); PG8_MMA(0, 1, At, B1); PG8_BAR; PG8_SCHED;
;             PG8_LDA(At, 1, 1); PG8_STAGE(PG8_SB(1, 0), b3, voffB); PG8_STAGE(PG8_SB(1, 1), b3 + hstep, voffB); PG8_STAGE(PG8_SA(1, 0), a3, voffA);
.Lspf8_a_rd:
	s_waitcnt lgkmcnt(0)
	s_setprio 1
	s_barrier
	v_mfma_f32_16x16x32_bf16 v[124:127], v[128:131], v[160:163], v[124:127]
	v_mfma_f32_16x16x32_bf16 v[120:123], v[136:139], v[160:163], v[120:123]
	v_mfma_f32_16x16x32_bf16 v[108:111], v[128:131], v[168:171], v[108:111]
	v_mfma_f32_16x16x32_bf16 v[104:107], v[136:139], v[168:171], v[104:107]
	v_mfma_f32_16x16x32_bf16 v[92:95], v[128:131], v[188:191], v[92:95]
	v_mfma_f32_16x16x32_bf16 v[88:91], v[136:139], v[188:191], v[88:91]
	v_mfma_f32_16x16x32_bf16 v[76:79], v[128:131], v[196:199], v[76:79]
	v_mfma_f32_16x16x32_bf16 v[72:75], v[136:139], v[196:199], v[72:75]
	v_mfma_f32_16x16x32_bf16 v[124:127], v[132:135], v[164:167], v[124:127]
	v_mfma_f32_16x16x32_bf16 v[120:123], v[140:143], v[164:167], v[120:123]
	v_mfma_f32_16x16x32_bf16 v[108:111], v[132:135], v[172:175], v[108:111]
	v_mfma_f32_16x16x32_bf16 v[104:107], v[140:143], v[172:175], v[104:107]
	v_mfma_f32_16x16x32_bf16 v[92:95], v[132:135], v[192:195], v[92:95]
	v_mfma_f32_16x16x32_bf16 v[88:91], v[140:143], v[192:195], v[88:91]
	v_mfma_f32_16x16x32_bf16 v[76:79], v[132:135], v[200:203], v[76:79]
	v_mfma_f32_16x16x32_bf16 v[72:75], v[140:143], v[200:203], v[72:75]
	v_mfma_f32_16x16x32_bf16 v[116:119], v[144:147], v[160:163], v[116:119]
	v_mfma_f32_16x16x32_bf16 v[112:115], v[152:155], v[160:163], v[112:115]
	v_mfma_f32_16x16x32_bf16 v[100:103], v[144:147], v[168:171], v[100:103]
	v_mfma_f32_16x16x32_bf16 v[96:99], v[152:155], v[168:171], v[96:99]
	v_mfma_f32_16x16x32_bf16 v[84:87], v[144:147], v[188:191], v[84:87]
	v_mfma_f32_16x16x32_bf16 v[80:83], v[152:155], v[188:191], v[80:83]
	v_mfma_f32_16x16x32_bf16 v[68:71], v[144:147], v[196:199], v[68:71]
	v_mfma_f32_16x16x32_bf16 v[64:67], v[152:155], v[196:199], v[64:67]
	v_mfma_f32_16x16x32_bf16 v[116:119], v[148:151], v[164:167], v[116:119]
	v_mfma_f32_16x16x32_bf16 v[112:115], v[156:159], v[164:167], v[112:115]
	v_mfma_f32_16x16x32_bf16 v[100:103], v[148:151], v[172:175], v[100:103]
	v_mfma_f32_16x16x32_bf16 v[96:99], v[156:159], v[172:175], v[96:99]
	v_mfma_f32_16x16x32_bf16 v[84:87], v[148:151], v[192:195], v[84:87]
	v_mfma_f32_16x16x32_bf16 v[80:83], v[156:159], v[192:195], v[80:83]
	v_mfma_f32_16x16x32_bf16 v[68:71], v[148:151], v[200:203], v[68:71]
	v_mfma_f32_16x16x32_bf16 v[64:67], v[156:159], v[200:203], v[64:67]
	v_mfma_f32_16x16x32_bf16 v[60:63], v[128:131], v[210:213], v[60:63]
	v_mfma_f32_16x16x32_bf16 v[56:59], v[136:139], v[210:213], v[56:59]
	v_mfma_f32_16x16x32_bf16 v[44:47], v[128:131], v[218:221], v[44:47]
	v_mfma_f32_16x16x32_bf16 v[40:43], v[136:139], v[218:221], v[40:43]
	v_mfma_f32_16x16x32_bf16 v[28:31], v[128:131], v[230:233], v[28:31]
	v_mfma_f32_16x16x32_bf16 v[24:27], v[136:139], v[230:233], v[24:27]
	v_mfma_f32_16x16x32_bf16 v[12:15], v[128:131], v[238:241], v[12:15]
	v_mfma_f32_16x16x32_bf16 v[8:11], v[136:139], v[238:241], v[8:11]
	v_mfma_f32_16x16x32_bf16 v[60:63], v[132:135], v[214:217], v[60:63]
	v_mfma_f32_16x16x32_bf16 v[56:59], v[140:143], v[214:217], v[56:59]
	v_mfma_f32_16x16x32_bf16 v[44:47], v[132:135], v[226:229], v[44:47]
	v_mfma_f32_16x16x32_bf16 v[40:43], v[140:143], v[226:229], v[40:43]
	v_mfma_f32_16x16x32_bf16 v[28:31], v[132:135], v[234:237], v[28:31]
	v_mfma_f32_16x16x32_bf16 v[24:27], v[140:143], v[234:237], v[24:27]
	v_mfma_f32_16x16x32_bf16 v[12:15], v[132:135], v[242:245], v[12:15]
	v_mfma_f32_16x16x32_bf16 v[8:11], v[140:143], v[242:245], v[8:11]
	v_mfma_f32_16x16x32_bf16 v[52:55], v[144:147], v[210:213], v[52:55]
	v_mfma_f32_16x16x32_bf16 v[48:51], v[152:155], v[210:213], v[48:51]
	v_mfma_f32_16x16x32_bf16 v[36:39], v[144:147], v[218:221], v[36:39]
	v_mfma_f32_16x16x32_bf16 v[32:35], v[152:155], v[218:221], v[32:35]
	v_mfma_f32_16x16x32_bf16 v[20:23], v[144:147], v[230:233], v[20:23]
	v_mfma_f32_16x16x32_bf16 v[16:19], v[152:155], v[230:233], v[16:19]
	v_mfma_f32_16x16x32_bf16 v[4:7], v[144:147], v[238:241], v[4:7]
	v_mfma_f32_16x16x32_bf16 v[0:3], v[152:155], v[238:241], v[0:3]
	v_mfma_f32_16x16x32_bf16 v[52:55], v[148:151], v[214:217], v[52:55]
	v_mfma_f32_16x16x32_bf16 v[48:51], v[156:159], v[214:217], v[48:51]
	v_mfma_f32_16x16x32_bf16 v[36:39], v[148:151], v[226:229], v[36:39]
	v_mfma_f32_16x16x32_bf16 v[32:35], v[156:159], v[226:229], v[32:35]
	v_mfma_f32_16x16x32_bf16 v[20:23], v[148:151], v[234:237], v[20:23]
	v_mfma_f32_16x16x32_bf16 v[16:19], v[156:159], v[234:237], v[16:19]
	v_mfma_f32_16x16x32_bf16 v[4:7], v[148:151], v[242:245], v[4:7]
	v_mfma_f32_16x16x32_bf16 v[0:3], v[156:159], v[242:245], v[0:3]
	s_waitcnt vmcnt(0)
	s_barrier
	s_setprio 0
	s_cmp_lg_u32 s24, 0
	s_cbranch_scc0 .Lspf8_b_h1
	s_add_i32 m0, s14, 0x10000
	ds_read_b128 v[128:131], v204
	ds_read_b128 v[132:135], v204 offset:1024
	ds_read_b128 v[136:139], v204 offset:2048
	global_load_lds_dwordx4 v176, s[36:37]
	s_add_i32 m0, s14, 0x12000
	ds_read_b128 v[140:143], v204 offset:3072
	ds_read_b128 v[144:147], v205
	ds_read_b128 v[148:151], v205 offset:1024
	global_load_lds_dwordx4 v178, s[36:37]
	s_add_u32 s98, s36, 0x58000
	s_addc_u32 s99, s37, 0
	s_add_i32 m0, s14, 0x11000
	ds_read_b128 v[152:155], v205 offset:2048
	ds_read_b128 v[156:159], v205 offset:3072
	ds_read_b128 v[160:163], v183 offset:32768
	global_load_lds_dwordx4 v176, s[98:99]
	s_add_i32 m0, s14, 0x13000
	ds_read_b128 v[164:167], v183 offset:33792
	ds_read_b128 v[168:171], v183 offset:34816
	ds_read_b128 v[172:175], v183 offset:35840
	global_load_lds_dwordx4 v178, s[98:99]
	s_add_u32 s98, s36, 0x160000
	s_addc_u32 s99, s37, 0
	s_add_i32 m0, s14, 0x14000
	ds_read_b128 v[188:191], v183 offset:36864
	ds_read_b128 v[192:195], v183 offset:37888
	ds_read_b128 v[196:199], v183 offset:38912
	global_load_lds_dwordx4 v176, s[98:99]
	s_add_i32 m0, s14, 0x16000
	ds_read_b128 v[200:203], v183 offset:39936
	ds_read_b128 v[210:213], v183 offset:49152
	ds_read_b128 v[214:217], v183 offset:50176
	global_load_lds_dwordx4 v178, s[98:99]
	s_add_u32 s98, s36, 0x1b8000
	s_addc_u32 s99, s37, 0
	s_add_i32 m0, s14, 0x15000
	ds_read_b128 v[218:221], v183 offset:51200
	ds_read_b128 v[226:229], v183 offset:52224
	ds_read_b128 v[230:233], v183 offset:53248
	global_load_lds_dwordx4 v176, s[98:99]
	s_add_i32 m0, s14, 0x17000
	ds_read_b128 v[234:237], v183 offset:54272
	ds_read_b128 v[238:241], v183 offset:55296
	ds_read_b128 v[242:245], v183 offset:56320
	global_load_lds_dwordx4 v178, s[98:99]
	s_branch .Lspf8_b_rd
; #define PG8_STAGE(bufoff, gbase, voff) do { _Pragma("unroll") for (int _i = 0; _i < 2; ++_i) \
;         __builtin_amdgcn_global_load_lds((const unsigned*)((const char*)(gbase) + (voff)[_i]), (PG8_LAS unsigned*)(lds + (bufoff) + ldsw + _i * 8192), 16, 0, 0); } while (0)
; #define PG8_LDA(dst, b, h) do { _Pragma("unroll") for (int m = 0; m < 4; ++m) _Pragma("unroll") for (int k = 0; k < 2; ++k) dst[m][k] = *(const PG8_LAS bf16x8*)(lds + PG8_SA(b, h) + aoff + m * 2048 + k * 1024); } while (0)
; #define PG8_LDB(dst, b, h) do { _Pragma("unroll") for (int n = 0; n < 2; ++n) _Pragma("unroll") for (int k = 0; k < 2; ++k) dst[n][k] = *(const PG8_LAS bf16x8*)(lds + PG8_SB(b, h) + boff + n * 2048 + k * 1024); } while (0)
; #define PG8_MMA(ai, bj, At, Bt) do { __builtin_amdgcn_s_setprio(1); _Pragma("unroll") for (int m = 0; m < 4; ++m) _Pragma("unroll") for (int n = 0; n < 2; ++n) _Pragma("unroll") for (int k = 0; k < 2; ++k) \
;         acc[ai][bj][m][n] = __builtin_amdgcn_mfma_f32_16x16x32_bf16(Bt[n][k], At[m][k], acc[ai][bj][m][n], 0, 0, 0); __builtin_amdgcn_s_setprio(0); } while (0)
; #define PG8_WAIT_V(n) asm volatile("s_waitcnt vmcnt(" #n ")" ::: "memory")
; #define PG8_WAIT_L(n) asm volatile("s_waitcnt lgkmcnt(" #n ")" ::: "memory")
; #define PG8_BAR __builtin_amdgcn_s_barrier()
; #define PG8_SCHED __builtin_amdgcn_sched_barrier(0)
; template <class Epi, class Sched, bool ALIGN_EPI = false, bool SP2 = false>
; __device__ __forceinline__ void gemm_phase(PG8_LAS unsigned char* lds, const Gemm g, const Sched& S, const Epi& E) {
;     ...
;         for (int t = 0; t < nt; t += 2) {
;             const bool last = (t == nt - 2);
;             const char* a1 = cA + (size_t)(t + 1) * kstep;
;             const char* a2 = last ? nA : cA + (size_t)(t + 2) * kstep; const char* b2 = last ? nB : cB + (size_t)(t + 2) * kstep;
;     ...
;             PG8_LDB(B0, 1, 0); PG8_LDB(B1, 1, 1); PG8_SCHED; PG8_LDA(At, 1, 0); PG8_STAGE(PG8_SA(0, 1), a2 + hstep, voffA);
;             PG8_WAIT_V(8); PG8_WAIT_L(0); PG8_BAR; PG8_MMA(0, 0, At, B0); PG8_MMA(0, 1, At, B1); PG8_BAR; PG8_SCHED;
;             PG8_LDA(At, 1, 1); PG8_STAGE(PG8_SB(1, 0), b3, voffB); PG8_STAGE(PG8_SB(1, 1), b3 + hstep, voffB); PG8_STAGE(PG8_SA(1, 0), a3, voffA);
;             PG8_WAIT_V(8); PG8_WAIT_L(0); PG8_BAR; PG8_MMA(1, 0, At, B0); PG8_MMA(1, 1, At, B1); PG8_BAR; PG8_SCHED;
.Lspf8_b_h1:
	s_add_i32 m0, s14, 0x2000
	ds_read_b128 v[128:131], v204
	ds_read_b128 v[132:135], v204 offset:1024
	ds_read_b128 v[136:139], v204 offset:2048
	global_load_lds_dwordx4 v178, s[40:41]
	s_add_u32 s98, s40, 0xfffa8000
	s_addc_u32 s99, s41, -1
	s_add_i32 m0, s14, 0x1000
	ds_read_b128 v[140:143], v204 offset:3072
	ds_read_b128 v[144:147], v205
	ds_read_b128 v[148:151], v205 offset:1024
	global_load_lds_dwordx4 v178, s[98:99]
	s_add_u32 s98, s40, 0x160000
	s_addc_u32 s99, s41, 0
	s_add_i32 m0, s14, 0x6000
	ds_read_b128 v[152:155], v205 offset:2048
	ds_read_b128 v[156:159], v205 offset:3072
	ds_read_b128 v[160:163], v183 offset:32768
	global_load_lds_dwordx4 v178, s[98:99]
	s_add_u32 s98, s40, 0x108000
	s_addc_u32 s99, s41, 0
	s_add_i32 m0, s14, 0x5000
	ds_read_b128 v[164:167], v183 offset:33792
	ds_read_b128 v[168:171], v183 offset:34816
	ds_read_b128 v[172:175], v183 offset:35840
	global_load_lds_dwordx4 v178, s[98:99]
	s_add_u32 s98, s40, 0x80
	s_addc_u32 s99, s41, 0
	s_add_i32 m0, s14, 0x8000
	ds_read_b128 v[188:191], v183 offset:36864
	ds_read_b128 v[192:195], v183 offset:37888
	ds_read_b128 v[196:199], v183 offset:38912
	global_load_lds_dwordx4 v176, s[98:99]
	s_add_u32 s98, s40, 0xfffa8080
	s_addc_u32 s99, s41, -1
	s_add_i32 m0, s14, 0x7000
	ds_read_b128 v[200:203], v183 offset:39936
	ds_read_b128 v[210:213], v183 offset:49152
	ds_read_b128 v[214:217], v183 offset:50176
	global_load_lds_dwordx4 v176, s[98:99]
	s_add_u32 s98, s40, 0x160080
	s_addc_u32 s99, s41, 0
	s_add_i32 m0, s14, 0xc000
	ds_read_b128 v[218:221], v183 offset:51200
	ds_read_b128 v[226:229], v183 offset:52224
	ds_read_b128 v[230:233], v183 offset:53248
	global_load_lds_dwordx4 v176, s[98:99]
	s_add_u32 s98, s40, 0x108080
	s_addc_u32 s99, s41, 0
	s_add_i32 m0, s14, 0xb000
	ds_read_b128 v[234:237], v183 offset:54272
	ds_read_b128 v[238:241], v183 offset:55296
	ds_read_b128 v[242:245], v183 offset:56320
	global_load_lds_dwordx4 v176, s[98:99]
.Lspf8_b_rd:
	s_waitcnt lgkmcnt(0)
	s_setprio 1
	s_barrier
	v_mfma_f32_16x16x32_bf16 v[124:127], v[128:131], v[160:163], v[124:127]
	v_mfma_f32_16x16x32_bf16 v[120:123], v[136:139], v[160:163], v[120:123]
	v_mfma_f32_16x16x32_bf16 v[108:111], v[128:131], v[168:171], v[108:111]
	v_mfma_f32_16x16x32_bf16 v[104:107], v[136:139], v[168:171], v[104:107]
	v_mfma_f32_16x16x32_bf16 v[92:95], v[128:131], v[188:191], v[92:95]
	v_mfma_f32_16x16x32_bf16 v[88:91], v[136:139], v[188:191], v[88:91]
	v_mfma_f32_16x16x32_bf16 v[76:79], v[128:131], v[196:199], v[76:79]
	v_mfma_f32_16x16x32_bf16 v[72:75], v[136:139], v[196:199], v[72:75]
	v_mfma_f32_16x16x32_bf16 v[124:127], v[132:135], v[164:167], v[124:127]
	v_mfma_f32_16x16x32_bf16 v[120:123], v[140:143], v[164:167], v[120:123]
	v_mfma_f32_16x16x32_bf16 v[108:111], v[132:135], v[172:175], v[108:111]
	v_mfma_f32_16x16x32_bf16 v[104:107], v[140:143], v[172:175], v[104:107]
	v_mfma_f32_16x16x32_bf16 v[92:95], v[132:135], v[192:195], v[92:95]
	v_mfma_f32_16x16x32_bf16 v[88:91], v[140:143], v[192:195], v[88:91]
	v_mfma_f32_16x16x32_bf16 v[76:79], v[132:135], v[200:203], v[76:79]
	v_mfma_f32_16x16x32_bf16 v[72:75], v[140:143], v[200:203], v[72:75]
	v_mfma_f32_16x16x32_bf16 v[116:119], v[144:147], v[160:163], v[116:119]
	v_mfma_f32_16x16x32_bf16 v[112:115], v[152:155], v[160:163], v[112:115]
	v_mfma_f32_16x16x32_bf16 v[100:103], v[144:147], v[168:171], v[100:103]
	v_mfma_f32_16x16x32_bf16 v[96:99], v[152:155], v[168:171], v[96:99]
	v_mfma_f32_16x16x32_bf16 v[84:87], v[144:147], v[188:191], v[84:87]
	v_mfma_f32_16x16x32_bf16 v[80:83], v[152:155], v[188:191], v[80:83]
	v_mfma_f32_16x16x32_bf16 v[68:71], v[144:147], v[196:199], v[68:71]
	v_mfma_f32_16x16x32_bf16 v[64:67], v[152:155], v[196:199], v[64:67]
	v_mfma_f32_16x16x32_bf16 v[116:119], v[148:151], v[164:167], v[116:119]
	v_mfma_f32_16x16x32_bf16 v[112:115], v[156:159], v[164:167], v[112:115]
	v_mfma_f32_16x16x32_bf16 v[100:103], v[148:151], v[172:175], v[100:103]
	v_mfma_f32_16x16x32_bf16 v[96:99], v[156:159], v[172:175], v[96:99]
	v_mfma_f32_16x16x32_bf16 v[84:87], v[148:151], v[192:195], v[84:87]
	v_mfma_f32_16x16x32_bf16 v[80:83], v[156:159], v[192:195], v[80:83]
	v_mfma_f32_16x16x32_bf16 v[68:71], v[148:151], v[200:203], v[68:71]
	v_mfma_f32_16x16x32_bf16 v[64:67], v[156:159], v[200:203], v[64:67]
	v_mfma_f32_16x16x32_bf16 v[60:63], v[128:131], v[210:213], v[60:63]
	v_mfma_f32_16x16x32_bf16 v[56:59], v[136:139], v[210:213], v[56:59]
	v_mfma_f32_16x16x32_bf16 v[44:47], v[128:131], v[218:221], v[44:47]
	v_mfma_f32_16x16x32_bf16 v[40:43], v[136:139], v[218:221], v[40:43]
	v_mfma_f32_16x16x32_bf16 v[28:31], v[128:131], v[230:233], v[28:31]
	v_mfma_f32_16x16x32_bf16 v[24:27], v[136:139], v[230:233], v[24:27]
	v_mfma_f32_16x16x32_bf16 v[12:15], v[128:131], v[238:241], v[12:15]
	v_mfma_f32_16x16x32_bf16 v[8:11], v[136:139], v[238:241], v[8:11]
	v_mfma_f32_16x16x32_bf16 v[60:63], v[132:135], v[214:217], v[60:63]
	v_mfma_f32_16x16x32_bf16 v[56:59], v[140:143], v[214:217], v[56:59]
	v_mfma_f32_16x16x32_bf16 v[44:47], v[132:135], v[226:229], v[44:47]
	v_mfma_f32_16x16x32_bf16 v[40:43], v[140:143], v[226:229], v[40:43]
	v_mfma_f32_16x16x32_bf16 v[28:31], v[132:135], v[234:237], v[28:31]
	v_mfma_f32_16x16x32_bf16 v[24:27], v[140:143], v[234:237], v[24:27]
	v_mfma_f32_16x16x32_bf16 v[12:15], v[132:135], v[242:245], v[12:15]
	v_mfma_f32_16x16x32_bf16 v[8:11], v[140:143], v[242:245], v[8:11]
	v_mfma_f32_16x16x32_bf16 v[52:55], v[144:147], v[210:213], v[52:55]
	v_mfma_f32_16x16x32_bf16 v[48:51], v[152:155], v[210:213], v[48:51]
	v_mfma_f32_16x16x32_bf16 v[36:39], v[144:147], v[218:221], v[36:39]
	v_mfma_f32_16x16x32_bf16 v[32:35], v[152:155], v[218:221], v[32:35]
	v_mfma_f32_16x16x32_bf16 v[20:23], v[144:147], v[230:233], v[20:23]
	v_mfma_f32_16x16x32_bf16 v[16:19], v[152:155], v[230:233], v[16:19]
	v_mfma_f32_16x16x32_bf16 v[4:7], v[144:147], v[238:241], v[4:7]
	v_mfma_f32_16x16x32_bf16 v[0:3], v[152:155], v[238:241], v[0:3]
	v_mfma_f32_16x16x32_bf16 v[52:55], v[148:151], v[214:217], v[52:55]
	v_mfma_f32_16x16x32_bf16 v[48:51], v[156:159], v[214:217], v[48:51]
	v_mfma_f32_16x16x32_bf16 v[36:39], v[148:151], v[226:229], v[36:39]
	v_mfma_f32_16x16x32_bf16 v[32:35], v[156:159], v[226:229], v[32:35]
	v_mfma_f32_16x16x32_bf16 v[20:23], v[148:151], v[234:237], v[20:23]
	v_mfma_f32_16x16x32_bf16 v[16:19], v[156:159], v[234:237], v[16:19]
	v_mfma_f32_16x16x32_bf16 v[4:7], v[148:151], v[242:245], v[4:7]
	v_mfma_f32_16x16x32_bf16 v[0:3], v[156:159], v[242:245], v[0:3]
	s_waitcnt vmcnt(0)
	s_barrier
	s_setprio 0
	s_add_i32 s50, s50, 2
	s_add_u32 s13, s13, 0x100
	s_addc_u32 s49, s49, 0
	s_cmpk_gt_u32 s50, 0x55
	s_mov_b64 s[28:29], s[30:31]
	s_cbranch_scc0 .LBB0_1108
	v_mov_b32_e32 v211, v183
	v_mov_b32_e32 v210, v181
	v_mov_b32_e32 v209, v179
	v_mov_b32_e32 v207, v177
	s_and_b64 vcc, exec, s[24:25]
	s_cbranch_vccz .LBB0_1111
	s_barrier
